# batched xs RMW epilogues (dn x2, m2) + 256x128 supertile gu
# speedup vs baseline: 1.0501x; 1.0501x over previous
; #define LAS __attribute__((address_space(3)))
; __global__ void __launch_bounds__(NTHR, 2) fwd_megakernel(Params p0) {
;   __shared__ __attribute__((aligned(16))) char lds[65536];
;   cg::grid_group grid = cg::this_grid();
;   __shared__ uint4 xb_words;
;   if (threadIdx.x == 0) xb_words = make_uint4(0u, 0u, 0u, 0u);
;   __syncthreads();
;   const XcdBarrier xb = xcd_barrier_post((unsigned*)(p0.ws + OFF_BAR), (volatile LAS unsigned*)&xb_words);
_Z14fwd_megakernel6Params:
	v_mov_b32_e32 v245, 0
	s_add_u32 s6, s0, 0x100
	v_and_b32_e32 v178, 0x3ff, v0
	s_mov_b32 s96, s2
	v_writelane_b32 v244, s0, 0
	s_addc_u32 s7, s1, 0
	v_cmp_ne_u32_e64 s[72:73], 0, v178
	v_cmp_eq_u32_e64 s[90:91], 0, v178
	v_writelane_b32 v244, s1, 1
	s_and_saveexec_b64 s[2:3], s[90:91]
	s_cbranch_execz .LBB0_2
	v_mov_b32_e32 v2, 0
	v_mov_b32_e32 v3, v2
	v_mov_b32_e32 v4, v2
	v_mov_b32_e32 v5, v2
	v_mov_b32_e32 v1, 0x10000
	ds_write_b128 v1, v[2:5]

; #define MFMA(a, b, c) __builtin_amdgcn_mfma_f32_32x32x16_bf16((a), (b), (c), 0, 0, 0)
; #define TIDX opaque_tid()
; #define GAS __attribute__((address_space(1)))
; DI int opaque0() { int z = 0; asm volatile("" : "+v"(z)); return z; }
; template <int AI, int BI>
; DI void gemm_tile(const u16* __restrict__ A, int lda, const u16* __restrict__ B, int ldb, int nk, bool swap,
;                   f32x16 (&acc)[AI][BI], char* lds) {
;   const int tid = TIDX, lane = tid & 63, wid = tid >> 6;
;   gemm_stage<AI, BI>(A, lda, B, ldb, lds, tid);
;   asm volatile("s_waitcnt vmcnt(0)" ::: "memory");
;   __syncthreads();
;   const int wa = wid >> 1, wb = wid & 1, r = lane & 31, h = lane >> 5, sw = (r >> 1) & 7;
;   const int offA = (swap ? 16384 : 0) + (wa * 32 * AI + r) * 128;
;   const int offB = (swap ? 0 : 16384) + (wb * 32 * BI + r) * 128;
;   for (int kt = 0; kt < nk; ++kt) {
;     const char* cur = lds + (kt & 1) * 32768;
;     if (kt + 1 < nk) gemm_stage<AI, BI>(A + (kt + 1) * 64, lda, B + (kt + 1) * 64, ldb, lds + ((kt + 1) & 1) * 32768, tid);
; #pragma unroll
;     for (int ks = 0; ks < 4; ++ks) {
;       const int co = ((ks * 2 + h) ^ sw) << 4;
;       s16x8 fa[AI], fb[BI];
; #pragma unroll
;       for (int i = 0; i < AI; ++i) fa[i] = *(const s16x8*)(cur + offA + i * 4096 + co);
; #pragma unroll
;       for (int i = 0; i < BI; ++i) fb[i] = *(const s16x8*)(cur + offB + i * 4096 + co);
; #pragma unroll
;       for (int i = 0; i < AI; ++i)
; #pragma unroll
;         for (int j = 0; j < BI; ++j) acc[i][j] = MFMA(fa[i], fb[j], acc[i][j]);
; template <int AI>
; DI void gu_tile(char* wsb, int sub, int m0, int n0, char* lds) {
;   const u16* H = (const u16*)(wsb + OFF_H);
;   const u16* W = (const u16*)(wsb + OFF_W) + (sub ? W_GU1 : W_GU0);
;   u16* HID = (u16*)(wsb + OFF_HID);
;   const int lane = TIDX & 63, wid = TIDX >> 6, wa = wid >> 1, wb = wid & 1, r = lane & 31, h = lane >> 5;
;   f32x16 acc[AI][2]; zero_acc<AI, 2>(acc);
;   gemm_tile<AI, 2>(H + (size_t)m0 * 1024, 1024, W + (size_t)n0 * 1024, 1024, 16, false, acc, lds);
;   const int m0e = m0 + opaque0();
;   const int hc = (n0 >> 1) + wb * 32 + r;
;   GAS u16* HIDu = uptr(HID);
;   const unsigned ib = (unsigned)((m0e + wa * 32 * AI + 4 * h) * 2816 + hc);
.LBB0_417:
	s_or_b64 exec, exec, s[6:7]
	s_mov_b32 s6, s19
	s_mov_b64 s[8:9], s[20:21]
	s_waitcnt lgkmcnt(0)
	s_barrier
	s_mov_b64 s[14:15], s[26:27]
	s_add_u32 s8, s14, s6
	v_readlane_b32 s6, v244, 48
	v_readlane_b32 s7, v244, 49
	s_mov_b64 s[10:11], s[22:23]
	s_addc_u32 s9, s15, 0
	v_cndmask_b32_e64 v0, 0, 1, s[6:7]
	v_cmp_ne_u32_e64 s[10:11], 1, v0
	s_andn2_b64 vcc, exec, s[6:7]
	s_mov_b64 s[12:13], s[24:25]
	v_writelane_b32 v242, s10, 3
	s_nop 1
	v_writelane_b32 v242, s11, 4
	s_cbranch_vccnz .LBB0_421
	s_add_u32 s10, s8, 0x77b7000
	s_addc_u32 s11, s9, 0
	s_add_u32 s12, s8, 0x1c4b7000
	s_addc_u32 s13, s9, 0
	s_add_u32 s6, s8, 0x9bb7000
	s_addc_u32 s7, s9, 0
	v_readlane_b32 s14, v243, 18
	v_readlane_b32 s15, v243, 5
	v_readlane_b32 s53, v243, 7
	s_mov_b32 s54, 0x1ffffc0
	s_mov_b64 s[70:71], 0x300
	s_mov_b64 s[72:73], 0x380
	s_mov_b64 s[74:75], 0x400
	s_mov_b64 s[76:77], 0x480
	s_mov_b64 s[80:81], 0x500
	s_mov_b64 s[82:83], 0x580
	s_mov_b64 s[84:85], 0x600
	s_mov_b64 s[56:57], 0x200
	s_mov_b64 s[64:65], 0x80
	s_mov_b64 s[66:67], 0x180
	s_mov_b64 s[68:69], 0x280
	s_cmpk_lg_u32 s92, 0x200
	s_cbranch_scc1 .LBB0_419
	v_and_b32_e32 v0, 31, v178
	v_bfe_u32 v122, v178, 5, 1
	v_bfe_u32 v123, v178, 2, 2
	v_xor_b32_e32 v122, v122, v123
	v_lshlrev_b32_e32 v122, 4, v122
	v_bfe_u32 v123, v178, 7, 1
	v_lshl_add_u32 v123, v123, 6, v0
	v_lshl_add_u32 v142, v123, 6, v122
	v_xor_b32_e32 v143, 32, v142
	v_bfe_u32 v123, v178, 6, 1
	v_lshl_add_u32 v123, v123, 6, v0
	v_lshl_add_u32 v144, v123, 6, v122
	v_add_u32_e32 v144, 0xc000, v144
	v_xor_b32_e32 v145, 32, v144
	v_bfe_u32 v122, v178, 7, 1
	v_lshlrev_b32_e32 v122, 6, v122
	v_bfe_u32 v123, v178, 5, 1
	v_lshl_add_u32 v122, v123, 2, v122
	v_mul_u32_u24_e32 v122, 0xb00, v122
	v_bfe_u32 v123, v178, 6, 1
	v_lshl_add_u32 v123, v123, 5, v0
	v_add_u32_e32 v122, v122, v123
	v_lshlrev_b32_e32 v124, 1, v122
	v_lshrrev_b32_e32 v0, 2, v178
	v_bfe_u32 v122, v178, 4, 2
	v_and_b32_e32 v123, 3, v178
	v_xor_b32_e32 v122, v122, v123
	v_lshlrev_b32_e32 v122, 4, v122
	v_lshl_add_u32 v126, v0, 11, v122
	v_add_u32_e32 v127, 0x20000, v126
	v_add_u32_e32 v128, 0x40000, v126
	v_add_u32_e32 v129, 0x60000, v126
	v_lshrrev_b32_e32 v0, 6, v178
	s_nop 1
	v_readfirstlane_b32 s18, v0
	s_lshl_b32 s18, s18, 10
	s_and_b32 s41, s96, 7
	s_lshr_b32 s40, s96, 3
	s_mov_b32 s32, 0
.Lgu1_round:
	s_lshr_b32 s37, s40, 3
	s_lshl_b32 s50, s32, 3
	s_add_u32 s37, s37, s50
	s_and_b32 s50, s40, 7
	s_lshl_b32 s51, s41, 3
	s_add_u32 s50, s50, s51
	s_lshl_b32 s51, s50, 19
	s_add_u32 s16, s10, s51
	s_addc_u32 s17, s11, 0
	s_lshl_b32 s51, s37, 18
	s_add_u32 s28, s12, s51
	s_addc_u32 s29, s13, 0
	s_mul_i32 s51, s50, 0x160000
	s_lshl_b32 s52, s37, 7
	s_add_u32 s51, s51, s52
	s_add_u32 s34, s6, s51
	s_addc_u32 s35, s7, 0
	s_add_u32 m0, s18, 0
	s_nop 0
	global_load_lds_dwordx4 v126, s[16:17]
	s_add_u32 m0, s18, 4096
	s_nop 0
	global_load_lds_dwordx4 v127, s[16:17]
	s_add_u32 m0, s18, 8192
	s_nop 0
	global_load_lds_dwordx4 v128, s[16:17]
	s_add_u32 m0, s18, 12288
	s_nop 0
	global_load_lds_dwordx4 v129, s[16:17]
	s_add_u32 m0, s18, 49152
	s_nop 0
	global_load_lds_dwordx4 v126, s[28:29]
	s_add_u32 m0, s18, 53248
	s_nop 0
	global_load_lds_dwordx4 v127, s[28:29]
	s_add_u32 s16, s16, 64
	s_addc_u32 s17, s17, 0
	s_add_u32 s28, s28, 64
	s_addc_u32 s29, s29, 0
	s_add_u32 m0, s18, 16384
	s_nop 0
	global_load_lds_dwordx4 v126, s[16:17]
	s_add_u32 m0, s18, 20480
	s_nop 0
	global_load_lds_dwordx4 v127, s[16:17]
	s_add_u32 m0, s18, 24576
	s_nop 0
	global_load_lds_dwordx4 v128, s[16:17]
	s_add_u32 m0, s18, 28672
	s_nop 0
	global_load_lds_dwordx4 v129, s[16:17]
	s_add_u32 m0, s18, 57344
	s_nop 0
	global_load_lds_dwordx4 v126, s[28:29]
	s_add_u32 m0, s18, 61440
	s_nop 0
	global_load_lds_dwordx4 v127, s[28:29]
	s_add_u32 s16, s16, 64
	s_addc_u32 s17, s17, 0
	s_add_u32 s28, s28, 64
	s_addc_u32 s29, s29, 0
	s_waitcnt vmcnt(6)
	s_barrier
	ds_read_b128 v[114:117], v142 offset:0
	ds_read_b128 v[230:233], v144 offset:0
	ds_read_b128 v[234:237], v144 offset:2048
	ds_read_b128 v[118:121], v142 offset:2048
	ds_read_b128 v[134:137], v142 offset:8192
	ds_read_b128 v[138:141], v142 offset:10240
	ds_read_b128 v[238:241], v145 offset:0
	ds_read_b128 v[246:249], v145 offset:2048
	s_add_u32 m0, s18, 32768
	s_nop 0
	global_load_lds_dwordx4 v126, s[16:17]
	s_add_u32 m0, s18, 36864
	s_nop 0
	global_load_lds_dwordx4 v127, s[16:17]
	s_add_u32 m0, s18, 40960
	s_nop 0
	global_load_lds_dwordx4 v128, s[16:17]
	s_add_u32 m0, s18, 45056
	s_nop 0
	global_load_lds_dwordx4 v129, s[16:17]
	s_add_u32 m0, s18, 65664
	s_nop 0
	global_load_lds_dwordx4 v126, s[28:29]
	s_add_u32 m0, s18, 69760
	s_nop 0
	global_load_lds_dwordx4 v127, s[28:29]
	s_add_u32 s16, s16, 64
	s_addc_u32 s17, s17, 0
	s_add_u32 s28, s28, 64
	s_addc_u32 s29, s29, 0
	s_waitcnt lgkmcnt(6)
	v_mfma_f32_32x32x16_bf16 v[2:17], v[114:117], v[230:233], 0
	s_waitcnt lgkmcnt(5)
	v_mfma_f32_32x32x16_bf16 v[18:33], v[114:117], v[234:237], 0
	ds_read_b128 v[114:117], v143 offset:0
	s_waitcnt lgkmcnt(5)
	v_mfma_f32_32x32x16_bf16 v[34:49], v[118:121], v[230:233], 0
	v_mfma_f32_32x32x16_bf16 v[50:65], v[118:121], v[234:237], 0
	ds_read_b128 v[118:121], v143 offset:2048
	s_waitcnt lgkmcnt(5)
	v_mfma_f32_32x32x16_bf16 v[66:81], v[134:137], v[230:233], 0
	v_mfma_f32_32x32x16_bf16 v[82:97], v[134:137], v[234:237], 0
	ds_read_b128 v[134:137], v143 offset:8192
	s_waitcnt lgkmcnt(5)
	v_mfma_f32_32x32x16_bf16 v[98:113], v[138:141], v[230:233], 0
	v_mfma_f32_32x32x16_bf16 v[214:229], v[138:141], v[234:237], 0
	ds_read_b128 v[138:141], v143 offset:10240
	s_waitcnt lgkmcnt(3)
	v_mfma_f32_32x32x16_bf16 v[2:17], v[114:117], v[238:241], v[2:17]
	v_mfma_f32_32x32x16_bf16 v[18:33], v[114:117], v[246:249], v[18:33]
	s_waitcnt lgkmcnt(2)
	v_mfma_f32_32x32x16_bf16 v[34:49], v[118:121], v[238:241], v[34:49]
	v_mfma_f32_32x32x16_bf16 v[50:65], v[118:121], v[246:249], v[50:65]
	s_waitcnt lgkmcnt(1)
	v_mfma_f32_32x32x16_bf16 v[66:81], v[134:137], v[238:241], v[66:81]
	v_mfma_f32_32x32x16_bf16 v[82:97], v[134:137], v[246:249], v[82:97]
	s_waitcnt lgkmcnt(0)
	v_mfma_f32_32x32x16_bf16 v[98:113], v[138:141], v[238:241], v[98:113]
	v_mfma_f32_32x32x16_bf16 v[214:229], v[138:141], v[246:249], v[214:229]
	s_waitcnt vmcnt(6)
	s_barrier
; #define MFMA(a, b, c) __builtin_amdgcn_mfma_f32_32x32x16_bf16((a), (b), (c), 0, 0, 0)
; template <int AI, int BI>
; DI void gemm_tile(const u16* __restrict__ A, int lda, const u16* __restrict__ B, int ldb, int nk, bool swap,
;                   f32x16 (&acc)[AI][BI], char* lds) {
;     ...
;   for (int kt = 0; kt < nk; ++kt) {
;     const char* cur = lds + (kt & 1) * 32768;
;     if (kt + 1 < nk) gemm_stage<AI, BI>(A + (kt + 1) * 64, lda, B + (kt + 1) * 64, ldb, lds + ((kt + 1) & 1) * 32768, tid);
; #pragma unroll
;     for (int ks = 0; ks < 4; ++ks) {
;       const int co = ((ks * 2 + h) ^ sw) << 4;
;       s16x8 fa[AI], fb[BI];
; #pragma unroll
;       for (int i = 0; i < AI; ++i) fa[i] = *(const s16x8*)(cur + offA + i * 4096 + co);
; #pragma unroll
;       for (int i = 0; i < BI; ++i) fb[i] = *(const s16x8*)(cur + offB + i * 4096 + co);
; #pragma unroll
;       for (int i = 0; i < AI; ++i)
; #pragma unroll
;         for (int j = 0; j < BI; ++j) acc[i][j] = MFMA(fa[i], fb[j], acc[i][j]);
;     }
;     asm volatile("s_waitcnt vmcnt(0)" ::: "memory");
;     __syncthreads();
;   }
	ds_read_b128 v[114:117], v142 offset:16384
	ds_read_b128 v[230:233], v144 offset:8192
	ds_read_b128 v[234:237], v144 offset:10240
	ds_read_b128 v[118:121], v142 offset:18432
	ds_read_b128 v[134:137], v142 offset:24576
	ds_read_b128 v[138:141], v142 offset:26624
	ds_read_b128 v[238:241], v145 offset:8192
	ds_read_b128 v[246:249], v145 offset:10240
	s_add_u32 m0, s18, 0
	s_nop 0
	global_load_lds_dwordx4 v126, s[16:17]
	s_add_u32 m0, s18, 4096
	s_nop 0
	global_load_lds_dwordx4 v127, s[16:17]
	s_add_u32 m0, s18, 8192
	s_nop 0
	global_load_lds_dwordx4 v128, s[16:17]
	s_add_u32 m0, s18, 12288
	s_nop 0
	global_load_lds_dwordx4 v129, s[16:17]
	s_add_u32 m0, s18, 49152
	s_nop 0
	global_load_lds_dwordx4 v126, s[28:29]
	s_add_u32 m0, s18, 53248
	s_nop 0
	global_load_lds_dwordx4 v127, s[28:29]
	s_add_u32 s16, s16, 64
	s_addc_u32 s17, s17, 0
	s_add_u32 s28, s28, 64
	s_addc_u32 s29, s29, 0
	s_waitcnt lgkmcnt(6)
	v_mfma_f32_32x32x16_bf16 v[2:17], v[114:117], v[230:233], v[2:17]
	s_waitcnt lgkmcnt(5)
	v_mfma_f32_32x32x16_bf16 v[18:33], v[114:117], v[234:237], v[18:33]
	ds_read_b128 v[114:117], v143 offset:16384
	s_waitcnt lgkmcnt(5)
	v_mfma_f32_32x32x16_bf16 v[34:49], v[118:121], v[230:233], v[34:49]
	v_mfma_f32_32x32x16_bf16 v[50:65], v[118:121], v[234:237], v[50:65]
	ds_read_b128 v[118:121], v143 offset:18432
	s_waitcnt lgkmcnt(5)
	v_mfma_f32_32x32x16_bf16 v[66:81], v[134:137], v[230:233], v[66:81]
	v_mfma_f32_32x32x16_bf16 v[82:97], v[134:137], v[234:237], v[82:97]
	ds_read_b128 v[134:137], v143 offset:24576
	s_waitcnt lgkmcnt(5)
	v_mfma_f32_32x32x16_bf16 v[98:113], v[138:141], v[230:233], v[98:113]
	v_mfma_f32_32x32x16_bf16 v[214:229], v[138:141], v[234:237], v[214:229]
	ds_read_b128 v[138:141], v143 offset:26624
	s_waitcnt lgkmcnt(3)
	v_mfma_f32_32x32x16_bf16 v[2:17], v[114:117], v[238:241], v[2:17]
	v_mfma_f32_32x32x16_bf16 v[18:33], v[114:117], v[246:249], v[18:33]
	s_waitcnt lgkmcnt(2)
	v_mfma_f32_32x32x16_bf16 v[34:49], v[118:121], v[238:241], v[34:49]
	v_mfma_f32_32x32x16_bf16 v[50:65], v[118:121], v[246:249], v[50:65]
	s_waitcnt lgkmcnt(1)
	v_mfma_f32_32x32x16_bf16 v[66:81], v[134:137], v[238:241], v[66:81]
	v_mfma_f32_32x32x16_bf16 v[82:97], v[134:137], v[246:249], v[82:97]
	s_waitcnt lgkmcnt(0)
	v_mfma_f32_32x32x16_bf16 v[98:113], v[138:141], v[238:241], v[98:113]
	v_mfma_f32_32x32x16_bf16 v[214:229], v[138:141], v[246:249], v[214:229]
	s_waitcnt vmcnt(6)
	s_barrier
	ds_read_b128 v[114:117], v142 offset:32768
	ds_read_b128 v[230:233], v144 offset:16512
	ds_read_b128 v[234:237], v144 offset:18560
	ds_read_b128 v[118:121], v142 offset:34816
	ds_read_b128 v[134:137], v142 offset:40960
	ds_read_b128 v[138:141], v142 offset:43008
	ds_read_b128 v[238:241], v145 offset:16512
	ds_read_b128 v[246:249], v145 offset:18560
	s_add_u32 m0, s18, 16384
	s_nop 0
	global_load_lds_dwordx4 v126, s[16:17]
	s_add_u32 m0, s18, 20480
	s_nop 0
	global_load_lds_dwordx4 v127, s[16:17]
	s_add_u32 m0, s18, 24576
	s_nop 0
	global_load_lds_dwordx4 v128, s[16:17]
	s_add_u32 m0, s18, 28672
	s_nop 0
	global_load_lds_dwordx4 v129, s[16:17]
	s_add_u32 m0, s18, 57344
	s_nop 0
	global_load_lds_dwordx4 v126, s[28:29]
	s_add_u32 m0, s18, 61440
	s_nop 0
	global_load_lds_dwordx4 v127, s[28:29]
	s_add_u32 s16, s16, 64
	s_addc_u32 s17, s17, 0
	s_add_u32 s28, s28, 64
	s_addc_u32 s29, s29, 0
	s_waitcnt lgkmcnt(6)
	v_mfma_f32_32x32x16_bf16 v[2:17], v[114:117], v[230:233], v[2:17]
	s_waitcnt lgkmcnt(5)
	v_mfma_f32_32x32x16_bf16 v[18:33], v[114:117], v[234:237], v[18:33]
	ds_read_b128 v[114:117], v143 offset:32768
	s_waitcnt lgkmcnt(5)
	v_mfma_f32_32x32x16_bf16 v[34:49], v[118:121], v[230:233], v[34:49]
	v_mfma_f32_32x32x16_bf16 v[50:65], v[118:121], v[234:237], v[50:65]
	ds_read_b128 v[118:121], v143 offset:34816
	s_waitcnt lgkmcnt(5)
	v_mfma_f32_32x32x16_bf16 v[66:81], v[134:137], v[230:233], v[66:81]
	v_mfma_f32_32x32x16_bf16 v[82:97], v[134:137], v[234:237], v[82:97]
	ds_read_b128 v[134:137], v143 offset:40960
	s_waitcnt lgkmcnt(5)
	v_mfma_f32_32x32x16_bf16 v[98:113], v[138:141], v[230:233], v[98:113]
	v_mfma_f32_32x32x16_bf16 v[214:229], v[138:141], v[234:237], v[214:229]
	ds_read_b128 v[138:141], v143 offset:43008
	s_waitcnt lgkmcnt(3)
	v_mfma_f32_32x32x16_bf16 v[2:17], v[114:117], v[238:241], v[2:17]
	v_mfma_f32_32x32x16_bf16 v[18:33], v[114:117], v[246:249], v[18:33]
	s_waitcnt lgkmcnt(2)
	v_mfma_f32_32x32x16_bf16 v[34:49], v[118:121], v[238:241], v[34:49]
	v_mfma_f32_32x32x16_bf16 v[50:65], v[118:121], v[246:249], v[50:65]
	s_waitcnt lgkmcnt(1)
	v_mfma_f32_32x32x16_bf16 v[66:81], v[134:137], v[238:241], v[66:81]
	v_mfma_f32_32x32x16_bf16 v[82:97], v[134:137], v[246:249], v[82:97]
	s_waitcnt lgkmcnt(0)
	v_mfma_f32_32x32x16_bf16 v[98:113], v[138:141], v[238:241], v[98:113]
	v_mfma_f32_32x32x16_bf16 v[214:229], v[138:141], v[246:249], v[214:229]
	s_mov_b32 s36, 9
; #define MFMA(a, b, c) __builtin_amdgcn_mfma_f32_32x32x16_bf16((a), (b), (c), 0, 0, 0)
; template <int AI, int BI>
; DI void gemm_tile(const u16* __restrict__ A, int lda, const u16* __restrict__ B, int ldb, int nk, bool swap,
;                   f32x16 (&acc)[AI][BI], char* lds) {
;     ...
;   for (int kt = 0; kt < nk; ++kt) {
;     const char* cur = lds + (kt & 1) * 32768;
;     if (kt + 1 < nk) gemm_stage<AI, BI>(A + (kt + 1) * 64, lda, B + (kt + 1) * 64, ldb, lds + ((kt + 1) & 1) * 32768, tid);
; #pragma unroll
;     for (int ks = 0; ks < 4; ++ks) {
;       const int co = ((ks * 2 + h) ^ sw) << 4;
;       s16x8 fa[AI], fb[BI];
; #pragma unroll
;       for (int i = 0; i < AI; ++i) fa[i] = *(const s16x8*)(cur + offA + i * 4096 + co);
; #pragma unroll
;       for (int i = 0; i < BI; ++i) fb[i] = *(const s16x8*)(cur + offB + i * 4096 + co);
; #pragma unroll
;       for (int i = 0; i < AI; ++i)
; #pragma unroll
;         for (int j = 0; j < BI; ++j) acc[i][j] = MFMA(fa[i], fb[j], acc[i][j]);
;     }
;     asm volatile("s_waitcnt vmcnt(0)" ::: "memory");
;     __syncthreads();
;   }
.Lgu1_kloop:
	s_waitcnt vmcnt(6)
	s_barrier
	ds_read_b128 v[114:117], v142 offset:0
	ds_read_b128 v[230:233], v144 offset:0
	ds_read_b128 v[234:237], v144 offset:2048
	ds_read_b128 v[118:121], v142 offset:2048
	ds_read_b128 v[134:137], v142 offset:8192
	ds_read_b128 v[138:141], v142 offset:10240
	ds_read_b128 v[238:241], v145 offset:0
	ds_read_b128 v[246:249], v145 offset:2048
	s_add_u32 m0, s18, 32768
	s_nop 0
	global_load_lds_dwordx4 v126, s[16:17]
	s_add_u32 m0, s18, 36864
	s_nop 0
	global_load_lds_dwordx4 v127, s[16:17]
	s_add_u32 m0, s18, 40960
	s_nop 0
	global_load_lds_dwordx4 v128, s[16:17]
	s_add_u32 m0, s18, 45056
	s_nop 0
	global_load_lds_dwordx4 v129, s[16:17]
	s_add_u32 m0, s18, 65664
	s_nop 0
	global_load_lds_dwordx4 v126, s[28:29]
	s_add_u32 m0, s18, 69760
	s_nop 0
	global_load_lds_dwordx4 v127, s[28:29]
	s_add_u32 s16, s16, 64
	s_addc_u32 s17, s17, 0
	s_add_u32 s28, s28, 64
	s_addc_u32 s29, s29, 0
	s_waitcnt lgkmcnt(6)
	v_mfma_f32_32x32x16_bf16 v[2:17], v[114:117], v[230:233], v[2:17]
	s_waitcnt lgkmcnt(5)
	v_mfma_f32_32x32x16_bf16 v[18:33], v[114:117], v[234:237], v[18:33]
	ds_read_b128 v[114:117], v143 offset:0
	s_waitcnt lgkmcnt(5)
	v_mfma_f32_32x32x16_bf16 v[34:49], v[118:121], v[230:233], v[34:49]
	v_mfma_f32_32x32x16_bf16 v[50:65], v[118:121], v[234:237], v[50:65]
	ds_read_b128 v[118:121], v143 offset:2048
	s_waitcnt lgkmcnt(5)
	v_mfma_f32_32x32x16_bf16 v[66:81], v[134:137], v[230:233], v[66:81]
	v_mfma_f32_32x32x16_bf16 v[82:97], v[134:137], v[234:237], v[82:97]
	ds_read_b128 v[134:137], v143 offset:8192
	s_waitcnt lgkmcnt(5)
	v_mfma_f32_32x32x16_bf16 v[98:113], v[138:141], v[230:233], v[98:113]
	v_mfma_f32_32x32x16_bf16 v[214:229], v[138:141], v[234:237], v[214:229]
	ds_read_b128 v[138:141], v143 offset:10240
	s_waitcnt lgkmcnt(3)
	v_mfma_f32_32x32x16_bf16 v[2:17], v[114:117], v[238:241], v[2:17]
	v_mfma_f32_32x32x16_bf16 v[18:33], v[114:117], v[246:249], v[18:33]
	s_waitcnt lgkmcnt(2)
	v_mfma_f32_32x32x16_bf16 v[34:49], v[118:121], v[238:241], v[34:49]
	v_mfma_f32_32x32x16_bf16 v[50:65], v[118:121], v[246:249], v[50:65]
	s_waitcnt lgkmcnt(1)
	v_mfma_f32_32x32x16_bf16 v[66:81], v[134:137], v[238:241], v[66:81]
	v_mfma_f32_32x32x16_bf16 v[82:97], v[134:137], v[246:249], v[82:97]
	s_waitcnt lgkmcnt(0)
	v_mfma_f32_32x32x16_bf16 v[98:113], v[138:141], v[238:241], v[98:113]
	v_mfma_f32_32x32x16_bf16 v[214:229], v[138:141], v[246:249], v[214:229]
	s_waitcnt vmcnt(6)
	s_barrier
	ds_read_b128 v[114:117], v142 offset:16384
	ds_read_b128 v[230:233], v144 offset:8192
	ds_read_b128 v[234:237], v144 offset:10240
	ds_read_b128 v[118:121], v142 offset:18432
	ds_read_b128 v[134:137], v142 offset:24576
	ds_read_b128 v[138:141], v142 offset:26624
	ds_read_b128 v[238:241], v145 offset:8192
	ds_read_b128 v[246:249], v145 offset:10240
	s_add_u32 m0, s18, 0
	s_nop 0
	global_load_lds_dwordx4 v126, s[16:17]
	s_add_u32 m0, s18, 4096
	s_nop 0
	global_load_lds_dwordx4 v127, s[16:17]
	s_add_u32 m0, s18, 8192
	s_nop 0
	global_load_lds_dwordx4 v128, s[16:17]
	s_add_u32 m0, s18, 12288
	s_nop 0
	global_load_lds_dwordx4 v129, s[16:17]
	s_add_u32 m0, s18, 49152
	s_nop 0
	global_load_lds_dwordx4 v126, s[28:29]
	s_add_u32 m0, s18, 53248
	s_nop 0
	global_load_lds_dwordx4 v127, s[28:29]
	s_add_u32 s16, s16, 64
	s_addc_u32 s17, s17, 0
	s_add_u32 s28, s28, 64
	s_addc_u32 s29, s29, 0
	s_waitcnt lgkmcnt(6)
	v_mfma_f32_32x32x16_bf16 v[2:17], v[114:117], v[230:233], v[2:17]
	s_waitcnt lgkmcnt(5)
	v_mfma_f32_32x32x16_bf16 v[18:33], v[114:117], v[234:237], v[18:33]
	ds_read_b128 v[114:117], v143 offset:16384
	s_waitcnt lgkmcnt(5)
	v_mfma_f32_32x32x16_bf16 v[34:49], v[118:121], v[230:233], v[34:49]
	v_mfma_f32_32x32x16_bf16 v[50:65], v[118:121], v[234:237], v[50:65]
	ds_read_b128 v[118:121], v143 offset:18432
	s_waitcnt lgkmcnt(5)
	v_mfma_f32_32x32x16_bf16 v[66:81], v[134:137], v[230:233], v[66:81]
	v_mfma_f32_32x32x16_bf16 v[82:97], v[134:137], v[234:237], v[82:97]
	ds_read_b128 v[134:137], v143 offset:24576
	s_waitcnt lgkmcnt(5)
	v_mfma_f32_32x32x16_bf16 v[98:113], v[138:141], v[230:233], v[98:113]
	v_mfma_f32_32x32x16_bf16 v[214:229], v[138:141], v[234:237], v[214:229]
	ds_read_b128 v[138:141], v143 offset:26624
	s_waitcnt lgkmcnt(3)
	v_mfma_f32_32x32x16_bf16 v[2:17], v[114:117], v[238:241], v[2:17]
	v_mfma_f32_32x32x16_bf16 v[18:33], v[114:117], v[246:249], v[18:33]
	s_waitcnt lgkmcnt(2)
	v_mfma_f32_32x32x16_bf16 v[34:49], v[118:121], v[238:241], v[34:49]
	v_mfma_f32_32x32x16_bf16 v[50:65], v[118:121], v[246:249], v[50:65]
	s_waitcnt lgkmcnt(1)
	v_mfma_f32_32x32x16_bf16 v[66:81], v[134:137], v[238:241], v[66:81]
	v_mfma_f32_32x32x16_bf16 v[82:97], v[134:137], v[246:249], v[82:97]
	s_waitcnt lgkmcnt(0)
	v_mfma_f32_32x32x16_bf16 v[98:113], v[138:141], v[238:241], v[98:113]
	v_mfma_f32_32x32x16_bf16 v[214:229], v[138:141], v[246:249], v[214:229]
	s_waitcnt vmcnt(6)
	s_barrier
; #define MFMA(a, b, c) __builtin_amdgcn_mfma_f32_32x32x16_bf16((a), (b), (c), 0, 0, 0)
; template <int AI, int BI>
; DI void gemm_tile(const u16* __restrict__ A, int lda, const u16* __restrict__ B, int ldb, int nk, bool swap,
;                   f32x16 (&acc)[AI][BI], char* lds) {
;     ...
;   for (int kt = 0; kt < nk; ++kt) {
;     const char* cur = lds + (kt & 1) * 32768;
;     if (kt + 1 < nk) gemm_stage<AI, BI>(A + (kt + 1) * 64, lda, B + (kt + 1) * 64, ldb, lds + ((kt + 1) & 1) * 32768, tid);
; #pragma unroll
;     for (int ks = 0; ks < 4; ++ks) {
;       const int co = ((ks * 2 + h) ^ sw) << 4;
;       s16x8 fa[AI], fb[BI];
; #pragma unroll
;       for (int i = 0; i < AI; ++i) fa[i] = *(const s16x8*)(cur + offA + i * 4096 + co);
; #pragma unroll
;       for (int i = 0; i < BI; ++i) fb[i] = *(const s16x8*)(cur + offB + i * 4096 + co);
; #pragma unroll
;       for (int i = 0; i < AI; ++i)
; #pragma unroll
;         for (int j = 0; j < BI; ++j) acc[i][j] = MFMA(fa[i], fb[j], acc[i][j]);
;     }
;     asm volatile("s_waitcnt vmcnt(0)" ::: "memory");
;     __syncthreads();
;   }
	ds_read_b128 v[114:117], v142 offset:32768
	ds_read_b128 v[230:233], v144 offset:16512
	ds_read_b128 v[234:237], v144 offset:18560
	ds_read_b128 v[118:121], v142 offset:34816
	ds_read_b128 v[134:137], v142 offset:40960
	ds_read_b128 v[138:141], v142 offset:43008
	ds_read_b128 v[238:241], v145 offset:16512
	ds_read_b128 v[246:249], v145 offset:18560
	s_add_u32 m0, s18, 16384
	s_nop 0
	global_load_lds_dwordx4 v126, s[16:17]
	s_add_u32 m0, s18, 20480
	s_nop 0
	global_load_lds_dwordx4 v127, s[16:17]
	s_add_u32 m0, s18, 24576
	s_nop 0
	global_load_lds_dwordx4 v128, s[16:17]
	s_add_u32 m0, s18, 28672
	s_nop 0
	global_load_lds_dwordx4 v129, s[16:17]
	s_add_u32 m0, s18, 57344
	s_nop 0
	global_load_lds_dwordx4 v126, s[28:29]
	s_add_u32 m0, s18, 61440
	s_nop 0
	global_load_lds_dwordx4 v127, s[28:29]
	s_add_u32 s16, s16, 64
	s_addc_u32 s17, s17, 0
	s_add_u32 s28, s28, 64
	s_addc_u32 s29, s29, 0
	s_waitcnt lgkmcnt(6)
	v_mfma_f32_32x32x16_bf16 v[2:17], v[114:117], v[230:233], v[2:17]
	s_waitcnt lgkmcnt(5)
	v_mfma_f32_32x32x16_bf16 v[18:33], v[114:117], v[234:237], v[18:33]
	ds_read_b128 v[114:117], v143 offset:32768
	s_waitcnt lgkmcnt(5)
	v_mfma_f32_32x32x16_bf16 v[34:49], v[118:121], v[230:233], v[34:49]
	v_mfma_f32_32x32x16_bf16 v[50:65], v[118:121], v[234:237], v[50:65]
	ds_read_b128 v[118:121], v143 offset:34816
	s_waitcnt lgkmcnt(5)
	v_mfma_f32_32x32x16_bf16 v[66:81], v[134:137], v[230:233], v[66:81]
	v_mfma_f32_32x32x16_bf16 v[82:97], v[134:137], v[234:237], v[82:97]
	ds_read_b128 v[134:137], v143 offset:40960
	s_waitcnt lgkmcnt(5)
	v_mfma_f32_32x32x16_bf16 v[98:113], v[138:141], v[230:233], v[98:113]
	v_mfma_f32_32x32x16_bf16 v[214:229], v[138:141], v[234:237], v[214:229]
	ds_read_b128 v[138:141], v143 offset:43008
	s_waitcnt lgkmcnt(3)
	v_mfma_f32_32x32x16_bf16 v[2:17], v[114:117], v[238:241], v[2:17]
	v_mfma_f32_32x32x16_bf16 v[18:33], v[114:117], v[246:249], v[18:33]
	s_waitcnt lgkmcnt(2)
	v_mfma_f32_32x32x16_bf16 v[34:49], v[118:121], v[238:241], v[34:49]
	v_mfma_f32_32x32x16_bf16 v[50:65], v[118:121], v[246:249], v[50:65]
	s_waitcnt lgkmcnt(1)
	v_mfma_f32_32x32x16_bf16 v[66:81], v[134:137], v[238:241], v[66:81]
	v_mfma_f32_32x32x16_bf16 v[82:97], v[134:137], v[246:249], v[82:97]
	s_waitcnt lgkmcnt(0)
	v_mfma_f32_32x32x16_bf16 v[98:113], v[138:141], v[238:241], v[98:113]
	v_mfma_f32_32x32x16_bf16 v[214:229], v[138:141], v[246:249], v[214:229]
	s_sub_u32 s36, s36, 1
	s_cmp_lg_u32 s36, 0
	s_cbranch_scc1 .Lgu1_kloop
	s_waitcnt vmcnt(6)
	s_barrier
	ds_read_b128 v[114:117], v142 offset:0
	ds_read_b128 v[230:233], v144 offset:0
	ds_read_b128 v[234:237], v144 offset:2048
	ds_read_b128 v[118:121], v142 offset:2048
	ds_read_b128 v[134:137], v142 offset:8192
	ds_read_b128 v[138:141], v142 offset:10240
	ds_read_b128 v[238:241], v145 offset:0
	ds_read_b128 v[246:249], v145 offset:2048
	s_waitcnt lgkmcnt(6)
	v_mfma_f32_32x32x16_bf16 v[2:17], v[114:117], v[230:233], v[2:17]
	s_waitcnt lgkmcnt(5)
	v_mfma_f32_32x32x16_bf16 v[18:33], v[114:117], v[234:237], v[18:33]
	ds_read_b128 v[114:117], v143 offset:0
	s_waitcnt lgkmcnt(5)
	v_mfma_f32_32x32x16_bf16 v[34:49], v[118:121], v[230:233], v[34:49]
	v_mfma_f32_32x32x16_bf16 v[50:65], v[118:121], v[234:237], v[50:65]
	ds_read_b128 v[118:121], v143 offset:2048
	s_waitcnt lgkmcnt(5)
	v_mfma_f32_32x32x16_bf16 v[66:81], v[134:137], v[230:233], v[66:81]
	v_mfma_f32_32x32x16_bf16 v[82:97], v[134:137], v[234:237], v[82:97]
	ds_read_b128 v[134:137], v143 offset:8192
	s_waitcnt lgkmcnt(5)
	v_mfma_f32_32x32x16_bf16 v[98:113], v[138:141], v[230:233], v[98:113]
	v_mfma_f32_32x32x16_bf16 v[214:229], v[138:141], v[234:237], v[214:229]
	ds_read_b128 v[138:141], v143 offset:10240
	s_waitcnt lgkmcnt(3)
	v_mfma_f32_32x32x16_bf16 v[2:17], v[114:117], v[238:241], v[2:17]
	v_mfma_f32_32x32x16_bf16 v[18:33], v[114:117], v[246:249], v[18:33]
	s_waitcnt lgkmcnt(2)
	v_mfma_f32_32x32x16_bf16 v[34:49], v[118:121], v[238:241], v[34:49]
	v_mfma_f32_32x32x16_bf16 v[50:65], v[118:121], v[246:249], v[50:65]
	s_waitcnt lgkmcnt(1)
	v_mfma_f32_32x32x16_bf16 v[66:81], v[134:137], v[238:241], v[66:81]
	v_mfma_f32_32x32x16_bf16 v[82:97], v[134:137], v[246:249], v[82:97]
	s_waitcnt lgkmcnt(0)
	v_mfma_f32_32x32x16_bf16 v[98:113], v[138:141], v[238:241], v[98:113]
	v_mfma_f32_32x32x16_bf16 v[214:229], v[138:141], v[246:249], v[214:229]
	s_waitcnt vmcnt(0)
	s_barrier
	ds_read_b128 v[114:117], v142 offset:16384
	ds_read_b128 v[230:233], v144 offset:8192
	ds_read_b128 v[234:237], v144 offset:10240
	ds_read_b128 v[118:121], v142 offset:18432
	ds_read_b128 v[134:137], v142 offset:24576
	ds_read_b128 v[138:141], v142 offset:26624
	ds_read_b128 v[238:241], v145 offset:8192
	ds_read_b128 v[246:249], v145 offset:10240
	s_waitcnt lgkmcnt(6)
	v_mfma_f32_32x32x16_bf16 v[2:17], v[114:117], v[230:233], v[2:17]
	s_waitcnt lgkmcnt(5)
	v_mfma_f32_32x32x16_bf16 v[18:33], v[114:117], v[234:237], v[18:33]
	ds_read_b128 v[114:117], v143 offset:16384
	s_waitcnt lgkmcnt(5)
	v_mfma_f32_32x32x16_bf16 v[34:49], v[118:121], v[230:233], v[34:49]
	v_mfma_f32_32x32x16_bf16 v[50:65], v[118:121], v[234:237], v[50:65]
	ds_read_b128 v[118:121], v143 offset:18432
	s_waitcnt lgkmcnt(5)
	v_mfma_f32_32x32x16_bf16 v[66:81], v[134:137], v[230:233], v[66:81]
	v_mfma_f32_32x32x16_bf16 v[82:97], v[134:137], v[234:237], v[82:97]
	ds_read_b128 v[134:137], v143 offset:24576
	s_waitcnt lgkmcnt(5)
	v_mfma_f32_32x32x16_bf16 v[98:113], v[138:141], v[230:233], v[98:113]
	v_mfma_f32_32x32x16_bf16 v[214:229], v[138:141], v[234:237], v[214:229]
	ds_read_b128 v[138:141], v143 offset:26624
	s_waitcnt lgkmcnt(3)
	v_mfma_f32_32x32x16_bf16 v[2:17], v[114:117], v[238:241], v[2:17]
	v_mfma_f32_32x32x16_bf16 v[18:33], v[114:117], v[246:249], v[18:33]
	s_waitcnt lgkmcnt(2)
	v_mfma_f32_32x32x16_bf16 v[34:49], v[118:121], v[238:241], v[34:49]
	v_mfma_f32_32x32x16_bf16 v[50:65], v[118:121], v[246:249], v[50:65]
	s_waitcnt lgkmcnt(1)
	v_mfma_f32_32x32x16_bf16 v[66:81], v[134:137], v[238:241], v[66:81]
	v_mfma_f32_32x32x16_bf16 v[82:97], v[134:137], v[246:249], v[82:97]
	s_waitcnt lgkmcnt(0)
	v_mfma_f32_32x32x16_bf16 v[98:113], v[138:141], v[238:241], v[98:113]
	v_mfma_f32_32x32x16_bf16 v[214:229], v[138:141], v[246:249], v[214:229]
	s_nop 7
	s_nop 7
	s_barrier
; template <int AI>
; DI void gu_tile(char* wsb, int sub, int m0, int n0, char* lds) {
;     ...
; #pragma unroll
;   for (int ai = 0; ai < AI; ++ai)
; #pragma unroll
;     for (int reg = 0; reg < 16; ++reg) {
;       float g = acc[ai][0][reg], u = acc[ai][1][reg];
;       float v = g * __builtin_amdgcn_rcpf(1.f + __expf(-g)) * u;
;       HIDu[ib + (unsigned)((ai * 32 + (reg & 3) + 8 * (reg >> 2)) * 2816)] = f2bf(v);
;       if ((reg & 7) == 7) __builtin_amdgcn_sched_barrier(0);
;     }
	v_mul_f32_e32 v250, 0xbfb8aa3b, v2
	v_mul_f32_e32 v252, 0xbfb8aa3b, v3
	v_exp_f32_e32 v250, v250
	v_exp_f32_e32 v252, v252
	v_add_u32_e32 v251, 0x0, v124
	v_add_f32_e32 v250, 1.0, v250
	v_add_f32_e32 v252, 1.0, v252
	v_rcp_f32_e32 v250, v250
	v_rcp_f32_e32 v252, v252
	v_add_u32_e32 v253, 0x1600, v124
	v_mul_f32_e32 v250, v2, v250
	v_mul_f32_e32 v252, v3, v252
	v_mul_f32_e32 v250, v18, v250
	v_mul_f32_e32 v252, v19, v252
	v_cvt_pk_bf16_f32 v250, v250, v250
	v_cvt_pk_bf16_f32 v252, v252, v252
	global_store_short v251, v250, s[34:35]
	global_store_short v253, v252, s[34:35]
	v_mul_f32_e32 v250, 0xbfb8aa3b, v4
	v_mul_f32_e32 v252, 0xbfb8aa3b, v5
	v_exp_f32_e32 v250, v250
	v_exp_f32_e32 v252, v252
	v_add_u32_e32 v251, 0x2c00, v124
	v_add_f32_e32 v250, 1.0, v250
	v_add_f32_e32 v252, 1.0, v252
	v_rcp_f32_e32 v250, v250
	v_rcp_f32_e32 v252, v252
	v_add_u32_e32 v253, 0x4200, v124
	v_mul_f32_e32 v250, v4, v250
	v_mul_f32_e32 v252, v5, v252
	v_mul_f32_e32 v250, v20, v250
	v_mul_f32_e32 v252, v21, v252
	v_cvt_pk_bf16_f32 v250, v250, v250
	v_cvt_pk_bf16_f32 v252, v252, v252
	global_store_short v251, v250, s[34:35]
	global_store_short v253, v252, s[34:35]
	v_mul_f32_e32 v250, 0xbfb8aa3b, v6
	v_mul_f32_e32 v252, 0xbfb8aa3b, v7
	v_exp_f32_e32 v250, v250
	v_exp_f32_e32 v252, v252
	v_add_u32_e32 v251, 0xb000, v124
	v_add_f32_e32 v250, 1.0, v250
	v_add_f32_e32 v252, 1.0, v252
	v_rcp_f32_e32 v250, v250
	v_rcp_f32_e32 v252, v252
	v_add_u32_e32 v253, 0xc600, v124
	v_mul_f32_e32 v250, v6, v250
	v_mul_f32_e32 v252, v7, v252
	v_mul_f32_e32 v250, v22, v250
	v_mul_f32_e32 v252, v23, v252
	v_cvt_pk_bf16_f32 v250, v250, v250
	v_cvt_pk_bf16_f32 v252, v252, v252
	global_store_short v251, v250, s[34:35]
	global_store_short v253, v252, s[34:35]
	v_mul_f32_e32 v250, 0xbfb8aa3b, v8
	v_mul_f32_e32 v252, 0xbfb8aa3b, v9
	v_exp_f32_e32 v250, v250
	v_exp_f32_e32 v252, v252
	v_add_u32_e32 v251, 0xdc00, v124
	v_add_f32_e32 v250, 1.0, v250
	v_add_f32_e32 v252, 1.0, v252
	v_rcp_f32_e32 v250, v250
	v_rcp_f32_e32 v252, v252
	v_add_u32_e32 v253, 0xf200, v124
	v_mul_f32_e32 v250, v8, v250
	v_mul_f32_e32 v252, v9, v252
	v_mul_f32_e32 v250, v24, v250
	v_mul_f32_e32 v252, v25, v252
	v_cvt_pk_bf16_f32 v250, v250, v250
	v_cvt_pk_bf16_f32 v252, v252, v252
	global_store_short v251, v250, s[34:35]
	global_store_short v253, v252, s[34:35]
	v_mul_f32_e32 v250, 0xbfb8aa3b, v10
	v_mul_f32_e32 v252, 0xbfb8aa3b, v11
	v_exp_f32_e32 v250, v250
	v_exp_f32_e32 v252, v252
	v_add_u32_e32 v251, 0x16000, v124
	v_add_f32_e32 v250, 1.0, v250
	v_add_f32_e32 v252, 1.0, v252
	v_rcp_f32_e32 v250, v250
	v_rcp_f32_e32 v252, v252
	v_add_u32_e32 v253, 0x17600, v124
	v_mul_f32_e32 v250, v10, v250
	v_mul_f32_e32 v252, v11, v252
	v_mul_f32_e32 v250, v26, v250
	v_mul_f32_e32 v252, v27, v252
	v_cvt_pk_bf16_f32 v250, v250, v250
	v_cvt_pk_bf16_f32 v252, v252, v252
	global_store_short v251, v250, s[34:35]
	global_store_short v253, v252, s[34:35]
	v_mul_f32_e32 v250, 0xbfb8aa3b, v12
	v_mul_f32_e32 v252, 0xbfb8aa3b, v13
	v_exp_f32_e32 v250, v250
	v_exp_f32_e32 v252, v252
	v_add_u32_e32 v251, 0x18c00, v124
	v_add_f32_e32 v250, 1.0, v250
	v_add_f32_e32 v252, 1.0, v252
	v_rcp_f32_e32 v250, v250
	v_rcp_f32_e32 v252, v252
	v_add_u32_e32 v253, 0x1a200, v124
	v_mul_f32_e32 v250, v12, v250
	v_mul_f32_e32 v252, v13, v252
	v_mul_f32_e32 v250, v28, v250
	v_mul_f32_e32 v252, v29, v252
	v_cvt_pk_bf16_f32 v250, v250, v250
	v_cvt_pk_bf16_f32 v252, v252, v252
	global_store_short v251, v250, s[34:35]
	global_store_short v253, v252, s[34:35]
	v_mul_f32_e32 v250, 0xbfb8aa3b, v14
	v_mul_f32_e32 v252, 0xbfb8aa3b, v15
	v_exp_f32_e32 v250, v250
	v_exp_f32_e32 v252, v252
	v_add_u32_e32 v251, 0x21000, v124
	v_add_f32_e32 v250, 1.0, v250
	v_add_f32_e32 v252, 1.0, v252
	v_rcp_f32_e32 v250, v250
	v_rcp_f32_e32 v252, v252
	v_add_u32_e32 v253, 0x22600, v124
	v_mul_f32_e32 v250, v14, v250
	v_mul_f32_e32 v252, v15, v252
	v_mul_f32_e32 v250, v30, v250
	v_mul_f32_e32 v252, v31, v252
	v_cvt_pk_bf16_f32 v250, v250, v250
	v_cvt_pk_bf16_f32 v252, v252, v252
	global_store_short v251, v250, s[34:35]
	global_store_short v253, v252, s[34:35]
	v_mul_f32_e32 v250, 0xbfb8aa3b, v16
	v_mul_f32_e32 v252, 0xbfb8aa3b, v17
	v_exp_f32_e32 v250, v250
	v_exp_f32_e32 v252, v252
	v_add_u32_e32 v251, 0x23c00, v124
	v_add_f32_e32 v250, 1.0, v250
	v_add_f32_e32 v252, 1.0, v252
	v_rcp_f32_e32 v250, v250
	v_rcp_f32_e32 v252, v252
	v_add_u32_e32 v253, 0x25200, v124
	v_mul_f32_e32 v250, v16, v250
	v_mul_f32_e32 v252, v17, v252
	v_mul_f32_e32 v250, v32, v250
	v_mul_f32_e32 v252, v33, v252
	v_cvt_pk_bf16_f32 v250, v250, v250
	v_cvt_pk_bf16_f32 v252, v252, v252
	global_store_short v251, v250, s[34:35]
	global_store_short v253, v252, s[34:35]
	v_mul_f32_e32 v250, 0xbfb8aa3b, v34
	v_mul_f32_e32 v252, 0xbfb8aa3b, v35
	v_exp_f32_e32 v250, v250
	v_exp_f32_e32 v252, v252
	v_add_u32_e32 v251, 0x2c000, v124
	v_add_f32_e32 v250, 1.0, v250
	v_add_f32_e32 v252, 1.0, v252
	v_rcp_f32_e32 v250, v250
	v_rcp_f32_e32 v252, v252
	v_add_u32_e32 v253, 0x2d600, v124
	v_mul_f32_e32 v250, v34, v250
	v_mul_f32_e32 v252, v35, v252
	v_mul_f32_e32 v250, v50, v250
	v_mul_f32_e32 v252, v51, v252
	v_cvt_pk_bf16_f32 v250, v250, v250
	v_cvt_pk_bf16_f32 v252, v252, v252
	global_store_short v251, v250, s[34:35]
	global_store_short v253, v252, s[34:35]
	v_mul_f32_e32 v250, 0xbfb8aa3b, v36
	v_mul_f32_e32 v252, 0xbfb8aa3b, v37
	v_exp_f32_e32 v250, v250
	v_exp_f32_e32 v252, v252
	v_add_u32_e32 v251, 0x2ec00, v124
	v_add_f32_e32 v250, 1.0, v250
	v_add_f32_e32 v252, 1.0, v252
	v_rcp_f32_e32 v250, v250
	v_rcp_f32_e32 v252, v252
	v_add_u32_e32 v253, 0x30200, v124
	v_mul_f32_e32 v250, v36, v250
	v_mul_f32_e32 v252, v37, v252
; template <int AI>
; DI void gu_tile(char* wsb, int sub, int m0, int n0, char* lds) {
;     ...
; #pragma unroll
;   for (int ai = 0; ai < AI; ++ai)
; #pragma unroll
;     for (int reg = 0; reg < 16; ++reg) {
;       float g = acc[ai][0][reg], u = acc[ai][1][reg];
;       float v = g * __builtin_amdgcn_rcpf(1.f + __expf(-g)) * u;
;       HIDu[ib + (unsigned)((ai * 32 + (reg & 3) + 8 * (reg >> 2)) * 2816)] = f2bf(v);
;       if ((reg & 7) == 7) __builtin_amdgcn_sched_barrier(0);
;     }
	v_mul_f32_e32 v250, v52, v250
	v_mul_f32_e32 v252, v53, v252
	v_cvt_pk_bf16_f32 v250, v250, v250
	v_cvt_pk_bf16_f32 v252, v252, v252
	global_store_short v251, v250, s[34:35]
	global_store_short v253, v252, s[34:35]
	v_mul_f32_e32 v250, 0xbfb8aa3b, v38
	v_mul_f32_e32 v252, 0xbfb8aa3b, v39
	v_exp_f32_e32 v250, v250
	v_exp_f32_e32 v252, v252
	v_add_u32_e32 v251, 0x37000, v124
	v_add_f32_e32 v250, 1.0, v250
	v_add_f32_e32 v252, 1.0, v252
	v_rcp_f32_e32 v250, v250
	v_rcp_f32_e32 v252, v252
	v_add_u32_e32 v253, 0x38600, v124
	v_mul_f32_e32 v250, v38, v250
	v_mul_f32_e32 v252, v39, v252
	v_mul_f32_e32 v250, v54, v250
	v_mul_f32_e32 v252, v55, v252
	v_cvt_pk_bf16_f32 v250, v250, v250
	v_cvt_pk_bf16_f32 v252, v252, v252
	global_store_short v251, v250, s[34:35]
	global_store_short v253, v252, s[34:35]
	v_mul_f32_e32 v250, 0xbfb8aa3b, v40
	v_mul_f32_e32 v252, 0xbfb8aa3b, v41
	v_exp_f32_e32 v250, v250
	v_exp_f32_e32 v252, v252
	v_add_u32_e32 v251, 0x39c00, v124
	v_add_f32_e32 v250, 1.0, v250
	v_add_f32_e32 v252, 1.0, v252
	v_rcp_f32_e32 v250, v250
	v_rcp_f32_e32 v252, v252
	v_add_u32_e32 v253, 0x3b200, v124
	v_mul_f32_e32 v250, v40, v250
	v_mul_f32_e32 v252, v41, v252
	v_mul_f32_e32 v250, v56, v250
	v_mul_f32_e32 v252, v57, v252
	v_cvt_pk_bf16_f32 v250, v250, v250
	v_cvt_pk_bf16_f32 v252, v252, v252
	global_store_short v251, v250, s[34:35]
	global_store_short v253, v252, s[34:35]
	v_mul_f32_e32 v250, 0xbfb8aa3b, v42
	v_mul_f32_e32 v252, 0xbfb8aa3b, v43
	v_exp_f32_e32 v250, v250
	v_exp_f32_e32 v252, v252
	v_add_u32_e32 v251, 0x42000, v124
	v_add_f32_e32 v250, 1.0, v250
	v_add_f32_e32 v252, 1.0, v252
	v_rcp_f32_e32 v250, v250
	v_rcp_f32_e32 v252, v252
	v_add_u32_e32 v253, 0x43600, v124
	v_mul_f32_e32 v250, v42, v250
	v_mul_f32_e32 v252, v43, v252
	v_mul_f32_e32 v250, v58, v250
	v_mul_f32_e32 v252, v59, v252
	v_cvt_pk_bf16_f32 v250, v250, v250
	v_cvt_pk_bf16_f32 v252, v252, v252
	global_store_short v251, v250, s[34:35]
	global_store_short v253, v252, s[34:35]
	v_mul_f32_e32 v250, 0xbfb8aa3b, v44
	v_mul_f32_e32 v252, 0xbfb8aa3b, v45
	v_exp_f32_e32 v250, v250
	v_exp_f32_e32 v252, v252
	v_add_u32_e32 v251, 0x44c00, v124
	v_add_f32_e32 v250, 1.0, v250
	v_add_f32_e32 v252, 1.0, v252
	v_rcp_f32_e32 v250, v250
	v_rcp_f32_e32 v252, v252
	v_add_u32_e32 v253, 0x46200, v124
	v_mul_f32_e32 v250, v44, v250
	v_mul_f32_e32 v252, v45, v252
	v_mul_f32_e32 v250, v60, v250
	v_mul_f32_e32 v252, v61, v252
	v_cvt_pk_bf16_f32 v250, v250, v250
	v_cvt_pk_bf16_f32 v252, v252, v252
	global_store_short v251, v250, s[34:35]
	global_store_short v253, v252, s[34:35]
	v_mul_f32_e32 v250, 0xbfb8aa3b, v46
	v_mul_f32_e32 v252, 0xbfb8aa3b, v47
	v_exp_f32_e32 v250, v250
	v_exp_f32_e32 v252, v252
	v_add_u32_e32 v251, 0x4d000, v124
	v_add_f32_e32 v250, 1.0, v250
	v_add_f32_e32 v252, 1.0, v252
	v_rcp_f32_e32 v250, v250
	v_rcp_f32_e32 v252, v252
	v_add_u32_e32 v253, 0x4e600, v124
	v_mul_f32_e32 v250, v46, v250
	v_mul_f32_e32 v252, v47, v252
	v_mul_f32_e32 v250, v62, v250
	v_mul_f32_e32 v252, v63, v252
	v_cvt_pk_bf16_f32 v250, v250, v250
	v_cvt_pk_bf16_f32 v252, v252, v252
	global_store_short v251, v250, s[34:35]
	global_store_short v253, v252, s[34:35]
	v_mul_f32_e32 v250, 0xbfb8aa3b, v48
	v_mul_f32_e32 v252, 0xbfb8aa3b, v49
	v_exp_f32_e32 v250, v250
	v_exp_f32_e32 v252, v252
	v_add_u32_e32 v251, 0x4fc00, v124
	v_add_f32_e32 v250, 1.0, v250
	v_add_f32_e32 v252, 1.0, v252
	v_rcp_f32_e32 v250, v250
	v_rcp_f32_e32 v252, v252
	v_add_u32_e32 v253, 0x51200, v124
	v_mul_f32_e32 v250, v48, v250
	v_mul_f32_e32 v252, v49, v252
	v_mul_f32_e32 v250, v64, v250
	v_mul_f32_e32 v252, v65, v252
	v_cvt_pk_bf16_f32 v250, v250, v250
	v_cvt_pk_bf16_f32 v252, v252, v252
	global_store_short v251, v250, s[34:35]
	global_store_short v253, v252, s[34:35]
	v_mul_f32_e32 v250, 0xbfb8aa3b, v66
	v_mul_f32_e32 v252, 0xbfb8aa3b, v67
	v_exp_f32_e32 v250, v250
	v_exp_f32_e32 v252, v252
	v_add_u32_e32 v251, 0xb0000, v124
	v_add_f32_e32 v250, 1.0, v250
	v_add_f32_e32 v252, 1.0, v252
	v_rcp_f32_e32 v250, v250
	v_rcp_f32_e32 v252, v252
	v_add_u32_e32 v253, 0xb1600, v124
	v_mul_f32_e32 v250, v66, v250
	v_mul_f32_e32 v252, v67, v252
	v_mul_f32_e32 v250, v82, v250
	v_mul_f32_e32 v252, v83, v252
	v_cvt_pk_bf16_f32 v250, v250, v250
	v_cvt_pk_bf16_f32 v252, v252, v252
	global_store_short v251, v250, s[34:35]
	global_store_short v253, v252, s[34:35]
	v_mul_f32_e32 v250, 0xbfb8aa3b, v68
	v_mul_f32_e32 v252, 0xbfb8aa3b, v69
	v_exp_f32_e32 v250, v250
	v_exp_f32_e32 v252, v252
	v_add_u32_e32 v251, 0xb2c00, v124
	v_add_f32_e32 v250, 1.0, v250
	v_add_f32_e32 v252, 1.0, v252
	v_rcp_f32_e32 v250, v250
	v_rcp_f32_e32 v252, v252
	v_add_u32_e32 v253, 0xb4200, v124
	v_mul_f32_e32 v250, v68, v250
	v_mul_f32_e32 v252, v69, v252
	v_mul_f32_e32 v250, v84, v250
	v_mul_f32_e32 v252, v85, v252
	v_cvt_pk_bf16_f32 v250, v250, v250
	v_cvt_pk_bf16_f32 v252, v252, v252
	global_store_short v251, v250, s[34:35]
	global_store_short v253, v252, s[34:35]
	v_mul_f32_e32 v250, 0xbfb8aa3b, v70
	v_mul_f32_e32 v252, 0xbfb8aa3b, v71
	v_exp_f32_e32 v250, v250
	v_exp_f32_e32 v252, v252
	v_add_u32_e32 v251, 0xbb000, v124
	v_add_f32_e32 v250, 1.0, v250
	v_add_f32_e32 v252, 1.0, v252
	v_rcp_f32_e32 v250, v250
	v_rcp_f32_e32 v252, v252
	v_add_u32_e32 v253, 0xbc600, v124
	v_mul_f32_e32 v250, v70, v250
	v_mul_f32_e32 v252, v71, v252
	v_mul_f32_e32 v250, v86, v250
	v_mul_f32_e32 v252, v87, v252
	v_cvt_pk_bf16_f32 v250, v250, v250
	v_cvt_pk_bf16_f32 v252, v252, v252
	global_store_short v251, v250, s[34:35]
	global_store_short v253, v252, s[34:35]
	v_mul_f32_e32 v250, 0xbfb8aa3b, v72
	v_mul_f32_e32 v252, 0xbfb8aa3b, v73
	v_exp_f32_e32 v250, v250
	v_exp_f32_e32 v252, v252
; template <int AI>
; DI void gu_tile(char* wsb, int sub, int m0, int n0, char* lds) {
;     ...
; #pragma unroll
;   for (int ai = 0; ai < AI; ++ai)
; #pragma unroll
;     for (int reg = 0; reg < 16; ++reg) {
;       float g = acc[ai][0][reg], u = acc[ai][1][reg];
;       float v = g * __builtin_amdgcn_rcpf(1.f + __expf(-g)) * u;
;       HIDu[ib + (unsigned)((ai * 32 + (reg & 3) + 8 * (reg >> 2)) * 2816)] = f2bf(v);
;       if ((reg & 7) == 7) __builtin_amdgcn_sched_barrier(0);
;     }
	v_add_u32_e32 v251, 0xbdc00, v124
	v_add_f32_e32 v250, 1.0, v250
	v_add_f32_e32 v252, 1.0, v252
	v_rcp_f32_e32 v250, v250
	v_rcp_f32_e32 v252, v252
	v_add_u32_e32 v253, 0xbf200, v124
	v_mul_f32_e32 v250, v72, v250
	v_mul_f32_e32 v252, v73, v252
	v_mul_f32_e32 v250, v88, v250
	v_mul_f32_e32 v252, v89, v252
	v_cvt_pk_bf16_f32 v250, v250, v250
	v_cvt_pk_bf16_f32 v252, v252, v252
	global_store_short v251, v250, s[34:35]
	global_store_short v253, v252, s[34:35]
	v_mul_f32_e32 v250, 0xbfb8aa3b, v74
	v_mul_f32_e32 v252, 0xbfb8aa3b, v75
	v_exp_f32_e32 v250, v250
	v_exp_f32_e32 v252, v252
	v_add_u32_e32 v251, 0xc6000, v124
	v_add_f32_e32 v250, 1.0, v250
	v_add_f32_e32 v252, 1.0, v252
	v_rcp_f32_e32 v250, v250
	v_rcp_f32_e32 v252, v252
	v_add_u32_e32 v253, 0xc7600, v124
	v_mul_f32_e32 v250, v74, v250
	v_mul_f32_e32 v252, v75, v252
	v_mul_f32_e32 v250, v90, v250
	v_mul_f32_e32 v252, v91, v252
	v_cvt_pk_bf16_f32 v250, v250, v250
	v_cvt_pk_bf16_f32 v252, v252, v252
	global_store_short v251, v250, s[34:35]
	global_store_short v253, v252, s[34:35]
	v_mul_f32_e32 v250, 0xbfb8aa3b, v76
	v_mul_f32_e32 v252, 0xbfb8aa3b, v77
	v_exp_f32_e32 v250, v250
	v_exp_f32_e32 v252, v252
	v_add_u32_e32 v251, 0xc8c00, v124
	v_add_f32_e32 v250, 1.0, v250
	v_add_f32_e32 v252, 1.0, v252
	v_rcp_f32_e32 v250, v250
	v_rcp_f32_e32 v252, v252
	v_add_u32_e32 v253, 0xca200, v124
	v_mul_f32_e32 v250, v76, v250
	v_mul_f32_e32 v252, v77, v252
	v_mul_f32_e32 v250, v92, v250
	v_mul_f32_e32 v252, v93, v252
	v_cvt_pk_bf16_f32 v250, v250, v250
	v_cvt_pk_bf16_f32 v252, v252, v252
	global_store_short v251, v250, s[34:35]
	global_store_short v253, v252, s[34:35]
	v_mul_f32_e32 v250, 0xbfb8aa3b, v78
	v_mul_f32_e32 v252, 0xbfb8aa3b, v79
	v_exp_f32_e32 v250, v250
	v_exp_f32_e32 v252, v252
	v_add_u32_e32 v251, 0xd1000, v124
	v_add_f32_e32 v250, 1.0, v250
	v_add_f32_e32 v252, 1.0, v252
	v_rcp_f32_e32 v250, v250
	v_rcp_f32_e32 v252, v252
	v_add_u32_e32 v253, 0xd2600, v124
	v_mul_f32_e32 v250, v78, v250
	v_mul_f32_e32 v252, v79, v252
	v_mul_f32_e32 v250, v94, v250
	v_mul_f32_e32 v252, v95, v252
	v_cvt_pk_bf16_f32 v250, v250, v250
	v_cvt_pk_bf16_f32 v252, v252, v252
	global_store_short v251, v250, s[34:35]
	global_store_short v253, v252, s[34:35]
	v_mul_f32_e32 v250, 0xbfb8aa3b, v80
	v_mul_f32_e32 v252, 0xbfb8aa3b, v81
	v_exp_f32_e32 v250, v250
	v_exp_f32_e32 v252, v252
	v_add_u32_e32 v251, 0xd3c00, v124
	v_add_f32_e32 v250, 1.0, v250
	v_add_f32_e32 v252, 1.0, v252
	v_rcp_f32_e32 v250, v250
	v_rcp_f32_e32 v252, v252
	v_add_u32_e32 v253, 0xd5200, v124
	v_mul_f32_e32 v250, v80, v250
	v_mul_f32_e32 v252, v81, v252
	v_mul_f32_e32 v250, v96, v250
	v_mul_f32_e32 v252, v97, v252
	v_cvt_pk_bf16_f32 v250, v250, v250
	v_cvt_pk_bf16_f32 v252, v252, v252
	global_store_short v251, v250, s[34:35]
	global_store_short v253, v252, s[34:35]
	v_mul_f32_e32 v250, 0xbfb8aa3b, v98
	v_mul_f32_e32 v252, 0xbfb8aa3b, v99
	v_exp_f32_e32 v250, v250
	v_exp_f32_e32 v252, v252
	v_add_u32_e32 v251, 0xdc000, v124
	v_add_f32_e32 v250, 1.0, v250
	v_add_f32_e32 v252, 1.0, v252
	v_rcp_f32_e32 v250, v250
	v_rcp_f32_e32 v252, v252
	v_add_u32_e32 v253, 0xdd600, v124
	v_mul_f32_e32 v250, v98, v250
	v_mul_f32_e32 v252, v99, v252
	v_mul_f32_e32 v250, v214, v250
	v_mul_f32_e32 v252, v215, v252
	v_cvt_pk_bf16_f32 v250, v250, v250
	v_cvt_pk_bf16_f32 v252, v252, v252
	global_store_short v251, v250, s[34:35]
	global_store_short v253, v252, s[34:35]
	v_mul_f32_e32 v250, 0xbfb8aa3b, v100
	v_mul_f32_e32 v252, 0xbfb8aa3b, v101
	v_exp_f32_e32 v250, v250
	v_exp_f32_e32 v252, v252
	v_add_u32_e32 v251, 0xdec00, v124
	v_add_f32_e32 v250, 1.0, v250
	v_add_f32_e32 v252, 1.0, v252
	v_rcp_f32_e32 v250, v250
	v_rcp_f32_e32 v252, v252
	v_add_u32_e32 v253, 0xe0200, v124
	v_mul_f32_e32 v250, v100, v250
	v_mul_f32_e32 v252, v101, v252
	v_mul_f32_e32 v250, v216, v250
	v_mul_f32_e32 v252, v217, v252
	v_cvt_pk_bf16_f32 v250, v250, v250
	v_cvt_pk_bf16_f32 v252, v252, v252
	global_store_short v251, v250, s[34:35]
	global_store_short v253, v252, s[34:35]
	v_mul_f32_e32 v250, 0xbfb8aa3b, v102
	v_mul_f32_e32 v252, 0xbfb8aa3b, v103
	v_exp_f32_e32 v250, v250
	v_exp_f32_e32 v252, v252
	v_add_u32_e32 v251, 0xe7000, v124
	v_add_f32_e32 v250, 1.0, v250
	v_add_f32_e32 v252, 1.0, v252
	v_rcp_f32_e32 v250, v250
	v_rcp_f32_e32 v252, v252
	v_add_u32_e32 v253, 0xe8600, v124
	v_mul_f32_e32 v250, v102, v250
	v_mul_f32_e32 v252, v103, v252
	v_mul_f32_e32 v250, v218, v250
	v_mul_f32_e32 v252, v219, v252
	v_cvt_pk_bf16_f32 v250, v250, v250
	v_cvt_pk_bf16_f32 v252, v252, v252
	global_store_short v251, v250, s[34:35]
	global_store_short v253, v252, s[34:35]
	v_mul_f32_e32 v250, 0xbfb8aa3b, v104
	v_mul_f32_e32 v252, 0xbfb8aa3b, v105
	v_exp_f32_e32 v250, v250
	v_exp_f32_e32 v252, v252
	v_add_u32_e32 v251, 0xe9c00, v124
	v_add_f32_e32 v250, 1.0, v250
	v_add_f32_e32 v252, 1.0, v252
	v_rcp_f32_e32 v250, v250
	v_rcp_f32_e32 v252, v252
	v_add_u32_e32 v253, 0xeb200, v124
	v_mul_f32_e32 v250, v104, v250
	v_mul_f32_e32 v252, v105, v252
	v_mul_f32_e32 v250, v220, v250
	v_mul_f32_e32 v252, v221, v252
	v_cvt_pk_bf16_f32 v250, v250, v250
	v_cvt_pk_bf16_f32 v252, v252, v252
	global_store_short v251, v250, s[34:35]
	global_store_short v253, v252, s[34:35]
	v_mul_f32_e32 v250, 0xbfb8aa3b, v106
	v_mul_f32_e32 v252, 0xbfb8aa3b, v107
	v_exp_f32_e32 v250, v250
	v_exp_f32_e32 v252, v252
	v_add_u32_e32 v251, 0xf2000, v124
	v_add_f32_e32 v250, 1.0, v250
	v_add_f32_e32 v252, 1.0, v252
	v_rcp_f32_e32 v250, v250
	v_rcp_f32_e32 v252, v252
	v_add_u32_e32 v253, 0xf3600, v124
	v_mul_f32_e32 v250, v106, v250
	v_mul_f32_e32 v252, v107, v252
	v_mul_f32_e32 v250, v222, v250
	v_mul_f32_e32 v252, v223, v252
; DI bool next_tile(int rnd, int MT, int NT, int& mt, int& nt) {
;   const int G8 = gridDim.x >> 3, x = blockIdx.x & 7, slot = blockIdx.x >> 3;
;   const int T = (rnd * 8 + x) * G8 + slot;
;   if (T >= MT * NT) return false;
;   const int band = T / (NT * 8), rem = T - band * NT * 8;
;   nt = rem >> 3; mt = band * 8 + (rem & 7);
;   return true;
; }
; template <int AI>
; DI void gu_tile(char* wsb, int sub, int m0, int n0, char* lds) {
;     ...
; #pragma unroll
;   for (int ai = 0; ai < AI; ++ai)
; #pragma unroll
;     for (int reg = 0; reg < 16; ++reg) {
;       float g = acc[ai][0][reg], u = acc[ai][1][reg];
;       float v = g * __builtin_amdgcn_rcpf(1.f + __expf(-g)) * u;
;       HIDu[ib + (unsigned)((ai * 32 + (reg & 3) + 8 * (reg >> 2)) * 2816)] = f2bf(v);
;       if ((reg & 7) == 7) __builtin_amdgcn_sched_barrier(0);
;     }
; }
; DI void phase_gu(const Params& p, char* wsb, int sub, int mrows, char* lds) {
;   int mt, nt;
;   for (int rnd = 0; next_tile(rnd, 128, 44, mt, nt); ++rnd) gu_tile<2>(wsb, sub, mt * 128, nt * 128, lds);
;   if (mrows > TL)
;     for (int rnd = 0; next_tile(rnd, 32, 44, mt, nt); ++rnd) gu_tile<1>(wsb, sub, TL + mt * 64, nt * 128, lds);
	v_cvt_pk_bf16_f32 v250, v250, v250
	v_cvt_pk_bf16_f32 v252, v252, v252
	global_store_short v251, v250, s[34:35]
	global_store_short v253, v252, s[34:35]
	v_mul_f32_e32 v250, 0xbfb8aa3b, v108
	v_mul_f32_e32 v252, 0xbfb8aa3b, v109
	v_exp_f32_e32 v250, v250
	v_exp_f32_e32 v252, v252
	v_add_u32_e32 v251, 0xf4c00, v124
	v_add_f32_e32 v250, 1.0, v250
	v_add_f32_e32 v252, 1.0, v252
	v_rcp_f32_e32 v250, v250
	v_rcp_f32_e32 v252, v252
	v_add_u32_e32 v253, 0xf6200, v124
	v_mul_f32_e32 v250, v108, v250
	v_mul_f32_e32 v252, v109, v252
	v_mul_f32_e32 v250, v224, v250
	v_mul_f32_e32 v252, v225, v252
	v_cvt_pk_bf16_f32 v250, v250, v250
	v_cvt_pk_bf16_f32 v252, v252, v252
	global_store_short v251, v250, s[34:35]
	global_store_short v253, v252, s[34:35]
	v_mul_f32_e32 v250, 0xbfb8aa3b, v110
	v_mul_f32_e32 v252, 0xbfb8aa3b, v111
	v_exp_f32_e32 v250, v250
	v_exp_f32_e32 v252, v252
	v_add_u32_e32 v251, 0xfd000, v124
	v_add_f32_e32 v250, 1.0, v250
	v_add_f32_e32 v252, 1.0, v252
	v_rcp_f32_e32 v250, v250
	v_rcp_f32_e32 v252, v252
	v_add_u32_e32 v253, 0xfe600, v124
	v_mul_f32_e32 v250, v110, v250
	v_mul_f32_e32 v252, v111, v252
	v_mul_f32_e32 v250, v226, v250
	v_mul_f32_e32 v252, v227, v252
	v_cvt_pk_bf16_f32 v250, v250, v250
	v_cvt_pk_bf16_f32 v252, v252, v252
	global_store_short v251, v250, s[34:35]
	global_store_short v253, v252, s[34:35]
	v_mul_f32_e32 v250, 0xbfb8aa3b, v112
	v_mul_f32_e32 v252, 0xbfb8aa3b, v113
	v_exp_f32_e32 v250, v250
	v_exp_f32_e32 v252, v252
	v_add_u32_e32 v251, 0xffc00, v124
	v_add_f32_e32 v250, 1.0, v250
	v_add_f32_e32 v252, 1.0, v252
	v_rcp_f32_e32 v250, v250
	v_rcp_f32_e32 v252, v252
	v_add_u32_e32 v253, 0x101200, v124
	v_mul_f32_e32 v250, v112, v250
	v_mul_f32_e32 v252, v113, v252
	v_mul_f32_e32 v250, v228, v250
	v_mul_f32_e32 v252, v229, v252
	v_cvt_pk_bf16_f32 v250, v250, v250
	v_cvt_pk_bf16_f32 v252, v252, v252
	global_store_short v251, v250, s[34:35]
	global_store_short v253, v252, s[34:35]
	s_add_u32 s32, s32, 1
	s_cmp_lt_u32 s32, 5
	s_cbranch_scc1 .Lgu1_round
	s_lshr_b32 s37, s40, 4
	s_add_u32 s37, s37, 40
	s_and_b32 s50, s40, 15
	s_lshl_b32 s51, s41, 4
	s_add_u32 s50, s50, s51
	s_lshr_b32 s51, s50, 3
	s_mul_i32 s51, s51, 0x160
	s_lshl_b32 s52, s37, 3
	s_add_u32 s51, s51, s52
	s_and_b32 s52, s50, 7
	s_add_u32 s14, s51, s52
	s_lshl_b32 s15, s14, 7
	s_mov_b32 s52, 1
	v_writelane_b32 v245, s52, 0
.LBB0_419:
	s_and_b32 s16, s14, 0xffff
	s_mul_hi_u32 s17, s16, 0xba2e8c
	s_mul_i32 s16, s16, 0xba2f
	s_mulk_i32 s17, 0x160
	s_lshr_b32 s16, s16, 24
	s_sub_i32 s17, s14, s17
	s_lshl_b32 s16, s16, 10
	s_and_b32 s18, s15, 0x380
	s_ashr_i32 s17, s17, 3
	s_or_b32 s16, s16, s18
	s_lshl_b32 s28, s17, 7
	s_waitcnt vmcnt(2)
	v_mov_b32_e32 v82, v178
	v_mov_b32_e32 v83, v178
	s_lshl_b32 s18, s16, 11
	v_mov_b32_e32 v12, v178
	s_add_u32 s34, s10, s18
	s_addc_u32 s35, s11, 0
	v_lshrrev_b32_e32 v0, 4, v12
	s_ashr_i32 s29, s28, 31
	v_xor_b32_e32 v0, v0, v12
	v_add_u32_e32 v8, 0x100, v12
	v_add_u32_e32 v10, 0x200, v12
	v_add_u32_e32 v13, 0x300, v12
	s_lshl_b64 s[28:29], s[28:29], 11
	v_lshlrev_b32_e32 v0, 4, v0
	v_ashrrev_i32_e32 v4, 3, v12
	v_ashrrev_i32_e32 v6, 3, v8
	v_lshlrev_b32_e32 v99, 4, v8
	v_ashrrev_i32_e32 v8, 3, v10
	v_lshlrev_b32_e32 v100, 4, v10
	v_ashrrev_i32_e32 v10, 3, v13
	s_add_u32 s28, s12, s28
	v_and_b32_e32 v0, 0x70, v0
	v_ashrrev_i32_e32 v5, 31, v4
	v_ashrrev_i32_e32 v7, 31, v6
	v_ashrrev_i32_e32 v9, 31, v8
	v_ashrrev_i32_e32 v11, 31, v10
	s_addc_u32 s29, s13, s29
	v_lshl_add_u64 v[2:3], s[34:35], 0, v[0:1]
	v_lshlrev_b64 v[4:5], 11, v[4:5]
	v_lshlrev_b32_e32 v95, 4, v12
	v_lshlrev_b64 v[6:7], 11, v[6:7]
	v_lshlrev_b64 v[8:9], 11, v[8:9]
	v_lshlrev_b64 v[10:11], 11, v[10:11]
	v_lshl_add_u64 v[66:67], v[2:3], 0, v[4:5]
	v_lshl_add_u64 v[68:69], v[2:3], 0, v[6:7]
	v_lshl_add_u64 v[70:71], v[2:3], 0, v[8:9]
	v_lshl_add_u64 v[72:73], v[2:3], 0, v[10:11]
	v_lshl_add_u64 v[2:3], s[28:29], 0, v[0:1]
	v_add_u32_e32 v0, 0x4000, v95
	v_readfirstlane_b32 s37, v95
	v_readfirstlane_b32 s28, v0
	v_add_u32_e32 v0, 0x4000, v99
	s_mov_b32 m0, s37
	v_readfirstlane_b32 s48, v99
	v_lshlrev_b32_e32 v101, 4, v13
	v_readfirstlane_b32 s29, v0
	v_add_u32_e32 v0, 0x4000, v100
	global_load_lds_dwordx4 v[66:67], off
	s_mov_b32 m0, s48
	v_readfirstlane_b32 s51, v100
	v_readfirstlane_b32 s34, v0
	v_add_u32_e32 v0, 0x4000, v101
	global_load_lds_dwordx4 v[68:69], off
	s_mov_b32 m0, s51
	v_readfirstlane_b32 s52, v101
	v_lshl_add_u64 v[74:75], v[2:3], 0, v[4:5]
	v_readfirstlane_b32 s35, v0
	v_and_b32_e32 v0, 31, v12
	v_lshrrev_b32_e32 v4, 1, v12
	global_load_lds_dwordx4 v[70:71], off
	s_mov_b32 m0, s52
	v_and_or_b32 v0, v4, s54, v0
	global_load_lds_dwordx4 v[72:73], off
	s_mov_b32 m0, s28
	v_lshl_add_u64 v[76:77], v[2:3], 0, v[6:7]
	v_lshl_add_u64 v[78:79], v[2:3], 0, v[8:9]
	v_lshl_add_u64 v[80:81], v[2:3], 0, v[10:11]
	v_lshrrev_b32_e32 v2, 5, v12
	v_bfe_u32 v5, v12, 1, 3
	v_lshlrev_b32_e32 v85, 7, v0
	v_lshlrev_b32_e32 v0, 7, v12
	global_load_lds_dwordx4 v[74:75], off
	s_mov_b32 m0, s29
	v_bfe_u32 v3, v12, 5, 1
	v_and_b32_e32 v87, 0x2f80, v0
	v_bitop3_b32 v0, v2, v5, 1 bitop3:0x6c
	global_load_lds_dwordx4 v[76:77], off
	s_mov_b32 m0, s34
	v_lshlrev_b32_e32 v6, 4, v0
	v_bitop3_b32 v0, v3, v5, 2 bitop3:0x36
	v_add_u32_e32 v91, 0x8000, v95
	global_load_lds_dwordx4 v[78:79], off
	s_mov_b32 m0, s35
	v_lshlrev_b32_e32 v84, 4, v0
	v_bitop3_b32 v0, v3, v5, 4 bitop3:0x36
	v_readfirstlane_b32 s36, v91
	v_add_u32_e32 v92, 0x8000, v99
	global_load_lds_dwordx4 v[80:81], off
	v_lshlrev_b32_e32 v118, 4, v0
	v_bitop3_b32 v0, v3, v5, 6 bitop3:0x36
	v_lshl_add_u64 v[2:3], v[66:67], 0, s[64:65]
	s_mov_b32 m0, s36
	v_readfirstlane_b32 s40, v92
	v_add_u32_e32 v93, 0x8000, v100
	s_waitcnt vmcnt(0)
	s_waitcnt vmcnt(0) lgkmcnt(0)
	s_barrier
; #define MFMA(a, b, c) __builtin_amdgcn_mfma_f32_32x32x16_bf16((a), (b), (c), 0, 0, 0)
; #define TIDX opaque_tid()
; template <int AI, int BI>
; DI void gemm_tile(const u16* __restrict__ A, int lda, const u16* __restrict__ B, int ldb, int nk, bool swap,
;                   f32x16 (&acc)[AI][BI], char* lds) {
;   const int tid = TIDX, lane = tid & 63, wid = tid >> 6;
;   gemm_stage<AI, BI>(A, lda, B, ldb, lds, tid);
;   asm volatile("s_waitcnt vmcnt(0)" ::: "memory");
;   __syncthreads();
;   const int wa = wid >> 1, wb = wid & 1, r = lane & 31, h = lane >> 5, sw = (r >> 1) & 7;
;   const int offA = (swap ? 16384 : 0) + (wa * 32 * AI + r) * 128;
;   const int offB = (swap ? 0 : 16384) + (wb * 32 * BI + r) * 128;
;   for (int kt = 0; kt < nk; ++kt) {
;     const char* cur = lds + (kt & 1) * 32768;
;     if (kt + 1 < nk) gemm_stage<AI, BI>(A + (kt + 1) * 64, lda, B + (kt + 1) * 64, ldb, lds + ((kt + 1) & 1) * 32768, tid);
; #pragma unroll
;     for (int ks = 0; ks < 4; ++ks) {
;       const int co = ((ks * 2 + h) ^ sw) << 4;
;       s16x8 fa[AI], fb[BI];
; #pragma unroll
;       for (int i = 0; i < AI; ++i) fa[i] = *(const s16x8*)(cur + offA + i * 4096 + co);
; #pragma unroll
;       for (int i = 0; i < BI; ++i) fb[i] = *(const s16x8*)(cur + offB + i * 4096 + co);
; #pragma unroll
;       for (int i = 0; i < AI; ++i)
; #pragma unroll
;         for (int j = 0; j < BI; ++j) acc[i][j] = MFMA(fa[i], fb[j], acc[i][j]);
;     }
;     asm volatile("s_waitcnt vmcnt(0)" ::: "memory");
;     __syncthreads();
;   }
	global_load_lds_dwordx4 v[2:3], off
	v_lshl_add_u64 v[2:3], v[68:69], 0, s[64:65]
	s_mov_b32 m0, s40
	v_readfirstlane_b32 s41, v93
	v_add_u32_e32 v94, 0x8000, v101
	global_load_lds_dwordx4 v[2:3], off
	v_lshl_add_u64 v[2:3], v[70:71], 0, s[64:65]
	s_mov_b32 m0, s41
	v_readfirstlane_b32 s46, v94
	v_add_u32_e32 v96, 0xc000, v95
	global_load_lds_dwordx4 v[2:3], off
	v_lshl_add_u64 v[2:3], v[72:73], 0, s[64:65]
	s_mov_b32 m0, s46
	v_readfirstlane_b32 s47, v96
	v_add_u32_e32 v97, 0xc000, v99
	global_load_lds_dwordx4 v[2:3], off
	v_lshl_add_u64 v[2:3], v[74:75], 0, s[64:65]
	s_mov_b32 m0, s47
	v_readfirstlane_b32 s49, v97
	v_add_u32_e32 v98, 0xc000, v100
	v_lshlrev_b32_e32 v119, 4, v0
	global_load_lds_dwordx4 v[2:3], off
	v_lshl_add_u64 v[2:3], v[76:77], 0, s[64:65]
	s_mov_b32 m0, s49
	v_readfirstlane_b32 s50, v98
	v_add_u32_e32 v0, 0xc000, v101
	global_load_lds_dwordx4 v[2:3], off
	v_lshl_add_u64 v[2:3], v[78:79], 0, s[64:65]
	s_mov_b32 m0, s50
	v_readfirstlane_b32 s18, v0
	global_load_lds_dwordx4 v[2:3], off
	v_lshl_add_u64 v[2:3], v[80:81], 0, s[64:65]
	s_mov_b32 m0, s18
	v_or_b32_e32 v0, v85, v6
	global_load_lds_dwordx4 v[2:3], off
	v_or_b32_e32 v86, v87, v6
	ds_read_b128 v[2:5], v0
	ds_read_b128 v[18:21], v0 offset:4096
	ds_read_b128 v[6:9], v86 offset:16384
	ds_read_b128 v[22:25], v86 offset:20480
	s_waitcnt lgkmcnt(0)
	v_mfma_f32_32x32x16_bf16 v[34:49], v[2:5], v[6:9], 0
	v_or_b32_e32 v88, v85, v84
	v_or_b32_e32 v89, v87, v84
	ds_read_b128 v[102:105], v88
	ds_read_b128 v[106:109], v88 offset:4096
	ds_read_b128 v[110:113], v89 offset:16384
	ds_read_b128 v[114:117], v89 offset:20480
	v_or_b32_e32 v90, v85, v118
	v_or_b32_e32 v84, v87, v118
	v_or_b32_e32 v85, v85, v119
	v_mfma_f32_32x32x16_bf16 v[50:65], v[2:5], v[22:25], 0
	v_or_b32_e32 v87, v87, v119
	s_mov_b32 m0, s37
	s_lshl_b32 s17, s17, 6
	v_mfma_f32_32x32x16_bf16 v[2:17], v[18:21], v[6:9], 0
	v_mfma_f32_32x32x16_bf16 v[18:33], v[18:21], v[22:25], 0
	s_waitcnt lgkmcnt(1)
	v_mfma_f32_32x32x16_bf16 v[34:49], v[102:105], v[110:113], v[34:49]
	s_waitcnt lgkmcnt(0)
	v_mfma_f32_32x32x16_bf16 v[50:65], v[102:105], v[114:117], v[50:65]
	v_mfma_f32_32x32x16_bf16 v[2:17], v[106:109], v[110:113], v[2:17]
	v_mfma_f32_32x32x16_bf16 v[18:33], v[106:109], v[114:117], v[18:33]
	ds_read_b128 v[102:105], v90
	ds_read_b128 v[106:109], v90 offset:4096
	ds_read_b128 v[110:113], v84 offset:16384
	ds_read_b128 v[114:117], v84 offset:20480
	s_waitcnt lgkmcnt(1)
	v_mfma_f32_32x32x16_bf16 v[34:49], v[102:105], v[110:113], v[34:49]
	s_waitcnt lgkmcnt(0)
	v_mfma_f32_32x32x16_bf16 v[50:65], v[102:105], v[114:117], v[50:65]
	v_mfma_f32_32x32x16_bf16 v[2:17], v[106:109], v[110:113], v[2:17]
	v_mfma_f32_32x32x16_bf16 v[18:33], v[106:109], v[114:117], v[18:33]
	ds_read_b128 v[102:105], v85
	ds_read_b128 v[106:109], v85 offset:4096
	ds_read_b128 v[110:113], v87 offset:16384
	ds_read_b128 v[114:117], v87 offset:20480
	s_waitcnt vmcnt(0)
	s_waitcnt lgkmcnt(0)
	s_barrier
	v_mfma_f32_32x32x16_bf16 v[34:49], v[102:105], v[110:113], v[34:49]
	v_mfma_f32_32x32x16_bf16 v[50:65], v[102:105], v[114:117], v[50:65]
	v_lshl_add_u64 v[102:103], v[66:67], 0, s[4:5]
	global_load_lds_dwordx4 v[102:103], off
	v_lshl_add_u64 v[102:103], v[68:69], 0, s[4:5]
	s_mov_b32 m0, s48
	s_nop 0
	global_load_lds_dwordx4 v[102:103], off
	v_lshl_add_u64 v[102:103], v[70:71], 0, s[4:5]
	s_mov_b32 m0, s51
	v_mfma_f32_32x32x16_bf16 v[2:17], v[106:109], v[110:113], v[2:17]
	global_load_lds_dwordx4 v[102:103], off
	v_lshl_add_u64 v[102:103], v[72:73], 0, s[4:5]
	s_mov_b32 m0, s52
	s_nop 0
	global_load_lds_dwordx4 v[102:103], off
	v_lshl_add_u64 v[102:103], v[74:75], 0, s[4:5]
	s_mov_b32 m0, s28
	v_mfma_f32_32x32x16_bf16 v[18:33], v[106:109], v[114:117], v[18:33]
	global_load_lds_dwordx4 v[102:103], off
	v_lshl_add_u64 v[102:103], v[76:77], 0, s[4:5]
	s_mov_b32 m0, s29
	s_nop 0
	global_load_lds_dwordx4 v[102:103], off
	v_lshl_add_u64 v[102:103], v[78:79], 0, s[4:5]
	s_mov_b32 m0, s34
	s_nop 0
	global_load_lds_dwordx4 v[102:103], off
	v_lshl_add_u64 v[102:103], v[80:81], 0, s[4:5]
	s_mov_b32 m0, s35
	s_nop 0
	global_load_lds_dwordx4 v[102:103], off
	ds_read_b128 v[102:105], v0 offset:32768
	ds_read_b128 v[106:109], v0 offset:36864
	ds_read_b128 v[110:113], v86 offset:49152
	ds_read_b128 v[114:117], v86 offset:53248
	s_waitcnt lgkmcnt(0)
	v_mfma_f32_32x32x16_bf16 v[34:49], v[102:105], v[110:113], v[34:49]
	s_mov_b32 m0, s36
	v_mfma_f32_32x32x16_bf16 v[50:65], v[102:105], v[114:117], v[50:65]
	v_mfma_f32_32x32x16_bf16 v[2:17], v[106:109], v[110:113], v[2:17]
	v_mfma_f32_32x32x16_bf16 v[18:33], v[106:109], v[114:117], v[18:33]
	ds_read_b128 v[102:105], v88 offset:32768
	ds_read_b128 v[106:109], v88 offset:36864
	ds_read_b128 v[110:113], v89 offset:49152
	ds_read_b128 v[114:117], v89 offset:53248
	s_waitcnt lgkmcnt(1)
	v_mfma_f32_32x32x16_bf16 v[34:49], v[102:105], v[110:113], v[34:49]
	s_waitcnt lgkmcnt(0)
	v_mfma_f32_32x32x16_bf16 v[50:65], v[102:105], v[114:117], v[50:65]
	v_mfma_f32_32x32x16_bf16 v[2:17], v[106:109], v[110:113], v[2:17]
	v_mfma_f32_32x32x16_bf16 v[18:33], v[106:109], v[114:117], v[18:33]
	ds_read_b128 v[102:105], v90 offset:32768
	ds_read_b128 v[106:109], v90 offset:36864
	ds_read_b128 v[110:113], v84 offset:49152
	ds_read_b128 v[114:117], v84 offset:53248
	s_waitcnt lgkmcnt(1)
	v_mfma_f32_32x32x16_bf16 v[34:49], v[102:105], v[110:113], v[34:49]
	s_waitcnt lgkmcnt(0)
	v_mfma_f32_32x32x16_bf16 v[50:65], v[102:105], v[114:117], v[50:65]
	v_mfma_f32_32x32x16_bf16 v[2:17], v[106:109], v[110:113], v[2:17]
	v_mfma_f32_32x32x16_bf16 v[18:33], v[106:109], v[114:117], v[18:33]
	ds_read_b128 v[102:105], v85 offset:32768
	ds_read_b128 v[106:109], v85 offset:36864
	ds_read_b128 v[110:113], v87 offset:49152
	ds_read_b128 v[114:117], v87 offset:53248
	s_waitcnt vmcnt(0)
	s_waitcnt lgkmcnt(0)
	s_barrier
; #define MFMA(a, b, c) __builtin_amdgcn_mfma_f32_32x32x16_bf16((a), (b), (c), 0, 0, 0)
; #define TIDX opaque_tid()
; template <int AI, int BI>
; DI void gemm_tile(const u16* __restrict__ A, int lda, const u16* __restrict__ B, int ldb, int nk, bool swap,
;                   f32x16 (&acc)[AI][BI], char* lds) {
;   const int tid = TIDX, lane = tid & 63, wid = tid >> 6;
;   gemm_stage<AI, BI>(A, lda, B, ldb, lds, tid);
;   asm volatile("s_waitcnt vmcnt(0)" ::: "memory");
;   __syncthreads();
;   const int wa = wid >> 1, wb = wid & 1, r = lane & 31, h = lane >> 5, sw = (r >> 1) & 7;
;   const int offA = (swap ? 16384 : 0) + (wa * 32 * AI + r) * 128;
;   const int offB = (swap ? 0 : 16384) + (wb * 32 * BI + r) * 128;
;   for (int kt = 0; kt < nk; ++kt) {
;     const char* cur = lds + (kt & 1) * 32768;
;     if (kt + 1 < nk) gemm_stage<AI, BI>(A + (kt + 1) * 64, lda, B + (kt + 1) * 64, ldb, lds + ((kt + 1) & 1) * 32768, tid);
; #pragma unroll
;     for (int ks = 0; ks < 4; ++ks) {
;       const int co = ((ks * 2 + h) ^ sw) << 4;
;       s16x8 fa[AI], fb[BI];
; #pragma unroll
;       for (int i = 0; i < AI; ++i) fa[i] = *(const s16x8*)(cur + offA + i * 4096 + co);
; #pragma unroll
;       for (int i = 0; i < BI; ++i) fb[i] = *(const s16x8*)(cur + offB + i * 4096 + co);
; #pragma unroll
;       for (int i = 0; i < AI; ++i)
; #pragma unroll
;         for (int j = 0; j < BI; ++j) acc[i][j] = MFMA(fa[i], fb[j], acc[i][j]);
;     }
;     asm volatile("s_waitcnt vmcnt(0)" ::: "memory");
;     __syncthreads();
;   }
	v_mfma_f32_32x32x16_bf16 v[34:49], v[102:105], v[110:113], v[34:49]
	v_mfma_f32_32x32x16_bf16 v[50:65], v[102:105], v[114:117], v[50:65]
	v_lshl_add_u64 v[102:103], v[66:67], 0, s[66:67]
	global_load_lds_dwordx4 v[102:103], off
	v_lshl_add_u64 v[102:103], v[68:69], 0, s[66:67]
	s_mov_b32 m0, s40
	s_nop 0
	global_load_lds_dwordx4 v[102:103], off
	v_lshl_add_u64 v[102:103], v[70:71], 0, s[66:67]
	s_mov_b32 m0, s41
	v_mfma_f32_32x32x16_bf16 v[2:17], v[106:109], v[110:113], v[2:17]
	global_load_lds_dwordx4 v[102:103], off
	v_lshl_add_u64 v[102:103], v[72:73], 0, s[66:67]
	s_mov_b32 m0, s46
	s_nop 0
	global_load_lds_dwordx4 v[102:103], off
	v_lshl_add_u64 v[102:103], v[74:75], 0, s[66:67]
	s_mov_b32 m0, s47
	v_mfma_f32_32x32x16_bf16 v[18:33], v[106:109], v[114:117], v[18:33]
	global_load_lds_dwordx4 v[102:103], off
	v_lshl_add_u64 v[102:103], v[76:77], 0, s[66:67]
	s_mov_b32 m0, s49
	s_nop 0
	global_load_lds_dwordx4 v[102:103], off
	v_lshl_add_u64 v[102:103], v[78:79], 0, s[66:67]
	s_mov_b32 m0, s50
	s_nop 0
	global_load_lds_dwordx4 v[102:103], off
	v_lshl_add_u64 v[102:103], v[80:81], 0, s[66:67]
	s_mov_b32 m0, s18
	s_nop 0
	global_load_lds_dwordx4 v[102:103], off
	ds_read_b128 v[102:105], v0
	ds_read_b128 v[106:109], v0 offset:4096
	ds_read_b128 v[110:113], v86 offset:16384
	ds_read_b128 v[114:117], v86 offset:20480
	s_waitcnt lgkmcnt(0)
	v_mfma_f32_32x32x16_bf16 v[34:49], v[102:105], v[110:113], v[34:49]
	s_mov_b32 m0, s37
	v_mfma_f32_32x32x16_bf16 v[50:65], v[102:105], v[114:117], v[50:65]
	v_mfma_f32_32x32x16_bf16 v[2:17], v[106:109], v[110:113], v[2:17]
	v_mfma_f32_32x32x16_bf16 v[18:33], v[106:109], v[114:117], v[18:33]
	ds_read_b128 v[102:105], v88
	ds_read_b128 v[106:109], v88 offset:4096
	ds_read_b128 v[110:113], v89 offset:16384
	ds_read_b128 v[114:117], v89 offset:20480
	s_waitcnt lgkmcnt(1)
	v_mfma_f32_32x32x16_bf16 v[34:49], v[102:105], v[110:113], v[34:49]
	s_waitcnt lgkmcnt(0)
	v_mfma_f32_32x32x16_bf16 v[50:65], v[102:105], v[114:117], v[50:65]
	v_mfma_f32_32x32x16_bf16 v[2:17], v[106:109], v[110:113], v[2:17]
	v_mfma_f32_32x32x16_bf16 v[18:33], v[106:109], v[114:117], v[18:33]
	ds_read_b128 v[102:105], v90
	ds_read_b128 v[106:109], v90 offset:4096
	ds_read_b128 v[110:113], v84 offset:16384
	ds_read_b128 v[114:117], v84 offset:20480
	s_waitcnt lgkmcnt(1)
	v_mfma_f32_32x32x16_bf16 v[34:49], v[102:105], v[110:113], v[34:49]
	s_waitcnt lgkmcnt(0)
	v_mfma_f32_32x32x16_bf16 v[50:65], v[102:105], v[114:117], v[50:65]
	v_mfma_f32_32x32x16_bf16 v[2:17], v[106:109], v[110:113], v[2:17]
	v_mfma_f32_32x32x16_bf16 v[18:33], v[106:109], v[114:117], v[18:33]
	ds_read_b128 v[102:105], v85
	ds_read_b128 v[106:109], v85 offset:4096
	ds_read_b128 v[110:113], v87 offset:16384
	ds_read_b128 v[114:117], v87 offset:20480
	s_waitcnt vmcnt(0)
	s_waitcnt lgkmcnt(0)
	s_barrier
	v_mfma_f32_32x32x16_bf16 v[34:49], v[102:105], v[110:113], v[34:49]
	v_mfma_f32_32x32x16_bf16 v[50:65], v[102:105], v[114:117], v[50:65]
	v_lshl_add_u64 v[102:103], v[66:67], 0, s[56:57]
	global_load_lds_dwordx4 v[102:103], off
	v_lshl_add_u64 v[102:103], v[68:69], 0, s[56:57]
	s_mov_b32 m0, s48
	s_nop 0
	global_load_lds_dwordx4 v[102:103], off
	v_lshl_add_u64 v[102:103], v[70:71], 0, s[56:57]
	s_mov_b32 m0, s51
	v_mfma_f32_32x32x16_bf16 v[2:17], v[106:109], v[110:113], v[2:17]
	global_load_lds_dwordx4 v[102:103], off
	v_lshl_add_u64 v[102:103], v[72:73], 0, s[56:57]
	s_mov_b32 m0, s52
	s_nop 0
	global_load_lds_dwordx4 v[102:103], off
	v_lshl_add_u64 v[102:103], v[74:75], 0, s[56:57]
	s_mov_b32 m0, s28
	v_mfma_f32_32x32x16_bf16 v[18:33], v[106:109], v[114:117], v[18:33]
	global_load_lds_dwordx4 v[102:103], off
	v_lshl_add_u64 v[102:103], v[76:77], 0, s[56:57]
	s_mov_b32 m0, s29
	s_nop 0
	global_load_lds_dwordx4 v[102:103], off
	v_lshl_add_u64 v[102:103], v[78:79], 0, s[56:57]
	s_mov_b32 m0, s34
	s_nop 0
	global_load_lds_dwordx4 v[102:103], off
	v_lshl_add_u64 v[102:103], v[80:81], 0, s[56:57]
	s_mov_b32 m0, s35
	s_nop 0
	global_load_lds_dwordx4 v[102:103], off
	ds_read_b128 v[102:105], v0 offset:32768
	ds_read_b128 v[106:109], v0 offset:36864
	ds_read_b128 v[110:113], v86 offset:49152
	ds_read_b128 v[114:117], v86 offset:53248
	s_waitcnt lgkmcnt(0)
	v_mfma_f32_32x32x16_bf16 v[34:49], v[102:105], v[110:113], v[34:49]
	s_mov_b32 m0, s36
	v_mfma_f32_32x32x16_bf16 v[50:65], v[102:105], v[114:117], v[50:65]
	v_mfma_f32_32x32x16_bf16 v[2:17], v[106:109], v[110:113], v[2:17]
	v_mfma_f32_32x32x16_bf16 v[18:33], v[106:109], v[114:117], v[18:33]
	ds_read_b128 v[102:105], v88 offset:32768
	ds_read_b128 v[106:109], v88 offset:36864
	ds_read_b128 v[110:113], v89 offset:49152
	ds_read_b128 v[114:117], v89 offset:53248
	s_waitcnt lgkmcnt(1)
	v_mfma_f32_32x32x16_bf16 v[34:49], v[102:105], v[110:113], v[34:49]
	s_waitcnt lgkmcnt(0)
	v_mfma_f32_32x32x16_bf16 v[50:65], v[102:105], v[114:117], v[50:65]
	v_mfma_f32_32x32x16_bf16 v[2:17], v[106:109], v[110:113], v[2:17]
	v_mfma_f32_32x32x16_bf16 v[18:33], v[106:109], v[114:117], v[18:33]
	ds_read_b128 v[102:105], v90 offset:32768
	ds_read_b128 v[106:109], v90 offset:36864
	ds_read_b128 v[110:113], v84 offset:49152
	ds_read_b128 v[114:117], v84 offset:53248
	s_waitcnt lgkmcnt(1)
	v_mfma_f32_32x32x16_bf16 v[34:49], v[102:105], v[110:113], v[34:49]
	s_waitcnt lgkmcnt(0)
	v_mfma_f32_32x32x16_bf16 v[50:65], v[102:105], v[114:117], v[50:65]
	v_mfma_f32_32x32x16_bf16 v[2:17], v[106:109], v[110:113], v[2:17]
	v_mfma_f32_32x32x16_bf16 v[18:33], v[106:109], v[114:117], v[18:33]
	ds_read_b128 v[102:105], v85 offset:32768
	ds_read_b128 v[106:109], v85 offset:36864
	ds_read_b128 v[110:113], v87 offset:49152
	ds_read_b128 v[114:117], v87 offset:53248
	s_waitcnt vmcnt(0)
	s_waitcnt lgkmcnt(0)
	s_barrier
; #define MFMA(a, b, c) __builtin_amdgcn_mfma_f32_32x32x16_bf16((a), (b), (c), 0, 0, 0)
; #define TIDX opaque_tid()
; template <int AI, int BI>
; DI void gemm_tile(const u16* __restrict__ A, int lda, const u16* __restrict__ B, int ldb, int nk, bool swap,
;                   f32x16 (&acc)[AI][BI], char* lds) {
;   const int tid = TIDX, lane = tid & 63, wid = tid >> 6;
;   gemm_stage<AI, BI>(A, lda, B, ldb, lds, tid);
;   asm volatile("s_waitcnt vmcnt(0)" ::: "memory");
;   __syncthreads();
;   const int wa = wid >> 1, wb = wid & 1, r = lane & 31, h = lane >> 5, sw = (r >> 1) & 7;
;   const int offA = (swap ? 16384 : 0) + (wa * 32 * AI + r) * 128;
;   const int offB = (swap ? 0 : 16384) + (wb * 32 * BI + r) * 128;
;   for (int kt = 0; kt < nk; ++kt) {
;     const char* cur = lds + (kt & 1) * 32768;
;     if (kt + 1 < nk) gemm_stage<AI, BI>(A + (kt + 1) * 64, lda, B + (kt + 1) * 64, ldb, lds + ((kt + 1) & 1) * 32768, tid);
; #pragma unroll
;     for (int ks = 0; ks < 4; ++ks) {
;       const int co = ((ks * 2 + h) ^ sw) << 4;
;       s16x8 fa[AI], fb[BI];
; #pragma unroll
;       for (int i = 0; i < AI; ++i) fa[i] = *(const s16x8*)(cur + offA + i * 4096 + co);
; #pragma unroll
;       for (int i = 0; i < BI; ++i) fb[i] = *(const s16x8*)(cur + offB + i * 4096 + co);
; #pragma unroll
;       for (int i = 0; i < AI; ++i)
; #pragma unroll
;         for (int j = 0; j < BI; ++j) acc[i][j] = MFMA(fa[i], fb[j], acc[i][j]);
;     }
;     asm volatile("s_waitcnt vmcnt(0)" ::: "memory");
;     __syncthreads();
;   }
	v_mfma_f32_32x32x16_bf16 v[34:49], v[102:105], v[110:113], v[34:49]
	v_mfma_f32_32x32x16_bf16 v[50:65], v[102:105], v[114:117], v[50:65]
	v_lshl_add_u64 v[102:103], v[66:67], 0, s[68:69]
	global_load_lds_dwordx4 v[102:103], off
	v_lshl_add_u64 v[102:103], v[68:69], 0, s[68:69]
	s_mov_b32 m0, s40
	s_nop 0
	global_load_lds_dwordx4 v[102:103], off
	v_lshl_add_u64 v[102:103], v[70:71], 0, s[68:69]
	s_mov_b32 m0, s41
	v_mfma_f32_32x32x16_bf16 v[2:17], v[106:109], v[110:113], v[2:17]
	global_load_lds_dwordx4 v[102:103], off
	v_lshl_add_u64 v[102:103], v[72:73], 0, s[68:69]
	s_mov_b32 m0, s46
	s_nop 0
	global_load_lds_dwordx4 v[102:103], off
	v_lshl_add_u64 v[102:103], v[74:75], 0, s[68:69]
	s_mov_b32 m0, s47
	v_mfma_f32_32x32x16_bf16 v[18:33], v[106:109], v[114:117], v[18:33]
	global_load_lds_dwordx4 v[102:103], off
	v_lshl_add_u64 v[102:103], v[76:77], 0, s[68:69]
	s_mov_b32 m0, s49
	s_nop 0
	global_load_lds_dwordx4 v[102:103], off
	v_lshl_add_u64 v[102:103], v[78:79], 0, s[68:69]
	s_mov_b32 m0, s50
	s_nop 0
	global_load_lds_dwordx4 v[102:103], off
	v_lshl_add_u64 v[102:103], v[80:81], 0, s[68:69]
	s_mov_b32 m0, s18
	s_nop 0
	global_load_lds_dwordx4 v[102:103], off
	ds_read_b128 v[102:105], v0
	ds_read_b128 v[106:109], v0 offset:4096
	ds_read_b128 v[110:113], v86 offset:16384
	ds_read_b128 v[114:117], v86 offset:20480
	s_waitcnt lgkmcnt(0)
	v_mfma_f32_32x32x16_bf16 v[34:49], v[102:105], v[110:113], v[34:49]
	s_mov_b32 m0, s37
	v_readfirstlane_b32 s37, v99
	v_mfma_f32_32x32x16_bf16 v[50:65], v[102:105], v[114:117], v[50:65]
	v_mfma_f32_32x32x16_bf16 v[2:17], v[106:109], v[110:113], v[2:17]
	v_mfma_f32_32x32x16_bf16 v[18:33], v[106:109], v[114:117], v[18:33]
	ds_read_b128 v[102:105], v88
	ds_read_b128 v[106:109], v88 offset:4096
	ds_read_b128 v[110:113], v89 offset:16384
	ds_read_b128 v[114:117], v89 offset:20480
	s_waitcnt lgkmcnt(1)
	v_mfma_f32_32x32x16_bf16 v[34:49], v[102:105], v[110:113], v[34:49]
	s_waitcnt lgkmcnt(0)
	v_mfma_f32_32x32x16_bf16 v[50:65], v[102:105], v[114:117], v[50:65]
	v_mfma_f32_32x32x16_bf16 v[2:17], v[106:109], v[110:113], v[2:17]
	v_mfma_f32_32x32x16_bf16 v[18:33], v[106:109], v[114:117], v[18:33]
	ds_read_b128 v[102:105], v90
	ds_read_b128 v[106:109], v90 offset:4096
	ds_read_b128 v[110:113], v84 offset:16384
	ds_read_b128 v[114:117], v84 offset:20480
	s_waitcnt lgkmcnt(1)
	v_mfma_f32_32x32x16_bf16 v[34:49], v[102:105], v[110:113], v[34:49]
	s_waitcnt lgkmcnt(0)
	v_mfma_f32_32x32x16_bf16 v[50:65], v[102:105], v[114:117], v[50:65]
	v_mfma_f32_32x32x16_bf16 v[2:17], v[106:109], v[110:113], v[2:17]
	v_mfma_f32_32x32x16_bf16 v[18:33], v[106:109], v[114:117], v[18:33]
	ds_read_b128 v[102:105], v85
	ds_read_b128 v[106:109], v85 offset:4096
	ds_read_b128 v[110:113], v87 offset:16384
	ds_read_b128 v[114:117], v87 offset:20480
	s_waitcnt vmcnt(0)
	s_waitcnt lgkmcnt(0)
	s_barrier
	v_mfma_f32_32x32x16_bf16 v[34:49], v[102:105], v[110:113], v[34:49]
	v_mfma_f32_32x32x16_bf16 v[50:65], v[102:105], v[114:117], v[50:65]
	v_lshl_add_u64 v[102:103], v[66:67], 0, s[70:71]
	global_load_lds_dwordx4 v[102:103], off
	v_lshl_add_u64 v[102:103], v[68:69], 0, s[70:71]
	s_mov_b32 m0, s48
	v_readfirstlane_b32 s48, v93
	global_load_lds_dwordx4 v[102:103], off
	v_lshl_add_u64 v[102:103], v[70:71], 0, s[70:71]
	s_mov_b32 m0, s51
	v_mfma_f32_32x32x16_bf16 v[2:17], v[106:109], v[110:113], v[2:17]
	global_load_lds_dwordx4 v[102:103], off
	v_lshl_add_u64 v[102:103], v[72:73], 0, s[70:71]
	s_mov_b32 m0, s52
	v_readfirstlane_b32 s51, v97
	global_load_lds_dwordx4 v[102:103], off
	v_lshl_add_u64 v[102:103], v[74:75], 0, s[70:71]
	s_mov_b32 m0, s28
	v_mfma_f32_32x32x16_bf16 v[18:33], v[106:109], v[114:117], v[18:33]
	global_load_lds_dwordx4 v[102:103], off
	v_lshl_add_u64 v[102:103], v[76:77], 0, s[70:71]
	s_mov_b32 m0, s29
	v_readfirstlane_b32 s52, v98
	global_load_lds_dwordx4 v[102:103], off
	v_lshl_add_u64 v[102:103], v[78:79], 0, s[70:71]
	s_mov_b32 m0, s34
	s_nop 0
	global_load_lds_dwordx4 v[102:103], off
	v_lshl_add_u64 v[102:103], v[80:81], 0, s[70:71]
	s_mov_b32 m0, s35
	s_nop 0
	global_load_lds_dwordx4 v[102:103], off
	ds_read_b128 v[102:105], v0 offset:32768
	ds_read_b128 v[106:109], v0 offset:36864
	ds_read_b128 v[110:113], v86 offset:49152
	ds_read_b128 v[114:117], v86 offset:53248
	s_waitcnt lgkmcnt(0)
	v_mfma_f32_32x32x16_bf16 v[34:49], v[102:105], v[110:113], v[34:49]
	s_mov_b32 m0, s36
	v_readfirstlane_b32 s36, v95
	v_mfma_f32_32x32x16_bf16 v[50:65], v[102:105], v[114:117], v[50:65]
	v_mfma_f32_32x32x16_bf16 v[2:17], v[106:109], v[110:113], v[2:17]
	v_mfma_f32_32x32x16_bf16 v[18:33], v[106:109], v[114:117], v[18:33]
	ds_read_b128 v[102:105], v88 offset:32768
	ds_read_b128 v[106:109], v88 offset:36864
	ds_read_b128 v[110:113], v89 offset:49152
	ds_read_b128 v[114:117], v89 offset:53248
	s_waitcnt lgkmcnt(1)
	v_mfma_f32_32x32x16_bf16 v[34:49], v[102:105], v[110:113], v[34:49]
	s_waitcnt lgkmcnt(0)
	v_mfma_f32_32x32x16_bf16 v[50:65], v[102:105], v[114:117], v[50:65]
	v_mfma_f32_32x32x16_bf16 v[2:17], v[106:109], v[110:113], v[2:17]
	v_mfma_f32_32x32x16_bf16 v[18:33], v[106:109], v[114:117], v[18:33]
	ds_read_b128 v[102:105], v90 offset:32768
	ds_read_b128 v[106:109], v90 offset:36864
	ds_read_b128 v[110:113], v84 offset:49152
	ds_read_b128 v[114:117], v84 offset:53248
	s_waitcnt lgkmcnt(1)
	v_mfma_f32_32x32x16_bf16 v[34:49], v[102:105], v[110:113], v[34:49]
	s_waitcnt lgkmcnt(0)
	v_mfma_f32_32x32x16_bf16 v[50:65], v[102:105], v[114:117], v[50:65]
	v_mfma_f32_32x32x16_bf16 v[2:17], v[106:109], v[110:113], v[2:17]
	v_mfma_f32_32x32x16_bf16 v[18:33], v[106:109], v[114:117], v[18:33]
	ds_read_b128 v[102:105], v85 offset:32768
	ds_read_b128 v[106:109], v85 offset:36864
	ds_read_b128 v[110:113], v87 offset:49152
	ds_read_b128 v[114:117], v87 offset:53248
	s_waitcnt vmcnt(0)
	s_waitcnt lgkmcnt(0)
	s_barrier
; #define MFMA(a, b, c) __builtin_amdgcn_mfma_f32_32x32x16_bf16((a), (b), (c), 0, 0, 0)
; #define TIDX opaque_tid()
; template <int AI, int BI>
; DI void gemm_tile(const u16* __restrict__ A, int lda, const u16* __restrict__ B, int ldb, int nk, bool swap,
;                   f32x16 (&acc)[AI][BI], char* lds) {
;   const int tid = TIDX, lane = tid & 63, wid = tid >> 6;
;   gemm_stage<AI, BI>(A, lda, B, ldb, lds, tid);
;   asm volatile("s_waitcnt vmcnt(0)" ::: "memory");
;   __syncthreads();
;   const int wa = wid >> 1, wb = wid & 1, r = lane & 31, h = lane >> 5, sw = (r >> 1) & 7;
;   const int offA = (swap ? 16384 : 0) + (wa * 32 * AI + r) * 128;
;   const int offB = (swap ? 0 : 16384) + (wb * 32 * BI + r) * 128;
;   for (int kt = 0; kt < nk; ++kt) {
;     const char* cur = lds + (kt & 1) * 32768;
;     if (kt + 1 < nk) gemm_stage<AI, BI>(A + (kt + 1) * 64, lda, B + (kt + 1) * 64, ldb, lds + ((kt + 1) & 1) * 32768, tid);
; #pragma unroll
;     for (int ks = 0; ks < 4; ++ks) {
;       const int co = ((ks * 2 + h) ^ sw) << 4;
;       s16x8 fa[AI], fb[BI];
; #pragma unroll
;       for (int i = 0; i < AI; ++i) fa[i] = *(const s16x8*)(cur + offA + i * 4096 + co);
; #pragma unroll
;       for (int i = 0; i < BI; ++i) fb[i] = *(const s16x8*)(cur + offB + i * 4096 + co);
; #pragma unroll
;       for (int i = 0; i < AI; ++i)
; #pragma unroll
;         for (int j = 0; j < BI; ++j) acc[i][j] = MFMA(fa[i], fb[j], acc[i][j]);
;     }
;     asm volatile("s_waitcnt vmcnt(0)" ::: "memory");
;     __syncthreads();
;   }
	v_mfma_f32_32x32x16_bf16 v[34:49], v[102:105], v[110:113], v[34:49]
	v_mfma_f32_32x32x16_bf16 v[50:65], v[102:105], v[114:117], v[50:65]
	v_lshl_add_u64 v[102:103], v[66:67], 0, s[72:73]
	global_load_lds_dwordx4 v[102:103], off
	v_lshl_add_u64 v[102:103], v[68:69], 0, s[72:73]
	s_mov_b32 m0, s40
	v_readfirstlane_b32 s40, v100
	global_load_lds_dwordx4 v[102:103], off
	v_lshl_add_u64 v[102:103], v[70:71], 0, s[72:73]
	s_mov_b32 m0, s41
	v_mfma_f32_32x32x16_bf16 v[2:17], v[106:109], v[110:113], v[2:17]
	global_load_lds_dwordx4 v[102:103], off
	v_lshl_add_u64 v[102:103], v[72:73], 0, s[72:73]
	s_mov_b32 m0, s46
	v_readfirstlane_b32 s41, v101
	global_load_lds_dwordx4 v[102:103], off
	v_lshl_add_u64 v[102:103], v[74:75], 0, s[72:73]
	s_mov_b32 m0, s47
	v_mfma_f32_32x32x16_bf16 v[18:33], v[106:109], v[114:117], v[18:33]
	global_load_lds_dwordx4 v[102:103], off
	v_lshl_add_u64 v[102:103], v[76:77], 0, s[72:73]
	s_mov_b32 m0, s49
	v_lshl_add_u64 v[100:101], v[74:75], 0, s[74:75]
	global_load_lds_dwordx4 v[102:103], off
	v_lshl_add_u64 v[102:103], v[78:79], 0, s[72:73]
	s_mov_b32 m0, s50
	v_readfirstlane_b32 s46, v91
	global_load_lds_dwordx4 v[102:103], off
	v_lshl_add_u64 v[102:103], v[80:81], 0, s[72:73]
	s_mov_b32 m0, s18
	v_readfirstlane_b32 s47, v92
	global_load_lds_dwordx4 v[102:103], off
	ds_read_b128 v[102:105], v0
	ds_read_b128 v[106:109], v0 offset:4096
	ds_read_b128 v[110:113], v86 offset:16384
	ds_read_b128 v[114:117], v86 offset:20480
	s_waitcnt lgkmcnt(0)
	v_mfma_f32_32x32x16_bf16 v[34:49], v[102:105], v[110:113], v[34:49]
	s_mov_b32 m0, s36
	v_readfirstlane_b32 s49, v94
	v_lshl_add_u64 v[92:93], v[72:73], 0, s[76:77]
	v_readfirstlane_b32 s50, v96
	v_and_b32_e32 v91, 31, v82
	v_mfma_f32_32x32x16_bf16 v[50:65], v[102:105], v[114:117], v[50:65]
	v_mfma_f32_32x32x16_bf16 v[2:17], v[106:109], v[110:113], v[2:17]
	v_mfma_f32_32x32x16_bf16 v[18:33], v[106:109], v[114:117], v[18:33]
	ds_read_b128 v[102:105], v88
	ds_read_b128 v[106:109], v88 offset:4096
	ds_read_b128 v[110:113], v89 offset:16384
	ds_read_b128 v[114:117], v89 offset:20480
	s_waitcnt lgkmcnt(1)
	v_mfma_f32_32x32x16_bf16 v[34:49], v[102:105], v[110:113], v[34:49]
	s_waitcnt lgkmcnt(0)
	v_mfma_f32_32x32x16_bf16 v[50:65], v[102:105], v[114:117], v[50:65]
	v_mfma_f32_32x32x16_bf16 v[2:17], v[106:109], v[110:113], v[2:17]
	v_mfma_f32_32x32x16_bf16 v[18:33], v[106:109], v[114:117], v[18:33]
	ds_read_b128 v[102:105], v90
	ds_read_b128 v[106:109], v90 offset:4096
	ds_read_b128 v[110:113], v84 offset:16384
	ds_read_b128 v[114:117], v84 offset:20480
	s_waitcnt lgkmcnt(1)
	v_mfma_f32_32x32x16_bf16 v[34:49], v[102:105], v[110:113], v[34:49]
	s_waitcnt lgkmcnt(0)
	v_mfma_f32_32x32x16_bf16 v[50:65], v[102:105], v[114:117], v[50:65]
	v_mfma_f32_32x32x16_bf16 v[2:17], v[106:109], v[110:113], v[2:17]
	v_mfma_f32_32x32x16_bf16 v[18:33], v[106:109], v[114:117], v[18:33]
	ds_read_b128 v[102:105], v85
	ds_read_b128 v[106:109], v85 offset:4096
	ds_read_b128 v[110:113], v87 offset:16384
	ds_read_b128 v[114:117], v87 offset:20480
	s_waitcnt vmcnt(0)
	s_waitcnt lgkmcnt(0)
	s_barrier
	v_mfma_f32_32x32x16_bf16 v[34:49], v[102:105], v[110:113], v[34:49]
	v_mfma_f32_32x32x16_bf16 v[50:65], v[102:105], v[114:117], v[50:65]
	v_lshl_add_u64 v[102:103], v[66:67], 0, s[74:75]
	global_load_lds_dwordx4 v[102:103], off
	v_lshl_add_u64 v[102:103], v[68:69], 0, s[74:75]
	s_mov_b32 m0, s37
	s_nop 0
	global_load_lds_dwordx4 v[102:103], off
	v_lshl_add_u64 v[102:103], v[70:71], 0, s[74:75]
	s_mov_b32 m0, s40
	v_mfma_f32_32x32x16_bf16 v[2:17], v[106:109], v[110:113], v[2:17]
	global_load_lds_dwordx4 v[102:103], off
	v_lshl_add_u64 v[102:103], v[72:73], 0, s[74:75]
	s_mov_b32 m0, s41
	s_nop 0
	global_load_lds_dwordx4 v[102:103], off
	s_mov_b32 m0, s28
	v_mfma_f32_32x32x16_bf16 v[18:33], v[106:109], v[114:117], v[18:33]
	global_load_lds_dwordx4 v[100:101], off
	v_lshl_add_u64 v[100:101], v[76:77], 0, s[74:75]
	s_mov_b32 m0, s29
	s_nop 0
	global_load_lds_dwordx4 v[100:101], off
	v_lshl_add_u64 v[100:101], v[78:79], 0, s[74:75]
	s_mov_b32 m0, s34
	s_nop 0
	global_load_lds_dwordx4 v[100:101], off
	v_lshl_add_u64 v[100:101], v[80:81], 0, s[74:75]
	s_mov_b32 m0, s35
	s_nop 0
	global_load_lds_dwordx4 v[100:101], off
	ds_read_b128 v[100:103], v0 offset:32768
	ds_read_b128 v[104:107], v0 offset:36864
	ds_read_b128 v[108:111], v86 offset:49152
	ds_read_b128 v[112:115], v86 offset:53248
	s_waitcnt lgkmcnt(0)
	v_mfma_f32_32x32x16_bf16 v[34:49], v[100:103], v[108:111], v[34:49]
	s_mov_b32 m0, s46
	v_mfma_f32_32x32x16_bf16 v[50:65], v[100:103], v[112:115], v[50:65]
	v_mfma_f32_32x32x16_bf16 v[2:17], v[104:107], v[108:111], v[2:17]
	v_mfma_f32_32x32x16_bf16 v[18:33], v[104:107], v[112:115], v[18:33]
	ds_read_b128 v[100:103], v88 offset:32768
	ds_read_b128 v[104:107], v88 offset:36864
	ds_read_b128 v[108:111], v89 offset:49152
	ds_read_b128 v[112:115], v89 offset:53248
	s_waitcnt lgkmcnt(1)
	v_mfma_f32_32x32x16_bf16 v[34:49], v[100:103], v[108:111], v[34:49]
	s_waitcnt lgkmcnt(0)
	v_mfma_f32_32x32x16_bf16 v[50:65], v[100:103], v[112:115], v[50:65]
	v_mfma_f32_32x32x16_bf16 v[2:17], v[104:107], v[108:111], v[2:17]
	v_mfma_f32_32x32x16_bf16 v[18:33], v[104:107], v[112:115], v[18:33]
	ds_read_b128 v[100:103], v90 offset:32768
	ds_read_b128 v[104:107], v90 offset:36864
	ds_read_b128 v[108:111], v84 offset:49152
	ds_read_b128 v[112:115], v84 offset:53248
	s_waitcnt lgkmcnt(1)
	v_mfma_f32_32x32x16_bf16 v[34:49], v[100:103], v[108:111], v[34:49]
	s_waitcnt lgkmcnt(0)
	v_mfma_f32_32x32x16_bf16 v[50:65], v[100:103], v[112:115], v[50:65]
	v_mfma_f32_32x32x16_bf16 v[2:17], v[104:107], v[108:111], v[2:17]
	v_mfma_f32_32x32x16_bf16 v[18:33], v[104:107], v[112:115], v[18:33]
	ds_read_b128 v[100:103], v85 offset:32768
	ds_read_b128 v[104:107], v85 offset:36864
	ds_read_b128 v[108:111], v87 offset:49152
	ds_read_b128 v[112:115], v87 offset:53248
	s_waitcnt vmcnt(0)
	s_waitcnt lgkmcnt(0)
	s_barrier
; #define MFMA(a, b, c) __builtin_amdgcn_mfma_f32_32x32x16_bf16((a), (b), (c), 0, 0, 0)
; #define TIDX opaque_tid()
; template <int AI, int BI>
; DI void gemm_tile(const u16* __restrict__ A, int lda, const u16* __restrict__ B, int ldb, int nk, bool swap,
;                   f32x16 (&acc)[AI][BI], char* lds) {
;   const int tid = TIDX, lane = tid & 63, wid = tid >> 6;
;   gemm_stage<AI, BI>(A, lda, B, ldb, lds, tid);
;   asm volatile("s_waitcnt vmcnt(0)" ::: "memory");
;   __syncthreads();
;   const int wa = wid >> 1, wb = wid & 1, r = lane & 31, h = lane >> 5, sw = (r >> 1) & 7;
;   const int offA = (swap ? 16384 : 0) + (wa * 32 * AI + r) * 128;
;   const int offB = (swap ? 0 : 16384) + (wb * 32 * BI + r) * 128;
;   for (int kt = 0; kt < nk; ++kt) {
;     const char* cur = lds + (kt & 1) * 32768;
;     if (kt + 1 < nk) gemm_stage<AI, BI>(A + (kt + 1) * 64, lda, B + (kt + 1) * 64, ldb, lds + ((kt + 1) & 1) * 32768, tid);
; #pragma unroll
;     for (int ks = 0; ks < 4; ++ks) {
;       const int co = ((ks * 2 + h) ^ sw) << 4;
;       s16x8 fa[AI], fb[BI];
; #pragma unroll
;       for (int i = 0; i < AI; ++i) fa[i] = *(const s16x8*)(cur + offA + i * 4096 + co);
; #pragma unroll
;       for (int i = 0; i < BI; ++i) fb[i] = *(const s16x8*)(cur + offB + i * 4096 + co);
; #pragma unroll
;       for (int i = 0; i < AI; ++i)
; #pragma unroll
;         for (int j = 0; j < BI; ++j) acc[i][j] = MFMA(fa[i], fb[j], acc[i][j]);
;     }
;     asm volatile("s_waitcnt vmcnt(0)" ::: "memory");
;     __syncthreads();
;   }
	v_mfma_f32_32x32x16_bf16 v[34:49], v[100:103], v[108:111], v[34:49]
	v_mfma_f32_32x32x16_bf16 v[50:65], v[100:103], v[112:115], v[50:65]
	v_lshl_add_u64 v[100:101], v[66:67], 0, s[76:77]
	global_load_lds_dwordx4 v[100:101], off
	v_lshl_add_u64 v[100:101], v[68:69], 0, s[76:77]
	s_mov_b32 m0, s47
	s_nop 0
	global_load_lds_dwordx4 v[100:101], off
	v_lshl_add_u64 v[100:101], v[70:71], 0, s[76:77]
	s_mov_b32 m0, s48
	v_mfma_f32_32x32x16_bf16 v[2:17], v[104:107], v[108:111], v[2:17]
	global_load_lds_dwordx4 v[100:101], off
	s_mov_b32 m0, s49
	s_nop 0
	global_load_lds_dwordx4 v[92:93], off
	v_lshl_add_u64 v[92:93], v[74:75], 0, s[76:77]
	s_mov_b32 m0, s50
	v_mfma_f32_32x32x16_bf16 v[18:33], v[104:107], v[112:115], v[18:33]
	global_load_lds_dwordx4 v[92:93], off
	v_lshl_add_u64 v[92:93], v[76:77], 0, s[76:77]
	s_mov_b32 m0, s51
	s_nop 0
	global_load_lds_dwordx4 v[92:93], off
	v_lshl_add_u64 v[92:93], v[78:79], 0, s[76:77]
	s_mov_b32 m0, s52
	s_nop 0
	global_load_lds_dwordx4 v[92:93], off
	v_lshl_add_u64 v[92:93], v[80:81], 0, s[76:77]
	s_mov_b32 m0, s18
	s_nop 0
	global_load_lds_dwordx4 v[92:93], off
	ds_read_b128 v[92:95], v0
	ds_read_b128 v[96:99], v0 offset:4096
	ds_read_b128 v[100:103], v86 offset:16384
	ds_read_b128 v[104:107], v86 offset:20480
	s_waitcnt lgkmcnt(0)
	v_mfma_f32_32x32x16_bf16 v[34:49], v[92:95], v[100:103], v[34:49]
	s_mov_b32 m0, s36
	v_mfma_f32_32x32x16_bf16 v[50:65], v[92:95], v[104:107], v[50:65]
	v_mfma_f32_32x32x16_bf16 v[2:17], v[96:99], v[100:103], v[2:17]
	v_mfma_f32_32x32x16_bf16 v[18:33], v[96:99], v[104:107], v[18:33]
	ds_read_b128 v[92:95], v88
	ds_read_b128 v[96:99], v88 offset:4096
	ds_read_b128 v[100:103], v89 offset:16384
	ds_read_b128 v[104:107], v89 offset:20480
	s_waitcnt lgkmcnt(1)
	v_mfma_f32_32x32x16_bf16 v[34:49], v[92:95], v[100:103], v[34:49]
	s_waitcnt lgkmcnt(0)
	v_mfma_f32_32x32x16_bf16 v[50:65], v[92:95], v[104:107], v[50:65]
	v_mfma_f32_32x32x16_bf16 v[2:17], v[96:99], v[100:103], v[2:17]
	v_mfma_f32_32x32x16_bf16 v[18:33], v[96:99], v[104:107], v[18:33]
	ds_read_b128 v[92:95], v90
	ds_read_b128 v[96:99], v90 offset:4096
	ds_read_b128 v[100:103], v84 offset:16384
	ds_read_b128 v[104:107], v84 offset:20480
	s_waitcnt lgkmcnt(1)
	v_mfma_f32_32x32x16_bf16 v[34:49], v[92:95], v[100:103], v[34:49]
	s_waitcnt lgkmcnt(0)
	v_mfma_f32_32x32x16_bf16 v[50:65], v[92:95], v[104:107], v[50:65]
	v_mfma_f32_32x32x16_bf16 v[2:17], v[96:99], v[100:103], v[2:17]
	v_mfma_f32_32x32x16_bf16 v[18:33], v[96:99], v[104:107], v[18:33]
	ds_read_b128 v[92:95], v85
	ds_read_b128 v[96:99], v85 offset:4096
	ds_read_b128 v[100:103], v87 offset:16384
	ds_read_b128 v[104:107], v87 offset:20480
	s_waitcnt vmcnt(0)
	s_waitcnt lgkmcnt(0)
	s_barrier
	v_mfma_f32_32x32x16_bf16 v[34:49], v[92:95], v[100:103], v[34:49]
	v_mfma_f32_32x32x16_bf16 v[50:65], v[92:95], v[104:107], v[50:65]
	v_lshl_add_u64 v[92:93], v[66:67], 0, s[80:81]
	global_load_lds_dwordx4 v[92:93], off
	v_lshl_add_u64 v[92:93], v[68:69], 0, s[80:81]
	s_mov_b32 m0, s37
	s_nop 0
	global_load_lds_dwordx4 v[92:93], off
	v_lshl_add_u64 v[92:93], v[70:71], 0, s[80:81]
	s_mov_b32 m0, s40
	v_mfma_f32_32x32x16_bf16 v[2:17], v[96:99], v[100:103], v[2:17]
	global_load_lds_dwordx4 v[92:93], off
	v_lshl_add_u64 v[92:93], v[72:73], 0, s[80:81]
	s_mov_b32 m0, s41
	s_nop 0
	global_load_lds_dwordx4 v[92:93], off
	v_lshl_add_u64 v[92:93], v[74:75], 0, s[80:81]
	s_mov_b32 m0, s28
	v_mfma_f32_32x32x16_bf16 v[18:33], v[96:99], v[104:107], v[18:33]
	global_load_lds_dwordx4 v[92:93], off
	v_lshl_add_u64 v[92:93], v[76:77], 0, s[80:81]
	s_mov_b32 m0, s29
	s_nop 0
	global_load_lds_dwordx4 v[92:93], off
	v_lshl_add_u64 v[92:93], v[78:79], 0, s[80:81]
	s_mov_b32 m0, s34
	s_nop 0
	global_load_lds_dwordx4 v[92:93], off
	v_lshl_add_u64 v[92:93], v[80:81], 0, s[80:81]
	s_mov_b32 m0, s35
	s_nop 0
	global_load_lds_dwordx4 v[92:93], off
	ds_read_b128 v[92:95], v0 offset:32768
	ds_read_b128 v[96:99], v0 offset:36864
	ds_read_b128 v[100:103], v86 offset:49152
	ds_read_b128 v[104:107], v86 offset:53248
	s_waitcnt lgkmcnt(0)
	v_mfma_f32_32x32x16_bf16 v[34:49], v[92:95], v[100:103], v[34:49]
	s_mov_b32 m0, s46
	v_mfma_f32_32x32x16_bf16 v[50:65], v[92:95], v[104:107], v[50:65]
	v_mfma_f32_32x32x16_bf16 v[2:17], v[96:99], v[100:103], v[2:17]
	v_mfma_f32_32x32x16_bf16 v[18:33], v[96:99], v[104:107], v[18:33]
	ds_read_b128 v[92:95], v88 offset:32768
	ds_read_b128 v[96:99], v88 offset:36864
	ds_read_b128 v[100:103], v89 offset:49152
	ds_read_b128 v[104:107], v89 offset:53248
	s_waitcnt lgkmcnt(1)
	v_mfma_f32_32x32x16_bf16 v[34:49], v[92:95], v[100:103], v[34:49]
	s_waitcnt lgkmcnt(0)
	v_mfma_f32_32x32x16_bf16 v[50:65], v[92:95], v[104:107], v[50:65]
	v_mfma_f32_32x32x16_bf16 v[2:17], v[96:99], v[100:103], v[2:17]
	v_mfma_f32_32x32x16_bf16 v[18:33], v[96:99], v[104:107], v[18:33]
	ds_read_b128 v[92:95], v90 offset:32768
	ds_read_b128 v[96:99], v90 offset:36864
	ds_read_b128 v[100:103], v84 offset:49152
	ds_read_b128 v[104:107], v84 offset:53248
	s_waitcnt lgkmcnt(1)
	v_mfma_f32_32x32x16_bf16 v[34:49], v[92:95], v[100:103], v[34:49]
	s_waitcnt lgkmcnt(0)
	v_mfma_f32_32x32x16_bf16 v[50:65], v[92:95], v[104:107], v[50:65]
	v_mfma_f32_32x32x16_bf16 v[2:17], v[96:99], v[100:103], v[2:17]
	v_mfma_f32_32x32x16_bf16 v[18:33], v[96:99], v[104:107], v[18:33]
	ds_read_b128 v[92:95], v85 offset:32768
	ds_read_b128 v[96:99], v85 offset:36864
	ds_read_b128 v[100:103], v87 offset:49152
	ds_read_b128 v[104:107], v87 offset:53248
	s_waitcnt vmcnt(0)
	s_waitcnt lgkmcnt(0)
	s_barrier
; #define MFMA(a, b, c) __builtin_amdgcn_mfma_f32_32x32x16_bf16((a), (b), (c), 0, 0, 0)
; #define TIDX opaque_tid()
; template <int AI, int BI>
; DI void gemm_tile(const u16* __restrict__ A, int lda, const u16* __restrict__ B, int ldb, int nk, bool swap,
;                   f32x16 (&acc)[AI][BI], char* lds) {
;   const int tid = TIDX, lane = tid & 63, wid = tid >> 6;
;   gemm_stage<AI, BI>(A, lda, B, ldb, lds, tid);
;   asm volatile("s_waitcnt vmcnt(0)" ::: "memory");
;   __syncthreads();
;   const int wa = wid >> 1, wb = wid & 1, r = lane & 31, h = lane >> 5, sw = (r >> 1) & 7;
;   const int offA = (swap ? 16384 : 0) + (wa * 32 * AI + r) * 128;
;   const int offB = (swap ? 0 : 16384) + (wb * 32 * BI + r) * 128;
;   for (int kt = 0; kt < nk; ++kt) {
;     const char* cur = lds + (kt & 1) * 32768;
;     if (kt + 1 < nk) gemm_stage<AI, BI>(A + (kt + 1) * 64, lda, B + (kt + 1) * 64, ldb, lds + ((kt + 1) & 1) * 32768, tid);
; #pragma unroll
;     for (int ks = 0; ks < 4; ++ks) {
;       const int co = ((ks * 2 + h) ^ sw) << 4;
;       s16x8 fa[AI], fb[BI];
; #pragma unroll
;       for (int i = 0; i < AI; ++i) fa[i] = *(const s16x8*)(cur + offA + i * 4096 + co);
; #pragma unroll
;       for (int i = 0; i < BI; ++i) fb[i] = *(const s16x8*)(cur + offB + i * 4096 + co);
; #pragma unroll
;       for (int i = 0; i < AI; ++i)
; #pragma unroll
;         for (int j = 0; j < BI; ++j) acc[i][j] = MFMA(fa[i], fb[j], acc[i][j]);
;     }
;     asm volatile("s_waitcnt vmcnt(0)" ::: "memory");
;     __syncthreads();
;   }
	v_mfma_f32_32x32x16_bf16 v[34:49], v[92:95], v[100:103], v[34:49]
	v_mfma_f32_32x32x16_bf16 v[50:65], v[92:95], v[104:107], v[50:65]
	v_lshl_add_u64 v[92:93], v[66:67], 0, s[82:83]
	global_load_lds_dwordx4 v[92:93], off
	v_lshl_add_u64 v[92:93], v[68:69], 0, s[82:83]
	s_mov_b32 m0, s47
	s_nop 0
	global_load_lds_dwordx4 v[92:93], off
	v_lshl_add_u64 v[92:93], v[70:71], 0, s[82:83]
	s_mov_b32 m0, s48
	v_mfma_f32_32x32x16_bf16 v[2:17], v[96:99], v[100:103], v[2:17]
	global_load_lds_dwordx4 v[92:93], off
	v_lshl_add_u64 v[92:93], v[72:73], 0, s[82:83]
	s_mov_b32 m0, s49
	s_nop 0
	global_load_lds_dwordx4 v[92:93], off
	v_lshl_add_u64 v[92:93], v[74:75], 0, s[82:83]
	s_mov_b32 m0, s50
	v_mfma_f32_32x32x16_bf16 v[18:33], v[96:99], v[104:107], v[18:33]
	global_load_lds_dwordx4 v[92:93], off
	v_lshl_add_u64 v[92:93], v[76:77], 0, s[82:83]
	s_mov_b32 m0, s51
	s_nop 0
	global_load_lds_dwordx4 v[92:93], off
	v_lshl_add_u64 v[92:93], v[78:79], 0, s[82:83]
	s_mov_b32 m0, s52
	s_nop 0
	global_load_lds_dwordx4 v[92:93], off
	v_lshl_add_u64 v[92:93], v[80:81], 0, s[82:83]
	s_mov_b32 m0, s18
	s_nop 0
	global_load_lds_dwordx4 v[92:93], off
	ds_read_b128 v[92:95], v0
	ds_read_b128 v[96:99], v0 offset:4096
	ds_read_b128 v[100:103], v86 offset:16384
	ds_read_b128 v[104:107], v86 offset:20480
	s_waitcnt lgkmcnt(0)
	v_mfma_f32_32x32x16_bf16 v[34:49], v[92:95], v[100:103], v[34:49]
	s_mov_b32 m0, s36
	v_mfma_f32_32x32x16_bf16 v[50:65], v[92:95], v[104:107], v[50:65]
	v_mfma_f32_32x32x16_bf16 v[2:17], v[96:99], v[100:103], v[2:17]
	v_mfma_f32_32x32x16_bf16 v[18:33], v[96:99], v[104:107], v[18:33]
	ds_read_b128 v[92:95], v88
	ds_read_b128 v[96:99], v88 offset:4096
	ds_read_b128 v[100:103], v89 offset:16384
	ds_read_b128 v[104:107], v89 offset:20480
	s_waitcnt lgkmcnt(1)
	v_mfma_f32_32x32x16_bf16 v[34:49], v[92:95], v[100:103], v[34:49]
	s_waitcnt lgkmcnt(0)
	v_mfma_f32_32x32x16_bf16 v[50:65], v[92:95], v[104:107], v[50:65]
	v_mfma_f32_32x32x16_bf16 v[2:17], v[96:99], v[100:103], v[2:17]
	v_mfma_f32_32x32x16_bf16 v[18:33], v[96:99], v[104:107], v[18:33]
	ds_read_b128 v[92:95], v90
	ds_read_b128 v[96:99], v90 offset:4096
	ds_read_b128 v[100:103], v84 offset:16384
	ds_read_b128 v[104:107], v84 offset:20480
	s_waitcnt lgkmcnt(1)
	v_mfma_f32_32x32x16_bf16 v[34:49], v[92:95], v[100:103], v[34:49]
	s_waitcnt lgkmcnt(0)
	v_mfma_f32_32x32x16_bf16 v[50:65], v[92:95], v[104:107], v[50:65]
	v_mfma_f32_32x32x16_bf16 v[2:17], v[96:99], v[100:103], v[2:17]
	v_mfma_f32_32x32x16_bf16 v[18:33], v[96:99], v[104:107], v[18:33]
	ds_read_b128 v[92:95], v85
	ds_read_b128 v[96:99], v85 offset:4096
	ds_read_b128 v[100:103], v87 offset:16384
	ds_read_b128 v[104:107], v87 offset:20480
	s_waitcnt vmcnt(0)
	s_waitcnt lgkmcnt(0)
	s_barrier
	v_mfma_f32_32x32x16_bf16 v[34:49], v[92:95], v[100:103], v[34:49]
	v_mfma_f32_32x32x16_bf16 v[50:65], v[92:95], v[104:107], v[50:65]
	v_lshl_add_u64 v[92:93], v[66:67], 0, s[84:85]
	global_load_lds_dwordx4 v[92:93], off
	v_lshl_add_u64 v[92:93], v[68:69], 0, s[84:85]
	s_mov_b32 m0, s37
	s_nop 0
	global_load_lds_dwordx4 v[92:93], off
	v_lshl_add_u64 v[92:93], v[70:71], 0, s[84:85]
	s_mov_b32 m0, s40
	v_mfma_f32_32x32x16_bf16 v[2:17], v[96:99], v[100:103], v[2:17]
	global_load_lds_dwordx4 v[92:93], off
	v_lshl_add_u64 v[92:93], v[72:73], 0, s[84:85]
	s_mov_b32 m0, s41
	s_nop 0
	global_load_lds_dwordx4 v[92:93], off
	v_lshl_add_u64 v[92:93], v[74:75], 0, s[84:85]
	s_mov_b32 m0, s28
	v_mfma_f32_32x32x16_bf16 v[18:33], v[96:99], v[104:107], v[18:33]
	global_load_lds_dwordx4 v[92:93], off
	v_lshl_add_u64 v[92:93], v[76:77], 0, s[84:85]
	s_mov_b32 m0, s29
	s_nop 0
	global_load_lds_dwordx4 v[92:93], off
	v_lshl_add_u64 v[92:93], v[78:79], 0, s[84:85]
	s_mov_b32 m0, s34
	s_nop 0
	global_load_lds_dwordx4 v[92:93], off
	v_lshl_add_u64 v[92:93], v[80:81], 0, s[84:85]
	s_mov_b32 m0, s35
	s_nop 0
	global_load_lds_dwordx4 v[92:93], off
	ds_read_b128 v[92:95], v0 offset:32768
	ds_read_b128 v[96:99], v0 offset:36864
	ds_read_b128 v[100:103], v86 offset:49152
	ds_read_b128 v[104:107], v86 offset:53248
	s_waitcnt lgkmcnt(0)
	v_mfma_f32_32x32x16_bf16 v[34:49], v[92:95], v[100:103], v[34:49]
	s_mov_b32 m0, s46
	v_mfma_f32_32x32x16_bf16 v[50:65], v[92:95], v[104:107], v[50:65]
	v_mfma_f32_32x32x16_bf16 v[2:17], v[96:99], v[100:103], v[2:17]
	v_mfma_f32_32x32x16_bf16 v[18:33], v[96:99], v[104:107], v[18:33]
	ds_read_b128 v[92:95], v88 offset:32768
	ds_read_b128 v[96:99], v88 offset:36864
	ds_read_b128 v[100:103], v89 offset:49152
	ds_read_b128 v[104:107], v89 offset:53248
	s_waitcnt lgkmcnt(1)
	v_mfma_f32_32x32x16_bf16 v[34:49], v[92:95], v[100:103], v[34:49]
	s_waitcnt lgkmcnt(0)
	v_mfma_f32_32x32x16_bf16 v[50:65], v[92:95], v[104:107], v[50:65]
	v_mfma_f32_32x32x16_bf16 v[2:17], v[96:99], v[100:103], v[2:17]
	v_mfma_f32_32x32x16_bf16 v[18:33], v[96:99], v[104:107], v[18:33]
	ds_read_b128 v[92:95], v90 offset:32768
	ds_read_b128 v[96:99], v90 offset:36864
	ds_read_b128 v[100:103], v84 offset:49152
	ds_read_b128 v[104:107], v84 offset:53248
	s_waitcnt lgkmcnt(1)
	v_mfma_f32_32x32x16_bf16 v[34:49], v[92:95], v[100:103], v[34:49]
	s_waitcnt lgkmcnt(0)
	v_mfma_f32_32x32x16_bf16 v[50:65], v[92:95], v[104:107], v[50:65]
	v_mfma_f32_32x32x16_bf16 v[2:17], v[96:99], v[100:103], v[2:17]
	v_mfma_f32_32x32x16_bf16 v[18:33], v[96:99], v[104:107], v[18:33]
	ds_read_b128 v[92:95], v85 offset:32768
	ds_read_b128 v[96:99], v85 offset:36864
	ds_read_b128 v[100:103], v87 offset:49152
	ds_read_b128 v[104:107], v87 offset:53248
	s_waitcnt vmcnt(0)
	s_waitcnt lgkmcnt(0)
	s_barrier
; #define MFMA(a, b, c) __builtin_amdgcn_mfma_f32_32x32x16_bf16((a), (b), (c), 0, 0, 0)
; #define TIDX opaque_tid()
; template <int AI, int BI>
; DI void gemm_tile(const u16* __restrict__ A, int lda, const u16* __restrict__ B, int ldb, int nk, bool swap,
;                   f32x16 (&acc)[AI][BI], char* lds) {
;   const int tid = TIDX, lane = tid & 63, wid = tid >> 6;
;   gemm_stage<AI, BI>(A, lda, B, ldb, lds, tid);
;   asm volatile("s_waitcnt vmcnt(0)" ::: "memory");
;   __syncthreads();
;   const int wa = wid >> 1, wb = wid & 1, r = lane & 31, h = lane >> 5, sw = (r >> 1) & 7;
;   const int offA = (swap ? 16384 : 0) + (wa * 32 * AI + r) * 128;
;   const int offB = (swap ? 0 : 16384) + (wb * 32 * BI + r) * 128;
;   for (int kt = 0; kt < nk; ++kt) {
;     const char* cur = lds + (kt & 1) * 32768;
;     if (kt + 1 < nk) gemm_stage<AI, BI>(A + (kt + 1) * 64, lda, B + (kt + 1) * 64, ldb, lds + ((kt + 1) & 1) * 32768, tid);
; #pragma unroll
;     for (int ks = 0; ks < 4; ++ks) {
;       const int co = ((ks * 2 + h) ^ sw) << 4;
;       s16x8 fa[AI], fb[BI];
; #pragma unroll
;       for (int i = 0; i < AI; ++i) fa[i] = *(const s16x8*)(cur + offA + i * 4096 + co);
; #pragma unroll
;       for (int i = 0; i < BI; ++i) fb[i] = *(const s16x8*)(cur + offB + i * 4096 + co);
; #pragma unroll
;       for (int i = 0; i < AI; ++i)
; #pragma unroll
;         for (int j = 0; j < BI; ++j) acc[i][j] = MFMA(fa[i], fb[j], acc[i][j]);
;     }
;     asm volatile("s_waitcnt vmcnt(0)" ::: "memory");
;     __syncthreads();
;   }
	v_mfma_f32_32x32x16_bf16 v[34:49], v[92:95], v[100:103], v[34:49]
	v_mfma_f32_32x32x16_bf16 v[50:65], v[92:95], v[104:107], v[50:65]
	v_lshl_add_u64 v[92:93], v[66:67], 0, s[78:79]
	global_load_lds_dwordx4 v[92:93], off
	v_lshl_add_u64 v[92:93], v[68:69], 0, s[78:79]
	s_mov_b32 m0, s47
	s_nop 0
	global_load_lds_dwordx4 v[92:93], off
	v_lshl_add_u64 v[92:93], v[70:71], 0, s[78:79]
	s_mov_b32 m0, s48
	v_mfma_f32_32x32x16_bf16 v[2:17], v[96:99], v[100:103], v[2:17]
	global_load_lds_dwordx4 v[92:93], off
	v_lshl_add_u64 v[92:93], v[72:73], 0, s[78:79]
	s_mov_b32 m0, s49
	s_nop 0
	global_load_lds_dwordx4 v[92:93], off
	v_lshl_add_u64 v[92:93], v[74:75], 0, s[78:79]
	s_mov_b32 m0, s50
	v_mfma_f32_32x32x16_bf16 v[18:33], v[96:99], v[104:107], v[18:33]
	global_load_lds_dwordx4 v[92:93], off
	v_lshl_add_u64 v[92:93], v[76:77], 0, s[78:79]
	s_mov_b32 m0, s51
	s_nop 0
	global_load_lds_dwordx4 v[92:93], off
	v_lshl_add_u64 v[92:93], v[78:79], 0, s[78:79]
	s_mov_b32 m0, s52
	s_nop 0
	global_load_lds_dwordx4 v[92:93], off
	v_lshl_add_u64 v[92:93], v[80:81], 0, s[78:79]
	s_mov_b32 m0, s18
	s_nop 0
	global_load_lds_dwordx4 v[92:93], off
	ds_read_b128 v[92:95], v0
	ds_read_b128 v[96:99], v0 offset:4096
	ds_read_b128 v[100:103], v86 offset:16384
	ds_read_b128 v[104:107], v86 offset:20480
	s_waitcnt lgkmcnt(0)
	v_mfma_f32_32x32x16_bf16 v[34:49], v[92:95], v[100:103], v[34:49]
	s_mov_b32 m0, s36
	v_mfma_f32_32x32x16_bf16 v[50:65], v[92:95], v[104:107], v[50:65]
	v_mfma_f32_32x32x16_bf16 v[2:17], v[96:99], v[100:103], v[2:17]
	v_mfma_f32_32x32x16_bf16 v[18:33], v[96:99], v[104:107], v[18:33]
	ds_read_b128 v[92:95], v88
	ds_read_b128 v[96:99], v88 offset:4096
	ds_read_b128 v[100:103], v89 offset:16384
	ds_read_b128 v[104:107], v89 offset:20480
	s_waitcnt lgkmcnt(1)
	v_mfma_f32_32x32x16_bf16 v[34:49], v[92:95], v[100:103], v[34:49]
	s_waitcnt lgkmcnt(0)
	v_mfma_f32_32x32x16_bf16 v[50:65], v[92:95], v[104:107], v[50:65]
	v_mfma_f32_32x32x16_bf16 v[2:17], v[96:99], v[100:103], v[2:17]
	v_mfma_f32_32x32x16_bf16 v[18:33], v[96:99], v[104:107], v[18:33]
	ds_read_b128 v[92:95], v90
	ds_read_b128 v[96:99], v90 offset:4096
	ds_read_b128 v[100:103], v84 offset:16384
	ds_read_b128 v[104:107], v84 offset:20480
	s_waitcnt lgkmcnt(1)
	v_mfma_f32_32x32x16_bf16 v[34:49], v[92:95], v[100:103], v[34:49]
	s_waitcnt lgkmcnt(0)
	v_mfma_f32_32x32x16_bf16 v[50:65], v[92:95], v[104:107], v[50:65]
	v_mfma_f32_32x32x16_bf16 v[2:17], v[96:99], v[100:103], v[2:17]
	v_mfma_f32_32x32x16_bf16 v[18:33], v[96:99], v[104:107], v[18:33]
	ds_read_b128 v[92:95], v85
	ds_read_b128 v[96:99], v85 offset:4096
	ds_read_b128 v[100:103], v87 offset:16384
	ds_read_b128 v[104:107], v87 offset:20480
	s_waitcnt vmcnt(0)
	s_waitcnt lgkmcnt(0)
	s_barrier
	v_mfma_f32_32x32x16_bf16 v[34:49], v[92:95], v[100:103], v[34:49]
	v_mfma_f32_32x32x16_bf16 v[50:65], v[92:95], v[104:107], v[50:65]
	v_lshl_add_u64 v[92:93], v[66:67], 0, s[2:3]
	global_load_lds_dwordx4 v[92:93], off
	v_lshl_add_u64 v[92:93], v[68:69], 0, s[2:3]
	s_mov_b32 m0, s37
	v_lshl_add_u64 v[66:67], v[66:67], 0, s[30:31]
	global_load_lds_dwordx4 v[92:93], off
	v_lshl_add_u64 v[92:93], v[70:71], 0, s[2:3]
	s_mov_b32 m0, s40
	v_mfma_f32_32x32x16_bf16 v[2:17], v[96:99], v[100:103], v[2:17]
	global_load_lds_dwordx4 v[92:93], off
	v_lshl_add_u64 v[92:93], v[72:73], 0, s[2:3]
	s_mov_b32 m0, s41
	s_nop 0
	global_load_lds_dwordx4 v[92:93], off
	v_lshl_add_u64 v[92:93], v[74:75], 0, s[2:3]
	s_mov_b32 m0, s28
	v_mfma_f32_32x32x16_bf16 v[18:33], v[96:99], v[104:107], v[18:33]
	global_load_lds_dwordx4 v[92:93], off
	v_lshl_add_u64 v[92:93], v[76:77], 0, s[2:3]
	s_mov_b32 m0, s29
	s_movk_i32 s28, 0xb00
	global_load_lds_dwordx4 v[92:93], off
	v_lshl_add_u64 v[92:93], v[78:79], 0, s[2:3]
	s_mov_b32 m0, s34
	s_nop 0
	global_load_lds_dwordx4 v[92:93], off
	v_lshl_add_u64 v[92:93], v[80:81], 0, s[2:3]
	s_mov_b32 m0, s35
	s_nop 0
	global_load_lds_dwordx4 v[92:93], off
	ds_read_b128 v[92:95], v0 offset:32768
	ds_read_b128 v[96:99], v0 offset:36864
	ds_read_b128 v[100:103], v86 offset:49152
	ds_read_b128 v[104:107], v86 offset:53248
	s_waitcnt lgkmcnt(0)
	v_mfma_f32_32x32x16_bf16 v[34:49], v[92:95], v[100:103], v[34:49]
	s_mov_b32 m0, s46
	v_mfma_f32_32x32x16_bf16 v[50:65], v[92:95], v[104:107], v[50:65]
	v_mfma_f32_32x32x16_bf16 v[2:17], v[96:99], v[100:103], v[2:17]
	v_mfma_f32_32x32x16_bf16 v[18:33], v[96:99], v[104:107], v[18:33]
	ds_read_b128 v[92:95], v88 offset:32768
	ds_read_b128 v[96:99], v88 offset:36864
	ds_read_b128 v[100:103], v89 offset:49152
	ds_read_b128 v[104:107], v89 offset:53248
	s_waitcnt lgkmcnt(1)
	v_mfma_f32_32x32x16_bf16 v[34:49], v[92:95], v[100:103], v[34:49]
	s_waitcnt lgkmcnt(0)
	v_mfma_f32_32x32x16_bf16 v[50:65], v[92:95], v[104:107], v[50:65]
	v_mfma_f32_32x32x16_bf16 v[2:17], v[96:99], v[100:103], v[2:17]
	v_mfma_f32_32x32x16_bf16 v[18:33], v[96:99], v[104:107], v[18:33]
	ds_read_b128 v[92:95], v90 offset:32768
	ds_read_b128 v[96:99], v90 offset:36864
	ds_read_b128 v[100:103], v84 offset:49152
	ds_read_b128 v[104:107], v84 offset:53248
	s_waitcnt lgkmcnt(1)
	v_mfma_f32_32x32x16_bf16 v[34:49], v[92:95], v[100:103], v[34:49]
	s_waitcnt lgkmcnt(0)
	v_mfma_f32_32x32x16_bf16 v[50:65], v[92:95], v[104:107], v[50:65]
	v_mfma_f32_32x32x16_bf16 v[2:17], v[96:99], v[100:103], v[2:17]
	v_mfma_f32_32x32x16_bf16 v[18:33], v[96:99], v[104:107], v[18:33]
	ds_read_b128 v[92:95], v85 offset:32768
	ds_read_b128 v[96:99], v85 offset:36864
	ds_read_b128 v[100:103], v87 offset:49152
	ds_read_b128 v[104:107], v87 offset:53248
	s_waitcnt vmcnt(0)
	s_waitcnt lgkmcnt(0)
	s_barrier
; #define MFMA(a, b, c) __builtin_amdgcn_mfma_f32_32x32x16_bf16((a), (b), (c), 0, 0, 0)
; #define TIDX opaque_tid()
; template <int AI, int BI>
; DI void gemm_tile(const u16* __restrict__ A, int lda, const u16* __restrict__ B, int ldb, int nk, bool swap,
;                   f32x16 (&acc)[AI][BI], char* lds) {
;   const int tid = TIDX, lane = tid & 63, wid = tid >> 6;
;   gemm_stage<AI, BI>(A, lda, B, ldb, lds, tid);
;   asm volatile("s_waitcnt vmcnt(0)" ::: "memory");
;   __syncthreads();
;   const int wa = wid >> 1, wb = wid & 1, r = lane & 31, h = lane >> 5, sw = (r >> 1) & 7;
;   const int offA = (swap ? 16384 : 0) + (wa * 32 * AI + r) * 128;
;   const int offB = (swap ? 0 : 16384) + (wb * 32 * BI + r) * 128;
;   for (int kt = 0; kt < nk; ++kt) {
;     const char* cur = lds + (kt & 1) * 32768;
;     if (kt + 1 < nk) gemm_stage<AI, BI>(A + (kt + 1) * 64, lda, B + (kt + 1) * 64, ldb, lds + ((kt + 1) & 1) * 32768, tid);
; #pragma unroll
;     for (int ks = 0; ks < 4; ++ks) {
;       const int co = ((ks * 2 + h) ^ sw) << 4;
;       s16x8 fa[AI], fb[BI];
; #pragma unroll
;       for (int i = 0; i < AI; ++i) fa[i] = *(const s16x8*)(cur + offA + i * 4096 + co);
; #pragma unroll
;       for (int i = 0; i < BI; ++i) fb[i] = *(const s16x8*)(cur + offB + i * 4096 + co);
; #pragma unroll
;       for (int i = 0; i < AI; ++i)
; #pragma unroll
;         for (int j = 0; j < BI; ++j) acc[i][j] = MFMA(fa[i], fb[j], acc[i][j]);
;     }
;     asm volatile("s_waitcnt vmcnt(0)" ::: "memory");
;     __syncthreads();
;   }
	global_load_lds_dwordx4 v[66:67], off
	v_lshl_add_u64 v[66:67], v[68:69], 0, s[30:31]
	s_mov_b32 m0, s47
	v_mfma_f32_32x32x16_bf16 v[34:49], v[92:95], v[100:103], v[34:49]
	global_load_lds_dwordx4 v[66:67], off
	v_lshl_add_u64 v[66:67], v[70:71], 0, s[30:31]
	s_mov_b32 m0, s48
	s_nop 0
	global_load_lds_dwordx4 v[66:67], off
	v_lshl_add_u64 v[66:67], v[72:73], 0, s[30:31]
	s_mov_b32 m0, s49
	v_mfma_f32_32x32x16_bf16 v[50:65], v[92:95], v[104:107], v[50:65]
	global_load_lds_dwordx4 v[66:67], off
	v_lshl_add_u64 v[66:67], v[74:75], 0, s[30:31]
	s_mov_b32 m0, s50
	s_nop 0
	global_load_lds_dwordx4 v[66:67], off
	v_lshl_add_u64 v[66:67], v[76:77], 0, s[30:31]
	s_mov_b32 m0, s51
	v_mfma_f32_32x32x16_bf16 v[2:17], v[96:99], v[100:103], v[2:17]
	global_load_lds_dwordx4 v[66:67], off
	v_lshl_add_u64 v[66:67], v[78:79], 0, s[30:31]
	s_mov_b32 m0, s52
	s_nop 0
	global_load_lds_dwordx4 v[66:67], off
	v_lshl_add_u64 v[66:67], v[80:81], 0, s[30:31]
	s_mov_b32 m0, s18
	v_mfma_f32_32x32x16_bf16 v[18:33], v[96:99], v[104:107], v[18:33]
	global_load_lds_dwordx4 v[66:67], off
	ds_read_b128 v[66:69], v0
	ds_read_b128 v[70:73], v0 offset:4096
	ds_read_b128 v[74:77], v86 offset:16384
	ds_read_b128 v[78:81], v86 offset:20480
	s_waitcnt lgkmcnt(0)
	v_mfma_f32_32x32x16_bf16 v[34:49], v[66:69], v[74:77], v[34:49]
	v_mfma_f32_32x32x16_bf16 v[50:65], v[66:69], v[78:81], v[50:65]
	v_mfma_f32_32x32x16_bf16 v[2:17], v[70:73], v[74:77], v[2:17]
	v_mfma_f32_32x32x16_bf16 v[18:33], v[70:73], v[78:81], v[18:33]
	ds_read_b128 v[66:69], v88
	ds_read_b128 v[70:73], v88 offset:4096
	ds_read_b128 v[74:77], v89 offset:16384
	ds_read_b128 v[78:81], v89 offset:20480
	s_waitcnt lgkmcnt(1)
	v_mfma_f32_32x32x16_bf16 v[34:49], v[66:69], v[74:77], v[34:49]
	s_waitcnt lgkmcnt(0)
	v_mfma_f32_32x32x16_bf16 v[50:65], v[66:69], v[78:81], v[50:65]
	v_mfma_f32_32x32x16_bf16 v[2:17], v[70:73], v[74:77], v[2:17]
	v_mfma_f32_32x32x16_bf16 v[18:33], v[70:73], v[78:81], v[18:33]
	ds_read_b128 v[66:69], v90
	ds_read_b128 v[70:73], v90 offset:4096
	ds_read_b128 v[74:77], v84 offset:16384
	ds_read_b128 v[78:81], v84 offset:20480
	s_waitcnt lgkmcnt(1)
	v_mfma_f32_32x32x16_bf16 v[34:49], v[66:69], v[74:77], v[34:49]
	s_waitcnt lgkmcnt(0)
	v_mfma_f32_32x32x16_bf16 v[50:65], v[66:69], v[78:81], v[50:65]
	v_mfma_f32_32x32x16_bf16 v[2:17], v[70:73], v[74:77], v[2:17]
	v_mfma_f32_32x32x16_bf16 v[18:33], v[70:73], v[78:81], v[18:33]
	ds_read_b128 v[66:69], v85
	ds_read_b128 v[70:73], v85 offset:4096
	ds_read_b128 v[74:77], v87 offset:16384
	ds_read_b128 v[78:81], v87 offset:20480
	s_waitcnt vmcnt(0)
	s_waitcnt lgkmcnt(0)
	s_barrier
	v_mfma_f32_32x32x16_bf16 v[34:49], v[66:69], v[74:77], v[34:49]
	v_mfma_f32_32x32x16_bf16 v[50:65], v[66:69], v[78:81], v[50:65]
	v_mfma_f32_32x32x16_bf16 v[2:17], v[70:73], v[74:77], v[2:17]
	v_mfma_f32_32x32x16_bf16 v[18:33], v[70:73], v[78:81], v[18:33]
	ds_read_b128 v[66:69], v0 offset:32768
	ds_read_b128 v[70:73], v0 offset:36864
	ds_read_b128 v[74:77], v86 offset:49152
	ds_read_b128 v[78:81], v86 offset:53248
	v_mov_b32_e32 v0, v1
	s_waitcnt lgkmcnt(1)
	v_mfma_f32_32x32x16_bf16 v[34:49], v[66:69], v[74:77], v[34:49]
	s_waitcnt lgkmcnt(0)
	v_mfma_f32_32x32x16_bf16 v[50:65], v[66:69], v[78:81], v[50:65]
	v_mfma_f32_32x32x16_bf16 v[2:17], v[70:73], v[74:77], v[2:17]
	v_mfma_f32_32x32x16_bf16 v[18:33], v[70:73], v[78:81], v[18:33]
	ds_read_b128 v[66:69], v88 offset:32768
	ds_read_b128 v[70:73], v88 offset:36864
	ds_read_b128 v[74:77], v89 offset:49152
	ds_read_b128 v[78:81], v89 offset:53248
	s_waitcnt lgkmcnt(1)
	v_mfma_f32_32x32x16_bf16 v[34:49], v[66:69], v[74:77], v[34:49]
	s_waitcnt lgkmcnt(0)
	v_mfma_f32_32x32x16_bf16 v[50:65], v[66:69], v[78:81], v[50:65]
	v_mfma_f32_32x32x16_bf16 v[2:17], v[70:73], v[74:77], v[2:17]
	v_mfma_f32_32x32x16_bf16 v[18:33], v[70:73], v[78:81], v[18:33]
	ds_read_b128 v[66:69], v90 offset:32768
	ds_read_b128 v[70:73], v90 offset:36864
	ds_read_b128 v[74:77], v84 offset:49152
	ds_read_b128 v[78:81], v84 offset:53248
	s_waitcnt lgkmcnt(1)
	v_mfma_f32_32x32x16_bf16 v[34:49], v[66:69], v[74:77], v[34:49]
	s_waitcnt lgkmcnt(0)
	v_mfma_f32_32x32x16_bf16 v[50:65], v[66:69], v[78:81], v[50:65]
	v_mfma_f32_32x32x16_bf16 v[2:17], v[70:73], v[74:77], v[2:17]
	v_mfma_f32_32x32x16_bf16 v[18:33], v[70:73], v[78:81], v[18:33]
	ds_read_b128 v[66:69], v85 offset:32768
	ds_read_b128 v[70:73], v85 offset:36864
	ds_read_b128 v[74:77], v87 offset:49152
	ds_read_b128 v[78:81], v87 offset:53248
	s_waitcnt vmcnt(0)
	s_waitcnt lgkmcnt(0)
	s_barrier
; #define GAS __attribute__((address_space(1)))
; DI int opaque0() { int z = 0; asm volatile("" : "+v"(z)); return z; }
; template <int AI>
; DI void gu_tile(char* wsb, int sub, int m0, int n0, char* lds) {
;     ...
;   const int m0e = m0 + opaque0();
;   const int hc = (n0 >> 1) + wb * 32 + r;
;   GAS u16* HIDu = uptr(HID);
;   const unsigned ib = (unsigned)((m0e + wa * 32 * AI + 4 * h) * 2816 + hc);
; #pragma unroll
;   for (int ai = 0; ai < AI; ++ai)
; #pragma unroll
;     for (int reg = 0; reg < 16; ++reg) {
;       float g = acc[ai][0][reg], u = acc[ai][1][reg];
;       float v = g * __builtin_amdgcn_rcpf(1.f + __expf(-g)) * u;
;       HIDu[ib + (unsigned)((ai * 32 + (reg & 3) + 8 * (reg >> 2)) * 2816)] = f2bf(v);
;       if ((reg & 7) == 7) __builtin_amdgcn_sched_barrier(0);
;     }
	v_mfma_f32_32x32x16_bf16 v[34:49], v[66:69], v[74:77], v[34:49]
	v_mfma_f32_32x32x16_bf16 v[50:65], v[66:69], v[78:81], v[50:65]
	v_lshrrev_b32_e32 v66, 1, v83
	v_lshrrev_b32_e32 v68, 3, v82
	v_and_b32_e32 v67, 32, v66
	v_and_b32_e32 v66, 0xffffc0, v66
	v_and_or_b32 v68, v68, 4, s16
	v_add3_u32 v66, v68, v66, v0
	v_or3_b32 v0, s17, v91, v67
	s_nop 3
	v_mul_f32_e32 v67, 0xbfb8aa3b, v34
	v_exp_f32_e32 v67, v67
	v_mfma_f32_32x32x16_bf16 v[2:17], v[70:73], v[74:77], v[2:17]
	v_add_f32_e32 v67, 1.0, v67
	v_rcp_f32_e32 v67, v67
	s_nop 0
	v_mul_f32_e32 v34, v34, v67
	v_mad_u64_u32 v[66:67], s[16:17], v66, s28, v[0:1]
	v_mul_f32_e32 v0, 0xbfb8aa3b, v35
	v_exp_f32_e32 v0, v0
	v_mul_f32_e32 v34, v50, v34
	v_mov_b32_e32 v67, v1
	v_cvt_pk_bf16_f32 v34, v34, s0
	v_add_f32_e32 v0, 1.0, v0
	v_rcp_f32_e32 v0, v0
	v_lshl_add_u64 v[68:69], v[66:67], 1, s[6:7]
	global_store_short v[68:69], v34, off
	v_mfma_f32_32x32x16_bf16 v[18:33], v[70:73], v[78:81], v[18:33]
	v_mul_f32_e32 v0, v35, v0
	v_mul_f32_e32 v0, v51, v0
	v_cvt_pk_bf16_f32 v50, v0, s0
	v_add_u32_e32 v0, 0xb00, v66
	v_lshl_add_u64 v[34:35], v[0:1], 1, s[6:7]
	v_mul_f32_e32 v0, 0xbfb8aa3b, v36
	v_exp_f32_e32 v0, v0
	global_store_short v[34:35], v50, off
	v_add_f32_e32 v0, 1.0, v0
	v_rcp_f32_e32 v0, v0
	s_nop 0
	v_mul_f32_e32 v0, v36, v0
	v_mul_f32_e32 v0, v52, v0
	v_cvt_pk_bf16_f32 v36, v0, s0
	v_add_u32_e32 v0, 0x1600, v66
	v_lshl_add_u64 v[34:35], v[0:1], 1, s[6:7]
	v_mul_f32_e32 v0, 0xbfb8aa3b, v37
	v_exp_f32_e32 v0, v0
	global_store_short v[34:35], v36, off
	v_add_f32_e32 v0, 1.0, v0
	v_rcp_f32_e32 v0, v0
	s_nop 0
	v_mul_f32_e32 v0, v37, v0
	v_mul_f32_e32 v0, v53, v0
	v_cvt_pk_bf16_f32 v36, v0, s0
	v_add_u32_e32 v0, 0x2100, v66
	v_lshl_add_u64 v[34:35], v[0:1], 1, s[6:7]
	v_mul_f32_e32 v0, 0xbfb8aa3b, v38
	v_exp_f32_e32 v0, v0
	global_store_short v[34:35], v36, off
	v_add_f32_e32 v0, 1.0, v0
	v_rcp_f32_e32 v0, v0
	s_nop 0
	v_mul_f32_e32 v0, v38, v0
	v_mul_f32_e32 v0, v54, v0
	v_cvt_pk_bf16_f32 v36, v0, s0
	v_add_u32_e32 v0, 0x5800, v66
	v_lshl_add_u64 v[34:35], v[0:1], 1, s[6:7]
	v_mul_f32_e32 v0, 0xbfb8aa3b, v39
	v_exp_f32_e32 v0, v0
	global_store_short v[34:35], v36, off
	v_add_f32_e32 v0, 1.0, v0
	v_rcp_f32_e32 v0, v0
	s_nop 0
	v_mul_f32_e32 v0, v39, v0
	v_mul_f32_e32 v0, v55, v0
	v_cvt_pk_bf16_f32 v36, v0, s0
	v_add_u32_e32 v0, 0x6300, v66
	v_lshl_add_u64 v[34:35], v[0:1], 1, s[6:7]
	v_mul_f32_e32 v0, 0xbfb8aa3b, v40
	v_exp_f32_e32 v0, v0
	global_store_short v[34:35], v36, off
	v_add_f32_e32 v0, 1.0, v0
	v_rcp_f32_e32 v0, v0
	s_nop 0
	v_mul_f32_e32 v0, v40, v0
	v_mul_f32_e32 v0, v56, v0
	v_cvt_pk_bf16_f32 v36, v0, s0
	v_add_u32_e32 v0, 0x6e00, v66
	v_lshl_add_u64 v[34:35], v[0:1], 1, s[6:7]
	v_mul_f32_e32 v0, 0xbfb8aa3b, v41
	v_exp_f32_e32 v0, v0
	global_store_short v[34:35], v36, off
	v_add_f32_e32 v0, 1.0, v0
	v_rcp_f32_e32 v0, v0
	s_nop 0
	v_mul_f32_e32 v0, v41, v0
	v_mul_f32_e32 v0, v57, v0
	v_cvt_pk_bf16_f32 v36, v0, s0
	v_add_u32_e32 v0, 0x7900, v66
	v_lshl_add_u64 v[34:35], v[0:1], 1, s[6:7]
	global_store_short v[34:35], v36, off
	v_mul_f32_e32 v0, 0xbfb8aa3b, v42
	v_exp_f32_e32 v0, v0
	s_nop 0
	v_add_f32_e32 v0, 1.0, v0
	v_rcp_f32_e32 v0, v0
	s_nop 0
	v_mul_f32_e32 v0, v42, v0
	v_mul_f32_e32 v0, v58, v0
	v_cvt_pk_bf16_f32 v36, v0, s0
	v_add_u32_e32 v0, 0xb000, v66
	v_lshl_add_u64 v[34:35], v[0:1], 1, s[6:7]
	v_mul_f32_e32 v0, 0xbfb8aa3b, v43
	v_exp_f32_e32 v0, v0
	global_store_short v[34:35], v36, off
	v_add_f32_e32 v0, 1.0, v0
	v_rcp_f32_e32 v0, v0
	s_nop 0
	v_mul_f32_e32 v0, v43, v0
	v_mul_f32_e32 v0, v59, v0
	v_cvt_pk_bf16_f32 v36, v0, s0
	v_add_u32_e32 v0, 0xbb00, v66
	v_lshl_add_u64 v[34:35], v[0:1], 1, s[6:7]
	v_mul_f32_e32 v0, 0xbfb8aa3b, v44
	v_exp_f32_e32 v0, v0
	global_store_short v[34:35], v36, off
	v_add_f32_e32 v0, 1.0, v0
	v_rcp_f32_e32 v0, v0
	s_nop 0
	v_mul_f32_e32 v0, v44, v0
	v_mul_f32_e32 v0, v60, v0
	v_cvt_pk_bf16_f32 v36, v0, s0
	v_add_u32_e32 v0, 0xc600, v66
	v_lshl_add_u64 v[34:35], v[0:1], 1, s[6:7]
	v_mul_f32_e32 v0, 0xbfb8aa3b, v45
	v_exp_f32_e32 v0, v0
	global_store_short v[34:35], v36, off
	v_add_f32_e32 v0, 1.0, v0
	v_rcp_f32_e32 v0, v0
	s_nop 0
	v_mul_f32_e32 v0, v45, v0
	v_mul_f32_e32 v0, v61, v0
	v_cvt_pk_bf16_f32 v36, v0, s0
	v_add_u32_e32 v0, 0xd100, v66
	v_lshl_add_u64 v[34:35], v[0:1], 1, s[6:7]
	v_mul_f32_e32 v0, 0xbfb8aa3b, v46
	v_exp_f32_e32 v0, v0
	global_store_short v[34:35], v36, off
	v_add_f32_e32 v0, 1.0, v0
	v_rcp_f32_e32 v0, v0
	s_nop 0
	v_mul_f32_e32 v0, v46, v0
	v_mul_f32_e32 v0, v62, v0
	v_cvt_pk_bf16_f32 v36, v0, s0
	v_add_u32_e32 v0, 0x10800, v66
	v_lshl_add_u64 v[34:35], v[0:1], 1, s[6:7]
	v_mul_f32_e32 v0, 0xbfb8aa3b, v47
	v_exp_f32_e32 v0, v0
	global_store_short v[34:35], v36, off
	v_add_f32_e32 v0, 1.0, v0
	v_rcp_f32_e32 v0, v0
	s_nop 0
	v_mul_f32_e32 v0, v47, v0
	v_mul_f32_e32 v0, v63, v0
	v_cvt_pk_bf16_f32 v36, v0, s0
	v_add_u32_e32 v0, 0x11300, v66
	v_lshl_add_u64 v[34:35], v[0:1], 1, s[6:7]
	v_mul_f32_e32 v0, 0xbfb8aa3b, v48
	v_exp_f32_e32 v0, v0
	global_store_short v[34:35], v36, off
	v_add_f32_e32 v0, 1.0, v0
	v_rcp_f32_e32 v0, v0
	s_nop 0
	v_mul_f32_e32 v0, v48, v0
	v_mul_f32_e32 v0, v64, v0
	v_cvt_pk_bf16_f32 v36, v0, s0
	v_add_u32_e32 v0, 0x11e00, v66
	v_lshl_add_u64 v[34:35], v[0:1], 1, s[6:7]
	v_mul_f32_e32 v0, 0xbfb8aa3b, v49
	v_exp_f32_e32 v0, v0
	global_store_short v[34:35], v36, off
	v_add_f32_e32 v0, 1.0, v0
	v_rcp_f32_e32 v0, v0
	s_nop 0
	v_mul_f32_e32 v0, v49, v0
	v_mul_f32_e32 v0, v65, v0
	v_cvt_pk_bf16_f32 v36, v0, s0
	v_add_u32_e32 v0, 0x12900, v66
	v_lshl_add_u64 v[34:35], v[0:1], 1, s[6:7]
	global_store_short v[34:35], v36, off
	v_mul_f32_e32 v0, 0xbfb8aa3b, v2
	v_exp_f32_e32 v0, v0
	s_nop 0
; template <int AI>
; DI void gu_tile(char* wsb, int sub, int m0, int n0, char* lds) {
;     ...
;   for (int ai = 0; ai < AI; ++ai)
; #pragma unroll
;     for (int reg = 0; reg < 16; ++reg) {
;       float g = acc[ai][0][reg], u = acc[ai][1][reg];
;       float v = g * __builtin_amdgcn_rcpf(1.f + __expf(-g)) * u;
;       HIDu[ib + (unsigned)((ai * 32 + (reg & 3) + 8 * (reg >> 2)) * 2816)] = f2bf(v);
;       if ((reg & 7) == 7) __builtin_amdgcn_sched_barrier(0);
;     }
; }
; DI void phase_gu(const Params& p, char* wsb, int sub, int mrows, char* lds) {
;   int mt, nt;
;   for (int rnd = 0; next_tile(rnd, 128, 44, mt, nt); ++rnd) gu_tile<2>(wsb, sub, mt * 128, nt * 128, lds);
;   if (mrows > TL)
;     for (int rnd = 0; next_tile(rnd, 32, 44, mt, nt); ++rnd) gu_tile<1>(wsb, sub, TL + mt * 64, nt * 128, lds);
	v_add_f32_e32 v0, 1.0, v0
	v_rcp_f32_e32 v0, v0
	s_nop 0
	v_mul_f32_e32 v0, v2, v0
	v_mul_f32_e32 v0, v18, v0
	v_cvt_pk_bf16_f32 v2, v0, s0
	v_add_u32_e32 v0, 0x16000, v66
	v_lshl_add_u64 v[34:35], v[0:1], 1, s[6:7]
	v_mul_f32_e32 v0, 0xbfb8aa3b, v3
	v_exp_f32_e32 v0, v0
	global_store_short v[34:35], v2, off
	v_add_f32_e32 v0, 1.0, v0
	v_rcp_f32_e32 v0, v0
	s_nop 0
	v_mul_f32_e32 v0, v3, v0
	v_mul_f32_e32 v0, v19, v0
	v_cvt_pk_bf16_f32 v18, v0, s0
	v_add_u32_e32 v0, 0x16b00, v66
	v_lshl_add_u64 v[2:3], v[0:1], 1, s[6:7]
	v_mul_f32_e32 v0, 0xbfb8aa3b, v4
	v_exp_f32_e32 v0, v0
	global_store_short v[2:3], v18, off
	v_add_f32_e32 v0, 1.0, v0
	v_rcp_f32_e32 v0, v0
	s_nop 0
	v_mul_f32_e32 v0, v4, v0
	v_mul_f32_e32 v0, v20, v0
	v_cvt_pk_bf16_f32 v4, v0, s0
	v_add_u32_e32 v0, 0x17600, v66
	v_lshl_add_u64 v[2:3], v[0:1], 1, s[6:7]
	v_mul_f32_e32 v0, 0xbfb8aa3b, v5
	v_exp_f32_e32 v0, v0
	global_store_short v[2:3], v4, off
	v_add_f32_e32 v0, 1.0, v0
	v_rcp_f32_e32 v0, v0
	s_nop 0
	v_mul_f32_e32 v0, v5, v0
	v_mul_f32_e32 v0, v21, v0
	v_cvt_pk_bf16_f32 v4, v0, s0
	v_add_u32_e32 v0, 0x18100, v66
	v_lshl_add_u64 v[2:3], v[0:1], 1, s[6:7]
	v_mul_f32_e32 v0, 0xbfb8aa3b, v6
	v_exp_f32_e32 v0, v0
	global_store_short v[2:3], v4, off
	v_add_f32_e32 v0, 1.0, v0
	v_rcp_f32_e32 v0, v0
	s_nop 0
	v_mul_f32_e32 v0, v6, v0
	v_mul_f32_e32 v0, v22, v0
	v_cvt_pk_bf16_f32 v4, v0, s0
	v_add_u32_e32 v0, 0x1b800, v66
	v_lshl_add_u64 v[2:3], v[0:1], 1, s[6:7]
	v_mul_f32_e32 v0, 0xbfb8aa3b, v7
	v_exp_f32_e32 v0, v0
	global_store_short v[2:3], v4, off
	v_add_f32_e32 v0, 1.0, v0
	v_rcp_f32_e32 v0, v0
	s_nop 0
	v_mul_f32_e32 v0, v7, v0
	v_mul_f32_e32 v0, v23, v0
	v_cvt_pk_bf16_f32 v4, v0, s0
	v_add_u32_e32 v0, 0x1c300, v66
	v_lshl_add_u64 v[2:3], v[0:1], 1, s[6:7]
	v_mul_f32_e32 v0, 0xbfb8aa3b, v8
	v_exp_f32_e32 v0, v0
	global_store_short v[2:3], v4, off
	v_add_f32_e32 v0, 1.0, v0
	v_rcp_f32_e32 v0, v0
	s_nop 0
	v_mul_f32_e32 v0, v8, v0
	v_mul_f32_e32 v0, v24, v0
	v_cvt_pk_bf16_f32 v4, v0, s0
	v_add_u32_e32 v0, 0x1ce00, v66
	v_lshl_add_u64 v[2:3], v[0:1], 1, s[6:7]
	v_mul_f32_e32 v0, 0xbfb8aa3b, v9
	v_exp_f32_e32 v0, v0
	global_store_short v[2:3], v4, off
	v_add_f32_e32 v0, 1.0, v0
	v_rcp_f32_e32 v0, v0
	s_nop 0
	v_mul_f32_e32 v0, v9, v0
	v_mul_f32_e32 v0, v25, v0
	v_cvt_pk_bf16_f32 v4, v0, s0
	v_add_u32_e32 v0, 0x1d900, v66
	v_lshl_add_u64 v[2:3], v[0:1], 1, s[6:7]
	global_store_short v[2:3], v4, off
	v_mul_f32_e32 v0, 0xbfb8aa3b, v10
	v_exp_f32_e32 v0, v0
	s_nop 0
	v_add_f32_e32 v0, 1.0, v0
	v_rcp_f32_e32 v0, v0
	s_nop 0
	v_mul_f32_e32 v0, v10, v0
	v_mul_f32_e32 v0, v26, v0
	v_cvt_pk_bf16_f32 v4, v0, s0
	v_add_u32_e32 v0, 0x21000, v66
	v_lshl_add_u64 v[2:3], v[0:1], 1, s[6:7]
	v_mul_f32_e32 v0, 0xbfb8aa3b, v11
	v_exp_f32_e32 v0, v0
	global_store_short v[2:3], v4, off
	v_add_f32_e32 v0, 1.0, v0
	v_rcp_f32_e32 v0, v0
	s_nop 0
	v_mul_f32_e32 v0, v11, v0
	v_mul_f32_e32 v0, v27, v0
	v_cvt_pk_bf16_f32 v4, v0, s0
	v_add_u32_e32 v0, 0x21b00, v66
	v_lshl_add_u64 v[2:3], v[0:1], 1, s[6:7]
	v_mul_f32_e32 v0, 0xbfb8aa3b, v12
	v_exp_f32_e32 v0, v0
	global_store_short v[2:3], v4, off
	v_add_f32_e32 v0, 1.0, v0
	v_rcp_f32_e32 v0, v0
	s_nop 0
	v_mul_f32_e32 v0, v12, v0
	v_mul_f32_e32 v0, v28, v0
	v_cvt_pk_bf16_f32 v4, v0, s0
	v_add_u32_e32 v0, 0x22600, v66
	v_lshl_add_u64 v[2:3], v[0:1], 1, s[6:7]
	v_mul_f32_e32 v0, 0xbfb8aa3b, v13
	v_exp_f32_e32 v0, v0
	global_store_short v[2:3], v4, off
	v_add_f32_e32 v0, 1.0, v0
	v_rcp_f32_e32 v0, v0
	s_nop 0
	v_mul_f32_e32 v0, v13, v0
	v_mul_f32_e32 v0, v29, v0
	v_cvt_pk_bf16_f32 v4, v0, s0
	v_add_u32_e32 v0, 0x23100, v66
	v_lshl_add_u64 v[2:3], v[0:1], 1, s[6:7]
	v_mul_f32_e32 v0, 0xbfb8aa3b, v14
	v_exp_f32_e32 v0, v0
	global_store_short v[2:3], v4, off
	v_add_f32_e32 v0, 1.0, v0
	v_rcp_f32_e32 v0, v0
	s_nop 0
	v_mul_f32_e32 v0, v14, v0
	v_mul_f32_e32 v0, v30, v0
	v_cvt_pk_bf16_f32 v4, v0, s0
	v_add_u32_e32 v0, 0x26800, v66
	v_lshl_add_u64 v[2:3], v[0:1], 1, s[6:7]
	v_mul_f32_e32 v0, 0xbfb8aa3b, v15
	v_exp_f32_e32 v0, v0
	global_store_short v[2:3], v4, off
	v_add_f32_e32 v0, 1.0, v0
	v_rcp_f32_e32 v0, v0
	s_nop 0
	v_mul_f32_e32 v0, v15, v0
	v_mul_f32_e32 v0, v31, v0
	v_cvt_pk_bf16_f32 v4, v0, s0
	v_add_u32_e32 v0, 0x27300, v66
	v_lshl_add_u64 v[2:3], v[0:1], 1, s[6:7]
	v_mul_f32_e32 v0, 0xbfb8aa3b, v16
	v_exp_f32_e32 v0, v0
	global_store_short v[2:3], v4, off
	v_add_f32_e32 v0, 1.0, v0
	v_rcp_f32_e32 v0, v0
	s_nop 0
	v_mul_f32_e32 v0, v16, v0
	v_mul_f32_e32 v0, v32, v0
	v_cvt_pk_bf16_f32 v4, v0, s0
	v_add_u32_e32 v0, 0x27e00, v66
	v_lshl_add_u64 v[2:3], v[0:1], 1, s[6:7]
	v_mul_f32_e32 v0, 0xbfb8aa3b, v17
	v_exp_f32_e32 v0, v0
	global_store_short v[2:3], v4, off
	v_add_f32_e32 v0, 1.0, v0
	v_rcp_f32_e32 v0, v0
	s_nop 0
	v_mul_f32_e32 v0, v17, v0
	v_mul_f32_e32 v0, v33, v0
	v_cvt_pk_bf16_f32 v4, v0, s0
	v_add_u32_e32 v0, 0x28900, v66
	v_lshl_add_u64 v[2:3], v[0:1], 1, s[6:7]
	global_store_short v[2:3], v4, off
	v_readlane_b32 s16, v245, 0
	s_cmp_eq_u32 s16, 1
	s_cbranch_scc1 .Lgu1_done
	v_readlane_b32 s16, v243, 6
	s_add_i32 s15, s15, s16
	s_add_i32 s14, s14, s53
	s_cmpk_lt_u32 s14, 0x1600
	s_cbranch_scc1 .LBB0_419
.Lgu1_done:
	v_readlane_b32 s16, v243, 45
	v_readlane_b32 s28, v243, 47
	v_readlane_b32 s17, v243, 46
	v_readlane_b32 s29, v243, 48
	v_readlane_b32 s47, v243, 51
.LBB0_421:
	v_readlane_b32 s6, v244, 50
	v_readlane_b32 s7, v244, 51
	s_andn2_b64 vcc, exec, s[6:7]
	s_mov_b32 s49, 0x1ffffe0
	s_cbranch_vccnz .LBB0_425
	s_add_u32 s10, s8, 0x77b7000
	s_addc_u32 s11, s9, 0
	s_add_u32 s12, s8, 0x1c4b7000
	s_addc_u32 s13, s9, 0
	s_add_u32 s6, s8, 0x9bb7000
	s_addc_u32 s7, s9, 0
	v_readlane_b32 s14, v243, 18
	v_readlane_b32 s15, v243, 10
	v_readlane_b32 s16, v243, 8
	v_readlane_b32 s48, v243, 7
	s_mov_b64 s[50:51], 0x200
	s_mov_b64 s[52:53], 0x80
	s_mov_b64 s[54:55], 0x180
	s_mov_b64 s[64:65], 0x300
	s_mov_b64 s[66:67], 0x380
	s_mov_b64 s[68:69], 0x400
	s_mov_b64 s[70:71], 0x480
	s_mov_b64 s[72:73], 0x500
	s_mov_b64 s[74:75], 0x580
	s_mov_b64 s[76:77], 0x600
	s_mov_b64 s[56:57], 0x280

; #define MFMA(a, b, c) __builtin_amdgcn_mfma_f32_32x32x16_bf16((a), (b), (c), 0, 0, 0)
; DI int opaque0() { int z = 0; asm volatile("" : "+v"(z)); return z; }
; template <int AI, int BI>
; DI void gemm_tile(const u16* __restrict__ A, int lda, const u16* __restrict__ B, int ldb, int nk, bool swap,
;                   f32x16 (&acc)[AI][BI], char* lds) {
;     ...
;   for (int kt = 0; kt < nk; ++kt) {
;     const char* cur = lds + (kt & 1) * 32768;
;     if (kt + 1 < nk) gemm_stage<AI, BI>(A + (kt + 1) * 64, lda, B + (kt + 1) * 64, ldb, lds + ((kt + 1) & 1) * 32768, tid);
; #pragma unroll
;     for (int ks = 0; ks < 4; ++ks) {
;       const int co = ((ks * 2 + h) ^ sw) << 4;
;       s16x8 fa[AI], fb[BI];
; #pragma unroll
;       for (int i = 0; i < AI; ++i) fa[i] = *(const s16x8*)(cur + offA + i * 4096 + co);
; #pragma unroll
;       for (int i = 0; i < BI; ++i) fb[i] = *(const s16x8*)(cur + offB + i * 4096 + co);
; #pragma unroll
;       for (int i = 0; i < AI; ++i)
; #pragma unroll
;         for (int j = 0; j < BI; ++j) acc[i][j] = MFMA(fa[i], fb[j], acc[i][j]);
;     }
;     asm volatile("s_waitcnt vmcnt(0)" ::: "memory");
;     __syncthreads();
;   }
; template <int AI, int BI>
; DI void dn_tile(const Params& p, char* wsb, int layer, int sub, bool final_out, int m0, int n0, char* lds) {
;     ...
;   gemm_tile<AI, BI>(HID + (size_t)m0 * 2816, 2816, W + (size_t)n0 * 2816, 2816, 44, false, acc, lds);
;   const int m0e = m0 + opaque0();
;   const int mr = m0 < TL ? (m0 >> 11) : 8;
;   const float* gate = mods + (size_t)mr * 9216 + (2 + 6 * sub) * 1024;
.LBB0_476:
	s_add_i32 s40, s37, 0xffff8000
	s_and_b32 s41, s40, 0x8000
	s_and_b32 s40, s37, 0x8000
	v_add_u32_e32 v93, s40, v85
	v_add_u32_e32 v96, s40, v86
	v_readfirstlane_b32 s46, v93
	v_lshl_add_u64 v[94:95], v[66:67], 0, s[10:11]
	s_mov_b32 m0, s46
	v_readfirstlane_b32 s46, v96
	v_add_u32_e32 v97, s40, v88
	global_load_lds_dwordx4 v[94:95], off
	v_lshl_add_u64 v[94:95], v[68:69], 0, s[10:11]
	s_mov_b32 m0, s46
	v_readfirstlane_b32 s46, v97
	v_add_u32_e32 v98, s40, v89
	global_load_lds_dwordx4 v[94:95], off
	v_lshl_add_u64 v[94:95], v[70:71], 0, s[10:11]
	s_mov_b32 m0, s46
	v_readfirstlane_b32 s46, v98
	v_add_u32_e32 v93, 0x4000, v93
	global_load_lds_dwordx4 v[94:95], off
	v_lshl_add_u64 v[94:95], v[72:73], 0, s[10:11]
	s_mov_b32 m0, s46
	v_readfirstlane_b32 s46, v93
	v_add_u32_e32 v93, 0x4000, v96
	global_load_lds_dwordx4 v[94:95], off
	v_lshl_add_u64 v[94:95], v[74:75], 0, s[10:11]
	s_mov_b32 m0, s46
	v_readfirstlane_b32 s46, v93
	v_add_u32_e32 v93, 0x4000, v97
	global_load_lds_dwordx4 v[94:95], off
	v_lshl_add_u64 v[94:95], v[76:77], 0, s[10:11]
	s_mov_b32 m0, s46
	v_readfirstlane_b32 s46, v93
	v_add_u32_e32 v93, 0x4000, v98
	global_load_lds_dwordx4 v[94:95], off
	v_lshl_add_u64 v[94:95], v[78:79], 0, s[10:11]
	s_mov_b32 m0, s46
	v_readfirstlane_b32 s46, v93
	global_load_lds_dwordx4 v[94:95], off
	v_lshl_add_u64 v[94:95], v[80:81], 0, s[10:11]
	s_mov_b32 m0, s46
	v_add_u32_e32 v93, s41, v91
	global_load_lds_dwordx4 v[94:95], off
	v_or_b32_e32 v110, s41, v92
	v_add_u32_e32 v98, v93, v90
	v_add_u32_e32 v106, v110, v90
	ds_read_b128 v[94:97], v98
	ds_read_b128 v[98:101], v98 offset:4096
	ds_read_b128 v[102:105], v106 offset:16384
	ds_read_b128 v[106:109], v106 offset:20480
	s_waitcnt lgkmcnt(0)
	v_mfma_f32_32x32x16_bf16 v[50:65], v[94:97], v[102:105], v[50:65]
	s_add_u32 s10, s10, 0x80
	s_addc_u32 s11, s11, 0
	s_add_i32 s37, s37, 0x8000
	s_cmpk_eq_i32 s10, 0x1580
	v_mfma_f32_32x32x16_bf16 v[18:33], v[94:97], v[106:109], v[18:33]
	v_mfma_f32_32x32x16_bf16 v[34:49], v[98:101], v[102:105], v[34:49]
	v_mfma_f32_32x32x16_bf16 v[2:17], v[98:101], v[106:109], v[2:17]
	v_add_u32_e32 v98, v93, v87
	v_add_u32_e32 v106, v110, v87
	ds_read_b128 v[94:97], v98
	ds_read_b128 v[98:101], v98 offset:4096
	ds_read_b128 v[102:105], v106 offset:16384
	ds_read_b128 v[106:109], v106 offset:20480
	s_waitcnt lgkmcnt(1)
	v_mfma_f32_32x32x16_bf16 v[50:65], v[94:97], v[102:105], v[50:65]
	s_waitcnt lgkmcnt(0)
	v_mfma_f32_32x32x16_bf16 v[18:33], v[94:97], v[106:109], v[18:33]
	v_mfma_f32_32x32x16_bf16 v[34:49], v[98:101], v[102:105], v[34:49]
	v_mfma_f32_32x32x16_bf16 v[2:17], v[98:101], v[106:109], v[2:17]
	v_add_u32_e32 v98, v93, v84
	v_add_u32_e32 v106, v110, v84
	ds_read_b128 v[94:97], v98
	ds_read_b128 v[98:101], v98 offset:4096
	ds_read_b128 v[102:105], v106 offset:16384
	ds_read_b128 v[106:109], v106 offset:20480
	v_add_u32_e32 v93, v93, v0
	s_waitcnt lgkmcnt(1)
	v_mfma_f32_32x32x16_bf16 v[50:65], v[94:97], v[102:105], v[50:65]
	s_waitcnt lgkmcnt(0)
	v_mfma_f32_32x32x16_bf16 v[18:33], v[94:97], v[106:109], v[18:33]
	v_mfma_f32_32x32x16_bf16 v[34:49], v[98:101], v[102:105], v[34:49]
	v_mfma_f32_32x32x16_bf16 v[2:17], v[98:101], v[106:109], v[2:17]
	ds_read_b128 v[94:97], v93
	ds_read_b128 v[98:101], v93 offset:4096
	v_add_u32_e32 v93, v110, v0
	ds_read_b128 v[102:105], v93 offset:16384
	ds_read_b128 v[106:109], v93 offset:20480
	s_waitcnt vmcnt(0)
	s_waitcnt lgkmcnt(0)
	s_barrier
	v_mfma_f32_32x32x16_bf16 v[50:65], v[94:97], v[102:105], v[50:65]
	v_mfma_f32_32x32x16_bf16 v[18:33], v[94:97], v[106:109], v[18:33]
	v_mfma_f32_32x32x16_bf16 v[34:49], v[98:101], v[102:105], v[34:49]
	v_mfma_f32_32x32x16_bf16 v[2:17], v[98:101], v[106:109], v[2:17]
	s_cbranch_scc0 .LBB0_476
	v_add_u32_e32 v86, s40, v91
	v_add_u32_e32 v88, s40, v92
	v_add_u32_e32 v70, v86, v90
	v_add_u32_e32 v78, v88, v90
	ds_read_b128 v[66:69], v70
	ds_read_b128 v[70:73], v70 offset:4096
	ds_read_b128 v[74:77], v78 offset:16384
	ds_read_b128 v[78:81], v78 offset:20480
	s_waitcnt lgkmcnt(1)
	v_mfma_f32_32x32x16_bf16 v[50:65], v[66:69], v[74:77], v[50:65]
	s_lshr_b32 s10, s34, 7
	s_lshl_b32 s36, s36, 7
	s_mul_i32 s10, s10, 0x9000
	s_add_u32 s10, s13, s10
	v_and_b32_e32 v85, 31, v82
	s_addc_u32 s11, s18, 0
	s_add_u32 s10, s10, 0x6000
	s_waitcnt lgkmcnt(0)
	v_mfma_f32_32x32x16_bf16 v[18:33], v[66:69], v[78:81], v[18:33]
	s_addc_u32 s11, s11, 0
	v_mfma_f32_32x32x16_bf16 v[34:49], v[70:73], v[74:77], v[34:49]
	v_mfma_f32_32x32x16_bf16 v[2:17], v[70:73], v[78:81], v[2:17]
	v_add_u32_e32 v70, v86, v87
	v_add_u32_e32 v78, v88, v87
	ds_read_b128 v[66:69], v70
	ds_read_b128 v[70:73], v70 offset:4096
	ds_read_b128 v[74:77], v78 offset:16384
	ds_read_b128 v[78:81], v78 offset:20480
	s_waitcnt lgkmcnt(1)
	v_mfma_f32_32x32x16_bf16 v[50:65], v[66:69], v[74:77], v[50:65]
	s_waitcnt lgkmcnt(0)
	v_mfma_f32_32x32x16_bf16 v[18:33], v[66:69], v[78:81], v[18:33]
	v_mfma_f32_32x32x16_bf16 v[34:49], v[70:73], v[74:77], v[34:49]
	v_mfma_f32_32x32x16_bf16 v[2:17], v[70:73], v[78:81], v[2:17]
	v_add_u32_e32 v70, v86, v84
	v_add_u32_e32 v78, v88, v84
	ds_read_b128 v[66:69], v70
	ds_read_b128 v[70:73], v70 offset:4096
	ds_read_b128 v[74:77], v78 offset:16384
	ds_read_b128 v[78:81], v78 offset:20480
	s_waitcnt lgkmcnt(1)
	v_mfma_f32_32x32x16_bf16 v[50:65], v[66:69], v[74:77], v[50:65]
	s_waitcnt lgkmcnt(0)
	v_mfma_f32_32x32x16_bf16 v[18:33], v[66:69], v[78:81], v[18:33]
	v_mfma_f32_32x32x16_bf16 v[34:49], v[70:73], v[74:77], v[34:49]
	v_mfma_f32_32x32x16_bf16 v[2:17], v[70:73], v[78:81], v[2:17]
	v_add_u32_e32 v70, v86, v0
	v_add_u32_e32 v0, v88, v0
	ds_read_b128 v[66:69], v70
	ds_read_b128 v[70:73], v70 offset:4096
	ds_read_b128 v[74:77], v0 offset:16384
	ds_read_b128 v[78:81], v0 offset:20480
	v_mov_b32_e32 v0, v1
	s_waitcnt vmcnt(0)
	s_waitcnt lgkmcnt(0)
	v_mfma_f32_32x32x16_bf16 v[50:65], v[66:69], v[74:77], v[50:65]
	s_barrier
; #define GAS __attribute__((address_space(1)))
; template <int AI, int BI>
; DI void dn_tile(const Params& p, char* wsb, int layer, int sub, bool final_out, int m0, int n0, char* lds) {
;     ...
;   GAS float* xsu = uptr(xs);
;   GAS float* outu = uptr(p.out);
; #pragma unroll
;   for (int bi = 0; bi < BI; ++bi) {
;     const int n = n0 + wb * 32 * BI + bi * 32 + r;
;     const float gv = 0.5f * gate[n];
;     const unsigned ib = (unsigned)((m0e + wa * 32 * AI + 4 * h) * 1024 + n);
; #pragma unroll
;     for (int ai = 0; ai < AI; ++ai)
; #pragma unroll
;       for (int reg = 0; reg < 16; ++reg) {
;         const unsigned idx = ib + (unsigned)((ai * 32 + (reg & 3) + 8 * (reg >> 2)) * 1024);
;         float v = xsu[idx] + gv * acc[ai][bi][reg];
;         if (final_out) outu[idx] = v; else xsu[idx] = v;
;         if ((reg & 7) == 7) __builtin_amdgcn_sched_barrier(0);
;       }
;   }
	v_mfma_f32_32x32x16_bf16 v[18:33], v[66:69], v[78:81], v[18:33]
	v_mfma_f32_32x32x16_bf16 v[34:49], v[70:73], v[74:77], v[34:49]
	v_mfma_f32_32x32x16_bf16 v[2:17], v[70:73], v[78:81], v[2:17]
	v_and_b32_e32 v143, 31, v178
	v_and_b32_e32 v140, 64, v178
	v_or_b32_e32 v140, v140, v143
	v_bfe_u32 v143, v178, 5, 1
	v_bfe_u32 v139, v178, 7, 1
	v_lshlrev_b32_e32 v139, 6, v139
	v_lshl_add_u32 v139, v143, 2, v139
	v_lshl_add_u32 v139, v139, 10, v140
	v_lshlrev_b32_e32 v139, 2, v139
	v_add_u32_e32 v140, s35, v140
	v_lshlrev_b32_e32 v140, 2, v140
	global_load_dword v141, v140, s[10:11]
	global_load_dword v142, v140, s[10:11] offset:128
	s_lshl_b32 s56, s36, 10
	s_add_u32 s56, s56, s35
	s_lshl_b32 s56, s56, 2
	s_add_u32 s54, s6, s56
	s_addc_u32 s55, s7, 0
	s_mov_b64 s[52:53], s[54:55]
	global_load_dword v66, v139, s[52:53]
	global_load_dword v67, v139, s[52:53] offset:128
	s_add_u32 s52, s52, 4096
	s_addc_u32 s53, s53, 0
	global_load_dword v68, v139, s[52:53]
	global_load_dword v69, v139, s[52:53] offset:128
	s_add_u32 s52, s52, 4096
	s_addc_u32 s53, s53, 0
	global_load_dword v70, v139, s[52:53]
	global_load_dword v71, v139, s[52:53] offset:128
	s_add_u32 s52, s52, 4096
	s_addc_u32 s53, s53, 0
	global_load_dword v72, v139, s[52:53]
	global_load_dword v73, v139, s[52:53] offset:128
	s_add_u32 s52, s52, 20480
	s_addc_u32 s53, s53, 0
	global_load_dword v74, v139, s[52:53]
	global_load_dword v75, v139, s[52:53] offset:128
	s_add_u32 s52, s52, 4096
	s_addc_u32 s53, s53, 0
	global_load_dword v76, v139, s[52:53]
	global_load_dword v77, v139, s[52:53] offset:128
	s_add_u32 s52, s52, 4096
	s_addc_u32 s53, s53, 0
	global_load_dword v78, v139, s[52:53]
	global_load_dword v79, v139, s[52:53] offset:128
	s_add_u32 s52, s52, 4096
	s_addc_u32 s53, s53, 0
	global_load_dword v80, v139, s[52:53]
	global_load_dword v81, v139, s[52:53] offset:128
	s_add_u32 s52, s52, 20480
	s_addc_u32 s53, s53, 0
	global_load_dword v82, v139, s[52:53]
	global_load_dword v83, v139, s[52:53] offset:128
	s_add_u32 s52, s52, 4096
	s_addc_u32 s53, s53, 0
	global_load_dword v84, v139, s[52:53]
	global_load_dword v85, v139, s[52:53] offset:128
	s_add_u32 s52, s52, 4096
	s_addc_u32 s53, s53, 0
	global_load_dword v86, v139, s[52:53]
	global_load_dword v87, v139, s[52:53] offset:128
	s_add_u32 s52, s52, 4096
	s_addc_u32 s53, s53, 0
	global_load_dword v88, v139, s[52:53]
	global_load_dword v89, v139, s[52:53] offset:128
	s_add_u32 s52, s52, 20480
	s_addc_u32 s53, s53, 0
	global_load_dword v90, v139, s[52:53]
	global_load_dword v91, v139, s[52:53] offset:128
	s_add_u32 s52, s52, 4096
	s_addc_u32 s53, s53, 0
	global_load_dword v92, v139, s[52:53]
	global_load_dword v93, v139, s[52:53] offset:128
	s_add_u32 s52, s52, 4096
	s_addc_u32 s53, s53, 0
	global_load_dword v94, v139, s[52:53]
	global_load_dword v95, v139, s[52:53] offset:128
	s_add_u32 s52, s52, 4096
	s_addc_u32 s53, s53, 0
	global_load_dword v96, v139, s[52:53]
	global_load_dword v97, v139, s[52:53] offset:128
	s_add_u32 s52, s52, 20480
	s_addc_u32 s53, s53, 0
	global_load_dword v98, v139, s[52:53]
	global_load_dword v99, v139, s[52:53] offset:128
	s_add_u32 s52, s52, 4096
	s_addc_u32 s53, s53, 0
	global_load_dword v100, v139, s[52:53]
	global_load_dword v101, v139, s[52:53] offset:128
	s_add_u32 s52, s52, 4096
	s_addc_u32 s53, s53, 0
	global_load_dword v102, v139, s[52:53]
	global_load_dword v103, v139, s[52:53] offset:128
	s_add_u32 s52, s52, 4096
	s_addc_u32 s53, s53, 0
	global_load_dword v104, v139, s[52:53]
	global_load_dword v105, v139, s[52:53] offset:128
	s_add_u32 s52, s52, 20480
	s_addc_u32 s53, s53, 0
	global_load_dword v106, v139, s[52:53]
	global_load_dword v107, v139, s[52:53] offset:128
	s_add_u32 s52, s52, 4096
	s_addc_u32 s53, s53, 0
	global_load_dword v108, v139, s[52:53]
	global_load_dword v109, v139, s[52:53] offset:128
	s_add_u32 s52, s52, 4096
	s_addc_u32 s53, s53, 0
	global_load_dword v110, v139, s[52:53]
	global_load_dword v111, v139, s[52:53] offset:128
	s_add_u32 s52, s52, 4096
	s_addc_u32 s53, s53, 0
	global_load_dword v112, v139, s[52:53]
	global_load_dword v113, v139, s[52:53] offset:128
	s_add_u32 s52, s52, 20480
	s_addc_u32 s53, s53, 0
	global_load_dword v114, v139, s[52:53]
	global_load_dword v115, v139, s[52:53] offset:128
	s_add_u32 s52, s52, 4096
	s_addc_u32 s53, s53, 0
	global_load_dword v116, v139, s[52:53]
	global_load_dword v117, v139, s[52:53] offset:128
	s_add_u32 s52, s52, 4096
	s_addc_u32 s53, s53, 0
	global_load_dword v118, v139, s[52:53]
	global_load_dword v119, v139, s[52:53] offset:128
	s_add_u32 s52, s52, 4096
	s_addc_u32 s53, s53, 0
	global_load_dword v120, v139, s[52:53]
	global_load_dword v121, v139, s[52:53] offset:128
	s_add_u32 s52, s52, 20480
	s_addc_u32 s53, s53, 0
	global_load_dword v122, v139, s[52:53]
	global_load_dword v123, v139, s[52:53] offset:128
	s_add_u32 s52, s52, 4096
	s_addc_u32 s53, s53, 0
	global_load_dword v124, v139, s[52:53]
	global_load_dword v134, v139, s[52:53] offset:128
	s_add_u32 s52, s52, 4096
	s_addc_u32 s53, s53, 0
	global_load_dword v135, v139, s[52:53]
	global_load_dword v136, v139, s[52:53] offset:128
	s_add_u32 s52, s52, 4096
	s_addc_u32 s53, s53, 0
	global_load_dword v137, v139, s[52:53]
	global_load_dword v138, v139, s[52:53] offset:128
	s_waitcnt vmcnt(48)
	v_mul_f32_e32 v141, 0.5, v141
	v_mul_f32_e32 v142, 0.5, v142
	v_fmac_f32_e32 v66, v50, v141
	v_fmac_f32_e32 v67, v18, v142
	v_fmac_f32_e32 v68, v51, v141
	v_fmac_f32_e32 v69, v19, v142
	v_fmac_f32_e32 v70, v52, v141
	v_fmac_f32_e32 v71, v20, v142
	v_fmac_f32_e32 v72, v53, v141
	v_fmac_f32_e32 v73, v21, v142
	v_fmac_f32_e32 v74, v54, v141
	v_fmac_f32_e32 v75, v22, v142
	v_fmac_f32_e32 v76, v55, v141
	v_fmac_f32_e32 v77, v23, v142
	v_fmac_f32_e32 v78, v56, v141
	v_fmac_f32_e32 v79, v24, v142
	v_fmac_f32_e32 v80, v57, v141
	v_fmac_f32_e32 v81, v25, v142
	s_waitcnt vmcnt(32)
; #define GAS __attribute__((address_space(1)))
; template <int AI, int BI>
; DI void dn_tile(const Params& p, char* wsb, int layer, int sub, bool final_out, int m0, int n0, char* lds) {
;     ...
;   GAS float* xsu = uptr(xs);
;   GAS float* outu = uptr(p.out);
; #pragma unroll
;   for (int bi = 0; bi < BI; ++bi) {
;     const int n = n0 + wb * 32 * BI + bi * 32 + r;
;     const float gv = 0.5f * gate[n];
;     const unsigned ib = (unsigned)((m0e + wa * 32 * AI + 4 * h) * 1024 + n);
; #pragma unroll
;     for (int ai = 0; ai < AI; ++ai)
; #pragma unroll
;       for (int reg = 0; reg < 16; ++reg) {
;         const unsigned idx = ib + (unsigned)((ai * 32 + (reg & 3) + 8 * (reg >> 2)) * 1024);
;         float v = xsu[idx] + gv * acc[ai][bi][reg];
;         if (final_out) outu[idx] = v; else xsu[idx] = v;
;         if ((reg & 7) == 7) __builtin_amdgcn_sched_barrier(0);
;       }
;   }
; }
; DI void phase_dn(const Params& p, char* wsb, int layer, int sub, int mrows, bool final_out, char* lds) {
;   int mt, nt;
;   for (int rnd = 0; next_tile(rnd, 128, 8, mt, nt); ++rnd) dn_tile<2, 2>(p, wsb, layer, sub, final_out, mt * 128, nt * 128, lds);
	v_fmac_f32_e32 v82, v58, v141
	v_fmac_f32_e32 v83, v26, v142
	v_fmac_f32_e32 v84, v59, v141
	v_fmac_f32_e32 v85, v27, v142
	v_fmac_f32_e32 v86, v60, v141
	v_fmac_f32_e32 v87, v28, v142
	v_fmac_f32_e32 v88, v61, v141
	v_fmac_f32_e32 v89, v29, v142
	v_fmac_f32_e32 v90, v62, v141
	v_fmac_f32_e32 v91, v30, v142
	v_fmac_f32_e32 v92, v63, v141
	v_fmac_f32_e32 v93, v31, v142
	v_fmac_f32_e32 v94, v64, v141
	v_fmac_f32_e32 v95, v32, v142
	v_fmac_f32_e32 v96, v65, v141
	v_fmac_f32_e32 v97, v33, v142
	s_waitcnt vmcnt(16)
	v_fmac_f32_e32 v98, v34, v141
	v_fmac_f32_e32 v99, v2, v142
	v_fmac_f32_e32 v100, v35, v141
	v_fmac_f32_e32 v101, v3, v142
	v_fmac_f32_e32 v102, v36, v141
	v_fmac_f32_e32 v103, v4, v142
	v_fmac_f32_e32 v104, v37, v141
	v_fmac_f32_e32 v105, v5, v142
	v_fmac_f32_e32 v106, v38, v141
	v_fmac_f32_e32 v107, v6, v142
	v_fmac_f32_e32 v108, v39, v141
	v_fmac_f32_e32 v109, v7, v142
	v_fmac_f32_e32 v110, v40, v141
	v_fmac_f32_e32 v111, v8, v142
	v_fmac_f32_e32 v112, v41, v141
	v_fmac_f32_e32 v113, v9, v142
	s_waitcnt vmcnt(0)
	v_fmac_f32_e32 v114, v42, v141
	v_fmac_f32_e32 v115, v10, v142
	v_fmac_f32_e32 v116, v43, v141
	v_fmac_f32_e32 v117, v11, v142
	v_fmac_f32_e32 v118, v44, v141
	v_fmac_f32_e32 v119, v12, v142
	v_fmac_f32_e32 v120, v45, v141
	v_fmac_f32_e32 v121, v13, v142
	v_fmac_f32_e32 v122, v46, v141
	v_fmac_f32_e32 v123, v14, v142
	v_fmac_f32_e32 v124, v47, v141
	v_fmac_f32_e32 v134, v15, v142
	v_fmac_f32_e32 v135, v48, v141
	v_fmac_f32_e32 v136, v16, v142
	v_fmac_f32_e32 v137, v49, v141
	v_fmac_f32_e32 v138, v17, v142
	s_mov_b64 s[52:53], s[54:55]
	global_store_dword v139, v66, s[52:53]
	global_store_dword v139, v67, s[52:53] offset:128
	s_add_u32 s52, s52, 4096
	s_addc_u32 s53, s53, 0
	global_store_dword v139, v68, s[52:53]
	global_store_dword v139, v69, s[52:53] offset:128
	s_add_u32 s52, s52, 4096
	s_addc_u32 s53, s53, 0
	global_store_dword v139, v70, s[52:53]
	global_store_dword v139, v71, s[52:53] offset:128
	s_add_u32 s52, s52, 4096
	s_addc_u32 s53, s53, 0
	global_store_dword v139, v72, s[52:53]
	global_store_dword v139, v73, s[52:53] offset:128
	s_add_u32 s52, s52, 20480
	s_addc_u32 s53, s53, 0
	global_store_dword v139, v74, s[52:53]
	global_store_dword v139, v75, s[52:53] offset:128
	s_add_u32 s52, s52, 4096
	s_addc_u32 s53, s53, 0
	global_store_dword v139, v76, s[52:53]
	global_store_dword v139, v77, s[52:53] offset:128
	s_add_u32 s52, s52, 4096
	s_addc_u32 s53, s53, 0
	global_store_dword v139, v78, s[52:53]
	global_store_dword v139, v79, s[52:53] offset:128
	s_add_u32 s52, s52, 4096
	s_addc_u32 s53, s53, 0
	global_store_dword v139, v80, s[52:53]
	global_store_dword v139, v81, s[52:53] offset:128
	s_add_u32 s52, s52, 20480
	s_addc_u32 s53, s53, 0
	global_store_dword v139, v82, s[52:53]
	global_store_dword v139, v83, s[52:53] offset:128
	s_add_u32 s52, s52, 4096
	s_addc_u32 s53, s53, 0
	global_store_dword v139, v84, s[52:53]
	global_store_dword v139, v85, s[52:53] offset:128
	s_add_u32 s52, s52, 4096
	s_addc_u32 s53, s53, 0
	global_store_dword v139, v86, s[52:53]
	global_store_dword v139, v87, s[52:53] offset:128
	s_add_u32 s52, s52, 4096
	s_addc_u32 s53, s53, 0
	global_store_dword v139, v88, s[52:53]
	global_store_dword v139, v89, s[52:53] offset:128
	s_add_u32 s52, s52, 20480
	s_addc_u32 s53, s53, 0
	global_store_dword v139, v90, s[52:53]
	global_store_dword v139, v91, s[52:53] offset:128
	s_add_u32 s52, s52, 4096
	s_addc_u32 s53, s53, 0
	global_store_dword v139, v92, s[52:53]
	global_store_dword v139, v93, s[52:53] offset:128
	s_add_u32 s52, s52, 4096
	s_addc_u32 s53, s53, 0
	global_store_dword v139, v94, s[52:53]
	global_store_dword v139, v95, s[52:53] offset:128
	s_add_u32 s52, s52, 4096
	s_addc_u32 s53, s53, 0
	global_store_dword v139, v96, s[52:53]
	global_store_dword v139, v97, s[52:53] offset:128
	s_add_u32 s52, s52, 20480
	s_addc_u32 s53, s53, 0
	global_store_dword v139, v98, s[52:53]
	global_store_dword v139, v99, s[52:53] offset:128
	s_add_u32 s52, s52, 4096
	s_addc_u32 s53, s53, 0
	global_store_dword v139, v100, s[52:53]
	global_store_dword v139, v101, s[52:53] offset:128
	s_add_u32 s52, s52, 4096
	s_addc_u32 s53, s53, 0
	global_store_dword v139, v102, s[52:53]
	global_store_dword v139, v103, s[52:53] offset:128
	s_add_u32 s52, s52, 4096
	s_addc_u32 s53, s53, 0
	global_store_dword v139, v104, s[52:53]
	global_store_dword v139, v105, s[52:53] offset:128
	s_add_u32 s52, s52, 20480
	s_addc_u32 s53, s53, 0
	global_store_dword v139, v106, s[52:53]
	global_store_dword v139, v107, s[52:53] offset:128
	s_add_u32 s52, s52, 4096
	s_addc_u32 s53, s53, 0
	global_store_dword v139, v108, s[52:53]
	global_store_dword v139, v109, s[52:53] offset:128
	s_add_u32 s52, s52, 4096
	s_addc_u32 s53, s53, 0
	global_store_dword v139, v110, s[52:53]
	global_store_dword v139, v111, s[52:53] offset:128
	s_add_u32 s52, s52, 4096
	s_addc_u32 s53, s53, 0
	global_store_dword v139, v112, s[52:53]
	global_store_dword v139, v113, s[52:53] offset:128
	s_add_u32 s52, s52, 20480
	s_addc_u32 s53, s53, 0
	global_store_dword v139, v114, s[52:53]
	global_store_dword v139, v115, s[52:53] offset:128
	s_add_u32 s52, s52, 4096
	s_addc_u32 s53, s53, 0
	global_store_dword v139, v116, s[52:53]
	global_store_dword v139, v117, s[52:53] offset:128
	s_add_u32 s52, s52, 4096
	s_addc_u32 s53, s53, 0
	global_store_dword v139, v118, s[52:53]
	global_store_dword v139, v119, s[52:53] offset:128
	s_add_u32 s52, s52, 4096
	s_addc_u32 s53, s53, 0
	global_store_dword v139, v120, s[52:53]
	global_store_dword v139, v121, s[52:53] offset:128
	s_add_u32 s52, s52, 20480
	s_addc_u32 s53, s53, 0
	global_store_dword v139, v122, s[52:53]
	global_store_dword v139, v123, s[52:53] offset:128
	s_add_u32 s52, s52, 4096
	s_addc_u32 s53, s53, 0
	global_store_dword v139, v124, s[52:53]
	global_store_dword v139, v134, s[52:53] offset:128
	s_add_u32 s52, s52, 4096
	s_addc_u32 s53, s53, 0
	global_store_dword v139, v135, s[52:53]
	global_store_dword v139, v136, s[52:53] offset:128
	s_add_u32 s52, s52, 4096
	s_addc_u32 s53, s53, 0
	global_store_dword v139, v137, s[52:53]
	global_store_dword v139, v138, s[52:53] offset:128
	v_readlane_b32 s10, v243, 7
	s_add_i32 s34, s34, s10
	s_cmpk_gt_u32 s34, 0x3ff
	s_cbranch_scc0 .LBB0_475

; #define TIDX opaque_tid()
; template <int AI, int BI>
; DI void gemm_tile(const u16* __restrict__ A, int lda, const u16* __restrict__ B, int ldb, int nk, bool swap,
;                   f32x16 (&acc)[AI][BI], char* lds) {
;   const int tid = TIDX, lane = tid & 63, wid = tid >> 6;
;   gemm_stage<AI, BI>(A, lda, B, ldb, lds, tid);
;   asm volatile("s_waitcnt vmcnt(0)" ::: "memory");
;   __syncthreads();
;   const int wa = wid >> 1, wb = wid & 1, r = lane & 31, h = lane >> 5, sw = (r >> 1) & 7;
;   const int offA = (swap ? 16384 : 0) + (wa * 32 * AI + r) * 128;
;   const int offB = (swap ? 0 : 16384) + (wb * 32 * BI + r) * 128;
;   for (int kt = 0; kt < nk; ++kt) {
;     const char* cur = lds + (kt & 1) * 32768;
;     if (kt + 1 < nk) gemm_stage<AI, BI>(A + (kt + 1) * 64, lda, B + (kt + 1) * 64, ldb, lds + ((kt + 1) & 1) * 32768, tid);
; #pragma unroll
;     for (int ks = 0; ks < 4; ++ks) {
;       const int co = ((ks * 2 + h) ^ sw) << 4;
;       s16x8 fa[AI], fb[BI];
; #pragma unroll
;       for (int i = 0; i < AI; ++i) fa[i] = *(const s16x8*)(cur + offA + i * 4096 + co);
; #pragma unroll
;       for (int i = 0; i < BI; ++i) fb[i] = *(const s16x8*)(cur + offB + i * 4096 + co);
; template <int AI, int BI>
; DI void m2_tile(char* wsb, int layer, int m0, int n0, char* lds) {
;   const u16* GM = (const u16*)(wsb + OFF_H);
;   const u16* W = (const u16*)(wsb + OFF_W) + W_O;
;   float* xs = (float*)(wsb + OFF_XS);
;   const float* mods = (const float*)(wsb + OFF_MODS) + (size_t)layer * 9 * 9216;
;   const int lane = TIDX & 63, wid = TIDX >> 6, wa = wid >> 1, wb = wid & 1, r = lane & 31, h = lane >> 5;
;   f32x16 acc[AI][BI]; zero_acc<AI, BI>(acc);
;   gemm_tile<AI, BI>(GM + (size_t)m0 * 1024, 1024, W + (size_t)n0 * 1024, 1024, 16, false, acc, lds);
.LBB0_1099:
	s_lshr_b32 s10, s34, 3
	s_and_b32 s10, s10, 0x78
	s_and_b32 s11, s34, 7
	s_or_b32 s10, s10, s11
	s_waitcnt vmcnt(2)
	v_mov_b32_e32 v82, v178
	v_mov_b32_e32 v83, v178
	v_mov_b32_e32 v12, v178
	s_and_b32 s35, s29, 0x380
	s_lshl_b32 s11, s10, 18
	s_add_u32 s36, s14, s11
	v_lshrrev_b32_e32 v0, 4, v12
	v_xor_b32_e32 v0, v0, v12
	v_add_u32_e32 v8, 0x100, v12
	v_add_u32_e32 v10, 0x200, v12
	v_add_u32_e32 v13, 0x300, v12
	s_addc_u32 s37, s15, 0
	s_lshl_b32 s11, s35, 11
	v_lshlrev_b32_e32 v0, 4, v0
	v_ashrrev_i32_e32 v4, 3, v12
	v_ashrrev_i32_e32 v6, 3, v8
	v_lshlrev_b32_e32 v99, 4, v8
	v_ashrrev_i32_e32 v8, 3, v10
	v_lshlrev_b32_e32 v100, 4, v10
	v_ashrrev_i32_e32 v10, 3, v13
	s_add_u32 s40, s16, s11
	v_and_b32_e32 v0, 0x70, v0
	v_ashrrev_i32_e32 v5, 31, v4
	v_ashrrev_i32_e32 v7, 31, v6
	v_ashrrev_i32_e32 v9, 31, v8
	v_ashrrev_i32_e32 v11, 31, v10
	s_addc_u32 s41, s17, 0
	v_lshl_add_u64 v[2:3], s[36:37], 0, v[0:1]
	v_lshlrev_b64 v[4:5], 11, v[4:5]
	v_lshlrev_b32_e32 v96, 4, v12
	v_lshlrev_b64 v[6:7], 11, v[6:7]
	v_lshlrev_b64 v[8:9], 11, v[8:9]
	v_lshlrev_b64 v[10:11], 11, v[10:11]
	v_lshl_add_u64 v[66:67], v[2:3], 0, v[4:5]
	v_lshl_add_u64 v[68:69], v[2:3], 0, v[6:7]
	v_lshl_add_u64 v[70:71], v[2:3], 0, v[8:9]
	v_lshl_add_u64 v[72:73], v[2:3], 0, v[10:11]
	v_lshl_add_u64 v[2:3], s[40:41], 0, v[0:1]
	v_add_u32_e32 v0, 0x4000, v96
	v_readfirstlane_b32 s47, v96
	v_readfirstlane_b32 s36, v0
	v_add_u32_e32 v0, 0x4000, v99
	s_mov_b32 m0, s47
	v_readfirstlane_b32 s52, v99
	v_lshlrev_b32_e32 v101, 4, v13
	v_readfirstlane_b32 s37, v0
	v_add_u32_e32 v0, 0x4000, v100
	global_load_lds_dwordx4 v[66:67], off
	s_mov_b32 m0, s52
	v_readfirstlane_b32 s55, v100
	v_readfirstlane_b32 s40, v0
	v_add_u32_e32 v0, 0x4000, v101
	global_load_lds_dwordx4 v[68:69], off
	s_mov_b32 m0, s55
	v_readfirstlane_b32 s56, v101
	v_lshl_add_u64 v[74:75], v[2:3], 0, v[4:5]
	v_readfirstlane_b32 s41, v0
	v_and_b32_e32 v0, 31, v12
	v_lshrrev_b32_e32 v4, 1, v12
	global_load_lds_dwordx4 v[70:71], off
	s_mov_b32 m0, s56
	v_and_or_b32 v0, v4, s65, v0
	global_load_lds_dwordx4 v[72:73], off
	s_mov_b32 m0, s36
	v_lshl_add_u64 v[76:77], v[2:3], 0, v[6:7]
	v_lshl_add_u64 v[78:79], v[2:3], 0, v[8:9]
	v_lshl_add_u64 v[80:81], v[2:3], 0, v[10:11]
	v_lshrrev_b32_e32 v2, 5, v12
	v_bfe_u32 v5, v12, 1, 3
	v_lshlrev_b32_e32 v86, 7, v0
	v_lshlrev_b32_e32 v0, 7, v12
	global_load_lds_dwordx4 v[74:75], off
	s_mov_b32 m0, s37
	v_bfe_u32 v3, v12, 5, 1
	v_and_b32_e32 v88, 0x2f80, v0
	v_bitop3_b32 v0, v2, v5, 1 bitop3:0x6c
	global_load_lds_dwordx4 v[76:77], off
	s_mov_b32 m0, s40
	v_lshlrev_b32_e32 v10, 4, v0
	v_bitop3_b32 v0, v3, v5, 2 bitop3:0x36
	v_add_u32_e32 v91, 0x8000, v96
	global_load_lds_dwordx4 v[78:79], off
	s_mov_b32 m0, s41
	v_lshlrev_b32_e32 v85, 4, v0
	v_bitop3_b32 v0, v3, v5, 4 bitop3:0x36
	v_readfirstlane_b32 s46, v91
	v_add_u32_e32 v92, 0x8000, v99
	global_load_lds_dwordx4 v[80:81], off
	v_lshlrev_b32_e32 v87, 4, v0
	v_bitop3_b32 v0, v3, v5, 6 bitop3:0x36
	v_lshl_add_u64 v[2:3], v[66:67], 0, s[68:69]
	s_mov_b32 m0, s46
	v_readfirstlane_b32 s48, v92
	v_add_u32_e32 v93, 0x8000, v100
	s_waitcnt vmcnt(0)
	s_waitcnt vmcnt(0) lgkmcnt(0)
	s_barrier
	global_load_lds_dwordx4 v[2:3], off
	v_lshl_add_u64 v[2:3], v[68:69], 0, s[68:69]
	s_mov_b32 m0, s48
	v_readfirstlane_b32 s49, v93
	v_add_u32_e32 v94, 0x8000, v101
	global_load_lds_dwordx4 v[2:3], off
	v_lshl_add_u64 v[2:3], v[70:71], 0, s[68:69]
	s_mov_b32 m0, s49
	v_readfirstlane_b32 s50, v94
	v_add_u32_e32 v95, 0xc000, v96
	global_load_lds_dwordx4 v[2:3], off
	v_lshl_add_u64 v[2:3], v[72:73], 0, s[68:69]
	s_mov_b32 m0, s50
	v_readfirstlane_b32 s51, v95
	v_add_u32_e32 v97, 0xc000, v99
	global_load_lds_dwordx4 v[2:3], off
	v_lshl_add_u64 v[2:3], v[74:75], 0, s[68:69]
	s_mov_b32 m0, s51
	v_readfirstlane_b32 s53, v97
	v_add_u32_e32 v98, 0xc000, v100
	v_lshlrev_b32_e32 v118, 4, v0
	global_load_lds_dwordx4 v[2:3], off
	v_lshl_add_u64 v[2:3], v[76:77], 0, s[68:69]
	s_mov_b32 m0, s53
	v_readfirstlane_b32 s54, v98
	v_add_u32_e32 v0, 0xc000, v101
	global_load_lds_dwordx4 v[2:3], off
	v_lshl_add_u64 v[2:3], v[78:79], 0, s[68:69]
	s_mov_b32 m0, s54
	v_readfirstlane_b32 s11, v0
	global_load_lds_dwordx4 v[2:3], off
	v_lshl_add_u64 v[2:3], v[80:81], 0, s[68:69]
	s_mov_b32 m0, s11
	v_or_b32_e32 v0, v86, v10
	global_load_lds_dwordx4 v[2:3], off
	v_or_b32_e32 v84, v88, v10
	ds_read_b128 v[2:5], v0
	ds_read_b128 v[6:9], v0 offset:4096
	ds_read_b128 v[10:13], v84 offset:16384
	ds_read_b128 v[14:17], v84 offset:20480
	s_waitcnt lgkmcnt(0)
	v_mfma_f32_32x32x16_bf16 v[50:65], v[2:5], v[10:13], 0
	v_or_b32_e32 v89, v86, v85
	v_or_b32_e32 v90, v88, v85
	ds_read_b128 v[102:105], v89
	ds_read_b128 v[106:109], v89 offset:4096
	ds_read_b128 v[110:113], v90 offset:16384
	ds_read_b128 v[114:117], v90 offset:20480
	v_or_b32_e32 v85, v86, v87
	v_or_b32_e32 v87, v88, v87
	v_or_b32_e32 v86, v86, v118
	v_mfma_f32_32x32x16_bf16 v[18:33], v[2:5], v[14:17], 0
	v_or_b32_e32 v88, v88, v118
	s_mov_b32 m0, s47
	v_mfma_f32_32x32x16_bf16 v[34:49], v[6:9], v[10:13], 0
	v_mfma_f32_32x32x16_bf16 v[2:17], v[6:9], v[14:17], 0
	s_waitcnt lgkmcnt(1)
	v_mfma_f32_32x32x16_bf16 v[50:65], v[102:105], v[110:113], v[50:65]
	s_waitcnt lgkmcnt(0)
	v_mfma_f32_32x32x16_bf16 v[18:33], v[102:105], v[114:117], v[18:33]
	v_mfma_f32_32x32x16_bf16 v[34:49], v[106:109], v[110:113], v[34:49]
	v_mfma_f32_32x32x16_bf16 v[2:17], v[106:109], v[114:117], v[2:17]
	ds_read_b128 v[102:105], v85
	ds_read_b128 v[106:109], v85 offset:4096
	ds_read_b128 v[110:113], v87 offset:16384
	ds_read_b128 v[114:117], v87 offset:20480
	s_waitcnt lgkmcnt(1)
	v_mfma_f32_32x32x16_bf16 v[50:65], v[102:105], v[110:113], v[50:65]
	s_waitcnt lgkmcnt(0)
	v_mfma_f32_32x32x16_bf16 v[18:33], v[102:105], v[114:117], v[18:33]
	v_mfma_f32_32x32x16_bf16 v[34:49], v[106:109], v[110:113], v[34:49]
	v_mfma_f32_32x32x16_bf16 v[2:17], v[106:109], v[114:117], v[2:17]
	ds_read_b128 v[102:105], v86
	ds_read_b128 v[106:109], v86 offset:4096
	ds_read_b128 v[110:113], v88 offset:16384
	ds_read_b128 v[114:117], v88 offset:20480
	s_waitcnt vmcnt(0)
	s_waitcnt lgkmcnt(0)
	s_barrier
; #define MFMA(a, b, c) __builtin_amdgcn_mfma_f32_32x32x16_bf16((a), (b), (c), 0, 0, 0)
; template <int AI, int BI>
; DI void gemm_tile(const u16* __restrict__ A, int lda, const u16* __restrict__ B, int ldb, int nk, bool swap,
;                   f32x16 (&acc)[AI][BI], char* lds) {
;     ...
;   for (int kt = 0; kt < nk; ++kt) {
;     const char* cur = lds + (kt & 1) * 32768;
;     if (kt + 1 < nk) gemm_stage<AI, BI>(A + (kt + 1) * 64, lda, B + (kt + 1) * 64, ldb, lds + ((kt + 1) & 1) * 32768, tid);
; #pragma unroll
;     for (int ks = 0; ks < 4; ++ks) {
;       const int co = ((ks * 2 + h) ^ sw) << 4;
;       s16x8 fa[AI], fb[BI];
; #pragma unroll
;       for (int i = 0; i < AI; ++i) fa[i] = *(const s16x8*)(cur + offA + i * 4096 + co);
; #pragma unroll
;       for (int i = 0; i < BI; ++i) fb[i] = *(const s16x8*)(cur + offB + i * 4096 + co);
; #pragma unroll
;       for (int i = 0; i < AI; ++i)
; #pragma unroll
;         for (int j = 0; j < BI; ++j) acc[i][j] = MFMA(fa[i], fb[j], acc[i][j]);
;     }
;     asm volatile("s_waitcnt vmcnt(0)" ::: "memory");
;     __syncthreads();
;   }
	v_mfma_f32_32x32x16_bf16 v[50:65], v[102:105], v[110:113], v[50:65]
	v_mfma_f32_32x32x16_bf16 v[18:33], v[102:105], v[114:117], v[18:33]
	v_lshl_add_u64 v[102:103], v[66:67], 0, s[4:5]
	global_load_lds_dwordx4 v[102:103], off
	v_lshl_add_u64 v[102:103], v[68:69], 0, s[4:5]
	s_mov_b32 m0, s52
	s_nop 0
	global_load_lds_dwordx4 v[102:103], off
	v_lshl_add_u64 v[102:103], v[70:71], 0, s[4:5]
	s_mov_b32 m0, s55
	v_mfma_f32_32x32x16_bf16 v[34:49], v[106:109], v[110:113], v[34:49]
	global_load_lds_dwordx4 v[102:103], off
	v_lshl_add_u64 v[102:103], v[72:73], 0, s[4:5]
	s_mov_b32 m0, s56
	s_nop 0
	global_load_lds_dwordx4 v[102:103], off
	v_lshl_add_u64 v[102:103], v[74:75], 0, s[4:5]
	s_mov_b32 m0, s36
	v_mfma_f32_32x32x16_bf16 v[2:17], v[106:109], v[114:117], v[2:17]
	global_load_lds_dwordx4 v[102:103], off
	v_lshl_add_u64 v[102:103], v[76:77], 0, s[4:5]
	s_mov_b32 m0, s37
	s_nop 0
	global_load_lds_dwordx4 v[102:103], off
	v_lshl_add_u64 v[102:103], v[78:79], 0, s[4:5]
	s_mov_b32 m0, s40
	s_nop 0
	global_load_lds_dwordx4 v[102:103], off
	v_lshl_add_u64 v[102:103], v[80:81], 0, s[4:5]
	s_mov_b32 m0, s41
	s_nop 0
	global_load_lds_dwordx4 v[102:103], off
	ds_read_b128 v[102:105], v0 offset:32768
	ds_read_b128 v[106:109], v0 offset:36864
	ds_read_b128 v[110:113], v84 offset:49152
	ds_read_b128 v[114:117], v84 offset:53248
	s_waitcnt lgkmcnt(0)
	v_mfma_f32_32x32x16_bf16 v[50:65], v[102:105], v[110:113], v[50:65]
	s_mov_b32 m0, s46
	v_mfma_f32_32x32x16_bf16 v[18:33], v[102:105], v[114:117], v[18:33]
	v_mfma_f32_32x32x16_bf16 v[34:49], v[106:109], v[110:113], v[34:49]
	v_mfma_f32_32x32x16_bf16 v[2:17], v[106:109], v[114:117], v[2:17]
	ds_read_b128 v[102:105], v89 offset:32768
	ds_read_b128 v[106:109], v89 offset:36864
	ds_read_b128 v[110:113], v90 offset:49152
	ds_read_b128 v[114:117], v90 offset:53248
	s_waitcnt lgkmcnt(1)
	v_mfma_f32_32x32x16_bf16 v[50:65], v[102:105], v[110:113], v[50:65]
	s_waitcnt lgkmcnt(0)
	v_mfma_f32_32x32x16_bf16 v[18:33], v[102:105], v[114:117], v[18:33]
	v_mfma_f32_32x32x16_bf16 v[34:49], v[106:109], v[110:113], v[34:49]
	v_mfma_f32_32x32x16_bf16 v[2:17], v[106:109], v[114:117], v[2:17]
	ds_read_b128 v[102:105], v85 offset:32768
	ds_read_b128 v[106:109], v85 offset:36864
	ds_read_b128 v[110:113], v87 offset:49152
	ds_read_b128 v[114:117], v87 offset:53248
	s_waitcnt lgkmcnt(1)
	v_mfma_f32_32x32x16_bf16 v[50:65], v[102:105], v[110:113], v[50:65]
	s_waitcnt lgkmcnt(0)
	v_mfma_f32_32x32x16_bf16 v[18:33], v[102:105], v[114:117], v[18:33]
	v_mfma_f32_32x32x16_bf16 v[34:49], v[106:109], v[110:113], v[34:49]
	v_mfma_f32_32x32x16_bf16 v[2:17], v[106:109], v[114:117], v[2:17]
	ds_read_b128 v[102:105], v86 offset:32768
	ds_read_b128 v[106:109], v86 offset:36864
	ds_read_b128 v[110:113], v88 offset:49152
	ds_read_b128 v[114:117], v88 offset:53248
	s_waitcnt vmcnt(0)
	s_waitcnt lgkmcnt(0)
	s_barrier
	v_mfma_f32_32x32x16_bf16 v[50:65], v[102:105], v[110:113], v[50:65]
	v_mfma_f32_32x32x16_bf16 v[18:33], v[102:105], v[114:117], v[18:33]
	v_lshl_add_u64 v[102:103], v[66:67], 0, s[70:71]
	global_load_lds_dwordx4 v[102:103], off
	v_lshl_add_u64 v[102:103], v[68:69], 0, s[70:71]
	s_mov_b32 m0, s48
	s_nop 0
	global_load_lds_dwordx4 v[102:103], off
	v_lshl_add_u64 v[102:103], v[70:71], 0, s[70:71]
	s_mov_b32 m0, s49
	v_mfma_f32_32x32x16_bf16 v[34:49], v[106:109], v[110:113], v[34:49]
	global_load_lds_dwordx4 v[102:103], off
	v_lshl_add_u64 v[102:103], v[72:73], 0, s[70:71]
	s_mov_b32 m0, s50
	s_nop 0
	global_load_lds_dwordx4 v[102:103], off
	v_lshl_add_u64 v[102:103], v[74:75], 0, s[70:71]
	s_mov_b32 m0, s51
	v_mfma_f32_32x32x16_bf16 v[2:17], v[106:109], v[114:117], v[2:17]
	global_load_lds_dwordx4 v[102:103], off
	v_lshl_add_u64 v[102:103], v[76:77], 0, s[70:71]
	s_mov_b32 m0, s53
	s_nop 0
	global_load_lds_dwordx4 v[102:103], off
	v_lshl_add_u64 v[102:103], v[78:79], 0, s[70:71]
	s_mov_b32 m0, s54
	s_nop 0
	global_load_lds_dwordx4 v[102:103], off
	v_lshl_add_u64 v[102:103], v[80:81], 0, s[70:71]
	s_mov_b32 m0, s11
	s_nop 0
	global_load_lds_dwordx4 v[102:103], off
	ds_read_b128 v[102:105], v0
	ds_read_b128 v[106:109], v0 offset:4096
	ds_read_b128 v[110:113], v84 offset:16384
	ds_read_b128 v[114:117], v84 offset:20480
	s_waitcnt lgkmcnt(0)
	v_mfma_f32_32x32x16_bf16 v[50:65], v[102:105], v[110:113], v[50:65]
	s_mov_b32 m0, s47
	v_mfma_f32_32x32x16_bf16 v[18:33], v[102:105], v[114:117], v[18:33]
	v_mfma_f32_32x32x16_bf16 v[34:49], v[106:109], v[110:113], v[34:49]
	v_mfma_f32_32x32x16_bf16 v[2:17], v[106:109], v[114:117], v[2:17]
	ds_read_b128 v[102:105], v89
	ds_read_b128 v[106:109], v89 offset:4096
	ds_read_b128 v[110:113], v90 offset:16384
	ds_read_b128 v[114:117], v90 offset:20480
	s_waitcnt lgkmcnt(1)
	v_mfma_f32_32x32x16_bf16 v[50:65], v[102:105], v[110:113], v[50:65]
	s_waitcnt lgkmcnt(0)
	v_mfma_f32_32x32x16_bf16 v[18:33], v[102:105], v[114:117], v[18:33]
	v_mfma_f32_32x32x16_bf16 v[34:49], v[106:109], v[110:113], v[34:49]
	v_mfma_f32_32x32x16_bf16 v[2:17], v[106:109], v[114:117], v[2:17]
	ds_read_b128 v[102:105], v85
	ds_read_b128 v[106:109], v85 offset:4096
	ds_read_b128 v[110:113], v87 offset:16384
	ds_read_b128 v[114:117], v87 offset:20480
	s_waitcnt lgkmcnt(1)
	v_mfma_f32_32x32x16_bf16 v[50:65], v[102:105], v[110:113], v[50:65]
	s_waitcnt lgkmcnt(0)
	v_mfma_f32_32x32x16_bf16 v[18:33], v[102:105], v[114:117], v[18:33]
	v_mfma_f32_32x32x16_bf16 v[34:49], v[106:109], v[110:113], v[34:49]
	v_mfma_f32_32x32x16_bf16 v[2:17], v[106:109], v[114:117], v[2:17]
	ds_read_b128 v[102:105], v86
	ds_read_b128 v[106:109], v86 offset:4096
	ds_read_b128 v[110:113], v88 offset:16384
	ds_read_b128 v[114:117], v88 offset:20480
	s_waitcnt vmcnt(0)
	s_waitcnt lgkmcnt(0)
	s_barrier
; #define MFMA(a, b, c) __builtin_amdgcn_mfma_f32_32x32x16_bf16((a), (b), (c), 0, 0, 0)
; template <int AI, int BI>
; DI void gemm_tile(const u16* __restrict__ A, int lda, const u16* __restrict__ B, int ldb, int nk, bool swap,
;                   f32x16 (&acc)[AI][BI], char* lds) {
;     ...
;   for (int kt = 0; kt < nk; ++kt) {
;     const char* cur = lds + (kt & 1) * 32768;
;     if (kt + 1 < nk) gemm_stage<AI, BI>(A + (kt + 1) * 64, lda, B + (kt + 1) * 64, ldb, lds + ((kt + 1) & 1) * 32768, tid);
; #pragma unroll
;     for (int ks = 0; ks < 4; ++ks) {
;       const int co = ((ks * 2 + h) ^ sw) << 4;
;       s16x8 fa[AI], fb[BI];
; #pragma unroll
;       for (int i = 0; i < AI; ++i) fa[i] = *(const s16x8*)(cur + offA + i * 4096 + co);
; #pragma unroll
;       for (int i = 0; i < BI; ++i) fb[i] = *(const s16x8*)(cur + offB + i * 4096 + co);
; #pragma unroll
;       for (int i = 0; i < AI; ++i)
; #pragma unroll
;         for (int j = 0; j < BI; ++j) acc[i][j] = MFMA(fa[i], fb[j], acc[i][j]);
;     }
;     asm volatile("s_waitcnt vmcnt(0)" ::: "memory");
;     __syncthreads();
;   }
	v_mfma_f32_32x32x16_bf16 v[50:65], v[102:105], v[110:113], v[50:65]
	v_mfma_f32_32x32x16_bf16 v[18:33], v[102:105], v[114:117], v[18:33]
	v_lshl_add_u64 v[102:103], v[66:67], 0, s[66:67]
	global_load_lds_dwordx4 v[102:103], off
	v_lshl_add_u64 v[102:103], v[68:69], 0, s[66:67]
	s_mov_b32 m0, s52
	s_nop 0
	global_load_lds_dwordx4 v[102:103], off
	v_lshl_add_u64 v[102:103], v[70:71], 0, s[66:67]
	s_mov_b32 m0, s55
	v_mfma_f32_32x32x16_bf16 v[34:49], v[106:109], v[110:113], v[34:49]
	global_load_lds_dwordx4 v[102:103], off
	v_lshl_add_u64 v[102:103], v[72:73], 0, s[66:67]
	s_mov_b32 m0, s56
	s_nop 0
	global_load_lds_dwordx4 v[102:103], off
	v_lshl_add_u64 v[102:103], v[74:75], 0, s[66:67]
	s_mov_b32 m0, s36
	v_mfma_f32_32x32x16_bf16 v[2:17], v[106:109], v[114:117], v[2:17]
	global_load_lds_dwordx4 v[102:103], off
	v_lshl_add_u64 v[102:103], v[76:77], 0, s[66:67]
	s_mov_b32 m0, s37
	s_nop 0
	global_load_lds_dwordx4 v[102:103], off
	v_lshl_add_u64 v[102:103], v[78:79], 0, s[66:67]
	s_mov_b32 m0, s40
	s_nop 0
	global_load_lds_dwordx4 v[102:103], off
	v_lshl_add_u64 v[102:103], v[80:81], 0, s[66:67]
	s_mov_b32 m0, s41
	s_nop 0
	global_load_lds_dwordx4 v[102:103], off
	ds_read_b128 v[102:105], v0 offset:32768
	ds_read_b128 v[106:109], v0 offset:36864
	ds_read_b128 v[110:113], v84 offset:49152
	ds_read_b128 v[114:117], v84 offset:53248
	s_waitcnt lgkmcnt(0)
	v_mfma_f32_32x32x16_bf16 v[50:65], v[102:105], v[110:113], v[50:65]
	s_mov_b32 m0, s46
	v_mfma_f32_32x32x16_bf16 v[18:33], v[102:105], v[114:117], v[18:33]
	v_mfma_f32_32x32x16_bf16 v[34:49], v[106:109], v[110:113], v[34:49]
	v_mfma_f32_32x32x16_bf16 v[2:17], v[106:109], v[114:117], v[2:17]
	ds_read_b128 v[102:105], v89 offset:32768
	ds_read_b128 v[106:109], v89 offset:36864
	ds_read_b128 v[110:113], v90 offset:49152
	ds_read_b128 v[114:117], v90 offset:53248
	s_waitcnt lgkmcnt(1)
	v_mfma_f32_32x32x16_bf16 v[50:65], v[102:105], v[110:113], v[50:65]
	s_waitcnt lgkmcnt(0)
	v_mfma_f32_32x32x16_bf16 v[18:33], v[102:105], v[114:117], v[18:33]
	v_mfma_f32_32x32x16_bf16 v[34:49], v[106:109], v[110:113], v[34:49]
	v_mfma_f32_32x32x16_bf16 v[2:17], v[106:109], v[114:117], v[2:17]
	ds_read_b128 v[102:105], v85 offset:32768
	ds_read_b128 v[106:109], v85 offset:36864
	ds_read_b128 v[110:113], v87 offset:49152
	ds_read_b128 v[114:117], v87 offset:53248
	s_waitcnt lgkmcnt(1)
	v_mfma_f32_32x32x16_bf16 v[50:65], v[102:105], v[110:113], v[50:65]
	s_waitcnt lgkmcnt(0)
	v_mfma_f32_32x32x16_bf16 v[18:33], v[102:105], v[114:117], v[18:33]
	v_mfma_f32_32x32x16_bf16 v[34:49], v[106:109], v[110:113], v[34:49]
	v_mfma_f32_32x32x16_bf16 v[2:17], v[106:109], v[114:117], v[2:17]
	ds_read_b128 v[102:105], v86 offset:32768
	ds_read_b128 v[106:109], v86 offset:36864
	ds_read_b128 v[110:113], v88 offset:49152
	ds_read_b128 v[114:117], v88 offset:53248
	s_waitcnt vmcnt(0)
	s_waitcnt lgkmcnt(0)
	s_barrier
	v_mfma_f32_32x32x16_bf16 v[50:65], v[102:105], v[110:113], v[50:65]
	v_mfma_f32_32x32x16_bf16 v[18:33], v[102:105], v[114:117], v[18:33]
	v_lshl_add_u64 v[102:103], v[66:67], 0, s[72:73]
	global_load_lds_dwordx4 v[102:103], off
	v_lshl_add_u64 v[102:103], v[68:69], 0, s[72:73]
	s_mov_b32 m0, s48
	s_nop 0
	global_load_lds_dwordx4 v[102:103], off
	v_lshl_add_u64 v[102:103], v[70:71], 0, s[72:73]
	s_mov_b32 m0, s49
	v_mfma_f32_32x32x16_bf16 v[34:49], v[106:109], v[110:113], v[34:49]
	global_load_lds_dwordx4 v[102:103], off
	v_lshl_add_u64 v[102:103], v[72:73], 0, s[72:73]
	s_mov_b32 m0, s50
	s_nop 0
	global_load_lds_dwordx4 v[102:103], off
	v_lshl_add_u64 v[102:103], v[74:75], 0, s[72:73]
	s_mov_b32 m0, s51
	v_mfma_f32_32x32x16_bf16 v[2:17], v[106:109], v[114:117], v[2:17]
	global_load_lds_dwordx4 v[102:103], off
	v_lshl_add_u64 v[102:103], v[76:77], 0, s[72:73]
	s_mov_b32 m0, s53
	s_nop 0
	global_load_lds_dwordx4 v[102:103], off
	v_lshl_add_u64 v[102:103], v[78:79], 0, s[72:73]
	s_mov_b32 m0, s54
	s_nop 0
	global_load_lds_dwordx4 v[102:103], off
	v_lshl_add_u64 v[102:103], v[80:81], 0, s[72:73]
	s_mov_b32 m0, s11
	s_nop 0
	global_load_lds_dwordx4 v[102:103], off
	ds_read_b128 v[102:105], v0
	ds_read_b128 v[106:109], v0 offset:4096
	ds_read_b128 v[110:113], v84 offset:16384
	ds_read_b128 v[114:117], v84 offset:20480
	s_waitcnt lgkmcnt(0)
	v_mfma_f32_32x32x16_bf16 v[50:65], v[102:105], v[110:113], v[50:65]
	s_mov_b32 m0, s47
	v_readfirstlane_b32 s47, v99
	v_mfma_f32_32x32x16_bf16 v[18:33], v[102:105], v[114:117], v[18:33]
	v_mfma_f32_32x32x16_bf16 v[34:49], v[106:109], v[110:113], v[34:49]
	v_mfma_f32_32x32x16_bf16 v[2:17], v[106:109], v[114:117], v[2:17]
	ds_read_b128 v[102:105], v89
	ds_read_b128 v[106:109], v89 offset:4096
	ds_read_b128 v[110:113], v90 offset:16384
	ds_read_b128 v[114:117], v90 offset:20480
	s_waitcnt lgkmcnt(1)
	v_mfma_f32_32x32x16_bf16 v[50:65], v[102:105], v[110:113], v[50:65]
	s_waitcnt lgkmcnt(0)
	v_mfma_f32_32x32x16_bf16 v[18:33], v[102:105], v[114:117], v[18:33]
	v_mfma_f32_32x32x16_bf16 v[34:49], v[106:109], v[110:113], v[34:49]
	v_mfma_f32_32x32x16_bf16 v[2:17], v[106:109], v[114:117], v[2:17]
	ds_read_b128 v[102:105], v85
	ds_read_b128 v[106:109], v85 offset:4096
	ds_read_b128 v[110:113], v87 offset:16384
	ds_read_b128 v[114:117], v87 offset:20480
	s_waitcnt lgkmcnt(1)
	v_mfma_f32_32x32x16_bf16 v[50:65], v[102:105], v[110:113], v[50:65]
	s_waitcnt lgkmcnt(0)
	v_mfma_f32_32x32x16_bf16 v[18:33], v[102:105], v[114:117], v[18:33]
	v_mfma_f32_32x32x16_bf16 v[34:49], v[106:109], v[110:113], v[34:49]
	v_mfma_f32_32x32x16_bf16 v[2:17], v[106:109], v[114:117], v[2:17]
	ds_read_b128 v[102:105], v86
	ds_read_b128 v[106:109], v86 offset:4096
	ds_read_b128 v[110:113], v88 offset:16384
	ds_read_b128 v[114:117], v88 offset:20480
	s_waitcnt vmcnt(0)
	s_waitcnt lgkmcnt(0)
	s_barrier
; #define MFMA(a, b, c) __builtin_amdgcn_mfma_f32_32x32x16_bf16((a), (b), (c), 0, 0, 0)
; template <int AI, int BI>
; DI void gemm_tile(const u16* __restrict__ A, int lda, const u16* __restrict__ B, int ldb, int nk, bool swap,
;                   f32x16 (&acc)[AI][BI], char* lds) {
;     ...
;   for (int kt = 0; kt < nk; ++kt) {
;     const char* cur = lds + (kt & 1) * 32768;
;     if (kt + 1 < nk) gemm_stage<AI, BI>(A + (kt + 1) * 64, lda, B + (kt + 1) * 64, ldb, lds + ((kt + 1) & 1) * 32768, tid);
; #pragma unroll
;     for (int ks = 0; ks < 4; ++ks) {
;       const int co = ((ks * 2 + h) ^ sw) << 4;
;       s16x8 fa[AI], fb[BI];
; #pragma unroll
;       for (int i = 0; i < AI; ++i) fa[i] = *(const s16x8*)(cur + offA + i * 4096 + co);
; #pragma unroll
;       for (int i = 0; i < BI; ++i) fb[i] = *(const s16x8*)(cur + offB + i * 4096 + co);
; #pragma unroll
;       for (int i = 0; i < AI; ++i)
; #pragma unroll
;         for (int j = 0; j < BI; ++j) acc[i][j] = MFMA(fa[i], fb[j], acc[i][j]);
;     }
;     asm volatile("s_waitcnt vmcnt(0)" ::: "memory");
;     __syncthreads();
;   }
	v_mfma_f32_32x32x16_bf16 v[50:65], v[102:105], v[110:113], v[50:65]
	v_mfma_f32_32x32x16_bf16 v[18:33], v[102:105], v[114:117], v[18:33]
	v_lshl_add_u64 v[102:103], v[66:67], 0, s[74:75]
	global_load_lds_dwordx4 v[102:103], off
	v_lshl_add_u64 v[102:103], v[68:69], 0, s[74:75]
	s_mov_b32 m0, s52
	v_readfirstlane_b32 s52, v93
	global_load_lds_dwordx4 v[102:103], off
	v_lshl_add_u64 v[102:103], v[70:71], 0, s[74:75]
	s_mov_b32 m0, s55
	v_mfma_f32_32x32x16_bf16 v[34:49], v[106:109], v[110:113], v[34:49]
	global_load_lds_dwordx4 v[102:103], off
	v_lshl_add_u64 v[102:103], v[72:73], 0, s[74:75]
	s_mov_b32 m0, s56
	v_readfirstlane_b32 s55, v97
	global_load_lds_dwordx4 v[102:103], off
	v_lshl_add_u64 v[102:103], v[74:75], 0, s[74:75]
	s_mov_b32 m0, s36
	v_mfma_f32_32x32x16_bf16 v[2:17], v[106:109], v[114:117], v[2:17]
	global_load_lds_dwordx4 v[102:103], off
	v_lshl_add_u64 v[102:103], v[76:77], 0, s[74:75]
	s_mov_b32 m0, s37
	v_readfirstlane_b32 s56, v98
	global_load_lds_dwordx4 v[102:103], off
	v_lshl_add_u64 v[102:103], v[78:79], 0, s[74:75]
	s_mov_b32 m0, s40
	s_nop 0
	global_load_lds_dwordx4 v[102:103], off
	v_lshl_add_u64 v[102:103], v[80:81], 0, s[74:75]
	s_mov_b32 m0, s41
	s_nop 0
	global_load_lds_dwordx4 v[102:103], off
	ds_read_b128 v[102:105], v0 offset:32768
	ds_read_b128 v[106:109], v0 offset:36864
	ds_read_b128 v[110:113], v84 offset:49152
	ds_read_b128 v[114:117], v84 offset:53248
	s_waitcnt lgkmcnt(0)
	v_mfma_f32_32x32x16_bf16 v[50:65], v[102:105], v[110:113], v[50:65]
	s_mov_b32 m0, s46
	v_readfirstlane_b32 s46, v96
	v_mfma_f32_32x32x16_bf16 v[18:33], v[102:105], v[114:117], v[18:33]
	v_mfma_f32_32x32x16_bf16 v[34:49], v[106:109], v[110:113], v[34:49]
	v_mfma_f32_32x32x16_bf16 v[2:17], v[106:109], v[114:117], v[2:17]
	ds_read_b128 v[102:105], v89 offset:32768
	ds_read_b128 v[106:109], v89 offset:36864
	ds_read_b128 v[110:113], v90 offset:49152
	ds_read_b128 v[114:117], v90 offset:53248
	s_waitcnt lgkmcnt(1)
	v_mfma_f32_32x32x16_bf16 v[50:65], v[102:105], v[110:113], v[50:65]
	s_waitcnt lgkmcnt(0)
	v_mfma_f32_32x32x16_bf16 v[18:33], v[102:105], v[114:117], v[18:33]
	v_mfma_f32_32x32x16_bf16 v[34:49], v[106:109], v[110:113], v[34:49]
	v_mfma_f32_32x32x16_bf16 v[2:17], v[106:109], v[114:117], v[2:17]
	ds_read_b128 v[102:105], v85 offset:32768
	ds_read_b128 v[106:109], v85 offset:36864
	ds_read_b128 v[110:113], v87 offset:49152
	ds_read_b128 v[114:117], v87 offset:53248
	s_waitcnt lgkmcnt(1)
	v_mfma_f32_32x32x16_bf16 v[50:65], v[102:105], v[110:113], v[50:65]
	s_waitcnt lgkmcnt(0)
	v_mfma_f32_32x32x16_bf16 v[18:33], v[102:105], v[114:117], v[18:33]
	v_mfma_f32_32x32x16_bf16 v[34:49], v[106:109], v[110:113], v[34:49]
	v_mfma_f32_32x32x16_bf16 v[2:17], v[106:109], v[114:117], v[2:17]
	ds_read_b128 v[102:105], v86 offset:32768
	ds_read_b128 v[106:109], v86 offset:36864
	ds_read_b128 v[110:113], v88 offset:49152
	ds_read_b128 v[114:117], v88 offset:53248
	s_waitcnt vmcnt(0)
	s_waitcnt lgkmcnt(0)
	s_barrier
	v_mfma_f32_32x32x16_bf16 v[50:65], v[102:105], v[110:113], v[50:65]
	v_mfma_f32_32x32x16_bf16 v[18:33], v[102:105], v[114:117], v[18:33]
	v_lshl_add_u64 v[102:103], v[66:67], 0, s[76:77]
	global_load_lds_dwordx4 v[102:103], off
	v_lshl_add_u64 v[102:103], v[68:69], 0, s[76:77]
	s_mov_b32 m0, s48
	v_readfirstlane_b32 s48, v100
	global_load_lds_dwordx4 v[102:103], off
	v_lshl_add_u64 v[102:103], v[70:71], 0, s[76:77]
	s_mov_b32 m0, s49
	v_mfma_f32_32x32x16_bf16 v[34:49], v[106:109], v[110:113], v[34:49]
	global_load_lds_dwordx4 v[102:103], off
	v_lshl_add_u64 v[102:103], v[72:73], 0, s[76:77]
	s_mov_b32 m0, s50
	v_readfirstlane_b32 s49, v101
	global_load_lds_dwordx4 v[102:103], off
	v_lshl_add_u64 v[102:103], v[74:75], 0, s[76:77]
	s_mov_b32 m0, s51
	v_mfma_f32_32x32x16_bf16 v[2:17], v[106:109], v[114:117], v[2:17]
	global_load_lds_dwordx4 v[102:103], off
	v_lshl_add_u64 v[102:103], v[76:77], 0, s[76:77]
	s_mov_b32 m0, s53
	v_lshl_add_u64 v[100:101], v[74:75], 0, s[80:81]
	global_load_lds_dwordx4 v[102:103], off
	v_lshl_add_u64 v[102:103], v[78:79], 0, s[76:77]
	s_mov_b32 m0, s54
	v_readfirstlane_b32 s50, v91
	global_load_lds_dwordx4 v[102:103], off
	v_lshl_add_u64 v[102:103], v[80:81], 0, s[76:77]
	s_mov_b32 m0, s11
	v_readfirstlane_b32 s51, v92
	global_load_lds_dwordx4 v[102:103], off
	ds_read_b128 v[102:105], v0
	ds_read_b128 v[106:109], v0 offset:4096
	ds_read_b128 v[110:113], v84 offset:16384
	ds_read_b128 v[114:117], v84 offset:20480
	s_waitcnt lgkmcnt(0)
	v_mfma_f32_32x32x16_bf16 v[50:65], v[102:105], v[110:113], v[50:65]
	s_mov_b32 m0, s46
	v_readfirstlane_b32 s53, v94
	v_lshl_add_u64 v[92:93], v[72:73], 0, s[82:83]
	v_readfirstlane_b32 s54, v95
	v_and_b32_e32 v91, 31, v82
	v_mfma_f32_32x32x16_bf16 v[18:33], v[102:105], v[114:117], v[18:33]
	v_mfma_f32_32x32x16_bf16 v[34:49], v[106:109], v[110:113], v[34:49]
	v_mfma_f32_32x32x16_bf16 v[2:17], v[106:109], v[114:117], v[2:17]
	ds_read_b128 v[102:105], v89
	ds_read_b128 v[106:109], v89 offset:4096
	ds_read_b128 v[110:113], v90 offset:16384
	ds_read_b128 v[114:117], v90 offset:20480
	s_waitcnt lgkmcnt(1)
	v_mfma_f32_32x32x16_bf16 v[50:65], v[102:105], v[110:113], v[50:65]
	s_waitcnt lgkmcnt(0)
	v_mfma_f32_32x32x16_bf16 v[18:33], v[102:105], v[114:117], v[18:33]
	v_mfma_f32_32x32x16_bf16 v[34:49], v[106:109], v[110:113], v[34:49]
	v_mfma_f32_32x32x16_bf16 v[2:17], v[106:109], v[114:117], v[2:17]
	ds_read_b128 v[102:105], v85
	ds_read_b128 v[106:109], v85 offset:4096
	ds_read_b128 v[110:113], v87 offset:16384
	ds_read_b128 v[114:117], v87 offset:20480
	s_waitcnt lgkmcnt(1)
	v_mfma_f32_32x32x16_bf16 v[50:65], v[102:105], v[110:113], v[50:65]
	s_waitcnt lgkmcnt(0)
	v_mfma_f32_32x32x16_bf16 v[18:33], v[102:105], v[114:117], v[18:33]
	v_mfma_f32_32x32x16_bf16 v[34:49], v[106:109], v[110:113], v[34:49]
	v_mfma_f32_32x32x16_bf16 v[2:17], v[106:109], v[114:117], v[2:17]
	ds_read_b128 v[102:105], v86
	ds_read_b128 v[106:109], v86 offset:4096
	ds_read_b128 v[110:113], v88 offset:16384
	ds_read_b128 v[114:117], v88 offset:20480
	s_waitcnt vmcnt(0)
	s_waitcnt lgkmcnt(0)
	s_barrier
; #define MFMA(a, b, c) __builtin_amdgcn_mfma_f32_32x32x16_bf16((a), (b), (c), 0, 0, 0)
; template <int AI, int BI>
; DI void gemm_tile(const u16* __restrict__ A, int lda, const u16* __restrict__ B, int ldb, int nk, bool swap,
;                   f32x16 (&acc)[AI][BI], char* lds) {
;     ...
;   for (int kt = 0; kt < nk; ++kt) {
;     const char* cur = lds + (kt & 1) * 32768;
;     if (kt + 1 < nk) gemm_stage<AI, BI>(A + (kt + 1) * 64, lda, B + (kt + 1) * 64, ldb, lds + ((kt + 1) & 1) * 32768, tid);
; #pragma unroll
;     for (int ks = 0; ks < 4; ++ks) {
;       const int co = ((ks * 2 + h) ^ sw) << 4;
;       s16x8 fa[AI], fb[BI];
; #pragma unroll
;       for (int i = 0; i < AI; ++i) fa[i] = *(const s16x8*)(cur + offA + i * 4096 + co);
; #pragma unroll
;       for (int i = 0; i < BI; ++i) fb[i] = *(const s16x8*)(cur + offB + i * 4096 + co);
; #pragma unroll
;       for (int i = 0; i < AI; ++i)
; #pragma unroll
;         for (int j = 0; j < BI; ++j) acc[i][j] = MFMA(fa[i], fb[j], acc[i][j]);
;     }
;     asm volatile("s_waitcnt vmcnt(0)" ::: "memory");
;     __syncthreads();
;   }
	v_mfma_f32_32x32x16_bf16 v[50:65], v[102:105], v[110:113], v[50:65]
	v_mfma_f32_32x32x16_bf16 v[18:33], v[102:105], v[114:117], v[18:33]
	v_lshl_add_u64 v[102:103], v[66:67], 0, s[80:81]
	global_load_lds_dwordx4 v[102:103], off
	v_lshl_add_u64 v[102:103], v[68:69], 0, s[80:81]
	s_mov_b32 m0, s47
	s_nop 0
	global_load_lds_dwordx4 v[102:103], off
	v_lshl_add_u64 v[102:103], v[70:71], 0, s[80:81]
	s_mov_b32 m0, s48
	v_mfma_f32_32x32x16_bf16 v[34:49], v[106:109], v[110:113], v[34:49]
	global_load_lds_dwordx4 v[102:103], off
	v_lshl_add_u64 v[102:103], v[72:73], 0, s[80:81]
	s_mov_b32 m0, s49
	s_nop 0
	global_load_lds_dwordx4 v[102:103], off
	s_mov_b32 m0, s36
	v_mfma_f32_32x32x16_bf16 v[2:17], v[106:109], v[114:117], v[2:17]
	global_load_lds_dwordx4 v[100:101], off
	v_lshl_add_u64 v[100:101], v[76:77], 0, s[80:81]
	s_mov_b32 m0, s37
	s_nop 0
	global_load_lds_dwordx4 v[100:101], off
	v_lshl_add_u64 v[100:101], v[78:79], 0, s[80:81]
	s_mov_b32 m0, s40
	s_nop 0
	global_load_lds_dwordx4 v[100:101], off
	v_lshl_add_u64 v[100:101], v[80:81], 0, s[80:81]
	s_mov_b32 m0, s41
	s_nop 0
	global_load_lds_dwordx4 v[100:101], off
	ds_read_b128 v[100:103], v0 offset:32768
	ds_read_b128 v[104:107], v0 offset:36864
	ds_read_b128 v[108:111], v84 offset:49152
	ds_read_b128 v[112:115], v84 offset:53248
	s_waitcnt lgkmcnt(0)
	v_mfma_f32_32x32x16_bf16 v[50:65], v[100:103], v[108:111], v[50:65]
	s_mov_b32 m0, s50
	v_mfma_f32_32x32x16_bf16 v[18:33], v[100:103], v[112:115], v[18:33]
	v_mfma_f32_32x32x16_bf16 v[34:49], v[104:107], v[108:111], v[34:49]
	v_mfma_f32_32x32x16_bf16 v[2:17], v[104:107], v[112:115], v[2:17]
	ds_read_b128 v[100:103], v89 offset:32768
	ds_read_b128 v[104:107], v89 offset:36864
	ds_read_b128 v[108:111], v90 offset:49152
	ds_read_b128 v[112:115], v90 offset:53248
	s_waitcnt lgkmcnt(1)
	v_mfma_f32_32x32x16_bf16 v[50:65], v[100:103], v[108:111], v[50:65]
	s_waitcnt lgkmcnt(0)
	v_mfma_f32_32x32x16_bf16 v[18:33], v[100:103], v[112:115], v[18:33]
	v_mfma_f32_32x32x16_bf16 v[34:49], v[104:107], v[108:111], v[34:49]
	v_mfma_f32_32x32x16_bf16 v[2:17], v[104:107], v[112:115], v[2:17]
	ds_read_b128 v[100:103], v85 offset:32768
	ds_read_b128 v[104:107], v85 offset:36864
	ds_read_b128 v[108:111], v87 offset:49152
	ds_read_b128 v[112:115], v87 offset:53248
	s_waitcnt lgkmcnt(1)
	v_mfma_f32_32x32x16_bf16 v[50:65], v[100:103], v[108:111], v[50:65]
	s_waitcnt lgkmcnt(0)
	v_mfma_f32_32x32x16_bf16 v[18:33], v[100:103], v[112:115], v[18:33]
	v_mfma_f32_32x32x16_bf16 v[34:49], v[104:107], v[108:111], v[34:49]
	v_mfma_f32_32x32x16_bf16 v[2:17], v[104:107], v[112:115], v[2:17]
	ds_read_b128 v[100:103], v86 offset:32768
	ds_read_b128 v[104:107], v86 offset:36864
	ds_read_b128 v[108:111], v88 offset:49152
	ds_read_b128 v[112:115], v88 offset:53248
	s_waitcnt vmcnt(0)
	s_waitcnt lgkmcnt(0)
	s_barrier
	v_mfma_f32_32x32x16_bf16 v[50:65], v[100:103], v[108:111], v[50:65]
	v_mfma_f32_32x32x16_bf16 v[18:33], v[100:103], v[112:115], v[18:33]
	v_lshl_add_u64 v[100:101], v[66:67], 0, s[82:83]
	global_load_lds_dwordx4 v[100:101], off
	v_lshl_add_u64 v[100:101], v[68:69], 0, s[82:83]
	s_mov_b32 m0, s51
	s_nop 0
	global_load_lds_dwordx4 v[100:101], off
	v_lshl_add_u64 v[100:101], v[70:71], 0, s[82:83]
	s_mov_b32 m0, s52
	v_mfma_f32_32x32x16_bf16 v[34:49], v[104:107], v[108:111], v[34:49]
	global_load_lds_dwordx4 v[100:101], off
	s_mov_b32 m0, s53
	s_nop 0
	global_load_lds_dwordx4 v[92:93], off
	v_lshl_add_u64 v[92:93], v[74:75], 0, s[82:83]
	s_mov_b32 m0, s54
	v_mfma_f32_32x32x16_bf16 v[2:17], v[104:107], v[112:115], v[2:17]
	global_load_lds_dwordx4 v[92:93], off
	v_lshl_add_u64 v[92:93], v[76:77], 0, s[82:83]
	s_mov_b32 m0, s55
	s_nop 0
	global_load_lds_dwordx4 v[92:93], off
	v_lshl_add_u64 v[92:93], v[78:79], 0, s[82:83]
	s_mov_b32 m0, s56
	s_nop 0
	global_load_lds_dwordx4 v[92:93], off
	v_lshl_add_u64 v[92:93], v[80:81], 0, s[82:83]
	s_mov_b32 m0, s11
	s_nop 0
	global_load_lds_dwordx4 v[92:93], off
	ds_read_b128 v[92:95], v0
	ds_read_b128 v[96:99], v0 offset:4096
	ds_read_b128 v[100:103], v84 offset:16384
	ds_read_b128 v[104:107], v84 offset:20480
	s_waitcnt lgkmcnt(0)
	v_mfma_f32_32x32x16_bf16 v[50:65], v[92:95], v[100:103], v[50:65]
	s_mov_b32 m0, s46
	v_mfma_f32_32x32x16_bf16 v[18:33], v[92:95], v[104:107], v[18:33]
	v_mfma_f32_32x32x16_bf16 v[34:49], v[96:99], v[100:103], v[34:49]
	v_mfma_f32_32x32x16_bf16 v[2:17], v[96:99], v[104:107], v[2:17]
	ds_read_b128 v[92:95], v89
	ds_read_b128 v[96:99], v89 offset:4096
	ds_read_b128 v[100:103], v90 offset:16384
	ds_read_b128 v[104:107], v90 offset:20480
	s_waitcnt lgkmcnt(1)
	v_mfma_f32_32x32x16_bf16 v[50:65], v[92:95], v[100:103], v[50:65]
	s_waitcnt lgkmcnt(0)
	v_mfma_f32_32x32x16_bf16 v[18:33], v[92:95], v[104:107], v[18:33]
	v_mfma_f32_32x32x16_bf16 v[34:49], v[96:99], v[100:103], v[34:49]
	v_mfma_f32_32x32x16_bf16 v[2:17], v[96:99], v[104:107], v[2:17]
	ds_read_b128 v[92:95], v85
	ds_read_b128 v[96:99], v85 offset:4096
	ds_read_b128 v[100:103], v87 offset:16384
	ds_read_b128 v[104:107], v87 offset:20480
	s_waitcnt lgkmcnt(1)
	v_mfma_f32_32x32x16_bf16 v[50:65], v[92:95], v[100:103], v[50:65]
	s_waitcnt lgkmcnt(0)
	v_mfma_f32_32x32x16_bf16 v[18:33], v[92:95], v[104:107], v[18:33]
	v_mfma_f32_32x32x16_bf16 v[34:49], v[96:99], v[100:103], v[34:49]
	v_mfma_f32_32x32x16_bf16 v[2:17], v[96:99], v[104:107], v[2:17]
	ds_read_b128 v[92:95], v86
	ds_read_b128 v[96:99], v86 offset:4096
	ds_read_b128 v[100:103], v88 offset:16384
	ds_read_b128 v[104:107], v88 offset:20480
	s_waitcnt vmcnt(0)
	s_waitcnt lgkmcnt(0)
	s_barrier
; #define MFMA(a, b, c) __builtin_amdgcn_mfma_f32_32x32x16_bf16((a), (b), (c), 0, 0, 0)
; template <int AI, int BI>
; DI void gemm_tile(const u16* __restrict__ A, int lda, const u16* __restrict__ B, int ldb, int nk, bool swap,
;                   f32x16 (&acc)[AI][BI], char* lds) {
;     ...
;   for (int kt = 0; kt < nk; ++kt) {
;     const char* cur = lds + (kt & 1) * 32768;
;     if (kt + 1 < nk) gemm_stage<AI, BI>(A + (kt + 1) * 64, lda, B + (kt + 1) * 64, ldb, lds + ((kt + 1) & 1) * 32768, tid);
; #pragma unroll
;     for (int ks = 0; ks < 4; ++ks) {
;       const int co = ((ks * 2 + h) ^ sw) << 4;
;       s16x8 fa[AI], fb[BI];
; #pragma unroll
;       for (int i = 0; i < AI; ++i) fa[i] = *(const s16x8*)(cur + offA + i * 4096 + co);
; #pragma unroll
;       for (int i = 0; i < BI; ++i) fb[i] = *(const s16x8*)(cur + offB + i * 4096 + co);
; #pragma unroll
;       for (int i = 0; i < AI; ++i)
; #pragma unroll
;         for (int j = 0; j < BI; ++j) acc[i][j] = MFMA(fa[i], fb[j], acc[i][j]);
;     }
;     asm volatile("s_waitcnt vmcnt(0)" ::: "memory");
;     __syncthreads();
;   }
	v_mfma_f32_32x32x16_bf16 v[50:65], v[92:95], v[100:103], v[50:65]
	v_mfma_f32_32x32x16_bf16 v[18:33], v[92:95], v[104:107], v[18:33]
	v_lshl_add_u64 v[92:93], v[66:67], 0, s[84:85]
	global_load_lds_dwordx4 v[92:93], off
	v_lshl_add_u64 v[92:93], v[68:69], 0, s[84:85]
	s_mov_b32 m0, s47
	s_nop 0
	global_load_lds_dwordx4 v[92:93], off
	v_lshl_add_u64 v[92:93], v[70:71], 0, s[84:85]
	s_mov_b32 m0, s48
	v_mfma_f32_32x32x16_bf16 v[34:49], v[96:99], v[100:103], v[34:49]
	global_load_lds_dwordx4 v[92:93], off
	v_lshl_add_u64 v[92:93], v[72:73], 0, s[84:85]
	s_mov_b32 m0, s49
	s_nop 0
	global_load_lds_dwordx4 v[92:93], off
	v_lshl_add_u64 v[92:93], v[74:75], 0, s[84:85]
	s_mov_b32 m0, s36
	v_mfma_f32_32x32x16_bf16 v[2:17], v[96:99], v[104:107], v[2:17]
	global_load_lds_dwordx4 v[92:93], off
	v_lshl_add_u64 v[92:93], v[76:77], 0, s[84:85]
	s_mov_b32 m0, s37
	s_nop 0
	global_load_lds_dwordx4 v[92:93], off
	v_lshl_add_u64 v[92:93], v[78:79], 0, s[84:85]
	s_mov_b32 m0, s40
	s_nop 0
	global_load_lds_dwordx4 v[92:93], off
	v_lshl_add_u64 v[92:93], v[80:81], 0, s[84:85]
	s_mov_b32 m0, s41
	s_nop 0
	global_load_lds_dwordx4 v[92:93], off
	ds_read_b128 v[92:95], v0 offset:32768
	ds_read_b128 v[96:99], v0 offset:36864
	ds_read_b128 v[100:103], v84 offset:49152
	ds_read_b128 v[104:107], v84 offset:53248
	s_waitcnt lgkmcnt(0)
	v_mfma_f32_32x32x16_bf16 v[50:65], v[92:95], v[100:103], v[50:65]
	s_mov_b32 m0, s50
	v_mfma_f32_32x32x16_bf16 v[18:33], v[92:95], v[104:107], v[18:33]
	v_mfma_f32_32x32x16_bf16 v[34:49], v[96:99], v[100:103], v[34:49]
	v_mfma_f32_32x32x16_bf16 v[2:17], v[96:99], v[104:107], v[2:17]
	ds_read_b128 v[92:95], v89 offset:32768
	ds_read_b128 v[96:99], v89 offset:36864
	ds_read_b128 v[100:103], v90 offset:49152
	ds_read_b128 v[104:107], v90 offset:53248
	s_waitcnt lgkmcnt(1)
	v_mfma_f32_32x32x16_bf16 v[50:65], v[92:95], v[100:103], v[50:65]
	s_waitcnt lgkmcnt(0)
	v_mfma_f32_32x32x16_bf16 v[18:33], v[92:95], v[104:107], v[18:33]
	v_mfma_f32_32x32x16_bf16 v[34:49], v[96:99], v[100:103], v[34:49]
	v_mfma_f32_32x32x16_bf16 v[2:17], v[96:99], v[104:107], v[2:17]
	ds_read_b128 v[92:95], v85 offset:32768
	ds_read_b128 v[96:99], v85 offset:36864
	ds_read_b128 v[100:103], v87 offset:49152
	ds_read_b128 v[104:107], v87 offset:53248
	s_waitcnt lgkmcnt(1)
	v_mfma_f32_32x32x16_bf16 v[50:65], v[92:95], v[100:103], v[50:65]
	s_waitcnt lgkmcnt(0)
	v_mfma_f32_32x32x16_bf16 v[18:33], v[92:95], v[104:107], v[18:33]
	v_mfma_f32_32x32x16_bf16 v[34:49], v[96:99], v[100:103], v[34:49]
	v_mfma_f32_32x32x16_bf16 v[2:17], v[96:99], v[104:107], v[2:17]
	ds_read_b128 v[92:95], v86 offset:32768
	ds_read_b128 v[96:99], v86 offset:36864
	ds_read_b128 v[100:103], v88 offset:49152
	ds_read_b128 v[104:107], v88 offset:53248
	s_waitcnt vmcnt(0)
	s_waitcnt lgkmcnt(0)
	s_barrier
	v_mfma_f32_32x32x16_bf16 v[50:65], v[92:95], v[100:103], v[50:65]
	v_mfma_f32_32x32x16_bf16 v[18:33], v[92:95], v[104:107], v[18:33]
	v_lshl_add_u64 v[92:93], v[66:67], 0, s[88:89]
	global_load_lds_dwordx4 v[92:93], off
	v_lshl_add_u64 v[92:93], v[68:69], 0, s[88:89]
	s_mov_b32 m0, s51
	s_nop 0
	global_load_lds_dwordx4 v[92:93], off
	v_lshl_add_u64 v[92:93], v[70:71], 0, s[88:89]
	s_mov_b32 m0, s52
	v_mfma_f32_32x32x16_bf16 v[34:49], v[96:99], v[100:103], v[34:49]
	global_load_lds_dwordx4 v[92:93], off
	v_lshl_add_u64 v[92:93], v[72:73], 0, s[88:89]
	s_mov_b32 m0, s53
	s_nop 0
	global_load_lds_dwordx4 v[92:93], off
	v_lshl_add_u64 v[92:93], v[74:75], 0, s[88:89]
	s_mov_b32 m0, s54
	v_mfma_f32_32x32x16_bf16 v[2:17], v[96:99], v[104:107], v[2:17]
	global_load_lds_dwordx4 v[92:93], off
	v_lshl_add_u64 v[92:93], v[76:77], 0, s[88:89]
	s_mov_b32 m0, s55
	s_nop 0
	global_load_lds_dwordx4 v[92:93], off
	v_lshl_add_u64 v[92:93], v[78:79], 0, s[88:89]
	s_mov_b32 m0, s56
	s_nop 0
	global_load_lds_dwordx4 v[92:93], off
	v_lshl_add_u64 v[92:93], v[80:81], 0, s[88:89]
	s_mov_b32 m0, s11
	s_nop 0
	global_load_lds_dwordx4 v[92:93], off
	ds_read_b128 v[92:95], v0
	ds_read_b128 v[96:99], v0 offset:4096
	ds_read_b128 v[100:103], v84 offset:16384
	ds_read_b128 v[104:107], v84 offset:20480
	s_waitcnt lgkmcnt(0)
	v_mfma_f32_32x32x16_bf16 v[50:65], v[92:95], v[100:103], v[50:65]
	s_mov_b32 m0, s46
	v_mfma_f32_32x32x16_bf16 v[18:33], v[92:95], v[104:107], v[18:33]
	v_mfma_f32_32x32x16_bf16 v[34:49], v[96:99], v[100:103], v[34:49]
	v_mfma_f32_32x32x16_bf16 v[2:17], v[96:99], v[104:107], v[2:17]
	ds_read_b128 v[92:95], v89
	ds_read_b128 v[96:99], v89 offset:4096
	ds_read_b128 v[100:103], v90 offset:16384
	ds_read_b128 v[104:107], v90 offset:20480
	s_waitcnt lgkmcnt(1)
	v_mfma_f32_32x32x16_bf16 v[50:65], v[92:95], v[100:103], v[50:65]
	s_waitcnt lgkmcnt(0)
	v_mfma_f32_32x32x16_bf16 v[18:33], v[92:95], v[104:107], v[18:33]
	v_mfma_f32_32x32x16_bf16 v[34:49], v[96:99], v[100:103], v[34:49]
	v_mfma_f32_32x32x16_bf16 v[2:17], v[96:99], v[104:107], v[2:17]
	ds_read_b128 v[92:95], v85
	ds_read_b128 v[96:99], v85 offset:4096
	ds_read_b128 v[100:103], v87 offset:16384
	ds_read_b128 v[104:107], v87 offset:20480
	s_waitcnt lgkmcnt(1)
	v_mfma_f32_32x32x16_bf16 v[50:65], v[92:95], v[100:103], v[50:65]
	s_waitcnt lgkmcnt(0)
	v_mfma_f32_32x32x16_bf16 v[18:33], v[92:95], v[104:107], v[18:33]
	v_mfma_f32_32x32x16_bf16 v[34:49], v[96:99], v[100:103], v[34:49]
	v_mfma_f32_32x32x16_bf16 v[2:17], v[96:99], v[104:107], v[2:17]
	ds_read_b128 v[92:95], v86
	ds_read_b128 v[96:99], v86 offset:4096
	ds_read_b128 v[100:103], v88 offset:16384
	ds_read_b128 v[104:107], v88 offset:20480
	s_waitcnt vmcnt(0)
	s_waitcnt lgkmcnt(0)
	s_barrier
; #define MFMA(a, b, c) __builtin_amdgcn_mfma_f32_32x32x16_bf16((a), (b), (c), 0, 0, 0)
; template <int AI, int BI>
; DI void gemm_tile(const u16* __restrict__ A, int lda, const u16* __restrict__ B, int ldb, int nk, bool swap,
;                   f32x16 (&acc)[AI][BI], char* lds) {
;     ...
;   for (int kt = 0; kt < nk; ++kt) {
;     const char* cur = lds + (kt & 1) * 32768;
;     if (kt + 1 < nk) gemm_stage<AI, BI>(A + (kt + 1) * 64, lda, B + (kt + 1) * 64, ldb, lds + ((kt + 1) & 1) * 32768, tid);
; #pragma unroll
;     for (int ks = 0; ks < 4; ++ks) {
;       const int co = ((ks * 2 + h) ^ sw) << 4;
;       s16x8 fa[AI], fb[BI];
; #pragma unroll
;       for (int i = 0; i < AI; ++i) fa[i] = *(const s16x8*)(cur + offA + i * 4096 + co);
; #pragma unroll
;       for (int i = 0; i < BI; ++i) fb[i] = *(const s16x8*)(cur + offB + i * 4096 + co);
; #pragma unroll
;       for (int i = 0; i < AI; ++i)
; #pragma unroll
;         for (int j = 0; j < BI; ++j) acc[i][j] = MFMA(fa[i], fb[j], acc[i][j]);
;     }
;     asm volatile("s_waitcnt vmcnt(0)" ::: "memory");
;     __syncthreads();
;   }
	v_mfma_f32_32x32x16_bf16 v[50:65], v[92:95], v[100:103], v[50:65]
	v_mfma_f32_32x32x16_bf16 v[18:33], v[92:95], v[104:107], v[18:33]
	v_lshl_add_u64 v[92:93], v[66:67], 0, vcc
	global_load_lds_dwordx4 v[92:93], off
	v_lshl_add_u64 v[92:93], v[68:69], 0, vcc
	s_mov_b32 m0, s47
	s_nop 0
	global_load_lds_dwordx4 v[92:93], off
	v_lshl_add_u64 v[92:93], v[70:71], 0, vcc
	s_mov_b32 m0, s48
	v_mfma_f32_32x32x16_bf16 v[34:49], v[96:99], v[100:103], v[34:49]
	global_load_lds_dwordx4 v[92:93], off
	v_lshl_add_u64 v[92:93], v[72:73], 0, vcc
	s_mov_b32 m0, s49
	s_nop 0
	global_load_lds_dwordx4 v[92:93], off
	v_lshl_add_u64 v[92:93], v[74:75], 0, vcc
	s_mov_b32 m0, s36
	v_mfma_f32_32x32x16_bf16 v[2:17], v[96:99], v[104:107], v[2:17]
	global_load_lds_dwordx4 v[92:93], off
	v_lshl_add_u64 v[92:93], v[76:77], 0, vcc
	s_mov_b32 m0, s37
	s_nop 0
	global_load_lds_dwordx4 v[92:93], off
	v_lshl_add_u64 v[92:93], v[78:79], 0, vcc
	s_mov_b32 m0, s40
	s_nop 0
	global_load_lds_dwordx4 v[92:93], off
	v_lshl_add_u64 v[92:93], v[80:81], 0, vcc
	s_mov_b32 m0, s41
	s_nop 0
	global_load_lds_dwordx4 v[92:93], off
	ds_read_b128 v[92:95], v0 offset:32768
	ds_read_b128 v[96:99], v0 offset:36864
	ds_read_b128 v[100:103], v84 offset:49152
	ds_read_b128 v[104:107], v84 offset:53248
	s_waitcnt lgkmcnt(0)
	v_mfma_f32_32x32x16_bf16 v[50:65], v[92:95], v[100:103], v[50:65]
	s_mov_b32 m0, s50
	v_mfma_f32_32x32x16_bf16 v[18:33], v[92:95], v[104:107], v[18:33]
	v_mfma_f32_32x32x16_bf16 v[34:49], v[96:99], v[100:103], v[34:49]
	v_mfma_f32_32x32x16_bf16 v[2:17], v[96:99], v[104:107], v[2:17]
	ds_read_b128 v[92:95], v89 offset:32768
	ds_read_b128 v[96:99], v89 offset:36864
	ds_read_b128 v[100:103], v90 offset:49152
	ds_read_b128 v[104:107], v90 offset:53248
	s_waitcnt lgkmcnt(1)
	v_mfma_f32_32x32x16_bf16 v[50:65], v[92:95], v[100:103], v[50:65]
	s_waitcnt lgkmcnt(0)
	v_mfma_f32_32x32x16_bf16 v[18:33], v[92:95], v[104:107], v[18:33]
	v_mfma_f32_32x32x16_bf16 v[34:49], v[96:99], v[100:103], v[34:49]
	v_mfma_f32_32x32x16_bf16 v[2:17], v[96:99], v[104:107], v[2:17]
	ds_read_b128 v[92:95], v85 offset:32768
	ds_read_b128 v[96:99], v85 offset:36864
	ds_read_b128 v[100:103], v87 offset:49152
	ds_read_b128 v[104:107], v87 offset:53248
	s_waitcnt lgkmcnt(1)
	v_mfma_f32_32x32x16_bf16 v[50:65], v[92:95], v[100:103], v[50:65]
	s_waitcnt lgkmcnt(0)
	v_mfma_f32_32x32x16_bf16 v[18:33], v[92:95], v[104:107], v[18:33]
	v_mfma_f32_32x32x16_bf16 v[34:49], v[96:99], v[100:103], v[34:49]
	v_mfma_f32_32x32x16_bf16 v[2:17], v[96:99], v[104:107], v[2:17]
	ds_read_b128 v[92:95], v86 offset:32768
	ds_read_b128 v[96:99], v86 offset:36864
	ds_read_b128 v[100:103], v88 offset:49152
	ds_read_b128 v[104:107], v88 offset:53248
	s_waitcnt vmcnt(0)
	s_waitcnt lgkmcnt(0)
	s_barrier
	v_mfma_f32_32x32x16_bf16 v[50:65], v[92:95], v[100:103], v[50:65]
	v_mfma_f32_32x32x16_bf16 v[18:33], v[92:95], v[104:107], v[18:33]
	v_lshl_add_u64 v[92:93], v[66:67], 0, s[78:79]
	global_load_lds_dwordx4 v[92:93], off
	v_lshl_add_u64 v[92:93], v[68:69], 0, s[78:79]
	s_mov_b32 m0, s51
	s_nop 0
	global_load_lds_dwordx4 v[92:93], off
	v_lshl_add_u64 v[92:93], v[70:71], 0, s[78:79]
	s_mov_b32 m0, s52
	v_mfma_f32_32x32x16_bf16 v[34:49], v[96:99], v[100:103], v[34:49]
	global_load_lds_dwordx4 v[92:93], off
	v_lshl_add_u64 v[92:93], v[72:73], 0, s[78:79]
	s_mov_b32 m0, s53
	s_nop 0
	global_load_lds_dwordx4 v[92:93], off
	v_lshl_add_u64 v[92:93], v[74:75], 0, s[78:79]
	s_mov_b32 m0, s54
	v_mfma_f32_32x32x16_bf16 v[2:17], v[96:99], v[104:107], v[2:17]
	global_load_lds_dwordx4 v[92:93], off
	v_lshl_add_u64 v[92:93], v[76:77], 0, s[78:79]
	s_mov_b32 m0, s55
	s_nop 0
	global_load_lds_dwordx4 v[92:93], off
	v_lshl_add_u64 v[92:93], v[78:79], 0, s[78:79]
	s_mov_b32 m0, s56
	s_nop 0
	global_load_lds_dwordx4 v[92:93], off
	v_lshl_add_u64 v[92:93], v[80:81], 0, s[78:79]
	s_mov_b32 m0, s11
	s_nop 0
	global_load_lds_dwordx4 v[92:93], off
	ds_read_b128 v[92:95], v0
	ds_read_b128 v[96:99], v0 offset:4096
	ds_read_b128 v[100:103], v84 offset:16384
	ds_read_b128 v[104:107], v84 offset:20480
	s_waitcnt lgkmcnt(0)
	v_mfma_f32_32x32x16_bf16 v[50:65], v[92:95], v[100:103], v[50:65]
	s_mov_b32 m0, s46
	v_mfma_f32_32x32x16_bf16 v[18:33], v[92:95], v[104:107], v[18:33]
	v_mfma_f32_32x32x16_bf16 v[34:49], v[96:99], v[100:103], v[34:49]
	v_mfma_f32_32x32x16_bf16 v[2:17], v[96:99], v[104:107], v[2:17]
	ds_read_b128 v[92:95], v89
	ds_read_b128 v[96:99], v89 offset:4096
	ds_read_b128 v[100:103], v90 offset:16384
	ds_read_b128 v[104:107], v90 offset:20480
	s_waitcnt lgkmcnt(1)
	v_mfma_f32_32x32x16_bf16 v[50:65], v[92:95], v[100:103], v[50:65]
	s_waitcnt lgkmcnt(0)
	v_mfma_f32_32x32x16_bf16 v[18:33], v[92:95], v[104:107], v[18:33]
	v_mfma_f32_32x32x16_bf16 v[34:49], v[96:99], v[100:103], v[34:49]
	v_mfma_f32_32x32x16_bf16 v[2:17], v[96:99], v[104:107], v[2:17]
	ds_read_b128 v[92:95], v85
	ds_read_b128 v[96:99], v85 offset:4096
	ds_read_b128 v[100:103], v87 offset:16384
	ds_read_b128 v[104:107], v87 offset:20480
	s_waitcnt lgkmcnt(1)
	v_mfma_f32_32x32x16_bf16 v[50:65], v[92:95], v[100:103], v[50:65]
	s_waitcnt lgkmcnt(0)
	v_mfma_f32_32x32x16_bf16 v[18:33], v[92:95], v[104:107], v[18:33]
	v_mfma_f32_32x32x16_bf16 v[34:49], v[96:99], v[100:103], v[34:49]
	v_mfma_f32_32x32x16_bf16 v[2:17], v[96:99], v[104:107], v[2:17]
	ds_read_b128 v[92:95], v86
	ds_read_b128 v[96:99], v86 offset:4096
	ds_read_b128 v[100:103], v88 offset:16384
	ds_read_b128 v[104:107], v88 offset:20480
	s_waitcnt vmcnt(0)
	s_waitcnt lgkmcnt(0)
	s_barrier
; #define MFMA(a, b, c) __builtin_amdgcn_mfma_f32_32x32x16_bf16((a), (b), (c), 0, 0, 0)
; DI int opaque0() { int z = 0; asm volatile("" : "+v"(z)); return z; }
; template <int AI, int BI>
; DI void gemm_tile(const u16* __restrict__ A, int lda, const u16* __restrict__ B, int ldb, int nk, bool swap,
;                   f32x16 (&acc)[AI][BI], char* lds) {
;     ...
;   for (int kt = 0; kt < nk; ++kt) {
;     const char* cur = lds + (kt & 1) * 32768;
;     if (kt + 1 < nk) gemm_stage<AI, BI>(A + (kt + 1) * 64, lda, B + (kt + 1) * 64, ldb, lds + ((kt + 1) & 1) * 32768, tid);
; #pragma unroll
;     for (int ks = 0; ks < 4; ++ks) {
;       const int co = ((ks * 2 + h) ^ sw) << 4;
;       s16x8 fa[AI], fb[BI];
; #pragma unroll
;       for (int i = 0; i < AI; ++i) fa[i] = *(const s16x8*)(cur + offA + i * 4096 + co);
; #pragma unroll
;       for (int i = 0; i < BI; ++i) fb[i] = *(const s16x8*)(cur + offB + i * 4096 + co);
; #pragma unroll
;       for (int i = 0; i < AI; ++i)
; #pragma unroll
;         for (int j = 0; j < BI; ++j) acc[i][j] = MFMA(fa[i], fb[j], acc[i][j]);
;     }
;     asm volatile("s_waitcnt vmcnt(0)" ::: "memory");
;     __syncthreads();
;   }
; template <int AI, int BI>
; DI void m2_tile(char* wsb, int layer, int m0, int n0, char* lds) {
;     ...
;   const int m0e = m0 + opaque0();
;   const int mr = m0 < TL ? (m0 >> 11) : 8;
;   const float* gate = mods + (size_t)mr * 9216 + 5 * 1024;
	v_mfma_f32_32x32x16_bf16 v[50:65], v[92:95], v[100:103], v[50:65]
	v_mfma_f32_32x32x16_bf16 v[18:33], v[92:95], v[104:107], v[18:33]
	v_lshl_add_u64 v[92:93], v[66:67], 0, s[2:3]
	global_load_lds_dwordx4 v[92:93], off
	v_lshl_add_u64 v[92:93], v[68:69], 0, s[2:3]
	s_mov_b32 m0, s47
	v_lshl_add_u64 v[66:67], v[66:67], 0, s[30:31]
	global_load_lds_dwordx4 v[92:93], off
	v_lshl_add_u64 v[92:93], v[70:71], 0, s[2:3]
	s_mov_b32 m0, s48
	v_mfma_f32_32x32x16_bf16 v[34:49], v[96:99], v[100:103], v[34:49]
	global_load_lds_dwordx4 v[92:93], off
	v_lshl_add_u64 v[92:93], v[72:73], 0, s[2:3]
	s_mov_b32 m0, s49
	s_nop 0
	global_load_lds_dwordx4 v[92:93], off
	v_lshl_add_u64 v[92:93], v[74:75], 0, s[2:3]
	s_mov_b32 m0, s36
	v_mfma_f32_32x32x16_bf16 v[2:17], v[96:99], v[104:107], v[2:17]
	global_load_lds_dwordx4 v[92:93], off
	v_lshl_add_u64 v[92:93], v[76:77], 0, s[2:3]
	s_mov_b32 m0, s37
	s_lshl_b32 s36, s10, 7
	global_load_lds_dwordx4 v[92:93], off
	v_lshl_add_u64 v[92:93], v[78:79], 0, s[2:3]
	s_mov_b32 m0, s40
	s_lshr_b32 s10, s34, 7
	global_load_lds_dwordx4 v[92:93], off
	v_lshl_add_u64 v[92:93], v[80:81], 0, s[2:3]
	s_mov_b32 m0, s41
	s_mul_i32 s10, s10, 0x9000
	global_load_lds_dwordx4 v[92:93], off
	ds_read_b128 v[92:95], v0 offset:32768
	ds_read_b128 v[96:99], v0 offset:36864
	ds_read_b128 v[100:103], v84 offset:49152
	ds_read_b128 v[104:107], v84 offset:53248
	s_waitcnt lgkmcnt(0)
	v_mfma_f32_32x32x16_bf16 v[50:65], v[92:95], v[100:103], v[50:65]
	s_mov_b32 m0, s50
	s_add_u32 s10, s18, s10
	v_mfma_f32_32x32x16_bf16 v[18:33], v[92:95], v[104:107], v[18:33]
	v_mfma_f32_32x32x16_bf16 v[34:49], v[96:99], v[100:103], v[34:49]
	v_mfma_f32_32x32x16_bf16 v[2:17], v[96:99], v[104:107], v[2:17]
	ds_read_b128 v[92:95], v89 offset:32768
	ds_read_b128 v[96:99], v89 offset:36864
	ds_read_b128 v[100:103], v90 offset:49152
	ds_read_b128 v[104:107], v90 offset:53248
	s_waitcnt lgkmcnt(1)
	v_mfma_f32_32x32x16_bf16 v[50:65], v[92:95], v[100:103], v[50:65]
	s_waitcnt lgkmcnt(0)
	v_mfma_f32_32x32x16_bf16 v[18:33], v[92:95], v[104:107], v[18:33]
	v_mfma_f32_32x32x16_bf16 v[34:49], v[96:99], v[100:103], v[34:49]
	v_mfma_f32_32x32x16_bf16 v[2:17], v[96:99], v[104:107], v[2:17]
	ds_read_b128 v[92:95], v85 offset:32768
	ds_read_b128 v[96:99], v85 offset:36864
	ds_read_b128 v[100:103], v87 offset:49152
	ds_read_b128 v[104:107], v87 offset:53248
	s_waitcnt lgkmcnt(1)
	v_mfma_f32_32x32x16_bf16 v[50:65], v[92:95], v[100:103], v[50:65]
	s_waitcnt lgkmcnt(0)
	v_mfma_f32_32x32x16_bf16 v[18:33], v[92:95], v[104:107], v[18:33]
	v_mfma_f32_32x32x16_bf16 v[34:49], v[96:99], v[100:103], v[34:49]
	v_mfma_f32_32x32x16_bf16 v[2:17], v[96:99], v[104:107], v[2:17]
	ds_read_b128 v[92:95], v86 offset:32768
	ds_read_b128 v[96:99], v86 offset:36864
	ds_read_b128 v[100:103], v88 offset:49152
	ds_read_b128 v[104:107], v88 offset:53248
	s_waitcnt vmcnt(0)
	s_waitcnt lgkmcnt(0)
	s_barrier
	global_load_lds_dwordx4 v[66:67], off
	v_lshl_add_u64 v[66:67], v[68:69], 0, s[30:31]
	s_mov_b32 m0, s51
	v_mfma_f32_32x32x16_bf16 v[50:65], v[92:95], v[100:103], v[50:65]
	global_load_lds_dwordx4 v[66:67], off
	v_lshl_add_u64 v[66:67], v[70:71], 0, s[30:31]
	s_mov_b32 m0, s52
	s_nop 0
	global_load_lds_dwordx4 v[66:67], off
	v_lshl_add_u64 v[66:67], v[72:73], 0, s[30:31]
	s_mov_b32 m0, s53
	v_mfma_f32_32x32x16_bf16 v[18:33], v[92:95], v[104:107], v[18:33]
	global_load_lds_dwordx4 v[66:67], off
	v_lshl_add_u64 v[66:67], v[74:75], 0, s[30:31]
	s_mov_b32 m0, s54
	s_nop 0
	global_load_lds_dwordx4 v[66:67], off
	v_lshl_add_u64 v[66:67], v[76:77], 0, s[30:31]
	s_mov_b32 m0, s55
	v_mfma_f32_32x32x16_bf16 v[34:49], v[96:99], v[100:103], v[34:49]
	global_load_lds_dwordx4 v[66:67], off
	v_lshl_add_u64 v[66:67], v[78:79], 0, s[30:31]
	s_mov_b32 m0, s56
	s_nop 0
	global_load_lds_dwordx4 v[66:67], off
	v_lshl_add_u64 v[66:67], v[80:81], 0, s[30:31]
	s_mov_b32 m0, s11
	v_mfma_f32_32x32x16_bf16 v[2:17], v[96:99], v[104:107], v[2:17]
	global_load_lds_dwordx4 v[66:67], off
	ds_read_b128 v[66:69], v0
	ds_read_b128 v[70:73], v0 offset:4096
	ds_read_b128 v[74:77], v84 offset:16384
	ds_read_b128 v[78:81], v84 offset:20480
	s_addc_u32 s11, s28, 0
	s_add_u32 s10, s10, 0x9000
	s_addc_u32 s11, s11, 0
	s_waitcnt lgkmcnt(0)
	v_mfma_f32_32x32x16_bf16 v[50:65], v[66:69], v[74:77], v[50:65]
	v_mfma_f32_32x32x16_bf16 v[18:33], v[66:69], v[78:81], v[18:33]
	v_mfma_f32_32x32x16_bf16 v[34:49], v[70:73], v[74:77], v[34:49]
	v_mfma_f32_32x32x16_bf16 v[2:17], v[70:73], v[78:81], v[2:17]
	ds_read_b128 v[66:69], v89
	ds_read_b128 v[70:73], v89 offset:4096
	ds_read_b128 v[74:77], v90 offset:16384
	ds_read_b128 v[78:81], v90 offset:20480
	s_waitcnt lgkmcnt(1)
	v_mfma_f32_32x32x16_bf16 v[50:65], v[66:69], v[74:77], v[50:65]
	s_waitcnt lgkmcnt(0)
	v_mfma_f32_32x32x16_bf16 v[18:33], v[66:69], v[78:81], v[18:33]
	v_mfma_f32_32x32x16_bf16 v[34:49], v[70:73], v[74:77], v[34:49]
	v_mfma_f32_32x32x16_bf16 v[2:17], v[70:73], v[78:81], v[2:17]
	ds_read_b128 v[66:69], v85
	ds_read_b128 v[70:73], v85 offset:4096
	ds_read_b128 v[74:77], v87 offset:16384
	ds_read_b128 v[78:81], v87 offset:20480
	s_waitcnt lgkmcnt(1)
	v_mfma_f32_32x32x16_bf16 v[50:65], v[66:69], v[74:77], v[50:65]
	s_waitcnt lgkmcnt(0)
	v_mfma_f32_32x32x16_bf16 v[18:33], v[66:69], v[78:81], v[18:33]
	v_mfma_f32_32x32x16_bf16 v[34:49], v[70:73], v[74:77], v[34:49]
	v_mfma_f32_32x32x16_bf16 v[2:17], v[70:73], v[78:81], v[2:17]
	ds_read_b128 v[66:69], v86
	ds_read_b128 v[70:73], v86 offset:4096
	ds_read_b128 v[74:77], v88 offset:16384
	ds_read_b128 v[78:81], v88 offset:20480
	s_waitcnt vmcnt(0)
	s_waitcnt lgkmcnt(0)
	s_barrier
; #define MFMA(a, b, c) __builtin_amdgcn_mfma_f32_32x32x16_bf16((a), (b), (c), 0, 0, 0)
; #define GAS __attribute__((address_space(1)))
; DI int opaque0() { int z = 0; asm volatile("" : "+v"(z)); return z; }
; template <int AI, int BI>
; DI void gemm_tile(const u16* __restrict__ A, int lda, const u16* __restrict__ B, int ldb, int nk, bool swap,
;                   f32x16 (&acc)[AI][BI], char* lds) {
;     ...
;   for (int kt = 0; kt < nk; ++kt) {
;     const char* cur = lds + (kt & 1) * 32768;
;     if (kt + 1 < nk) gemm_stage<AI, BI>(A + (kt + 1) * 64, lda, B + (kt + 1) * 64, ldb, lds + ((kt + 1) & 1) * 32768, tid);
; #pragma unroll
;     for (int ks = 0; ks < 4; ++ks) {
;       const int co = ((ks * 2 + h) ^ sw) << 4;
;       s16x8 fa[AI], fb[BI];
; #pragma unroll
;       for (int i = 0; i < AI; ++i) fa[i] = *(const s16x8*)(cur + offA + i * 4096 + co);
; #pragma unroll
;       for (int i = 0; i < BI; ++i) fb[i] = *(const s16x8*)(cur + offB + i * 4096 + co);
; #pragma unroll
;       for (int i = 0; i < AI; ++i)
; #pragma unroll
;         for (int j = 0; j < BI; ++j) acc[i][j] = MFMA(fa[i], fb[j], acc[i][j]);
;     }
;     asm volatile("s_waitcnt vmcnt(0)" ::: "memory");
;     __syncthreads();
;   }
; template <int AI, int BI>
; DI void m2_tile(char* wsb, int layer, int m0, int n0, char* lds) {
;     ...
;   const int m0e = m0 + opaque0();
;   const int mr = m0 < TL ? (m0 >> 11) : 8;
;   const float* gate = mods + (size_t)mr * 9216 + 5 * 1024;
;   GAS float* xsu = uptr(xs);
; #pragma unroll
;   for (int bi = 0; bi < BI; ++bi) {
;     const int n = n0 + wb * 32 * BI + bi * 32 + r;
;     const float gv = gate[n];
;     const unsigned ib = (unsigned)((m0e + wa * 32 * AI + 4 * h) * 1024 + n);
; #pragma unroll
;     for (int ai = 0; ai < AI; ++ai)
; #pragma unroll
;       for (int reg = 0; reg < 16; ++reg) {
;         const unsigned idx = ib + (unsigned)((ai * 32 + (reg & 3) + 8 * (reg >> 2)) * 1024);
;         xsu[idx] += gv * acc[ai][bi][reg];
;         if ((reg & 7) == 7) __builtin_amdgcn_sched_barrier(0);
;       }
	v_mfma_f32_32x32x16_bf16 v[50:65], v[66:69], v[74:77], v[50:65]
	v_mfma_f32_32x32x16_bf16 v[18:33], v[66:69], v[78:81], v[18:33]
	v_mfma_f32_32x32x16_bf16 v[34:49], v[70:73], v[74:77], v[34:49]
	v_mfma_f32_32x32x16_bf16 v[2:17], v[70:73], v[78:81], v[2:17]
	ds_read_b128 v[66:69], v0 offset:32768
	ds_read_b128 v[70:73], v0 offset:36864
	ds_read_b128 v[74:77], v84 offset:49152
	ds_read_b128 v[78:81], v84 offset:53248
	v_mov_b32_e32 v0, v1
	s_waitcnt lgkmcnt(1)
	v_mfma_f32_32x32x16_bf16 v[50:65], v[66:69], v[74:77], v[50:65]
	s_waitcnt lgkmcnt(0)
	v_mfma_f32_32x32x16_bf16 v[18:33], v[66:69], v[78:81], v[18:33]
	v_mfma_f32_32x32x16_bf16 v[34:49], v[70:73], v[74:77], v[34:49]
	v_mfma_f32_32x32x16_bf16 v[2:17], v[70:73], v[78:81], v[2:17]
	ds_read_b128 v[66:69], v89 offset:32768
	ds_read_b128 v[70:73], v89 offset:36864
	ds_read_b128 v[74:77], v90 offset:49152
	ds_read_b128 v[78:81], v90 offset:53248
	s_waitcnt lgkmcnt(1)
	v_mfma_f32_32x32x16_bf16 v[50:65], v[66:69], v[74:77], v[50:65]
	s_waitcnt lgkmcnt(0)
	v_mfma_f32_32x32x16_bf16 v[18:33], v[66:69], v[78:81], v[18:33]
	v_mfma_f32_32x32x16_bf16 v[34:49], v[70:73], v[74:77], v[34:49]
	v_mfma_f32_32x32x16_bf16 v[2:17], v[70:73], v[78:81], v[2:17]
	ds_read_b128 v[66:69], v85 offset:32768
	ds_read_b128 v[70:73], v85 offset:36864
	ds_read_b128 v[74:77], v87 offset:49152
	ds_read_b128 v[78:81], v87 offset:53248
	s_waitcnt lgkmcnt(1)
	v_mfma_f32_32x32x16_bf16 v[50:65], v[66:69], v[74:77], v[50:65]
	s_waitcnt lgkmcnt(0)
	v_mfma_f32_32x32x16_bf16 v[18:33], v[66:69], v[78:81], v[18:33]
	v_mfma_f32_32x32x16_bf16 v[34:49], v[70:73], v[74:77], v[34:49]
	v_mfma_f32_32x32x16_bf16 v[2:17], v[70:73], v[78:81], v[2:17]
	ds_read_b128 v[66:69], v86 offset:32768
	ds_read_b128 v[70:73], v86 offset:36864
	ds_read_b128 v[74:77], v88 offset:49152
	ds_read_b128 v[78:81], v88 offset:53248
	s_waitcnt vmcnt(0)
	s_waitcnt lgkmcnt(0)
	s_barrier
	v_mfma_f32_32x32x16_bf16 v[50:65], v[66:69], v[74:77], v[50:65]
	v_mfma_f32_32x32x16_bf16 v[18:33], v[66:69], v[78:81], v[18:33]
	v_mfma_f32_32x32x16_bf16 v[34:49], v[70:73], v[74:77], v[34:49]
	v_mfma_f32_32x32x16_bf16 v[2:17], v[70:73], v[78:81], v[2:17]
	v_and_b32_e32 v143, 31, v178
	v_and_b32_e32 v140, 64, v178
	v_or_b32_e32 v140, v140, v143
	v_bfe_u32 v143, v178, 5, 1
	v_bfe_u32 v139, v178, 7, 1
	v_lshlrev_b32_e32 v139, 6, v139
	v_lshl_add_u32 v139, v143, 2, v139
	v_lshl_add_u32 v139, v139, 10, v140
	v_lshlrev_b32_e32 v139, 2, v139
	v_add_u32_e32 v140, s35, v140
	v_lshlrev_b32_e32 v140, 2, v140
	global_load_dword v141, v140, s[10:11]
	global_load_dword v142, v140, s[10:11] offset:128
	s_lshl_b32 s56, s36, 10
	s_add_u32 s56, s56, s35
	s_lshl_b32 s56, s56, 2
	s_add_u32 s54, s8, s56
	s_addc_u32 s55, s9, 0
	s_mov_b64 s[52:53], s[54:55]
	global_load_dword v66, v139, s[52:53]
	global_load_dword v67, v139, s[52:53] offset:128
	s_add_u32 s52, s52, 4096
	s_addc_u32 s53, s53, 0
	global_load_dword v68, v139, s[52:53]
	global_load_dword v69, v139, s[52:53] offset:128
	s_add_u32 s52, s52, 4096
	s_addc_u32 s53, s53, 0
	global_load_dword v70, v139, s[52:53]
	global_load_dword v71, v139, s[52:53] offset:128
	s_add_u32 s52, s52, 4096
	s_addc_u32 s53, s53, 0
	global_load_dword v72, v139, s[52:53]
	global_load_dword v73, v139, s[52:53] offset:128
	s_add_u32 s52, s52, 20480
	s_addc_u32 s53, s53, 0
	global_load_dword v74, v139, s[52:53]
	global_load_dword v75, v139, s[52:53] offset:128
	s_add_u32 s52, s52, 4096
	s_addc_u32 s53, s53, 0
	global_load_dword v76, v139, s[52:53]
	global_load_dword v77, v139, s[52:53] offset:128
	s_add_u32 s52, s52, 4096
	s_addc_u32 s53, s53, 0
	global_load_dword v78, v139, s[52:53]
	global_load_dword v79, v139, s[52:53] offset:128
	s_add_u32 s52, s52, 4096
	s_addc_u32 s53, s53, 0
	global_load_dword v80, v139, s[52:53]
	global_load_dword v81, v139, s[52:53] offset:128
	s_add_u32 s52, s52, 20480
	s_addc_u32 s53, s53, 0
	global_load_dword v82, v139, s[52:53]
	global_load_dword v83, v139, s[52:53] offset:128
	s_add_u32 s52, s52, 4096
	s_addc_u32 s53, s53, 0
	global_load_dword v84, v139, s[52:53]
	global_load_dword v85, v139, s[52:53] offset:128
	s_add_u32 s52, s52, 4096
	s_addc_u32 s53, s53, 0
	global_load_dword v86, v139, s[52:53]
	global_load_dword v87, v139, s[52:53] offset:128
	s_add_u32 s52, s52, 4096
	s_addc_u32 s53, s53, 0
	global_load_dword v88, v139, s[52:53]
	global_load_dword v89, v139, s[52:53] offset:128
	s_add_u32 s52, s52, 20480
	s_addc_u32 s53, s53, 0
	global_load_dword v90, v139, s[52:53]
	global_load_dword v91, v139, s[52:53] offset:128
	s_add_u32 s52, s52, 4096
	s_addc_u32 s53, s53, 0
	global_load_dword v92, v139, s[52:53]
	global_load_dword v93, v139, s[52:53] offset:128
	s_add_u32 s52, s52, 4096
	s_addc_u32 s53, s53, 0
	global_load_dword v94, v139, s[52:53]
	global_load_dword v95, v139, s[52:53] offset:128
	s_add_u32 s52, s52, 4096
	s_addc_u32 s53, s53, 0
	global_load_dword v96, v139, s[52:53]
	global_load_dword v97, v139, s[52:53] offset:128
	s_add_u32 s52, s52, 20480
	s_addc_u32 s53, s53, 0
	global_load_dword v98, v139, s[52:53]
	global_load_dword v99, v139, s[52:53] offset:128
	s_add_u32 s52, s52, 4096
	s_addc_u32 s53, s53, 0
	global_load_dword v100, v139, s[52:53]
	global_load_dword v101, v139, s[52:53] offset:128
	s_add_u32 s52, s52, 4096
	s_addc_u32 s53, s53, 0
	global_load_dword v102, v139, s[52:53]
	global_load_dword v103, v139, s[52:53] offset:128
	s_add_u32 s52, s52, 4096
	s_addc_u32 s53, s53, 0
	global_load_dword v104, v139, s[52:53]
	global_load_dword v105, v139, s[52:53] offset:128
	s_add_u32 s52, s52, 20480
	s_addc_u32 s53, s53, 0
	global_load_dword v106, v139, s[52:53]
	global_load_dword v107, v139, s[52:53] offset:128
	s_add_u32 s52, s52, 4096
; #define GAS __attribute__((address_space(1)))
; DI int opaque0() { int z = 0; asm volatile("" : "+v"(z)); return z; }
; template <int AI, int BI>
; DI void m2_tile(char* wsb, int layer, int m0, int n0, char* lds) {
;     ...
;   const int m0e = m0 + opaque0();
;   const int mr = m0 < TL ? (m0 >> 11) : 8;
;   const float* gate = mods + (size_t)mr * 9216 + 5 * 1024;
;   GAS float* xsu = uptr(xs);
; #pragma unroll
;   for (int bi = 0; bi < BI; ++bi) {
;     const int n = n0 + wb * 32 * BI + bi * 32 + r;
;     const float gv = gate[n];
;     const unsigned ib = (unsigned)((m0e + wa * 32 * AI + 4 * h) * 1024 + n);
; #pragma unroll
;     for (int ai = 0; ai < AI; ++ai)
; #pragma unroll
;       for (int reg = 0; reg < 16; ++reg) {
;         const unsigned idx = ib + (unsigned)((ai * 32 + (reg & 3) + 8 * (reg >> 2)) * 1024);
;         xsu[idx] += gv * acc[ai][bi][reg];
;         if ((reg & 7) == 7) __builtin_amdgcn_sched_barrier(0);
;       }
	s_addc_u32 s53, s53, 0
	global_load_dword v108, v139, s[52:53]
	global_load_dword v109, v139, s[52:53] offset:128
	s_add_u32 s52, s52, 4096
	s_addc_u32 s53, s53, 0
	global_load_dword v110, v139, s[52:53]
	global_load_dword v111, v139, s[52:53] offset:128
	s_add_u32 s52, s52, 4096
	s_addc_u32 s53, s53, 0
	global_load_dword v112, v139, s[52:53]
	global_load_dword v113, v139, s[52:53] offset:128
	s_add_u32 s52, s52, 20480
	s_addc_u32 s53, s53, 0
	global_load_dword v114, v139, s[52:53]
	global_load_dword v115, v139, s[52:53] offset:128
	s_add_u32 s52, s52, 4096
	s_addc_u32 s53, s53, 0
	global_load_dword v116, v139, s[52:53]
	global_load_dword v117, v139, s[52:53] offset:128
	s_add_u32 s52, s52, 4096
	s_addc_u32 s53, s53, 0
	global_load_dword v118, v139, s[52:53]
	global_load_dword v119, v139, s[52:53] offset:128
	s_add_u32 s52, s52, 4096
	s_addc_u32 s53, s53, 0
	global_load_dword v120, v139, s[52:53]
	global_load_dword v121, v139, s[52:53] offset:128
	s_add_u32 s52, s52, 20480
	s_addc_u32 s53, s53, 0
	global_load_dword v122, v139, s[52:53]
	global_load_dword v123, v139, s[52:53] offset:128
	s_add_u32 s52, s52, 4096
	s_addc_u32 s53, s53, 0
	global_load_dword v124, v139, s[52:53]
	global_load_dword v134, v139, s[52:53] offset:128
	s_add_u32 s52, s52, 4096
	s_addc_u32 s53, s53, 0
	global_load_dword v135, v139, s[52:53]
	global_load_dword v136, v139, s[52:53] offset:128
	s_add_u32 s52, s52, 4096
	s_addc_u32 s53, s53, 0
	global_load_dword v137, v139, s[52:53]
	global_load_dword v138, v139, s[52:53] offset:128
	s_waitcnt vmcnt(48)
	v_fmac_f32_e32 v66, v50, v141
	v_fmac_f32_e32 v67, v18, v142
	v_fmac_f32_e32 v68, v51, v141
	v_fmac_f32_e32 v69, v19, v142
	v_fmac_f32_e32 v70, v52, v141
	v_fmac_f32_e32 v71, v20, v142
	v_fmac_f32_e32 v72, v53, v141
	v_fmac_f32_e32 v73, v21, v142
	v_fmac_f32_e32 v74, v54, v141
	v_fmac_f32_e32 v75, v22, v142
	v_fmac_f32_e32 v76, v55, v141
	v_fmac_f32_e32 v77, v23, v142
	v_fmac_f32_e32 v78, v56, v141
	v_fmac_f32_e32 v79, v24, v142
	v_fmac_f32_e32 v80, v57, v141
	v_fmac_f32_e32 v81, v25, v142
	s_waitcnt vmcnt(32)
	v_fmac_f32_e32 v82, v58, v141
	v_fmac_f32_e32 v83, v26, v142
	v_fmac_f32_e32 v84, v59, v141
	v_fmac_f32_e32 v85, v27, v142
	v_fmac_f32_e32 v86, v60, v141
	v_fmac_f32_e32 v87, v28, v142
	v_fmac_f32_e32 v88, v61, v141
	v_fmac_f32_e32 v89, v29, v142
	v_fmac_f32_e32 v90, v62, v141
	v_fmac_f32_e32 v91, v30, v142
	v_fmac_f32_e32 v92, v63, v141
	v_fmac_f32_e32 v93, v31, v142
	v_fmac_f32_e32 v94, v64, v141
	v_fmac_f32_e32 v95, v32, v142
	v_fmac_f32_e32 v96, v65, v141
	v_fmac_f32_e32 v97, v33, v142
	s_waitcnt vmcnt(16)
	v_fmac_f32_e32 v98, v34, v141
	v_fmac_f32_e32 v99, v2, v142
	v_fmac_f32_e32 v100, v35, v141
	v_fmac_f32_e32 v101, v3, v142
	v_fmac_f32_e32 v102, v36, v141
	v_fmac_f32_e32 v103, v4, v142
	v_fmac_f32_e32 v104, v37, v141
	v_fmac_f32_e32 v105, v5, v142
	v_fmac_f32_e32 v106, v38, v141
	v_fmac_f32_e32 v107, v6, v142
	v_fmac_f32_e32 v108, v39, v141
	v_fmac_f32_e32 v109, v7, v142
	v_fmac_f32_e32 v110, v40, v141
	v_fmac_f32_e32 v111, v8, v142
	v_fmac_f32_e32 v112, v41, v141
	v_fmac_f32_e32 v113, v9, v142
	s_waitcnt vmcnt(0)
; #define GAS __attribute__((address_space(1)))
; DI int opaque0() { int z = 0; asm volatile("" : "+v"(z)); return z; }
; template <int AI, int BI>
; DI void m2_tile(char* wsb, int layer, int m0, int n0, char* lds) {
;     ...
;   const int m0e = m0 + opaque0();
;   const int mr = m0 < TL ? (m0 >> 11) : 8;
;   const float* gate = mods + (size_t)mr * 9216 + 5 * 1024;
;   GAS float* xsu = uptr(xs);
; #pragma unroll
;   for (int bi = 0; bi < BI; ++bi) {
;     const int n = n0 + wb * 32 * BI + bi * 32 + r;
;     const float gv = gate[n];
;     const unsigned ib = (unsigned)((m0e + wa * 32 * AI + 4 * h) * 1024 + n);
; #pragma unroll
;     for (int ai = 0; ai < AI; ++ai)
; #pragma unroll
;       for (int reg = 0; reg < 16; ++reg) {
;         const unsigned idx = ib + (unsigned)((ai * 32 + (reg & 3) + 8 * (reg >> 2)) * 1024);
;         xsu[idx] += gv * acc[ai][bi][reg];
;         if ((reg & 7) == 7) __builtin_amdgcn_sched_barrier(0);
;       }
;   }
; }
; DI void phase_m2(const Params& p, char* wsb, int layer, int mrows, char* lds) {
;   int mt, nt;
;   for (int rnd = 0; next_tile(rnd, 128, 8, mt, nt); ++rnd) m2_tile<2, 2>(wsb, layer, mt * 128, nt * 128, lds);
	v_fmac_f32_e32 v114, v42, v141
	v_fmac_f32_e32 v115, v10, v142
	v_fmac_f32_e32 v116, v43, v141
	v_fmac_f32_e32 v117, v11, v142
	v_fmac_f32_e32 v118, v44, v141
	v_fmac_f32_e32 v119, v12, v142
	v_fmac_f32_e32 v120, v45, v141
	v_fmac_f32_e32 v121, v13, v142
	v_fmac_f32_e32 v122, v46, v141
	v_fmac_f32_e32 v123, v14, v142
	v_fmac_f32_e32 v124, v47, v141
	v_fmac_f32_e32 v134, v15, v142
	v_fmac_f32_e32 v135, v48, v141
	v_fmac_f32_e32 v136, v16, v142
	v_fmac_f32_e32 v137, v49, v141
	v_fmac_f32_e32 v138, v17, v142
	s_mov_b64 s[52:53], s[54:55]
	global_store_dword v139, v66, s[52:53]
	global_store_dword v139, v67, s[52:53] offset:128
	s_add_u32 s52, s52, 4096
	s_addc_u32 s53, s53, 0
	global_store_dword v139, v68, s[52:53]
	global_store_dword v139, v69, s[52:53] offset:128
	s_add_u32 s52, s52, 4096
	s_addc_u32 s53, s53, 0
	global_store_dword v139, v70, s[52:53]
	global_store_dword v139, v71, s[52:53] offset:128
	s_add_u32 s52, s52, 4096
	s_addc_u32 s53, s53, 0
	global_store_dword v139, v72, s[52:53]
	global_store_dword v139, v73, s[52:53] offset:128
	s_add_u32 s52, s52, 20480
	s_addc_u32 s53, s53, 0
	global_store_dword v139, v74, s[52:53]
	global_store_dword v139, v75, s[52:53] offset:128
	s_add_u32 s52, s52, 4096
	s_addc_u32 s53, s53, 0
	global_store_dword v139, v76, s[52:53]
	global_store_dword v139, v77, s[52:53] offset:128
	s_add_u32 s52, s52, 4096
	s_addc_u32 s53, s53, 0
	global_store_dword v139, v78, s[52:53]
	global_store_dword v139, v79, s[52:53] offset:128
	s_add_u32 s52, s52, 4096
	s_addc_u32 s53, s53, 0
	global_store_dword v139, v80, s[52:53]
	global_store_dword v139, v81, s[52:53] offset:128
	s_add_u32 s52, s52, 20480
	s_addc_u32 s53, s53, 0
	global_store_dword v139, v82, s[52:53]
	global_store_dword v139, v83, s[52:53] offset:128
	s_add_u32 s52, s52, 4096
	s_addc_u32 s53, s53, 0
	global_store_dword v139, v84, s[52:53]
	global_store_dword v139, v85, s[52:53] offset:128
	s_add_u32 s52, s52, 4096
	s_addc_u32 s53, s53, 0
	global_store_dword v139, v86, s[52:53]
	global_store_dword v139, v87, s[52:53] offset:128
	s_add_u32 s52, s52, 4096
	s_addc_u32 s53, s53, 0
	global_store_dword v139, v88, s[52:53]
	global_store_dword v139, v89, s[52:53] offset:128
	s_add_u32 s52, s52, 20480
	s_addc_u32 s53, s53, 0
	global_store_dword v139, v90, s[52:53]
	global_store_dword v139, v91, s[52:53] offset:128
	s_add_u32 s52, s52, 4096
	s_addc_u32 s53, s53, 0
	global_store_dword v139, v92, s[52:53]
	global_store_dword v139, v93, s[52:53] offset:128
	s_add_u32 s52, s52, 4096
	s_addc_u32 s53, s53, 0
	global_store_dword v139, v94, s[52:53]
	global_store_dword v139, v95, s[52:53] offset:128
	s_add_u32 s52, s52, 4096
	s_addc_u32 s53, s53, 0
	global_store_dword v139, v96, s[52:53]
	global_store_dword v139, v97, s[52:53] offset:128
	s_add_u32 s52, s52, 20480
	s_addc_u32 s53, s53, 0
	global_store_dword v139, v98, s[52:53]
	global_store_dword v139, v99, s[52:53] offset:128
	s_add_u32 s52, s52, 4096
	s_addc_u32 s53, s53, 0
	global_store_dword v139, v100, s[52:53]
	global_store_dword v139, v101, s[52:53] offset:128
	s_add_u32 s52, s52, 4096
	s_addc_u32 s53, s53, 0
	global_store_dword v139, v102, s[52:53]
	global_store_dword v139, v103, s[52:53] offset:128
	s_add_u32 s52, s52, 4096
	s_addc_u32 s53, s53, 0
	global_store_dword v139, v104, s[52:53]
	global_store_dword v139, v105, s[52:53] offset:128
	s_add_u32 s52, s52, 20480
	s_addc_u32 s53, s53, 0
	global_store_dword v139, v106, s[52:53]
	global_store_dword v139, v107, s[52:53] offset:128
	s_add_u32 s52, s52, 4096
	s_addc_u32 s53, s53, 0
	global_store_dword v139, v108, s[52:53]
	global_store_dword v139, v109, s[52:53] offset:128
	s_add_u32 s52, s52, 4096
	s_addc_u32 s53, s53, 0
	global_store_dword v139, v110, s[52:53]
	global_store_dword v139, v111, s[52:53] offset:128
	s_add_u32 s52, s52, 4096
	s_addc_u32 s53, s53, 0
	global_store_dword v139, v112, s[52:53]
	global_store_dword v139, v113, s[52:53] offset:128
	s_add_u32 s52, s52, 20480
	s_addc_u32 s53, s53, 0
	global_store_dword v139, v114, s[52:53]
	global_store_dword v139, v115, s[52:53] offset:128
	s_add_u32 s52, s52, 4096
	s_addc_u32 s53, s53, 0
	global_store_dword v139, v116, s[52:53]
	global_store_dword v139, v117, s[52:53] offset:128
	s_add_u32 s52, s52, 4096
	s_addc_u32 s53, s53, 0
	global_store_dword v139, v118, s[52:53]
	global_store_dword v139, v119, s[52:53] offset:128
	s_add_u32 s52, s52, 4096
	s_addc_u32 s53, s53, 0
	global_store_dword v139, v120, s[52:53]
	global_store_dword v139, v121, s[52:53] offset:128
	s_add_u32 s52, s52, 20480
	s_addc_u32 s53, s53, 0
	global_store_dword v139, v122, s[52:53]
	global_store_dword v139, v123, s[52:53] offset:128
	s_add_u32 s52, s52, 4096
	s_addc_u32 s53, s53, 0
	global_store_dword v139, v124, s[52:53]
	global_store_dword v139, v134, s[52:53] offset:128
	s_add_u32 s52, s52, 4096
	s_addc_u32 s53, s53, 0
	global_store_dword v139, v135, s[52:53]
	global_store_dword v139, v136, s[52:53] offset:128
	s_add_u32 s52, s52, 4096
	s_addc_u32 s53, s53, 0
	global_store_dword v139, v137, s[52:53]
	global_store_dword v139, v138, s[52:53] offset:128
	s_add_i32 s34, s34, s57
	s_add_i32 s29, s29, s64
	s_cmpk_lt_u32 s34, 0x400
	s_cbranch_scc1 .LBB0_1099
	v_readlane_b32 s28, v243, 45
	v_readlane_b32 s34, v243, 47
	v_readlane_b32 s29, v243, 46
	v_readlane_b32 s35, v243, 48

; #define TIDX opaque_tid()
; #define GAS __attribute__((address_space(1)))
; DI int opaque0() { int z = 0; asm volatile("" : "+v"(z)); return z; }
; DI void gemm_stage_w(const u16* __restrict__ A, int lda, const u16* __restrict__ B, int ldb, char* buf, int tid) {
; #pragma unroll
;   for (int i = 0; i < 2; ++i) {
;     const int S = tid + NTHR * i, row = S >> 2, c = (S & 3) ^ ((row >> 2) & 3);
;     __builtin_amdgcn_global_load_lds((const unsigned*)(A + (size_t)row * lda + c * 8), (__attribute__((address_space(3))) unsigned*)(buf + S * 16), 16, 0, 0);
;   }
; #pragma unroll
;   for (int i = 0; i < 4; ++i) {
;     const int S = tid + NTHR * i, row = S >> 2, c = (S & 3) ^ ((row >> 2) & 3);
;     __builtin_amdgcn_global_load_lds((const unsigned*)(B + (size_t)row * ldb + c * 8), (__attribute__((address_space(3))) unsigned*)(buf + 8192 + S * 16), 16, 0, 0);
;   }
; }
; DI void gemm_tile_w(const u16* __restrict__ A, int lda, const u16* __restrict__ B, int ldb, int nk, bool swap,
;                     f32x16 (&acc)[2][4], char* lds) {
;   const int tid = TIDX, lane = tid & 63, wid = tid >> 6;
;   gemm_stage_w(A, lda, B, ldb, lds, tid);
;   asm volatile("s_waitcnt vmcnt(0)" ::: "memory");
;   __syncthreads();
;   const int r = lane & 31, h = lane >> 5, sw = (r >> 2) & 3;
;   const int wa = swap ? wid : (wid >> 1), wb = swap ? 0 : (wid & 1);
;   const int offF = (swap ? 8192 : 0) + (wa * 64 + r) * 64;
;   const int offS = (swap ? 0 : 8192) + (wb * 128 + r) * 64;
; template <int AI>
; DI void gu_tile(char* wsb, int sub, int m0, int n0, char* lds) {
;   const u16* H = (const u16*)(wsb + OFF_H);
;   const u16* W = (const u16*)(wsb + OFF_W) + (sub ? W_GU1 : W_GU0);
;   u16* HID = (u16*)(wsb + OFF_HID);
;   const int lane = TIDX & 63, wid = TIDX >> 6, wa = wid >> 1, wb = wid & 1, r = lane & 31, h = lane >> 5;
;   f32x16 acc[AI][2]; zero_acc<AI, 2>(acc);
;   gemm_tile<AI, 2>(H + (size_t)m0 * 1024, 1024, W + (size_t)n0 * 1024, 1024, 16, false, acc, lds);
;   const int m0e = m0 + opaque0();
;   const int hc = (n0 >> 1) + wb * 32 + r;
;   GAS u16* HIDu = uptr(HID);
;   const unsigned ib = (unsigned)((m0e + wa * 32 * AI + 4 * h) * 2816 + hc);
.LBB0_1204:
	s_or_b64 exec, exec, s[6:7]
	s_mov_b32 s6, s19
	s_mov_b64 s[8:9], s[20:21]
	s_waitcnt lgkmcnt(0)
	s_barrier
	s_mov_b64 s[14:15], s[26:27]
	s_add_u32 s8, s14, s6
	v_readlane_b32 s6, v242, 3
	v_readlane_b32 s7, v242, 4
	s_addc_u32 s9, s15, 0
	s_and_b64 vcc, exec, s[6:7]
	s_mov_b64 s[10:11], s[22:23]
	s_mov_b64 s[12:13], s[24:25]
	s_cbranch_vccnz .LBB0_1208
	s_add_u32 s10, s8, 0x77b7000
	s_addc_u32 s11, s9, 0
	s_add_u32 s12, s8, 0x1d537000
	s_addc_u32 s13, s9, 0
	s_add_u32 s6, s8, 0x9bb7000
	s_addc_u32 s7, s9, 0
	v_readlane_b32 s14, v243, 18
	v_readlane_b32 s15, v243, 5
	v_readlane_b32 s53, v243, 6
	v_readlane_b32 s56, v243, 7
	s_mov_b32 s57, 0x1ffffc0
	s_movk_i32 s64, 0xb00
	s_mov_b64 s[66:67], 0x200
	s_mov_b64 s[68:69], 0x80
	s_mov_b64 s[70:71], 0x180
	s_mov_b64 s[72:73], 0x280
	s_mov_b64 s[74:75], 0x300
	s_mov_b64 s[76:77], 0x380
	s_mov_b64 s[80:81], 0x400
	s_mov_b64 s[82:83], 0x480
	s_mov_b64 s[84:85], 0x500
	s_mov_b64 s[88:89], 0x580
	s_mov_b64 vcc, 0x600
	s_waitcnt vmcnt(0)
	s_cmpk_lg_u32 s92, 0x200
	s_cbranch_scc1 .LBB0_1206
	v_and_b32_e32 v0, 31, v178
	v_bfe_u32 v122, v178, 5, 1
	v_bfe_u32 v123, v178, 2, 2
	v_xor_b32_e32 v122, v122, v123
	v_lshlrev_b32_e32 v122, 4, v122
	v_bfe_u32 v123, v178, 7, 1
	v_lshl_add_u32 v123, v123, 6, v0
	v_lshl_add_u32 v142, v123, 6, v122
	v_xor_b32_e32 v143, 32, v142
	v_bfe_u32 v123, v178, 6, 1
	v_lshl_add_u32 v123, v123, 6, v0
	v_lshl_add_u32 v144, v123, 6, v122
	v_add_u32_e32 v144, 0xc000, v144
	v_xor_b32_e32 v145, 32, v144
	v_bfe_u32 v122, v178, 7, 1
	v_lshlrev_b32_e32 v122, 6, v122
	v_bfe_u32 v123, v178, 5, 1
	v_lshl_add_u32 v122, v123, 2, v122
	v_mul_u32_u24_e32 v122, 0xb00, v122
	v_bfe_u32 v123, v178, 6, 1
	v_lshl_add_u32 v123, v123, 5, v0
	v_add_u32_e32 v122, v122, v123
	v_lshlrev_b32_e32 v124, 1, v122
	v_lshrrev_b32_e32 v0, 2, v178
	v_bfe_u32 v122, v178, 4, 2
	v_and_b32_e32 v123, 3, v178
	v_xor_b32_e32 v122, v122, v123
	v_lshlrev_b32_e32 v122, 4, v122
	v_lshl_add_u32 v126, v0, 11, v122
	v_add_u32_e32 v127, 0x20000, v126
	v_add_u32_e32 v128, 0x40000, v126
	v_add_u32_e32 v129, 0x60000, v126
	v_lshrrev_b32_e32 v0, 6, v178
	s_nop 1
	v_readfirstlane_b32 s18, v0
	s_lshl_b32 s18, s18, 10
	s_and_b32 s41, s96, 7
	s_lshr_b32 s40, s96, 3
	s_mov_b32 s32, 0

; #define TIDX opaque_tid()
; template <int AI, int BI>
; DI void gemm_tile(const u16* __restrict__ A, int lda, const u16* __restrict__ B, int ldb, int nk, bool swap,
;                   f32x16 (&acc)[AI][BI], char* lds) {
;   const int tid = TIDX, lane = tid & 63, wid = tid >> 6;
;   gemm_stage<AI, BI>(A, lda, B, ldb, lds, tid);
;   asm volatile("s_waitcnt vmcnt(0)" ::: "memory");
;   __syncthreads();
;   const int wa = wid >> 1, wb = wid & 1, r = lane & 31, h = lane >> 5, sw = (r >> 1) & 7;
;   const int offA = (swap ? 16384 : 0) + (wa * 32 * AI + r) * 128;
;   const int offB = (swap ? 0 : 16384) + (wb * 32 * BI + r) * 128;
;   for (int kt = 0; kt < nk; ++kt) {
;     const char* cur = lds + (kt & 1) * 32768;
;     if (kt + 1 < nk) gemm_stage<AI, BI>(A + (kt + 1) * 64, lda, B + (kt + 1) * 64, ldb, lds + ((kt + 1) & 1) * 32768, tid);
; #pragma unroll
;     for (int ks = 0; ks < 4; ++ks) {
;       const int co = ((ks * 2 + h) ^ sw) << 4;
;       s16x8 fa[AI], fb[BI];
; #pragma unroll
;       for (int i = 0; i < AI; ++i) fa[i] = *(const s16x8*)(cur + offA + i * 4096 + co);
; #pragma unroll
;       for (int i = 0; i < BI; ++i) fb[i] = *(const s16x8*)(cur + offB + i * 4096 + co);
; template <int AI>
; DI void gu_tile(char* wsb, int sub, int m0, int n0, char* lds) {
;   const u16* H = (const u16*)(wsb + OFF_H);
;   const u16* W = (const u16*)(wsb + OFF_W) + (sub ? W_GU1 : W_GU0);
;   u16* HID = (u16*)(wsb + OFF_HID);
;   const int lane = TIDX & 63, wid = TIDX >> 6, wa = wid >> 1, wb = wid & 1, r = lane & 31, h = lane >> 5;
;   f32x16 acc[AI][2]; zero_acc<AI, 2>(acc);
;   gemm_tile<AI, 2>(H + (size_t)m0 * 1024, 1024, W + (size_t)n0 * 1024, 1024, 16, false, acc, lds);
.LBB0_1206:
	s_and_b32 s16, s14, 0xffff
	s_mul_hi_u32 s17, s16, 0xba2e8c
	s_mul_i32 s16, s16, 0xba2f
	s_mulk_i32 s17, 0x160
	s_lshr_b32 s16, s16, 24
	s_sub_i32 s17, s14, s17
	s_lshl_b32 s16, s16, 10
	s_and_b32 s18, s15, 0x380
	s_ashr_i32 s17, s17, 3
	s_or_b32 s16, s16, s18
	s_lshl_b32 s28, s17, 7
	v_mov_b32_e32 v82, v178
	v_mov_b32_e32 v83, v178
	s_lshl_b32 s18, s16, 11
	v_mov_b32_e32 v12, v178
	s_add_u32 s34, s10, s18
	s_addc_u32 s35, s11, 0
	v_lshrrev_b32_e32 v0, 4, v12
	s_ashr_i32 s29, s28, 31
	v_xor_b32_e32 v0, v0, v12
	v_add_u32_e32 v8, 0x100, v12
	v_add_u32_e32 v10, 0x200, v12
	v_add_u32_e32 v13, 0x300, v12
	s_lshl_b64 s[28:29], s[28:29], 11
	v_lshlrev_b32_e32 v0, 4, v0
	v_ashrrev_i32_e32 v4, 3, v12
	v_ashrrev_i32_e32 v6, 3, v8
	v_lshlrev_b32_e32 v99, 4, v8
	v_ashrrev_i32_e32 v8, 3, v10
	v_lshlrev_b32_e32 v100, 4, v10
	v_ashrrev_i32_e32 v10, 3, v13
	s_add_u32 s28, s12, s28
	v_and_b32_e32 v0, 0x70, v0
	v_ashrrev_i32_e32 v5, 31, v4
	v_ashrrev_i32_e32 v7, 31, v6
	v_ashrrev_i32_e32 v9, 31, v8
	v_ashrrev_i32_e32 v11, 31, v10
	s_addc_u32 s29, s13, s29
	v_lshl_add_u64 v[2:3], s[34:35], 0, v[0:1]
	v_lshlrev_b64 v[4:5], 11, v[4:5]
	v_lshlrev_b32_e32 v96, 4, v12
	v_lshlrev_b64 v[6:7], 11, v[6:7]
	v_lshlrev_b64 v[8:9], 11, v[8:9]
	v_lshlrev_b64 v[10:11], 11, v[10:11]
	v_lshl_add_u64 v[66:67], v[2:3], 0, v[4:5]
	v_lshl_add_u64 v[68:69], v[2:3], 0, v[6:7]
	v_lshl_add_u64 v[70:71], v[2:3], 0, v[8:9]
	v_lshl_add_u64 v[72:73], v[2:3], 0, v[10:11]
	v_lshl_add_u64 v[2:3], s[28:29], 0, v[0:1]
	v_add_u32_e32 v0, 0x4000, v96
	v_readfirstlane_b32 s37, v96
	v_readfirstlane_b32 s28, v0
	v_add_u32_e32 v0, 0x4000, v99
	s_mov_b32 m0, s37
	v_readfirstlane_b32 s48, v99
	v_lshlrev_b32_e32 v101, 4, v13
	v_readfirstlane_b32 s29, v0
	v_add_u32_e32 v0, 0x4000, v100
	global_load_lds_dwordx4 v[66:67], off
	s_mov_b32 m0, s48
	v_readfirstlane_b32 s51, v100
	v_readfirstlane_b32 s34, v0
	v_add_u32_e32 v0, 0x4000, v101
	global_load_lds_dwordx4 v[68:69], off
	s_mov_b32 m0, s51
	v_readfirstlane_b32 s52, v101
	v_lshl_add_u64 v[74:75], v[2:3], 0, v[4:5]
	v_readfirstlane_b32 s35, v0
	v_and_b32_e32 v0, 31, v12
	v_lshrrev_b32_e32 v4, 1, v12
	global_load_lds_dwordx4 v[70:71], off
	s_mov_b32 m0, s52
	v_and_or_b32 v0, v4, s57, v0
	global_load_lds_dwordx4 v[72:73], off
	s_mov_b32 m0, s28
	v_lshl_add_u64 v[76:77], v[2:3], 0, v[6:7]
	v_lshl_add_u64 v[78:79], v[2:3], 0, v[8:9]
	v_lshl_add_u64 v[80:81], v[2:3], 0, v[10:11]
	v_lshrrev_b32_e32 v2, 5, v12
	v_bfe_u32 v5, v12, 1, 3
	v_lshlrev_b32_e32 v85, 7, v0
	v_lshlrev_b32_e32 v0, 7, v12
	global_load_lds_dwordx4 v[74:75], off
	s_mov_b32 m0, s29
	v_bfe_u32 v3, v12, 5, 1
	v_and_b32_e32 v87, 0x2f80, v0
	v_bitop3_b32 v0, v2, v5, 1 bitop3:0x6c
	global_load_lds_dwordx4 v[76:77], off
	s_mov_b32 m0, s34
	v_lshlrev_b32_e32 v6, 4, v0
	v_bitop3_b32 v0, v3, v5, 2 bitop3:0x36
	v_add_u32_e32 v91, 0x8000, v96
	global_load_lds_dwordx4 v[78:79], off
	s_mov_b32 m0, s35
	v_lshlrev_b32_e32 v84, 4, v0
	v_bitop3_b32 v0, v3, v5, 4 bitop3:0x36
	v_readfirstlane_b32 s36, v91
	v_add_u32_e32 v92, 0x8000, v99
	global_load_lds_dwordx4 v[80:81], off
	v_lshlrev_b32_e32 v118, 4, v0
	v_bitop3_b32 v0, v3, v5, 6 bitop3:0x36
	v_lshl_add_u64 v[2:3], v[66:67], 0, s[68:69]
	s_mov_b32 m0, s36
	v_readfirstlane_b32 s40, v92
	v_add_u32_e32 v93, 0x8000, v100
	s_waitcnt vmcnt(0)
	s_waitcnt vmcnt(0) lgkmcnt(0)
	s_barrier
	global_load_lds_dwordx4 v[2:3], off
	v_lshl_add_u64 v[2:3], v[68:69], 0, s[68:69]
	s_mov_b32 m0, s40
	v_readfirstlane_b32 s41, v93
	v_add_u32_e32 v94, 0x8000, v101
	global_load_lds_dwordx4 v[2:3], off
	v_lshl_add_u64 v[2:3], v[70:71], 0, s[68:69]
	s_mov_b32 m0, s41
	v_readfirstlane_b32 s46, v94
	v_add_u32_e32 v95, 0xc000, v96
	global_load_lds_dwordx4 v[2:3], off
	v_lshl_add_u64 v[2:3], v[72:73], 0, s[68:69]
	s_mov_b32 m0, s46
	v_readfirstlane_b32 s47, v95
	v_add_u32_e32 v97, 0xc000, v99
	global_load_lds_dwordx4 v[2:3], off
	v_lshl_add_u64 v[2:3], v[74:75], 0, s[68:69]
	s_mov_b32 m0, s47
	v_readfirstlane_b32 s49, v97
	v_add_u32_e32 v98, 0xc000, v100
	v_lshlrev_b32_e32 v119, 4, v0
	global_load_lds_dwordx4 v[2:3], off
	v_lshl_add_u64 v[2:3], v[76:77], 0, s[68:69]
	s_mov_b32 m0, s49
	v_readfirstlane_b32 s50, v98
	v_add_u32_e32 v0, 0xc000, v101
	global_load_lds_dwordx4 v[2:3], off
	v_lshl_add_u64 v[2:3], v[78:79], 0, s[68:69]
	s_mov_b32 m0, s50
	v_readfirstlane_b32 s18, v0
	global_load_lds_dwordx4 v[2:3], off
	v_lshl_add_u64 v[2:3], v[80:81], 0, s[68:69]
	s_mov_b32 m0, s18
	v_or_b32_e32 v0, v85, v6
	global_load_lds_dwordx4 v[2:3], off
	v_or_b32_e32 v86, v87, v6
	ds_read_b128 v[2:5], v0
	ds_read_b128 v[18:21], v0 offset:4096
	ds_read_b128 v[6:9], v86 offset:16384
	ds_read_b128 v[22:25], v86 offset:20480
	s_waitcnt lgkmcnt(0)
	v_mfma_f32_32x32x16_bf16 v[34:49], v[2:5], v[6:9], 0
	v_or_b32_e32 v88, v85, v84
	v_or_b32_e32 v89, v87, v84
	ds_read_b128 v[102:105], v88
	ds_read_b128 v[106:109], v88 offset:4096
	ds_read_b128 v[110:113], v89 offset:16384
	ds_read_b128 v[114:117], v89 offset:20480
	v_or_b32_e32 v90, v85, v118
	v_or_b32_e32 v84, v87, v118
	v_or_b32_e32 v85, v85, v119
	v_mfma_f32_32x32x16_bf16 v[50:65], v[2:5], v[22:25], 0
	v_or_b32_e32 v87, v87, v119
	s_mov_b32 m0, s37
	s_lshl_b32 s17, s17, 6
	v_mfma_f32_32x32x16_bf16 v[2:17], v[18:21], v[6:9], 0
	v_mfma_f32_32x32x16_bf16 v[18:33], v[18:21], v[22:25], 0
	s_waitcnt lgkmcnt(1)
	v_mfma_f32_32x32x16_bf16 v[34:49], v[102:105], v[110:113], v[34:49]
	s_waitcnt lgkmcnt(0)
	v_mfma_f32_32x32x16_bf16 v[50:65], v[102:105], v[114:117], v[50:65]
	v_mfma_f32_32x32x16_bf16 v[2:17], v[106:109], v[110:113], v[2:17]
	v_mfma_f32_32x32x16_bf16 v[18:33], v[106:109], v[114:117], v[18:33]
	ds_read_b128 v[102:105], v90
	ds_read_b128 v[106:109], v90 offset:4096
	ds_read_b128 v[110:113], v84 offset:16384
	ds_read_b128 v[114:117], v84 offset:20480
	s_waitcnt lgkmcnt(1)
	v_mfma_f32_32x32x16_bf16 v[34:49], v[102:105], v[110:113], v[34:49]
	s_waitcnt lgkmcnt(0)
	v_mfma_f32_32x32x16_bf16 v[50:65], v[102:105], v[114:117], v[50:65]
	v_mfma_f32_32x32x16_bf16 v[2:17], v[106:109], v[110:113], v[2:17]
	v_mfma_f32_32x32x16_bf16 v[18:33], v[106:109], v[114:117], v[18:33]
	ds_read_b128 v[102:105], v85
	ds_read_b128 v[106:109], v85 offset:4096
	ds_read_b128 v[110:113], v87 offset:16384
	ds_read_b128 v[114:117], v87 offset:20480
	s_waitcnt vmcnt(0)
	s_waitcnt lgkmcnt(0)
	s_barrier
; #define MFMA(a, b, c) __builtin_amdgcn_mfma_f32_32x32x16_bf16((a), (b), (c), 0, 0, 0)
; template <int AI, int BI>
; DI void gemm_tile(const u16* __restrict__ A, int lda, const u16* __restrict__ B, int ldb, int nk, bool swap,
;                   f32x16 (&acc)[AI][BI], char* lds) {
;     ...
;   for (int kt = 0; kt < nk; ++kt) {
;     const char* cur = lds + (kt & 1) * 32768;
;     if (kt + 1 < nk) gemm_stage<AI, BI>(A + (kt + 1) * 64, lda, B + (kt + 1) * 64, ldb, lds + ((kt + 1) & 1) * 32768, tid);
; #pragma unroll
;     for (int ks = 0; ks < 4; ++ks) {
;       const int co = ((ks * 2 + h) ^ sw) << 4;
;       s16x8 fa[AI], fb[BI];
; #pragma unroll
;       for (int i = 0; i < AI; ++i) fa[i] = *(const s16x8*)(cur + offA + i * 4096 + co);
; #pragma unroll
;       for (int i = 0; i < BI; ++i) fb[i] = *(const s16x8*)(cur + offB + i * 4096 + co);
; #pragma unroll
;       for (int i = 0; i < AI; ++i)
; #pragma unroll
;         for (int j = 0; j < BI; ++j) acc[i][j] = MFMA(fa[i], fb[j], acc[i][j]);
;     }
;     asm volatile("s_waitcnt vmcnt(0)" ::: "memory");
;     __syncthreads();
;   }
	v_mfma_f32_32x32x16_bf16 v[34:49], v[102:105], v[110:113], v[34:49]
	v_mfma_f32_32x32x16_bf16 v[50:65], v[102:105], v[114:117], v[50:65]
	v_lshl_add_u64 v[102:103], v[66:67], 0, s[4:5]
	global_load_lds_dwordx4 v[102:103], off
	v_lshl_add_u64 v[102:103], v[68:69], 0, s[4:5]
	s_mov_b32 m0, s48
	s_nop 0
	global_load_lds_dwordx4 v[102:103], off
	v_lshl_add_u64 v[102:103], v[70:71], 0, s[4:5]
	s_mov_b32 m0, s51
	v_mfma_f32_32x32x16_bf16 v[2:17], v[106:109], v[110:113], v[2:17]
	global_load_lds_dwordx4 v[102:103], off
	v_lshl_add_u64 v[102:103], v[72:73], 0, s[4:5]
	s_mov_b32 m0, s52
	s_nop 0
	global_load_lds_dwordx4 v[102:103], off
	v_lshl_add_u64 v[102:103], v[74:75], 0, s[4:5]
	s_mov_b32 m0, s28
	v_mfma_f32_32x32x16_bf16 v[18:33], v[106:109], v[114:117], v[18:33]
	global_load_lds_dwordx4 v[102:103], off
	v_lshl_add_u64 v[102:103], v[76:77], 0, s[4:5]
	s_mov_b32 m0, s29
	s_nop 0
	global_load_lds_dwordx4 v[102:103], off
	v_lshl_add_u64 v[102:103], v[78:79], 0, s[4:5]
	s_mov_b32 m0, s34
	s_nop 0
	global_load_lds_dwordx4 v[102:103], off
	v_lshl_add_u64 v[102:103], v[80:81], 0, s[4:5]
	s_mov_b32 m0, s35
	s_nop 0
	global_load_lds_dwordx4 v[102:103], off
	ds_read_b128 v[102:105], v0 offset:32768
	ds_read_b128 v[106:109], v0 offset:36864
	ds_read_b128 v[110:113], v86 offset:49152
	ds_read_b128 v[114:117], v86 offset:53248
	s_waitcnt lgkmcnt(0)
	v_mfma_f32_32x32x16_bf16 v[34:49], v[102:105], v[110:113], v[34:49]
	s_mov_b32 m0, s36
	v_mfma_f32_32x32x16_bf16 v[50:65], v[102:105], v[114:117], v[50:65]
	v_mfma_f32_32x32x16_bf16 v[2:17], v[106:109], v[110:113], v[2:17]
	v_mfma_f32_32x32x16_bf16 v[18:33], v[106:109], v[114:117], v[18:33]
	ds_read_b128 v[102:105], v88 offset:32768
	ds_read_b128 v[106:109], v88 offset:36864
	ds_read_b128 v[110:113], v89 offset:49152
	ds_read_b128 v[114:117], v89 offset:53248
	s_waitcnt lgkmcnt(1)
	v_mfma_f32_32x32x16_bf16 v[34:49], v[102:105], v[110:113], v[34:49]
	s_waitcnt lgkmcnt(0)
	v_mfma_f32_32x32x16_bf16 v[50:65], v[102:105], v[114:117], v[50:65]
	v_mfma_f32_32x32x16_bf16 v[2:17], v[106:109], v[110:113], v[2:17]
	v_mfma_f32_32x32x16_bf16 v[18:33], v[106:109], v[114:117], v[18:33]
	ds_read_b128 v[102:105], v90 offset:32768
	ds_read_b128 v[106:109], v90 offset:36864
	ds_read_b128 v[110:113], v84 offset:49152
	ds_read_b128 v[114:117], v84 offset:53248
	s_waitcnt lgkmcnt(1)
	v_mfma_f32_32x32x16_bf16 v[34:49], v[102:105], v[110:113], v[34:49]
	s_waitcnt lgkmcnt(0)
	v_mfma_f32_32x32x16_bf16 v[50:65], v[102:105], v[114:117], v[50:65]
	v_mfma_f32_32x32x16_bf16 v[2:17], v[106:109], v[110:113], v[2:17]
	v_mfma_f32_32x32x16_bf16 v[18:33], v[106:109], v[114:117], v[18:33]
	ds_read_b128 v[102:105], v85 offset:32768
	ds_read_b128 v[106:109], v85 offset:36864
	ds_read_b128 v[110:113], v87 offset:49152
	ds_read_b128 v[114:117], v87 offset:53248
	s_waitcnt vmcnt(0)
	s_waitcnt lgkmcnt(0)
	s_barrier
	v_mfma_f32_32x32x16_bf16 v[34:49], v[102:105], v[110:113], v[34:49]
	v_mfma_f32_32x32x16_bf16 v[50:65], v[102:105], v[114:117], v[50:65]
	v_lshl_add_u64 v[102:103], v[66:67], 0, s[70:71]
	global_load_lds_dwordx4 v[102:103], off
	v_lshl_add_u64 v[102:103], v[68:69], 0, s[70:71]
	s_mov_b32 m0, s40
	s_nop 0
	global_load_lds_dwordx4 v[102:103], off
	v_lshl_add_u64 v[102:103], v[70:71], 0, s[70:71]
	s_mov_b32 m0, s41
	v_mfma_f32_32x32x16_bf16 v[2:17], v[106:109], v[110:113], v[2:17]
	global_load_lds_dwordx4 v[102:103], off
	v_lshl_add_u64 v[102:103], v[72:73], 0, s[70:71]
	s_mov_b32 m0, s46
	s_nop 0
	global_load_lds_dwordx4 v[102:103], off
	v_lshl_add_u64 v[102:103], v[74:75], 0, s[70:71]
	s_mov_b32 m0, s47
	v_mfma_f32_32x32x16_bf16 v[18:33], v[106:109], v[114:117], v[18:33]
	global_load_lds_dwordx4 v[102:103], off
	v_lshl_add_u64 v[102:103], v[76:77], 0, s[70:71]
	s_mov_b32 m0, s49
	s_nop 0
	global_load_lds_dwordx4 v[102:103], off
	v_lshl_add_u64 v[102:103], v[78:79], 0, s[70:71]
	s_mov_b32 m0, s50
	s_nop 0
	global_load_lds_dwordx4 v[102:103], off
	v_lshl_add_u64 v[102:103], v[80:81], 0, s[70:71]
	s_mov_b32 m0, s18
	s_nop 0
	global_load_lds_dwordx4 v[102:103], off
	ds_read_b128 v[102:105], v0
	ds_read_b128 v[106:109], v0 offset:4096
	ds_read_b128 v[110:113], v86 offset:16384
	ds_read_b128 v[114:117], v86 offset:20480
	s_waitcnt lgkmcnt(0)
	v_mfma_f32_32x32x16_bf16 v[34:49], v[102:105], v[110:113], v[34:49]
	s_mov_b32 m0, s37
	v_mfma_f32_32x32x16_bf16 v[50:65], v[102:105], v[114:117], v[50:65]
	v_mfma_f32_32x32x16_bf16 v[2:17], v[106:109], v[110:113], v[2:17]
	v_mfma_f32_32x32x16_bf16 v[18:33], v[106:109], v[114:117], v[18:33]
	ds_read_b128 v[102:105], v88
	ds_read_b128 v[106:109], v88 offset:4096
	ds_read_b128 v[110:113], v89 offset:16384
	ds_read_b128 v[114:117], v89 offset:20480
	s_waitcnt lgkmcnt(1)
	v_mfma_f32_32x32x16_bf16 v[34:49], v[102:105], v[110:113], v[34:49]
	s_waitcnt lgkmcnt(0)
	v_mfma_f32_32x32x16_bf16 v[50:65], v[102:105], v[114:117], v[50:65]
	v_mfma_f32_32x32x16_bf16 v[2:17], v[106:109], v[110:113], v[2:17]
	v_mfma_f32_32x32x16_bf16 v[18:33], v[106:109], v[114:117], v[18:33]
	ds_read_b128 v[102:105], v90
	ds_read_b128 v[106:109], v90 offset:4096
	ds_read_b128 v[110:113], v84 offset:16384
	ds_read_b128 v[114:117], v84 offset:20480
	s_waitcnt lgkmcnt(1)
	v_mfma_f32_32x32x16_bf16 v[34:49], v[102:105], v[110:113], v[34:49]
	s_waitcnt lgkmcnt(0)
	v_mfma_f32_32x32x16_bf16 v[50:65], v[102:105], v[114:117], v[50:65]
	v_mfma_f32_32x32x16_bf16 v[2:17], v[106:109], v[110:113], v[2:17]
	v_mfma_f32_32x32x16_bf16 v[18:33], v[106:109], v[114:117], v[18:33]
	ds_read_b128 v[102:105], v85
	ds_read_b128 v[106:109], v85 offset:4096
	ds_read_b128 v[110:113], v87 offset:16384
	ds_read_b128 v[114:117], v87 offset:20480
	s_waitcnt vmcnt(0)
	s_waitcnt lgkmcnt(0)
	s_barrier
; #define MFMA(a, b, c) __builtin_amdgcn_mfma_f32_32x32x16_bf16((a), (b), (c), 0, 0, 0)
; template <int AI, int BI>
; DI void gemm_tile(const u16* __restrict__ A, int lda, const u16* __restrict__ B, int ldb, int nk, bool swap,
;                   f32x16 (&acc)[AI][BI], char* lds) {
;     ...
;   for (int kt = 0; kt < nk; ++kt) {
;     const char* cur = lds + (kt & 1) * 32768;
;     if (kt + 1 < nk) gemm_stage<AI, BI>(A + (kt + 1) * 64, lda, B + (kt + 1) * 64, ldb, lds + ((kt + 1) & 1) * 32768, tid);
; #pragma unroll
;     for (int ks = 0; ks < 4; ++ks) {
;       const int co = ((ks * 2 + h) ^ sw) << 4;
;       s16x8 fa[AI], fb[BI];
; #pragma unroll
;       for (int i = 0; i < AI; ++i) fa[i] = *(const s16x8*)(cur + offA + i * 4096 + co);
; #pragma unroll
;       for (int i = 0; i < BI; ++i) fb[i] = *(const s16x8*)(cur + offB + i * 4096 + co);
; #pragma unroll
;       for (int i = 0; i < AI; ++i)
; #pragma unroll
;         for (int j = 0; j < BI; ++j) acc[i][j] = MFMA(fa[i], fb[j], acc[i][j]);
;     }
;     asm volatile("s_waitcnt vmcnt(0)" ::: "memory");
;     __syncthreads();
;   }
	v_mfma_f32_32x32x16_bf16 v[34:49], v[102:105], v[110:113], v[34:49]
	v_mfma_f32_32x32x16_bf16 v[50:65], v[102:105], v[114:117], v[50:65]
	v_lshl_add_u64 v[102:103], v[66:67], 0, s[66:67]
	global_load_lds_dwordx4 v[102:103], off
	v_lshl_add_u64 v[102:103], v[68:69], 0, s[66:67]
	s_mov_b32 m0, s48
	s_nop 0
	global_load_lds_dwordx4 v[102:103], off
	v_lshl_add_u64 v[102:103], v[70:71], 0, s[66:67]
	s_mov_b32 m0, s51
	v_mfma_f32_32x32x16_bf16 v[2:17], v[106:109], v[110:113], v[2:17]
	global_load_lds_dwordx4 v[102:103], off
	v_lshl_add_u64 v[102:103], v[72:73], 0, s[66:67]
	s_mov_b32 m0, s52
	s_nop 0
	global_load_lds_dwordx4 v[102:103], off
	v_lshl_add_u64 v[102:103], v[74:75], 0, s[66:67]
	s_mov_b32 m0, s28
	v_mfma_f32_32x32x16_bf16 v[18:33], v[106:109], v[114:117], v[18:33]
	global_load_lds_dwordx4 v[102:103], off
	v_lshl_add_u64 v[102:103], v[76:77], 0, s[66:67]
	s_mov_b32 m0, s29
	s_nop 0
	global_load_lds_dwordx4 v[102:103], off
	v_lshl_add_u64 v[102:103], v[78:79], 0, s[66:67]
	s_mov_b32 m0, s34
	s_nop 0
	global_load_lds_dwordx4 v[102:103], off
	v_lshl_add_u64 v[102:103], v[80:81], 0, s[66:67]
	s_mov_b32 m0, s35
	s_nop 0
	global_load_lds_dwordx4 v[102:103], off
	ds_read_b128 v[102:105], v0 offset:32768
	ds_read_b128 v[106:109], v0 offset:36864
	ds_read_b128 v[110:113], v86 offset:49152
	ds_read_b128 v[114:117], v86 offset:53248
	s_waitcnt lgkmcnt(0)
	v_mfma_f32_32x32x16_bf16 v[34:49], v[102:105], v[110:113], v[34:49]
	s_mov_b32 m0, s36
	v_mfma_f32_32x32x16_bf16 v[50:65], v[102:105], v[114:117], v[50:65]
	v_mfma_f32_32x32x16_bf16 v[2:17], v[106:109], v[110:113], v[2:17]
	v_mfma_f32_32x32x16_bf16 v[18:33], v[106:109], v[114:117], v[18:33]
	ds_read_b128 v[102:105], v88 offset:32768
	ds_read_b128 v[106:109], v88 offset:36864
	ds_read_b128 v[110:113], v89 offset:49152
	ds_read_b128 v[114:117], v89 offset:53248
	s_waitcnt lgkmcnt(1)
	v_mfma_f32_32x32x16_bf16 v[34:49], v[102:105], v[110:113], v[34:49]
	s_waitcnt lgkmcnt(0)
	v_mfma_f32_32x32x16_bf16 v[50:65], v[102:105], v[114:117], v[50:65]
	v_mfma_f32_32x32x16_bf16 v[2:17], v[106:109], v[110:113], v[2:17]
	v_mfma_f32_32x32x16_bf16 v[18:33], v[106:109], v[114:117], v[18:33]
	ds_read_b128 v[102:105], v90 offset:32768
	ds_read_b128 v[106:109], v90 offset:36864
	ds_read_b128 v[110:113], v84 offset:49152
	ds_read_b128 v[114:117], v84 offset:53248
	s_waitcnt lgkmcnt(1)
	v_mfma_f32_32x32x16_bf16 v[34:49], v[102:105], v[110:113], v[34:49]
	s_waitcnt lgkmcnt(0)
	v_mfma_f32_32x32x16_bf16 v[50:65], v[102:105], v[114:117], v[50:65]
	v_mfma_f32_32x32x16_bf16 v[2:17], v[106:109], v[110:113], v[2:17]
	v_mfma_f32_32x32x16_bf16 v[18:33], v[106:109], v[114:117], v[18:33]
	ds_read_b128 v[102:105], v85 offset:32768
	ds_read_b128 v[106:109], v85 offset:36864
	ds_read_b128 v[110:113], v87 offset:49152
	ds_read_b128 v[114:117], v87 offset:53248
	s_waitcnt vmcnt(0)
	s_waitcnt lgkmcnt(0)
	s_barrier
	v_mfma_f32_32x32x16_bf16 v[34:49], v[102:105], v[110:113], v[34:49]
	v_mfma_f32_32x32x16_bf16 v[50:65], v[102:105], v[114:117], v[50:65]
	v_lshl_add_u64 v[102:103], v[66:67], 0, s[72:73]
	global_load_lds_dwordx4 v[102:103], off
	v_lshl_add_u64 v[102:103], v[68:69], 0, s[72:73]
	s_mov_b32 m0, s40
	s_nop 0
	global_load_lds_dwordx4 v[102:103], off
	v_lshl_add_u64 v[102:103], v[70:71], 0, s[72:73]
	s_mov_b32 m0, s41
	v_mfma_f32_32x32x16_bf16 v[2:17], v[106:109], v[110:113], v[2:17]
	global_load_lds_dwordx4 v[102:103], off
	v_lshl_add_u64 v[102:103], v[72:73], 0, s[72:73]
	s_mov_b32 m0, s46
	s_nop 0
	global_load_lds_dwordx4 v[102:103], off
	v_lshl_add_u64 v[102:103], v[74:75], 0, s[72:73]
	s_mov_b32 m0, s47
	v_mfma_f32_32x32x16_bf16 v[18:33], v[106:109], v[114:117], v[18:33]
	global_load_lds_dwordx4 v[102:103], off
	v_lshl_add_u64 v[102:103], v[76:77], 0, s[72:73]
	s_mov_b32 m0, s49
	s_nop 0
	global_load_lds_dwordx4 v[102:103], off
	v_lshl_add_u64 v[102:103], v[78:79], 0, s[72:73]
	s_mov_b32 m0, s50
	s_nop 0
	global_load_lds_dwordx4 v[102:103], off
	v_lshl_add_u64 v[102:103], v[80:81], 0, s[72:73]
	s_mov_b32 m0, s18
	s_nop 0
	global_load_lds_dwordx4 v[102:103], off
	ds_read_b128 v[102:105], v0
	ds_read_b128 v[106:109], v0 offset:4096
	ds_read_b128 v[110:113], v86 offset:16384
	ds_read_b128 v[114:117], v86 offset:20480
	s_waitcnt lgkmcnt(0)
	v_mfma_f32_32x32x16_bf16 v[34:49], v[102:105], v[110:113], v[34:49]
	s_mov_b32 m0, s37
	v_readfirstlane_b32 s37, v99
	v_mfma_f32_32x32x16_bf16 v[50:65], v[102:105], v[114:117], v[50:65]
	v_mfma_f32_32x32x16_bf16 v[2:17], v[106:109], v[110:113], v[2:17]
	v_mfma_f32_32x32x16_bf16 v[18:33], v[106:109], v[114:117], v[18:33]
	ds_read_b128 v[102:105], v88
	ds_read_b128 v[106:109], v88 offset:4096
	ds_read_b128 v[110:113], v89 offset:16384
	ds_read_b128 v[114:117], v89 offset:20480
	s_waitcnt lgkmcnt(1)
	v_mfma_f32_32x32x16_bf16 v[34:49], v[102:105], v[110:113], v[34:49]
	s_waitcnt lgkmcnt(0)
	v_mfma_f32_32x32x16_bf16 v[50:65], v[102:105], v[114:117], v[50:65]
	v_mfma_f32_32x32x16_bf16 v[2:17], v[106:109], v[110:113], v[2:17]
	v_mfma_f32_32x32x16_bf16 v[18:33], v[106:109], v[114:117], v[18:33]
	ds_read_b128 v[102:105], v90
	ds_read_b128 v[106:109], v90 offset:4096
	ds_read_b128 v[110:113], v84 offset:16384
	ds_read_b128 v[114:117], v84 offset:20480
	s_waitcnt lgkmcnt(1)
	v_mfma_f32_32x32x16_bf16 v[34:49], v[102:105], v[110:113], v[34:49]
	s_waitcnt lgkmcnt(0)
	v_mfma_f32_32x32x16_bf16 v[50:65], v[102:105], v[114:117], v[50:65]
	v_mfma_f32_32x32x16_bf16 v[2:17], v[106:109], v[110:113], v[2:17]
	v_mfma_f32_32x32x16_bf16 v[18:33], v[106:109], v[114:117], v[18:33]
	ds_read_b128 v[102:105], v85
	ds_read_b128 v[106:109], v85 offset:4096
	ds_read_b128 v[110:113], v87 offset:16384
	ds_read_b128 v[114:117], v87 offset:20480
	s_waitcnt vmcnt(0)
	s_waitcnt lgkmcnt(0)
	s_barrier
; #define MFMA(a, b, c) __builtin_amdgcn_mfma_f32_32x32x16_bf16((a), (b), (c), 0, 0, 0)
; template <int AI, int BI>
; DI void gemm_tile(const u16* __restrict__ A, int lda, const u16* __restrict__ B, int ldb, int nk, bool swap,
;                   f32x16 (&acc)[AI][BI], char* lds) {
;     ...
;   for (int kt = 0; kt < nk; ++kt) {
;     const char* cur = lds + (kt & 1) * 32768;
;     if (kt + 1 < nk) gemm_stage<AI, BI>(A + (kt + 1) * 64, lda, B + (kt + 1) * 64, ldb, lds + ((kt + 1) & 1) * 32768, tid);
; #pragma unroll
;     for (int ks = 0; ks < 4; ++ks) {
;       const int co = ((ks * 2 + h) ^ sw) << 4;
;       s16x8 fa[AI], fb[BI];
; #pragma unroll
;       for (int i = 0; i < AI; ++i) fa[i] = *(const s16x8*)(cur + offA + i * 4096 + co);
; #pragma unroll
;       for (int i = 0; i < BI; ++i) fb[i] = *(const s16x8*)(cur + offB + i * 4096 + co);
; #pragma unroll
;       for (int i = 0; i < AI; ++i)
; #pragma unroll
;         for (int j = 0; j < BI; ++j) acc[i][j] = MFMA(fa[i], fb[j], acc[i][j]);
;     }
;     asm volatile("s_waitcnt vmcnt(0)" ::: "memory");
;     __syncthreads();
;   }
	v_mfma_f32_32x32x16_bf16 v[34:49], v[102:105], v[110:113], v[34:49]
	v_mfma_f32_32x32x16_bf16 v[50:65], v[102:105], v[114:117], v[50:65]
	v_lshl_add_u64 v[102:103], v[66:67], 0, s[74:75]
	global_load_lds_dwordx4 v[102:103], off
	v_lshl_add_u64 v[102:103], v[68:69], 0, s[74:75]
	s_mov_b32 m0, s48
	v_readfirstlane_b32 s48, v93
	global_load_lds_dwordx4 v[102:103], off
	v_lshl_add_u64 v[102:103], v[70:71], 0, s[74:75]
	s_mov_b32 m0, s51
	v_mfma_f32_32x32x16_bf16 v[2:17], v[106:109], v[110:113], v[2:17]
	global_load_lds_dwordx4 v[102:103], off
	v_lshl_add_u64 v[102:103], v[72:73], 0, s[74:75]
	s_mov_b32 m0, s52
	v_readfirstlane_b32 s51, v97
	global_load_lds_dwordx4 v[102:103], off
	v_lshl_add_u64 v[102:103], v[74:75], 0, s[74:75]
	s_mov_b32 m0, s28
	v_mfma_f32_32x32x16_bf16 v[18:33], v[106:109], v[114:117], v[18:33]
	global_load_lds_dwordx4 v[102:103], off
	v_lshl_add_u64 v[102:103], v[76:77], 0, s[74:75]
	s_mov_b32 m0, s29
	v_readfirstlane_b32 s52, v98
	global_load_lds_dwordx4 v[102:103], off
	v_lshl_add_u64 v[102:103], v[78:79], 0, s[74:75]
	s_mov_b32 m0, s34
	s_nop 0
	global_load_lds_dwordx4 v[102:103], off
	v_lshl_add_u64 v[102:103], v[80:81], 0, s[74:75]
	s_mov_b32 m0, s35
	s_nop 0
	global_load_lds_dwordx4 v[102:103], off
	ds_read_b128 v[102:105], v0 offset:32768
	ds_read_b128 v[106:109], v0 offset:36864
	ds_read_b128 v[110:113], v86 offset:49152
	ds_read_b128 v[114:117], v86 offset:53248
	s_waitcnt lgkmcnt(0)
	v_mfma_f32_32x32x16_bf16 v[34:49], v[102:105], v[110:113], v[34:49]
	s_mov_b32 m0, s36
	v_readfirstlane_b32 s36, v96
	v_mfma_f32_32x32x16_bf16 v[50:65], v[102:105], v[114:117], v[50:65]
	v_mfma_f32_32x32x16_bf16 v[2:17], v[106:109], v[110:113], v[2:17]
	v_mfma_f32_32x32x16_bf16 v[18:33], v[106:109], v[114:117], v[18:33]
	ds_read_b128 v[102:105], v88 offset:32768
	ds_read_b128 v[106:109], v88 offset:36864
	ds_read_b128 v[110:113], v89 offset:49152
	ds_read_b128 v[114:117], v89 offset:53248
	s_waitcnt lgkmcnt(1)
	v_mfma_f32_32x32x16_bf16 v[34:49], v[102:105], v[110:113], v[34:49]
	s_waitcnt lgkmcnt(0)
	v_mfma_f32_32x32x16_bf16 v[50:65], v[102:105], v[114:117], v[50:65]
	v_mfma_f32_32x32x16_bf16 v[2:17], v[106:109], v[110:113], v[2:17]
	v_mfma_f32_32x32x16_bf16 v[18:33], v[106:109], v[114:117], v[18:33]
	ds_read_b128 v[102:105], v90 offset:32768
	ds_read_b128 v[106:109], v90 offset:36864
	ds_read_b128 v[110:113], v84 offset:49152
	ds_read_b128 v[114:117], v84 offset:53248
	s_waitcnt lgkmcnt(1)
	v_mfma_f32_32x32x16_bf16 v[34:49], v[102:105], v[110:113], v[34:49]
	s_waitcnt lgkmcnt(0)
	v_mfma_f32_32x32x16_bf16 v[50:65], v[102:105], v[114:117], v[50:65]
	v_mfma_f32_32x32x16_bf16 v[2:17], v[106:109], v[110:113], v[2:17]
	v_mfma_f32_32x32x16_bf16 v[18:33], v[106:109], v[114:117], v[18:33]
	ds_read_b128 v[102:105], v85 offset:32768
	ds_read_b128 v[106:109], v85 offset:36864
	ds_read_b128 v[110:113], v87 offset:49152
	ds_read_b128 v[114:117], v87 offset:53248
	s_waitcnt vmcnt(0)
	s_waitcnt lgkmcnt(0)
	s_barrier
	v_mfma_f32_32x32x16_bf16 v[34:49], v[102:105], v[110:113], v[34:49]
	v_mfma_f32_32x32x16_bf16 v[50:65], v[102:105], v[114:117], v[50:65]
	v_lshl_add_u64 v[102:103], v[66:67], 0, s[76:77]
	global_load_lds_dwordx4 v[102:103], off
	v_lshl_add_u64 v[102:103], v[68:69], 0, s[76:77]
	s_mov_b32 m0, s40
	v_readfirstlane_b32 s40, v100
	global_load_lds_dwordx4 v[102:103], off
	v_lshl_add_u64 v[102:103], v[70:71], 0, s[76:77]
	s_mov_b32 m0, s41
	v_mfma_f32_32x32x16_bf16 v[2:17], v[106:109], v[110:113], v[2:17]
	global_load_lds_dwordx4 v[102:103], off
	v_lshl_add_u64 v[102:103], v[72:73], 0, s[76:77]
	s_mov_b32 m0, s46
	v_readfirstlane_b32 s41, v101
	global_load_lds_dwordx4 v[102:103], off
	v_lshl_add_u64 v[102:103], v[74:75], 0, s[76:77]
	s_mov_b32 m0, s47
	v_mfma_f32_32x32x16_bf16 v[18:33], v[106:109], v[114:117], v[18:33]
	global_load_lds_dwordx4 v[102:103], off
	v_lshl_add_u64 v[102:103], v[76:77], 0, s[76:77]
	s_mov_b32 m0, s49
	v_lshl_add_u64 v[100:101], v[74:75], 0, s[80:81]
	global_load_lds_dwordx4 v[102:103], off
	v_lshl_add_u64 v[102:103], v[78:79], 0, s[76:77]
	s_mov_b32 m0, s50
	v_readfirstlane_b32 s46, v91
	global_load_lds_dwordx4 v[102:103], off
	v_lshl_add_u64 v[102:103], v[80:81], 0, s[76:77]
	s_mov_b32 m0, s18
	v_readfirstlane_b32 s47, v92
	global_load_lds_dwordx4 v[102:103], off
	ds_read_b128 v[102:105], v0
	ds_read_b128 v[106:109], v0 offset:4096
	ds_read_b128 v[110:113], v86 offset:16384
	ds_read_b128 v[114:117], v86 offset:20480
	s_waitcnt lgkmcnt(0)
	v_mfma_f32_32x32x16_bf16 v[34:49], v[102:105], v[110:113], v[34:49]
	s_mov_b32 m0, s36
	v_readfirstlane_b32 s49, v94
	v_lshl_add_u64 v[92:93], v[72:73], 0, s[82:83]
	v_readfirstlane_b32 s50, v95
	v_and_b32_e32 v91, 31, v82
	v_mfma_f32_32x32x16_bf16 v[50:65], v[102:105], v[114:117], v[50:65]
	v_mfma_f32_32x32x16_bf16 v[2:17], v[106:109], v[110:113], v[2:17]
	v_mfma_f32_32x32x16_bf16 v[18:33], v[106:109], v[114:117], v[18:33]
	ds_read_b128 v[102:105], v88
	ds_read_b128 v[106:109], v88 offset:4096
	ds_read_b128 v[110:113], v89 offset:16384
	ds_read_b128 v[114:117], v89 offset:20480
	s_waitcnt lgkmcnt(1)
	v_mfma_f32_32x32x16_bf16 v[34:49], v[102:105], v[110:113], v[34:49]
	s_waitcnt lgkmcnt(0)
	v_mfma_f32_32x32x16_bf16 v[50:65], v[102:105], v[114:117], v[50:65]
	v_mfma_f32_32x32x16_bf16 v[2:17], v[106:109], v[110:113], v[2:17]
	v_mfma_f32_32x32x16_bf16 v[18:33], v[106:109], v[114:117], v[18:33]
	ds_read_b128 v[102:105], v90
	ds_read_b128 v[106:109], v90 offset:4096
	ds_read_b128 v[110:113], v84 offset:16384
	ds_read_b128 v[114:117], v84 offset:20480
	s_waitcnt lgkmcnt(1)
	v_mfma_f32_32x32x16_bf16 v[34:49], v[102:105], v[110:113], v[34:49]
	s_waitcnt lgkmcnt(0)
	v_mfma_f32_32x32x16_bf16 v[50:65], v[102:105], v[114:117], v[50:65]
	v_mfma_f32_32x32x16_bf16 v[2:17], v[106:109], v[110:113], v[2:17]
	v_mfma_f32_32x32x16_bf16 v[18:33], v[106:109], v[114:117], v[18:33]
	ds_read_b128 v[102:105], v85
	ds_read_b128 v[106:109], v85 offset:4096
	ds_read_b128 v[110:113], v87 offset:16384
	ds_read_b128 v[114:117], v87 offset:20480
	s_waitcnt vmcnt(0)
	s_waitcnt lgkmcnt(0)
	s_barrier
; #define MFMA(a, b, c) __builtin_amdgcn_mfma_f32_32x32x16_bf16((a), (b), (c), 0, 0, 0)
; template <int AI, int BI>
; DI void gemm_tile(const u16* __restrict__ A, int lda, const u16* __restrict__ B, int ldb, int nk, bool swap,
;                   f32x16 (&acc)[AI][BI], char* lds) {
;     ...
;   for (int kt = 0; kt < nk; ++kt) {
;     const char* cur = lds + (kt & 1) * 32768;
;     if (kt + 1 < nk) gemm_stage<AI, BI>(A + (kt + 1) * 64, lda, B + (kt + 1) * 64, ldb, lds + ((kt + 1) & 1) * 32768, tid);
; #pragma unroll
;     for (int ks = 0; ks < 4; ++ks) {
;       const int co = ((ks * 2 + h) ^ sw) << 4;
;       s16x8 fa[AI], fb[BI];
; #pragma unroll
;       for (int i = 0; i < AI; ++i) fa[i] = *(const s16x8*)(cur + offA + i * 4096 + co);
; #pragma unroll
;       for (int i = 0; i < BI; ++i) fb[i] = *(const s16x8*)(cur + offB + i * 4096 + co);
; #pragma unroll
;       for (int i = 0; i < AI; ++i)
; #pragma unroll
;         for (int j = 0; j < BI; ++j) acc[i][j] = MFMA(fa[i], fb[j], acc[i][j]);
;     }
;     asm volatile("s_waitcnt vmcnt(0)" ::: "memory");
;     __syncthreads();
;   }
	v_mfma_f32_32x32x16_bf16 v[34:49], v[102:105], v[110:113], v[34:49]
	v_mfma_f32_32x32x16_bf16 v[50:65], v[102:105], v[114:117], v[50:65]
	v_lshl_add_u64 v[102:103], v[66:67], 0, s[80:81]
	global_load_lds_dwordx4 v[102:103], off
	v_lshl_add_u64 v[102:103], v[68:69], 0, s[80:81]
	s_mov_b32 m0, s37
	s_nop 0
	global_load_lds_dwordx4 v[102:103], off
	v_lshl_add_u64 v[102:103], v[70:71], 0, s[80:81]
	s_mov_b32 m0, s40
	v_mfma_f32_32x32x16_bf16 v[2:17], v[106:109], v[110:113], v[2:17]
	global_load_lds_dwordx4 v[102:103], off
	v_lshl_add_u64 v[102:103], v[72:73], 0, s[80:81]
	s_mov_b32 m0, s41
	s_nop 0
	global_load_lds_dwordx4 v[102:103], off
	s_mov_b32 m0, s28
	v_mfma_f32_32x32x16_bf16 v[18:33], v[106:109], v[114:117], v[18:33]
	global_load_lds_dwordx4 v[100:101], off
	v_lshl_add_u64 v[100:101], v[76:77], 0, s[80:81]
	s_mov_b32 m0, s29
	s_nop 0
	global_load_lds_dwordx4 v[100:101], off
	v_lshl_add_u64 v[100:101], v[78:79], 0, s[80:81]
	s_mov_b32 m0, s34
	s_nop 0
	global_load_lds_dwordx4 v[100:101], off
	v_lshl_add_u64 v[100:101], v[80:81], 0, s[80:81]
	s_mov_b32 m0, s35
	s_nop 0
	global_load_lds_dwordx4 v[100:101], off
	ds_read_b128 v[100:103], v0 offset:32768
	ds_read_b128 v[104:107], v0 offset:36864
	ds_read_b128 v[108:111], v86 offset:49152
	ds_read_b128 v[112:115], v86 offset:53248
	s_waitcnt lgkmcnt(0)
	v_mfma_f32_32x32x16_bf16 v[34:49], v[100:103], v[108:111], v[34:49]
	s_mov_b32 m0, s46
	v_mfma_f32_32x32x16_bf16 v[50:65], v[100:103], v[112:115], v[50:65]
	v_mfma_f32_32x32x16_bf16 v[2:17], v[104:107], v[108:111], v[2:17]
	v_mfma_f32_32x32x16_bf16 v[18:33], v[104:107], v[112:115], v[18:33]
	ds_read_b128 v[100:103], v88 offset:32768
	ds_read_b128 v[104:107], v88 offset:36864
	ds_read_b128 v[108:111], v89 offset:49152
	ds_read_b128 v[112:115], v89 offset:53248
	s_waitcnt lgkmcnt(1)
	v_mfma_f32_32x32x16_bf16 v[34:49], v[100:103], v[108:111], v[34:49]
	s_waitcnt lgkmcnt(0)
	v_mfma_f32_32x32x16_bf16 v[50:65], v[100:103], v[112:115], v[50:65]
	v_mfma_f32_32x32x16_bf16 v[2:17], v[104:107], v[108:111], v[2:17]
	v_mfma_f32_32x32x16_bf16 v[18:33], v[104:107], v[112:115], v[18:33]
	ds_read_b128 v[100:103], v90 offset:32768
	ds_read_b128 v[104:107], v90 offset:36864
	ds_read_b128 v[108:111], v84 offset:49152
	ds_read_b128 v[112:115], v84 offset:53248
	s_waitcnt lgkmcnt(1)
	v_mfma_f32_32x32x16_bf16 v[34:49], v[100:103], v[108:111], v[34:49]
	s_waitcnt lgkmcnt(0)
	v_mfma_f32_32x32x16_bf16 v[50:65], v[100:103], v[112:115], v[50:65]
	v_mfma_f32_32x32x16_bf16 v[2:17], v[104:107], v[108:111], v[2:17]
	v_mfma_f32_32x32x16_bf16 v[18:33], v[104:107], v[112:115], v[18:33]
	ds_read_b128 v[100:103], v85 offset:32768
	ds_read_b128 v[104:107], v85 offset:36864
	ds_read_b128 v[108:111], v87 offset:49152
	ds_read_b128 v[112:115], v87 offset:53248
	s_waitcnt vmcnt(0)
	s_waitcnt lgkmcnt(0)
	s_barrier
	v_mfma_f32_32x32x16_bf16 v[34:49], v[100:103], v[108:111], v[34:49]
	v_mfma_f32_32x32x16_bf16 v[50:65], v[100:103], v[112:115], v[50:65]
	v_lshl_add_u64 v[100:101], v[66:67], 0, s[82:83]
	global_load_lds_dwordx4 v[100:101], off
	v_lshl_add_u64 v[100:101], v[68:69], 0, s[82:83]
	s_mov_b32 m0, s47
	s_nop 0
	global_load_lds_dwordx4 v[100:101], off
	v_lshl_add_u64 v[100:101], v[70:71], 0, s[82:83]
	s_mov_b32 m0, s48
	v_mfma_f32_32x32x16_bf16 v[2:17], v[104:107], v[108:111], v[2:17]
	global_load_lds_dwordx4 v[100:101], off
	s_mov_b32 m0, s49
	s_nop 0
	global_load_lds_dwordx4 v[92:93], off
	v_lshl_add_u64 v[92:93], v[74:75], 0, s[82:83]
	s_mov_b32 m0, s50
	v_mfma_f32_32x32x16_bf16 v[18:33], v[104:107], v[112:115], v[18:33]
	global_load_lds_dwordx4 v[92:93], off
	v_lshl_add_u64 v[92:93], v[76:77], 0, s[82:83]
	s_mov_b32 m0, s51
	s_nop 0
	global_load_lds_dwordx4 v[92:93], off
	v_lshl_add_u64 v[92:93], v[78:79], 0, s[82:83]
	s_mov_b32 m0, s52
	s_nop 0
	global_load_lds_dwordx4 v[92:93], off
	v_lshl_add_u64 v[92:93], v[80:81], 0, s[82:83]
	s_mov_b32 m0, s18
	s_nop 0
	global_load_lds_dwordx4 v[92:93], off
	ds_read_b128 v[92:95], v0
	ds_read_b128 v[96:99], v0 offset:4096
	ds_read_b128 v[100:103], v86 offset:16384
	ds_read_b128 v[104:107], v86 offset:20480
	s_waitcnt lgkmcnt(0)
	v_mfma_f32_32x32x16_bf16 v[34:49], v[92:95], v[100:103], v[34:49]
	s_mov_b32 m0, s36
	v_mfma_f32_32x32x16_bf16 v[50:65], v[92:95], v[104:107], v[50:65]
	v_mfma_f32_32x32x16_bf16 v[2:17], v[96:99], v[100:103], v[2:17]
	v_mfma_f32_32x32x16_bf16 v[18:33], v[96:99], v[104:107], v[18:33]
	ds_read_b128 v[92:95], v88
	ds_read_b128 v[96:99], v88 offset:4096
	ds_read_b128 v[100:103], v89 offset:16384
	ds_read_b128 v[104:107], v89 offset:20480
	s_waitcnt lgkmcnt(1)
	v_mfma_f32_32x32x16_bf16 v[34:49], v[92:95], v[100:103], v[34:49]
	s_waitcnt lgkmcnt(0)
	v_mfma_f32_32x32x16_bf16 v[50:65], v[92:95], v[104:107], v[50:65]
	v_mfma_f32_32x32x16_bf16 v[2:17], v[96:99], v[100:103], v[2:17]
	v_mfma_f32_32x32x16_bf16 v[18:33], v[96:99], v[104:107], v[18:33]
	ds_read_b128 v[92:95], v90
	ds_read_b128 v[96:99], v90 offset:4096
	ds_read_b128 v[100:103], v84 offset:16384
	ds_read_b128 v[104:107], v84 offset:20480
	s_waitcnt lgkmcnt(1)
	v_mfma_f32_32x32x16_bf16 v[34:49], v[92:95], v[100:103], v[34:49]
	s_waitcnt lgkmcnt(0)
	v_mfma_f32_32x32x16_bf16 v[50:65], v[92:95], v[104:107], v[50:65]
	v_mfma_f32_32x32x16_bf16 v[2:17], v[96:99], v[100:103], v[2:17]
	v_mfma_f32_32x32x16_bf16 v[18:33], v[96:99], v[104:107], v[18:33]
	ds_read_b128 v[92:95], v85
	ds_read_b128 v[96:99], v85 offset:4096
	ds_read_b128 v[100:103], v87 offset:16384
	ds_read_b128 v[104:107], v87 offset:20480
	s_waitcnt vmcnt(0)
	s_waitcnt lgkmcnt(0)
	s_barrier
; #define MFMA(a, b, c) __builtin_amdgcn_mfma_f32_32x32x16_bf16((a), (b), (c), 0, 0, 0)
; template <int AI, int BI>
; DI void gemm_tile(const u16* __restrict__ A, int lda, const u16* __restrict__ B, int ldb, int nk, bool swap,
;                   f32x16 (&acc)[AI][BI], char* lds) {
;     ...
;   for (int kt = 0; kt < nk; ++kt) {
;     const char* cur = lds + (kt & 1) * 32768;
;     if (kt + 1 < nk) gemm_stage<AI, BI>(A + (kt + 1) * 64, lda, B + (kt + 1) * 64, ldb, lds + ((kt + 1) & 1) * 32768, tid);
; #pragma unroll
;     for (int ks = 0; ks < 4; ++ks) {
;       const int co = ((ks * 2 + h) ^ sw) << 4;
;       s16x8 fa[AI], fb[BI];
; #pragma unroll
;       for (int i = 0; i < AI; ++i) fa[i] = *(const s16x8*)(cur + offA + i * 4096 + co);
; #pragma unroll
;       for (int i = 0; i < BI; ++i) fb[i] = *(const s16x8*)(cur + offB + i * 4096 + co);
; #pragma unroll
;       for (int i = 0; i < AI; ++i)
; #pragma unroll
;         for (int j = 0; j < BI; ++j) acc[i][j] = MFMA(fa[i], fb[j], acc[i][j]);
;     }
;     asm volatile("s_waitcnt vmcnt(0)" ::: "memory");
;     __syncthreads();
;   }
	v_mfma_f32_32x32x16_bf16 v[34:49], v[92:95], v[100:103], v[34:49]
	v_mfma_f32_32x32x16_bf16 v[50:65], v[92:95], v[104:107], v[50:65]
	v_lshl_add_u64 v[92:93], v[66:67], 0, s[84:85]
	global_load_lds_dwordx4 v[92:93], off
	v_lshl_add_u64 v[92:93], v[68:69], 0, s[84:85]
	s_mov_b32 m0, s37
	s_nop 0
	global_load_lds_dwordx4 v[92:93], off
	v_lshl_add_u64 v[92:93], v[70:71], 0, s[84:85]
	s_mov_b32 m0, s40
	v_mfma_f32_32x32x16_bf16 v[2:17], v[96:99], v[100:103], v[2:17]
	global_load_lds_dwordx4 v[92:93], off
	v_lshl_add_u64 v[92:93], v[72:73], 0, s[84:85]
	s_mov_b32 m0, s41
	s_nop 0
	global_load_lds_dwordx4 v[92:93], off
	v_lshl_add_u64 v[92:93], v[74:75], 0, s[84:85]
	s_mov_b32 m0, s28
	v_mfma_f32_32x32x16_bf16 v[18:33], v[96:99], v[104:107], v[18:33]
	global_load_lds_dwordx4 v[92:93], off
	v_lshl_add_u64 v[92:93], v[76:77], 0, s[84:85]
	s_mov_b32 m0, s29
	s_nop 0
	global_load_lds_dwordx4 v[92:93], off
	v_lshl_add_u64 v[92:93], v[78:79], 0, s[84:85]
	s_mov_b32 m0, s34
	s_nop 0
	global_load_lds_dwordx4 v[92:93], off
	v_lshl_add_u64 v[92:93], v[80:81], 0, s[84:85]
	s_mov_b32 m0, s35
	s_nop 0
	global_load_lds_dwordx4 v[92:93], off
	ds_read_b128 v[92:95], v0 offset:32768
	ds_read_b128 v[96:99], v0 offset:36864
	ds_read_b128 v[100:103], v86 offset:49152
	ds_read_b128 v[104:107], v86 offset:53248
	s_waitcnt lgkmcnt(0)
	v_mfma_f32_32x32x16_bf16 v[34:49], v[92:95], v[100:103], v[34:49]
	s_mov_b32 m0, s46
	v_mfma_f32_32x32x16_bf16 v[50:65], v[92:95], v[104:107], v[50:65]
	v_mfma_f32_32x32x16_bf16 v[2:17], v[96:99], v[100:103], v[2:17]
	v_mfma_f32_32x32x16_bf16 v[18:33], v[96:99], v[104:107], v[18:33]
	ds_read_b128 v[92:95], v88 offset:32768
	ds_read_b128 v[96:99], v88 offset:36864
	ds_read_b128 v[100:103], v89 offset:49152
	ds_read_b128 v[104:107], v89 offset:53248
	s_waitcnt lgkmcnt(1)
	v_mfma_f32_32x32x16_bf16 v[34:49], v[92:95], v[100:103], v[34:49]
	s_waitcnt lgkmcnt(0)
	v_mfma_f32_32x32x16_bf16 v[50:65], v[92:95], v[104:107], v[50:65]
	v_mfma_f32_32x32x16_bf16 v[2:17], v[96:99], v[100:103], v[2:17]
	v_mfma_f32_32x32x16_bf16 v[18:33], v[96:99], v[104:107], v[18:33]
	ds_read_b128 v[92:95], v90 offset:32768
	ds_read_b128 v[96:99], v90 offset:36864
	ds_read_b128 v[100:103], v84 offset:49152
	ds_read_b128 v[104:107], v84 offset:53248
	s_waitcnt lgkmcnt(1)
	v_mfma_f32_32x32x16_bf16 v[34:49], v[92:95], v[100:103], v[34:49]
	s_waitcnt lgkmcnt(0)
	v_mfma_f32_32x32x16_bf16 v[50:65], v[92:95], v[104:107], v[50:65]
	v_mfma_f32_32x32x16_bf16 v[2:17], v[96:99], v[100:103], v[2:17]
	v_mfma_f32_32x32x16_bf16 v[18:33], v[96:99], v[104:107], v[18:33]
	ds_read_b128 v[92:95], v85 offset:32768
	ds_read_b128 v[96:99], v85 offset:36864
	ds_read_b128 v[100:103], v87 offset:49152
	ds_read_b128 v[104:107], v87 offset:53248
	s_waitcnt vmcnt(0)
	s_waitcnt lgkmcnt(0)
	s_barrier
	v_mfma_f32_32x32x16_bf16 v[34:49], v[92:95], v[100:103], v[34:49]
	v_mfma_f32_32x32x16_bf16 v[50:65], v[92:95], v[104:107], v[50:65]
	v_lshl_add_u64 v[92:93], v[66:67], 0, s[88:89]
	global_load_lds_dwordx4 v[92:93], off
	v_lshl_add_u64 v[92:93], v[68:69], 0, s[88:89]
	s_mov_b32 m0, s47
	s_nop 0
	global_load_lds_dwordx4 v[92:93], off
	v_lshl_add_u64 v[92:93], v[70:71], 0, s[88:89]
	s_mov_b32 m0, s48
	v_mfma_f32_32x32x16_bf16 v[2:17], v[96:99], v[100:103], v[2:17]
	global_load_lds_dwordx4 v[92:93], off
	v_lshl_add_u64 v[92:93], v[72:73], 0, s[88:89]
	s_mov_b32 m0, s49
	s_nop 0
	global_load_lds_dwordx4 v[92:93], off
	v_lshl_add_u64 v[92:93], v[74:75], 0, s[88:89]
	s_mov_b32 m0, s50
	v_mfma_f32_32x32x16_bf16 v[18:33], v[96:99], v[104:107], v[18:33]
	global_load_lds_dwordx4 v[92:93], off
	v_lshl_add_u64 v[92:93], v[76:77], 0, s[88:89]
	s_mov_b32 m0, s51
	s_nop 0
	global_load_lds_dwordx4 v[92:93], off
	v_lshl_add_u64 v[92:93], v[78:79], 0, s[88:89]
	s_mov_b32 m0, s52
	s_nop 0
	global_load_lds_dwordx4 v[92:93], off
	v_lshl_add_u64 v[92:93], v[80:81], 0, s[88:89]
	s_mov_b32 m0, s18
	s_nop 0
	global_load_lds_dwordx4 v[92:93], off
	ds_read_b128 v[92:95], v0
	ds_read_b128 v[96:99], v0 offset:4096
	ds_read_b128 v[100:103], v86 offset:16384
	ds_read_b128 v[104:107], v86 offset:20480
	s_waitcnt lgkmcnt(0)
	v_mfma_f32_32x32x16_bf16 v[34:49], v[92:95], v[100:103], v[34:49]
	s_mov_b32 m0, s36
	v_mfma_f32_32x32x16_bf16 v[50:65], v[92:95], v[104:107], v[50:65]
	v_mfma_f32_32x32x16_bf16 v[2:17], v[96:99], v[100:103], v[2:17]
	v_mfma_f32_32x32x16_bf16 v[18:33], v[96:99], v[104:107], v[18:33]
	ds_read_b128 v[92:95], v88
	ds_read_b128 v[96:99], v88 offset:4096
	ds_read_b128 v[100:103], v89 offset:16384
	ds_read_b128 v[104:107], v89 offset:20480
	s_waitcnt lgkmcnt(1)
	v_mfma_f32_32x32x16_bf16 v[34:49], v[92:95], v[100:103], v[34:49]
	s_waitcnt lgkmcnt(0)
	v_mfma_f32_32x32x16_bf16 v[50:65], v[92:95], v[104:107], v[50:65]
	v_mfma_f32_32x32x16_bf16 v[2:17], v[96:99], v[100:103], v[2:17]
	v_mfma_f32_32x32x16_bf16 v[18:33], v[96:99], v[104:107], v[18:33]
	ds_read_b128 v[92:95], v90
	ds_read_b128 v[96:99], v90 offset:4096
	ds_read_b128 v[100:103], v84 offset:16384
	ds_read_b128 v[104:107], v84 offset:20480
	s_waitcnt lgkmcnt(1)
	v_mfma_f32_32x32x16_bf16 v[34:49], v[92:95], v[100:103], v[34:49]
	s_waitcnt lgkmcnt(0)
	v_mfma_f32_32x32x16_bf16 v[50:65], v[92:95], v[104:107], v[50:65]
	v_mfma_f32_32x32x16_bf16 v[2:17], v[96:99], v[100:103], v[2:17]
	v_mfma_f32_32x32x16_bf16 v[18:33], v[96:99], v[104:107], v[18:33]
	ds_read_b128 v[92:95], v85
	ds_read_b128 v[96:99], v85 offset:4096
	ds_read_b128 v[100:103], v87 offset:16384
	ds_read_b128 v[104:107], v87 offset:20480
	s_waitcnt vmcnt(0)
	s_waitcnt lgkmcnt(0)
	s_barrier
; #define MFMA(a, b, c) __builtin_amdgcn_mfma_f32_32x32x16_bf16((a), (b), (c), 0, 0, 0)
; template <int AI, int BI>
; DI void gemm_tile(const u16* __restrict__ A, int lda, const u16* __restrict__ B, int ldb, int nk, bool swap,
;                   f32x16 (&acc)[AI][BI], char* lds) {
;     ...
;   for (int kt = 0; kt < nk; ++kt) {
;     const char* cur = lds + (kt & 1) * 32768;
;     if (kt + 1 < nk) gemm_stage<AI, BI>(A + (kt + 1) * 64, lda, B + (kt + 1) * 64, ldb, lds + ((kt + 1) & 1) * 32768, tid);
; #pragma unroll
;     for (int ks = 0; ks < 4; ++ks) {
;       const int co = ((ks * 2 + h) ^ sw) << 4;
;       s16x8 fa[AI], fb[BI];
; #pragma unroll
;       for (int i = 0; i < AI; ++i) fa[i] = *(const s16x8*)(cur + offA + i * 4096 + co);
; #pragma unroll
;       for (int i = 0; i < BI; ++i) fb[i] = *(const s16x8*)(cur + offB + i * 4096 + co);
; #pragma unroll
;       for (int i = 0; i < AI; ++i)
; #pragma unroll
;         for (int j = 0; j < BI; ++j) acc[i][j] = MFMA(fa[i], fb[j], acc[i][j]);
;     }
;     asm volatile("s_waitcnt vmcnt(0)" ::: "memory");
;     __syncthreads();
;   }
	v_mfma_f32_32x32x16_bf16 v[34:49], v[92:95], v[100:103], v[34:49]
	v_mfma_f32_32x32x16_bf16 v[50:65], v[92:95], v[104:107], v[50:65]
	v_lshl_add_u64 v[92:93], v[66:67], 0, vcc
	global_load_lds_dwordx4 v[92:93], off
	v_lshl_add_u64 v[92:93], v[68:69], 0, vcc
	s_mov_b32 m0, s37
	s_nop 0
	global_load_lds_dwordx4 v[92:93], off
	v_lshl_add_u64 v[92:93], v[70:71], 0, vcc
	s_mov_b32 m0, s40
	v_mfma_f32_32x32x16_bf16 v[2:17], v[96:99], v[100:103], v[2:17]
	global_load_lds_dwordx4 v[92:93], off
	v_lshl_add_u64 v[92:93], v[72:73], 0, vcc
	s_mov_b32 m0, s41
	s_nop 0
	global_load_lds_dwordx4 v[92:93], off
	v_lshl_add_u64 v[92:93], v[74:75], 0, vcc
	s_mov_b32 m0, s28
	v_mfma_f32_32x32x16_bf16 v[18:33], v[96:99], v[104:107], v[18:33]
	global_load_lds_dwordx4 v[92:93], off
	v_lshl_add_u64 v[92:93], v[76:77], 0, vcc
	s_mov_b32 m0, s29
	s_nop 0
	global_load_lds_dwordx4 v[92:93], off
	v_lshl_add_u64 v[92:93], v[78:79], 0, vcc
	s_mov_b32 m0, s34
	s_nop 0
	global_load_lds_dwordx4 v[92:93], off
	v_lshl_add_u64 v[92:93], v[80:81], 0, vcc
	s_mov_b32 m0, s35
	s_nop 0
	global_load_lds_dwordx4 v[92:93], off
	ds_read_b128 v[92:95], v0 offset:32768
	ds_read_b128 v[96:99], v0 offset:36864
	ds_read_b128 v[100:103], v86 offset:49152
	ds_read_b128 v[104:107], v86 offset:53248
	s_waitcnt lgkmcnt(0)
	v_mfma_f32_32x32x16_bf16 v[34:49], v[92:95], v[100:103], v[34:49]
	s_mov_b32 m0, s46
	v_mfma_f32_32x32x16_bf16 v[50:65], v[92:95], v[104:107], v[50:65]
	v_mfma_f32_32x32x16_bf16 v[2:17], v[96:99], v[100:103], v[2:17]
	v_mfma_f32_32x32x16_bf16 v[18:33], v[96:99], v[104:107], v[18:33]
	ds_read_b128 v[92:95], v88 offset:32768
	ds_read_b128 v[96:99], v88 offset:36864
	ds_read_b128 v[100:103], v89 offset:49152
	ds_read_b128 v[104:107], v89 offset:53248
	s_waitcnt lgkmcnt(1)
	v_mfma_f32_32x32x16_bf16 v[34:49], v[92:95], v[100:103], v[34:49]
	s_waitcnt lgkmcnt(0)
	v_mfma_f32_32x32x16_bf16 v[50:65], v[92:95], v[104:107], v[50:65]
	v_mfma_f32_32x32x16_bf16 v[2:17], v[96:99], v[100:103], v[2:17]
	v_mfma_f32_32x32x16_bf16 v[18:33], v[96:99], v[104:107], v[18:33]
	ds_read_b128 v[92:95], v90 offset:32768
	ds_read_b128 v[96:99], v90 offset:36864
	ds_read_b128 v[100:103], v84 offset:49152
	ds_read_b128 v[104:107], v84 offset:53248
	s_waitcnt lgkmcnt(1)
	v_mfma_f32_32x32x16_bf16 v[34:49], v[92:95], v[100:103], v[34:49]
	s_waitcnt lgkmcnt(0)
	v_mfma_f32_32x32x16_bf16 v[50:65], v[92:95], v[104:107], v[50:65]
	v_mfma_f32_32x32x16_bf16 v[2:17], v[96:99], v[100:103], v[2:17]
	v_mfma_f32_32x32x16_bf16 v[18:33], v[96:99], v[104:107], v[18:33]
	ds_read_b128 v[92:95], v85 offset:32768
	ds_read_b128 v[96:99], v85 offset:36864
	ds_read_b128 v[100:103], v87 offset:49152
	ds_read_b128 v[104:107], v87 offset:53248
	s_waitcnt vmcnt(0)
	s_waitcnt lgkmcnt(0)
	s_barrier
	v_mfma_f32_32x32x16_bf16 v[34:49], v[92:95], v[100:103], v[34:49]
	v_mfma_f32_32x32x16_bf16 v[50:65], v[92:95], v[104:107], v[50:65]
	v_lshl_add_u64 v[92:93], v[66:67], 0, s[78:79]
	global_load_lds_dwordx4 v[92:93], off
	v_lshl_add_u64 v[92:93], v[68:69], 0, s[78:79]
	s_mov_b32 m0, s47
	s_nop 0
	global_load_lds_dwordx4 v[92:93], off
	v_lshl_add_u64 v[92:93], v[70:71], 0, s[78:79]
	s_mov_b32 m0, s48
	v_mfma_f32_32x32x16_bf16 v[2:17], v[96:99], v[100:103], v[2:17]
	global_load_lds_dwordx4 v[92:93], off
	v_lshl_add_u64 v[92:93], v[72:73], 0, s[78:79]
	s_mov_b32 m0, s49
	s_nop 0
	global_load_lds_dwordx4 v[92:93], off
	v_lshl_add_u64 v[92:93], v[74:75], 0, s[78:79]
	s_mov_b32 m0, s50
	v_mfma_f32_32x32x16_bf16 v[18:33], v[96:99], v[104:107], v[18:33]
	global_load_lds_dwordx4 v[92:93], off
	v_lshl_add_u64 v[92:93], v[76:77], 0, s[78:79]
	s_mov_b32 m0, s51
	s_nop 0
	global_load_lds_dwordx4 v[92:93], off
	v_lshl_add_u64 v[92:93], v[78:79], 0, s[78:79]
	s_mov_b32 m0, s52
	s_nop 0
	global_load_lds_dwordx4 v[92:93], off
	v_lshl_add_u64 v[92:93], v[80:81], 0, s[78:79]
	s_mov_b32 m0, s18
	s_nop 0
	global_load_lds_dwordx4 v[92:93], off
	ds_read_b128 v[92:95], v0
	ds_read_b128 v[96:99], v0 offset:4096
	ds_read_b128 v[100:103], v86 offset:16384
	ds_read_b128 v[104:107], v86 offset:20480
	s_waitcnt lgkmcnt(0)
	v_mfma_f32_32x32x16_bf16 v[34:49], v[92:95], v[100:103], v[34:49]
	s_mov_b32 m0, s36
	v_mfma_f32_32x32x16_bf16 v[50:65], v[92:95], v[104:107], v[50:65]
	v_mfma_f32_32x32x16_bf16 v[2:17], v[96:99], v[100:103], v[2:17]
	v_mfma_f32_32x32x16_bf16 v[18:33], v[96:99], v[104:107], v[18:33]
	ds_read_b128 v[92:95], v88
	ds_read_b128 v[96:99], v88 offset:4096
	ds_read_b128 v[100:103], v89 offset:16384
	ds_read_b128 v[104:107], v89 offset:20480
	s_waitcnt lgkmcnt(1)
	v_mfma_f32_32x32x16_bf16 v[34:49], v[92:95], v[100:103], v[34:49]
	s_waitcnt lgkmcnt(0)
	v_mfma_f32_32x32x16_bf16 v[50:65], v[92:95], v[104:107], v[50:65]
	v_mfma_f32_32x32x16_bf16 v[2:17], v[96:99], v[100:103], v[2:17]
	v_mfma_f32_32x32x16_bf16 v[18:33], v[96:99], v[104:107], v[18:33]
	ds_read_b128 v[92:95], v90
	ds_read_b128 v[96:99], v90 offset:4096
	ds_read_b128 v[100:103], v84 offset:16384
	ds_read_b128 v[104:107], v84 offset:20480
	s_waitcnt lgkmcnt(1)
	v_mfma_f32_32x32x16_bf16 v[34:49], v[92:95], v[100:103], v[34:49]
	s_waitcnt lgkmcnt(0)
	v_mfma_f32_32x32x16_bf16 v[50:65], v[92:95], v[104:107], v[50:65]
	v_mfma_f32_32x32x16_bf16 v[2:17], v[96:99], v[100:103], v[2:17]
	v_mfma_f32_32x32x16_bf16 v[18:33], v[96:99], v[104:107], v[18:33]
	ds_read_b128 v[92:95], v85
	ds_read_b128 v[96:99], v85 offset:4096
	ds_read_b128 v[100:103], v87 offset:16384
	ds_read_b128 v[104:107], v87 offset:20480
	s_waitcnt vmcnt(0)
	s_waitcnt lgkmcnt(0)
	s_barrier
; #define MFMA(a, b, c) __builtin_amdgcn_mfma_f32_32x32x16_bf16((a), (b), (c), 0, 0, 0)
; template <int AI, int BI>
; DI void gemm_tile(const u16* __restrict__ A, int lda, const u16* __restrict__ B, int ldb, int nk, bool swap,
;                   f32x16 (&acc)[AI][BI], char* lds) {
;     ...
;   for (int kt = 0; kt < nk; ++kt) {
;     const char* cur = lds + (kt & 1) * 32768;
;     if (kt + 1 < nk) gemm_stage<AI, BI>(A + (kt + 1) * 64, lda, B + (kt + 1) * 64, ldb, lds + ((kt + 1) & 1) * 32768, tid);
; #pragma unroll
;     for (int ks = 0; ks < 4; ++ks) {
;       const int co = ((ks * 2 + h) ^ sw) << 4;
;       s16x8 fa[AI], fb[BI];
; #pragma unroll
;       for (int i = 0; i < AI; ++i) fa[i] = *(const s16x8*)(cur + offA + i * 4096 + co);
; #pragma unroll
;       for (int i = 0; i < BI; ++i) fb[i] = *(const s16x8*)(cur + offB + i * 4096 + co);
; #pragma unroll
;       for (int i = 0; i < AI; ++i)
; #pragma unroll
;         for (int j = 0; j < BI; ++j) acc[i][j] = MFMA(fa[i], fb[j], acc[i][j]);
;     }
;     asm volatile("s_waitcnt vmcnt(0)" ::: "memory");
;     __syncthreads();
;   }
	v_mfma_f32_32x32x16_bf16 v[34:49], v[92:95], v[100:103], v[34:49]
	v_mfma_f32_32x32x16_bf16 v[50:65], v[92:95], v[104:107], v[50:65]
	v_lshl_add_u64 v[92:93], v[66:67], 0, s[2:3]
	global_load_lds_dwordx4 v[92:93], off
	v_lshl_add_u64 v[92:93], v[68:69], 0, s[2:3]
	s_mov_b32 m0, s37
	v_lshl_add_u64 v[66:67], v[66:67], 0, s[30:31]
	global_load_lds_dwordx4 v[92:93], off
	v_lshl_add_u64 v[92:93], v[70:71], 0, s[2:3]
	s_mov_b32 m0, s40
	v_mfma_f32_32x32x16_bf16 v[2:17], v[96:99], v[100:103], v[2:17]
	global_load_lds_dwordx4 v[92:93], off
	v_lshl_add_u64 v[92:93], v[72:73], 0, s[2:3]
	s_mov_b32 m0, s41
	s_nop 0
	global_load_lds_dwordx4 v[92:93], off
	v_lshl_add_u64 v[92:93], v[74:75], 0, s[2:3]
	s_mov_b32 m0, s28
	v_mfma_f32_32x32x16_bf16 v[18:33], v[96:99], v[104:107], v[18:33]
	global_load_lds_dwordx4 v[92:93], off
	v_lshl_add_u64 v[92:93], v[76:77], 0, s[2:3]
	s_mov_b32 m0, s29
	s_nop 0
	global_load_lds_dwordx4 v[92:93], off
	v_lshl_add_u64 v[92:93], v[78:79], 0, s[2:3]
	s_mov_b32 m0, s34
	s_nop 0
	global_load_lds_dwordx4 v[92:93], off
	v_lshl_add_u64 v[92:93], v[80:81], 0, s[2:3]
	s_mov_b32 m0, s35
	s_nop 0
	global_load_lds_dwordx4 v[92:93], off
	ds_read_b128 v[92:95], v0 offset:32768
	ds_read_b128 v[96:99], v0 offset:36864
	ds_read_b128 v[100:103], v86 offset:49152
	ds_read_b128 v[104:107], v86 offset:53248
	s_waitcnt lgkmcnt(0)
	v_mfma_f32_32x32x16_bf16 v[34:49], v[92:95], v[100:103], v[34:49]
	s_mov_b32 m0, s46
	v_mfma_f32_32x32x16_bf16 v[50:65], v[92:95], v[104:107], v[50:65]
	v_mfma_f32_32x32x16_bf16 v[2:17], v[96:99], v[100:103], v[2:17]
	v_mfma_f32_32x32x16_bf16 v[18:33], v[96:99], v[104:107], v[18:33]
	ds_read_b128 v[92:95], v88 offset:32768
	ds_read_b128 v[96:99], v88 offset:36864
	ds_read_b128 v[100:103], v89 offset:49152
	ds_read_b128 v[104:107], v89 offset:53248
	s_waitcnt lgkmcnt(1)
	v_mfma_f32_32x32x16_bf16 v[34:49], v[92:95], v[100:103], v[34:49]
	s_waitcnt lgkmcnt(0)
	v_mfma_f32_32x32x16_bf16 v[50:65], v[92:95], v[104:107], v[50:65]
	v_mfma_f32_32x32x16_bf16 v[2:17], v[96:99], v[100:103], v[2:17]
	v_mfma_f32_32x32x16_bf16 v[18:33], v[96:99], v[104:107], v[18:33]
	ds_read_b128 v[92:95], v90 offset:32768
	ds_read_b128 v[96:99], v90 offset:36864
	ds_read_b128 v[100:103], v84 offset:49152
	ds_read_b128 v[104:107], v84 offset:53248
	s_waitcnt lgkmcnt(1)
	v_mfma_f32_32x32x16_bf16 v[34:49], v[92:95], v[100:103], v[34:49]
	s_waitcnt lgkmcnt(0)
	v_mfma_f32_32x32x16_bf16 v[50:65], v[92:95], v[104:107], v[50:65]
	v_mfma_f32_32x32x16_bf16 v[2:17], v[96:99], v[100:103], v[2:17]
	v_mfma_f32_32x32x16_bf16 v[18:33], v[96:99], v[104:107], v[18:33]
	ds_read_b128 v[92:95], v85 offset:32768
	ds_read_b128 v[96:99], v85 offset:36864
	ds_read_b128 v[100:103], v87 offset:49152
	ds_read_b128 v[104:107], v87 offset:53248
	s_waitcnt vmcnt(0)
	s_waitcnt lgkmcnt(0)
	s_barrier
	global_load_lds_dwordx4 v[66:67], off
	v_lshl_add_u64 v[66:67], v[68:69], 0, s[30:31]
	s_mov_b32 m0, s47
	v_mfma_f32_32x32x16_bf16 v[34:49], v[92:95], v[100:103], v[34:49]
	global_load_lds_dwordx4 v[66:67], off
	v_lshl_add_u64 v[66:67], v[70:71], 0, s[30:31]
	s_mov_b32 m0, s48
	s_nop 0
	global_load_lds_dwordx4 v[66:67], off
	v_lshl_add_u64 v[66:67], v[72:73], 0, s[30:31]
	s_mov_b32 m0, s49
	v_mfma_f32_32x32x16_bf16 v[50:65], v[92:95], v[104:107], v[50:65]
	global_load_lds_dwordx4 v[66:67], off
	v_lshl_add_u64 v[66:67], v[74:75], 0, s[30:31]
	s_mov_b32 m0, s50
	s_nop 0
	global_load_lds_dwordx4 v[66:67], off
	v_lshl_add_u64 v[66:67], v[76:77], 0, s[30:31]
	s_mov_b32 m0, s51
	v_mfma_f32_32x32x16_bf16 v[2:17], v[96:99], v[100:103], v[2:17]
	global_load_lds_dwordx4 v[66:67], off
	v_lshl_add_u64 v[66:67], v[78:79], 0, s[30:31]
	s_mov_b32 m0, s52
	s_nop 0
	global_load_lds_dwordx4 v[66:67], off
	v_lshl_add_u64 v[66:67], v[80:81], 0, s[30:31]
	s_mov_b32 m0, s18
	v_mfma_f32_32x32x16_bf16 v[18:33], v[96:99], v[104:107], v[18:33]
	global_load_lds_dwordx4 v[66:67], off
	ds_read_b128 v[66:69], v0
	ds_read_b128 v[70:73], v0 offset:4096
	ds_read_b128 v[74:77], v86 offset:16384
	ds_read_b128 v[78:81], v86 offset:20480
	s_waitcnt lgkmcnt(0)
	v_mfma_f32_32x32x16_bf16 v[34:49], v[66:69], v[74:77], v[34:49]
	v_mfma_f32_32x32x16_bf16 v[50:65], v[66:69], v[78:81], v[50:65]
	v_mfma_f32_32x32x16_bf16 v[2:17], v[70:73], v[74:77], v[2:17]
	v_mfma_f32_32x32x16_bf16 v[18:33], v[70:73], v[78:81], v[18:33]
	ds_read_b128 v[66:69], v88
	ds_read_b128 v[70:73], v88 offset:4096
	ds_read_b128 v[74:77], v89 offset:16384
	ds_read_b128 v[78:81], v89 offset:20480
	s_waitcnt lgkmcnt(1)
	v_mfma_f32_32x32x16_bf16 v[34:49], v[66:69], v[74:77], v[34:49]
	s_waitcnt lgkmcnt(0)
	v_mfma_f32_32x32x16_bf16 v[50:65], v[66:69], v[78:81], v[50:65]
	v_mfma_f32_32x32x16_bf16 v[2:17], v[70:73], v[74:77], v[2:17]
	v_mfma_f32_32x32x16_bf16 v[18:33], v[70:73], v[78:81], v[18:33]
	ds_read_b128 v[66:69], v90
	ds_read_b128 v[70:73], v90 offset:4096
	ds_read_b128 v[74:77], v84 offset:16384
	ds_read_b128 v[78:81], v84 offset:20480
	s_waitcnt lgkmcnt(1)
	v_mfma_f32_32x32x16_bf16 v[34:49], v[66:69], v[74:77], v[34:49]
	s_waitcnt lgkmcnt(0)
	v_mfma_f32_32x32x16_bf16 v[50:65], v[66:69], v[78:81], v[50:65]
	v_mfma_f32_32x32x16_bf16 v[2:17], v[70:73], v[74:77], v[2:17]
	v_mfma_f32_32x32x16_bf16 v[18:33], v[70:73], v[78:81], v[18:33]
	ds_read_b128 v[66:69], v85
	ds_read_b128 v[70:73], v85 offset:4096
	ds_read_b128 v[74:77], v87 offset:16384
	ds_read_b128 v[78:81], v87 offset:20480
	s_waitcnt vmcnt(0)
	s_waitcnt lgkmcnt(0)
	s_barrier
; #define MFMA(a, b, c) __builtin_amdgcn_mfma_f32_32x32x16_bf16((a), (b), (c), 0, 0, 0)
; #define GAS __attribute__((address_space(1)))
; DI int opaque0() { int z = 0; asm volatile("" : "+v"(z)); return z; }
; template <int AI, int BI>
; DI void gemm_tile(const u16* __restrict__ A, int lda, const u16* __restrict__ B, int ldb, int nk, bool swap,
;                   f32x16 (&acc)[AI][BI], char* lds) {
;     ...
;   for (int kt = 0; kt < nk; ++kt) {
;     const char* cur = lds + (kt & 1) * 32768;
;     if (kt + 1 < nk) gemm_stage<AI, BI>(A + (kt + 1) * 64, lda, B + (kt + 1) * 64, ldb, lds + ((kt + 1) & 1) * 32768, tid);
; #pragma unroll
;     for (int ks = 0; ks < 4; ++ks) {
;       const int co = ((ks * 2 + h) ^ sw) << 4;
;       s16x8 fa[AI], fb[BI];
; #pragma unroll
;       for (int i = 0; i < AI; ++i) fa[i] = *(const s16x8*)(cur + offA + i * 4096 + co);
; #pragma unroll
;       for (int i = 0; i < BI; ++i) fb[i] = *(const s16x8*)(cur + offB + i * 4096 + co);
; #pragma unroll
;       for (int i = 0; i < AI; ++i)
; #pragma unroll
;         for (int j = 0; j < BI; ++j) acc[i][j] = MFMA(fa[i], fb[j], acc[i][j]);
;     }
;     asm volatile("s_waitcnt vmcnt(0)" ::: "memory");
;     __syncthreads();
;   }
; template <int AI>
; DI void gu_tile(char* wsb, int sub, int m0, int n0, char* lds) {
;     ...
;   const int m0e = m0 + opaque0();
;   const int hc = (n0 >> 1) + wb * 32 + r;
;   GAS u16* HIDu = uptr(HID);
;   const unsigned ib = (unsigned)((m0e + wa * 32 * AI + 4 * h) * 2816 + hc);
; #pragma unroll
;   for (int ai = 0; ai < AI; ++ai)
; #pragma unroll
;     for (int reg = 0; reg < 16; ++reg) {
;       float g = acc[ai][0][reg], u = acc[ai][1][reg];
;       float v = g * __builtin_amdgcn_rcpf(1.f + __expf(-g)) * u;
;       HIDu[ib + (unsigned)((ai * 32 + (reg & 3) + 8 * (reg >> 2)) * 2816)] = f2bf(v);
;       if ((reg & 7) == 7) __builtin_amdgcn_sched_barrier(0);
;     }
	v_mfma_f32_32x32x16_bf16 v[34:49], v[66:69], v[74:77], v[34:49]
	v_mfma_f32_32x32x16_bf16 v[50:65], v[66:69], v[78:81], v[50:65]
	v_mfma_f32_32x32x16_bf16 v[2:17], v[70:73], v[74:77], v[2:17]
	v_mfma_f32_32x32x16_bf16 v[18:33], v[70:73], v[78:81], v[18:33]
	ds_read_b128 v[66:69], v0 offset:32768
	ds_read_b128 v[70:73], v0 offset:36864
	ds_read_b128 v[74:77], v86 offset:49152
	ds_read_b128 v[78:81], v86 offset:53248
	v_mov_b32_e32 v0, v1
	s_waitcnt lgkmcnt(1)
	v_mfma_f32_32x32x16_bf16 v[34:49], v[66:69], v[74:77], v[34:49]
	s_waitcnt lgkmcnt(0)
	v_mfma_f32_32x32x16_bf16 v[50:65], v[66:69], v[78:81], v[50:65]
	v_mfma_f32_32x32x16_bf16 v[2:17], v[70:73], v[74:77], v[2:17]
	v_mfma_f32_32x32x16_bf16 v[18:33], v[70:73], v[78:81], v[18:33]
	ds_read_b128 v[66:69], v88 offset:32768
	ds_read_b128 v[70:73], v88 offset:36864
	ds_read_b128 v[74:77], v89 offset:49152
	ds_read_b128 v[78:81], v89 offset:53248
	s_waitcnt lgkmcnt(1)
	v_mfma_f32_32x32x16_bf16 v[34:49], v[66:69], v[74:77], v[34:49]
	s_waitcnt lgkmcnt(0)
	v_mfma_f32_32x32x16_bf16 v[50:65], v[66:69], v[78:81], v[50:65]
	v_mfma_f32_32x32x16_bf16 v[2:17], v[70:73], v[74:77], v[2:17]
	v_mfma_f32_32x32x16_bf16 v[18:33], v[70:73], v[78:81], v[18:33]
	ds_read_b128 v[66:69], v90 offset:32768
	ds_read_b128 v[70:73], v90 offset:36864
	ds_read_b128 v[74:77], v84 offset:49152
	ds_read_b128 v[78:81], v84 offset:53248
	s_waitcnt lgkmcnt(1)
	v_mfma_f32_32x32x16_bf16 v[34:49], v[66:69], v[74:77], v[34:49]
	s_waitcnt lgkmcnt(0)
	v_mfma_f32_32x32x16_bf16 v[50:65], v[66:69], v[78:81], v[50:65]
	v_mfma_f32_32x32x16_bf16 v[2:17], v[70:73], v[74:77], v[2:17]
	v_mfma_f32_32x32x16_bf16 v[18:33], v[70:73], v[78:81], v[18:33]
	ds_read_b128 v[66:69], v85 offset:32768
	ds_read_b128 v[70:73], v85 offset:36864
	ds_read_b128 v[74:77], v87 offset:49152
	ds_read_b128 v[78:81], v87 offset:53248
	s_waitcnt vmcnt(0)
	s_waitcnt lgkmcnt(0)
	s_barrier
	v_mfma_f32_32x32x16_bf16 v[34:49], v[66:69], v[74:77], v[34:49]
	v_mfma_f32_32x32x16_bf16 v[50:65], v[66:69], v[78:81], v[50:65]
	v_lshrrev_b32_e32 v66, 1, v83
	v_lshrrev_b32_e32 v68, 3, v82
	v_and_b32_e32 v67, 32, v66
	v_and_b32_e32 v66, 0xffffc0, v66
	v_and_or_b32 v68, v68, 4, s16
	v_add3_u32 v66, v68, v66, v0
	v_or3_b32 v0, s17, v91, v67
	s_nop 3
	v_mul_f32_e32 v67, 0xbfb8aa3b, v34
	v_exp_f32_e32 v67, v67
	v_mfma_f32_32x32x16_bf16 v[2:17], v[70:73], v[74:77], v[2:17]
	v_add_f32_e32 v67, 1.0, v67
	v_rcp_f32_e32 v67, v67
	s_nop 0
	v_mul_f32_e32 v34, v34, v67
	v_mad_u64_u32 v[66:67], s[16:17], v66, s64, v[0:1]
	v_mul_f32_e32 v0, 0xbfb8aa3b, v35
	v_exp_f32_e32 v0, v0
	v_mul_f32_e32 v34, v50, v34
	v_mov_b32_e32 v67, v1
	v_cvt_pk_bf16_f32 v34, v34, s0
	v_add_f32_e32 v0, 1.0, v0
	v_rcp_f32_e32 v0, v0
	v_lshl_add_u64 v[68:69], v[66:67], 1, s[6:7]
	global_store_short v[68:69], v34, off
	v_mfma_f32_32x32x16_bf16 v[18:33], v[70:73], v[78:81], v[18:33]
	v_mul_f32_e32 v0, v35, v0
	v_mul_f32_e32 v0, v51, v0
	v_cvt_pk_bf16_f32 v50, v0, s0
	v_add_u32_e32 v0, 0xb00, v66
	v_lshl_add_u64 v[34:35], v[0:1], 1, s[6:7]
	v_mul_f32_e32 v0, 0xbfb8aa3b, v36
	v_exp_f32_e32 v0, v0
	global_store_short v[34:35], v50, off
	v_add_f32_e32 v0, 1.0, v0
	v_rcp_f32_e32 v0, v0
	s_nop 0
	v_mul_f32_e32 v0, v36, v0
	v_mul_f32_e32 v0, v52, v0
	v_cvt_pk_bf16_f32 v36, v0, s0
	v_add_u32_e32 v0, 0x1600, v66
	v_lshl_add_u64 v[34:35], v[0:1], 1, s[6:7]
	v_mul_f32_e32 v0, 0xbfb8aa3b, v37
	v_exp_f32_e32 v0, v0
	global_store_short v[34:35], v36, off
	v_add_f32_e32 v0, 1.0, v0
	v_rcp_f32_e32 v0, v0
	s_nop 0
	v_mul_f32_e32 v0, v37, v0
	v_mul_f32_e32 v0, v53, v0
	v_cvt_pk_bf16_f32 v36, v0, s0
	v_add_u32_e32 v0, 0x2100, v66
	v_lshl_add_u64 v[34:35], v[0:1], 1, s[6:7]
	v_mul_f32_e32 v0, 0xbfb8aa3b, v38
	v_exp_f32_e32 v0, v0
	global_store_short v[34:35], v36, off
	v_add_f32_e32 v0, 1.0, v0
	v_rcp_f32_e32 v0, v0
	s_nop 0
	v_mul_f32_e32 v0, v38, v0
	v_mul_f32_e32 v0, v54, v0
	v_cvt_pk_bf16_f32 v36, v0, s0
	v_add_u32_e32 v0, 0x5800, v66
	v_lshl_add_u64 v[34:35], v[0:1], 1, s[6:7]
	v_mul_f32_e32 v0, 0xbfb8aa3b, v39
	v_exp_f32_e32 v0, v0
	global_store_short v[34:35], v36, off
	v_add_f32_e32 v0, 1.0, v0
	v_rcp_f32_e32 v0, v0
	s_nop 0
	v_mul_f32_e32 v0, v39, v0
	v_mul_f32_e32 v0, v55, v0
	v_cvt_pk_bf16_f32 v36, v0, s0
	v_add_u32_e32 v0, 0x6300, v66
	v_lshl_add_u64 v[34:35], v[0:1], 1, s[6:7]
	v_mul_f32_e32 v0, 0xbfb8aa3b, v40
	v_exp_f32_e32 v0, v0
	global_store_short v[34:35], v36, off
	v_add_f32_e32 v0, 1.0, v0
	v_rcp_f32_e32 v0, v0
	s_nop 0
	v_mul_f32_e32 v0, v40, v0
	v_mul_f32_e32 v0, v56, v0
	v_cvt_pk_bf16_f32 v36, v0, s0
	v_add_u32_e32 v0, 0x6e00, v66
	v_lshl_add_u64 v[34:35], v[0:1], 1, s[6:7]
	v_mul_f32_e32 v0, 0xbfb8aa3b, v41
	v_exp_f32_e32 v0, v0
	global_store_short v[34:35], v36, off
	v_add_f32_e32 v0, 1.0, v0
	v_rcp_f32_e32 v0, v0
	s_nop 0
	v_mul_f32_e32 v0, v41, v0
	v_mul_f32_e32 v0, v57, v0
	v_cvt_pk_bf16_f32 v36, v0, s0
	v_add_u32_e32 v0, 0x7900, v66
	v_lshl_add_u64 v[34:35], v[0:1], 1, s[6:7]
	global_store_short v[34:35], v36, off
	v_mul_f32_e32 v0, 0xbfb8aa3b, v42
	v_exp_f32_e32 v0, v0
	s_nop 0
	v_add_f32_e32 v0, 1.0, v0
	v_rcp_f32_e32 v0, v0
	s_nop 0
	v_mul_f32_e32 v0, v42, v0
	v_mul_f32_e32 v0, v58, v0
	v_cvt_pk_bf16_f32 v36, v0, s0
	v_add_u32_e32 v0, 0xb000, v66
	v_lshl_add_u64 v[34:35], v[0:1], 1, s[6:7]
	v_mul_f32_e32 v0, 0xbfb8aa3b, v43
	v_exp_f32_e32 v0, v0
	global_store_short v[34:35], v36, off
	v_add_f32_e32 v0, 1.0, v0
	v_rcp_f32_e32 v0, v0
	s_nop 0
	v_mul_f32_e32 v0, v43, v0
	v_mul_f32_e32 v0, v59, v0
	v_cvt_pk_bf16_f32 v36, v0, s0
	v_add_u32_e32 v0, 0xbb00, v66
	v_lshl_add_u64 v[34:35], v[0:1], 1, s[6:7]
	v_mul_f32_e32 v0, 0xbfb8aa3b, v44
	v_exp_f32_e32 v0, v0
	global_store_short v[34:35], v36, off
; template <int AI>
; DI void gu_tile(char* wsb, int sub, int m0, int n0, char* lds) {
;     ...
; #pragma unroll
;   for (int ai = 0; ai < AI; ++ai)
; #pragma unroll
;     for (int reg = 0; reg < 16; ++reg) {
;       float g = acc[ai][0][reg], u = acc[ai][1][reg];
;       float v = g * __builtin_amdgcn_rcpf(1.f + __expf(-g)) * u;
;       HIDu[ib + (unsigned)((ai * 32 + (reg & 3) + 8 * (reg >> 2)) * 2816)] = f2bf(v);
;       if ((reg & 7) == 7) __builtin_amdgcn_sched_barrier(0);
;     }
; }
; DI void phase_gu(const Params& p, char* wsb, int sub, int mrows, char* lds) {
;   int mt, nt;
;   for (int rnd = 0; next_tile(rnd, 128, 44, mt, nt); ++rnd) gu_tile<2>(wsb, sub, mt * 128, nt * 128, lds);
	v_add_f32_e32 v0, 1.0, v0
	v_rcp_f32_e32 v0, v0
	s_nop 0
	v_mul_f32_e32 v0, v44, v0
	v_mul_f32_e32 v0, v60, v0
	v_cvt_pk_bf16_f32 v36, v0, s0
	v_add_u32_e32 v0, 0xc600, v66
	v_lshl_add_u64 v[34:35], v[0:1], 1, s[6:7]
	v_mul_f32_e32 v0, 0xbfb8aa3b, v45
	v_exp_f32_e32 v0, v0
	global_store_short v[34:35], v36, off
	v_add_f32_e32 v0, 1.0, v0
	v_rcp_f32_e32 v0, v0
	s_nop 0
	v_mul_f32_e32 v0, v45, v0
	v_mul_f32_e32 v0, v61, v0
	v_cvt_pk_bf16_f32 v36, v0, s0
	v_add_u32_e32 v0, 0xd100, v66
	v_lshl_add_u64 v[34:35], v[0:1], 1, s[6:7]
	v_mul_f32_e32 v0, 0xbfb8aa3b, v46
	v_exp_f32_e32 v0, v0
	global_store_short v[34:35], v36, off
	v_add_f32_e32 v0, 1.0, v0
	v_rcp_f32_e32 v0, v0
	s_nop 0
	v_mul_f32_e32 v0, v46, v0
	v_mul_f32_e32 v0, v62, v0
	v_cvt_pk_bf16_f32 v36, v0, s0
	v_add_u32_e32 v0, 0x10800, v66
	v_lshl_add_u64 v[34:35], v[0:1], 1, s[6:7]
	v_mul_f32_e32 v0, 0xbfb8aa3b, v47
	v_exp_f32_e32 v0, v0
	global_store_short v[34:35], v36, off
	v_add_f32_e32 v0, 1.0, v0
	v_rcp_f32_e32 v0, v0
	s_nop 0
	v_mul_f32_e32 v0, v47, v0
	v_mul_f32_e32 v0, v63, v0
	v_cvt_pk_bf16_f32 v36, v0, s0
	v_add_u32_e32 v0, 0x11300, v66
	v_lshl_add_u64 v[34:35], v[0:1], 1, s[6:7]
	v_mul_f32_e32 v0, 0xbfb8aa3b, v48
	v_exp_f32_e32 v0, v0
	global_store_short v[34:35], v36, off
	v_add_f32_e32 v0, 1.0, v0
	v_rcp_f32_e32 v0, v0
	s_nop 0
	v_mul_f32_e32 v0, v48, v0
	v_mul_f32_e32 v0, v64, v0
	v_cvt_pk_bf16_f32 v36, v0, s0
	v_add_u32_e32 v0, 0x11e00, v66
	v_lshl_add_u64 v[34:35], v[0:1], 1, s[6:7]
	v_mul_f32_e32 v0, 0xbfb8aa3b, v49
	v_exp_f32_e32 v0, v0
	global_store_short v[34:35], v36, off
	v_add_f32_e32 v0, 1.0, v0
	v_rcp_f32_e32 v0, v0
	s_nop 0
	v_mul_f32_e32 v0, v49, v0
	v_mul_f32_e32 v0, v65, v0
	v_cvt_pk_bf16_f32 v36, v0, s0
	v_add_u32_e32 v0, 0x12900, v66
	v_lshl_add_u64 v[34:35], v[0:1], 1, s[6:7]
	global_store_short v[34:35], v36, off
	v_mul_f32_e32 v0, 0xbfb8aa3b, v2
	v_exp_f32_e32 v0, v0
	s_nop 0
	v_add_f32_e32 v0, 1.0, v0
	v_rcp_f32_e32 v0, v0
	s_nop 0
	v_mul_f32_e32 v0, v2, v0
	v_mul_f32_e32 v0, v18, v0
	v_cvt_pk_bf16_f32 v2, v0, s0
	v_add_u32_e32 v0, 0x16000, v66
	v_lshl_add_u64 v[34:35], v[0:1], 1, s[6:7]
	v_mul_f32_e32 v0, 0xbfb8aa3b, v3
	v_exp_f32_e32 v0, v0
	global_store_short v[34:35], v2, off
	v_add_f32_e32 v0, 1.0, v0
	v_rcp_f32_e32 v0, v0
	s_nop 0
	v_mul_f32_e32 v0, v3, v0
	v_mul_f32_e32 v0, v19, v0
	v_cvt_pk_bf16_f32 v18, v0, s0
	v_add_u32_e32 v0, 0x16b00, v66
	v_lshl_add_u64 v[2:3], v[0:1], 1, s[6:7]
	v_mul_f32_e32 v0, 0xbfb8aa3b, v4
	v_exp_f32_e32 v0, v0
	global_store_short v[2:3], v18, off
	v_add_f32_e32 v0, 1.0, v0
	v_rcp_f32_e32 v0, v0
	s_nop 0
	v_mul_f32_e32 v0, v4, v0
	v_mul_f32_e32 v0, v20, v0
	v_cvt_pk_bf16_f32 v4, v0, s0
	v_add_u32_e32 v0, 0x17600, v66
	v_lshl_add_u64 v[2:3], v[0:1], 1, s[6:7]
	v_mul_f32_e32 v0, 0xbfb8aa3b, v5
	v_exp_f32_e32 v0, v0
	global_store_short v[2:3], v4, off
	v_add_f32_e32 v0, 1.0, v0
	v_rcp_f32_e32 v0, v0
	s_nop 0
	v_mul_f32_e32 v0, v5, v0
	v_mul_f32_e32 v0, v21, v0
	v_cvt_pk_bf16_f32 v4, v0, s0
	v_add_u32_e32 v0, 0x18100, v66
	v_lshl_add_u64 v[2:3], v[0:1], 1, s[6:7]
	v_mul_f32_e32 v0, 0xbfb8aa3b, v6
	v_exp_f32_e32 v0, v0
	global_store_short v[2:3], v4, off
	v_add_f32_e32 v0, 1.0, v0
	v_rcp_f32_e32 v0, v0
	s_nop 0
	v_mul_f32_e32 v0, v6, v0
	v_mul_f32_e32 v0, v22, v0
	v_cvt_pk_bf16_f32 v4, v0, s0
	v_add_u32_e32 v0, 0x1b800, v66
	v_lshl_add_u64 v[2:3], v[0:1], 1, s[6:7]
	v_mul_f32_e32 v0, 0xbfb8aa3b, v7
	v_exp_f32_e32 v0, v0
	global_store_short v[2:3], v4, off
	v_add_f32_e32 v0, 1.0, v0
	v_rcp_f32_e32 v0, v0
	s_nop 0
	v_mul_f32_e32 v0, v7, v0
	v_mul_f32_e32 v0, v23, v0
	v_cvt_pk_bf16_f32 v4, v0, s0
	v_add_u32_e32 v0, 0x1c300, v66
	v_lshl_add_u64 v[2:3], v[0:1], 1, s[6:7]
	v_mul_f32_e32 v0, 0xbfb8aa3b, v8
	v_exp_f32_e32 v0, v0
	global_store_short v[2:3], v4, off
	v_add_f32_e32 v0, 1.0, v0
	v_rcp_f32_e32 v0, v0
	s_nop 0
	v_mul_f32_e32 v0, v8, v0
	v_mul_f32_e32 v0, v24, v0
	v_cvt_pk_bf16_f32 v4, v0, s0
	v_add_u32_e32 v0, 0x1ce00, v66
	v_lshl_add_u64 v[2:3], v[0:1], 1, s[6:7]
	v_mul_f32_e32 v0, 0xbfb8aa3b, v9
	v_exp_f32_e32 v0, v0
	global_store_short v[2:3], v4, off
	v_add_f32_e32 v0, 1.0, v0
	v_rcp_f32_e32 v0, v0
	s_nop 0
	v_mul_f32_e32 v0, v9, v0
	v_mul_f32_e32 v0, v25, v0
	v_cvt_pk_bf16_f32 v4, v0, s0
	v_add_u32_e32 v0, 0x1d900, v66
	v_lshl_add_u64 v[2:3], v[0:1], 1, s[6:7]
	global_store_short v[2:3], v4, off
	v_mul_f32_e32 v0, 0xbfb8aa3b, v10
	v_exp_f32_e32 v0, v0
	s_nop 0
	v_add_f32_e32 v0, 1.0, v0
	v_rcp_f32_e32 v0, v0
	s_nop 0
	v_mul_f32_e32 v0, v10, v0
	v_mul_f32_e32 v0, v26, v0
	v_cvt_pk_bf16_f32 v4, v0, s0
	v_add_u32_e32 v0, 0x21000, v66
	v_lshl_add_u64 v[2:3], v[0:1], 1, s[6:7]
	v_mul_f32_e32 v0, 0xbfb8aa3b, v11
	v_exp_f32_e32 v0, v0
	global_store_short v[2:3], v4, off
	v_add_f32_e32 v0, 1.0, v0
	v_rcp_f32_e32 v0, v0
	s_nop 0
	v_mul_f32_e32 v0, v11, v0
	v_mul_f32_e32 v0, v27, v0
	v_cvt_pk_bf16_f32 v4, v0, s0
	v_add_u32_e32 v0, 0x21b00, v66
	v_lshl_add_u64 v[2:3], v[0:1], 1, s[6:7]
	v_mul_f32_e32 v0, 0xbfb8aa3b, v12
	v_exp_f32_e32 v0, v0
	global_store_short v[2:3], v4, off
	v_add_f32_e32 v0, 1.0, v0
	v_rcp_f32_e32 v0, v0
	s_nop 0
	v_mul_f32_e32 v0, v12, v0
	v_mul_f32_e32 v0, v28, v0
	v_cvt_pk_bf16_f32 v4, v0, s0
	v_add_u32_e32 v0, 0x22600, v66
	v_lshl_add_u64 v[2:3], v[0:1], 1, s[6:7]
	v_mul_f32_e32 v0, 0xbfb8aa3b, v13
	v_exp_f32_e32 v0, v0
	global_store_short v[2:3], v4, off
	v_add_f32_e32 v0, 1.0, v0
	v_rcp_f32_e32 v0, v0
	s_nop 0
	v_mul_f32_e32 v0, v13, v0
	v_mul_f32_e32 v0, v29, v0
	v_cvt_pk_bf16_f32 v4, v0, s0
	v_add_u32_e32 v0, 0x23100, v66
	v_lshl_add_u64 v[2:3], v[0:1], 1, s[6:7]
	v_mul_f32_e32 v0, 0xbfb8aa3b, v14
	v_exp_f32_e32 v0, v0
	global_store_short v[2:3], v4, off
	v_add_f32_e32 v0, 1.0, v0
	v_rcp_f32_e32 v0, v0
	s_nop 0
	v_mul_f32_e32 v0, v14, v0
	v_mul_f32_e32 v0, v30, v0
	v_cvt_pk_bf16_f32 v4, v0, s0
	v_add_u32_e32 v0, 0x26800, v66
	v_lshl_add_u64 v[2:3], v[0:1], 1, s[6:7]
	v_mul_f32_e32 v0, 0xbfb8aa3b, v15
	v_exp_f32_e32 v0, v0
	global_store_short v[2:3], v4, off
	v_add_f32_e32 v0, 1.0, v0
	v_rcp_f32_e32 v0, v0
	s_nop 0
	v_mul_f32_e32 v0, v15, v0
	v_mul_f32_e32 v0, v31, v0
	v_cvt_pk_bf16_f32 v4, v0, s0
	v_add_u32_e32 v0, 0x27300, v66
	v_lshl_add_u64 v[2:3], v[0:1], 1, s[6:7]
	v_mul_f32_e32 v0, 0xbfb8aa3b, v16
	v_exp_f32_e32 v0, v0
	global_store_short v[2:3], v4, off
	v_add_f32_e32 v0, 1.0, v0
	v_rcp_f32_e32 v0, v0
	s_nop 0
	v_mul_f32_e32 v0, v16, v0
	v_mul_f32_e32 v0, v32, v0
	v_cvt_pk_bf16_f32 v4, v0, s0
	v_add_u32_e32 v0, 0x27e00, v66
	v_lshl_add_u64 v[2:3], v[0:1], 1, s[6:7]
	v_mul_f32_e32 v0, 0xbfb8aa3b, v17
	v_exp_f32_e32 v0, v0
	global_store_short v[2:3], v4, off
	v_add_f32_e32 v0, 1.0, v0
	v_rcp_f32_e32 v0, v0
	s_nop 0
	v_mul_f32_e32 v0, v17, v0
	v_mul_f32_e32 v0, v33, v0
	v_cvt_pk_bf16_f32 v4, v0, s0
	v_add_u32_e32 v0, 0x28900, v66
	v_lshl_add_u64 v[2:3], v[0:1], 1, s[6:7]
	global_store_short v[2:3], v4, off
	v_readlane_b32 s16, v245, 0
	s_cmp_eq_u32 s16, 1
	s_cbranch_scc1 .Lgu2_done
	s_add_i32 s15, s15, s53
	s_add_i32 s14, s14, s56
	s_cmpk_lt_u32 s14, 0x1600
	s_cbranch_scc1 .LBB0_1206
; DI void phase_gu(const Params& p, char* wsb, int sub, int mrows, char* lds) {
;   int mt, nt;
;   for (int rnd = 0; next_tile(rnd, 128, 44, mt, nt); ++rnd) gu_tile<2>(wsb, sub, mt * 128, nt * 128, lds);
;   if (mrows > TL)
;     for (int rnd = 0; next_tile(rnd, 32, 44, mt, nt); ++rnd) gu_tile<1>(wsb, sub, TL + mt * 64, nt * 128, lds);
.Lgu2_done:
	v_readlane_b32 s28, v243, 45
	v_readlane_b32 s34, v243, 47
	v_readlane_b32 s29, v243, 46
	v_readlane_b32 s35, v243, 48

; #define MFMA(a, b, c) __builtin_amdgcn_mfma_f32_32x32x16_bf16((a), (b), (c), 0, 0, 0)
; #define GAS __attribute__((address_space(1)))
; DI int opaque0() { int z = 0; asm volatile("" : "+v"(z)); return z; }
; template <int AI, int BI>
; DI void gemm_tile(const u16* __restrict__ A, int lda, const u16* __restrict__ B, int ldb, int nk, bool swap,
;                   f32x16 (&acc)[AI][BI], char* lds) {
;     ...
;   for (int kt = 0; kt < nk; ++kt) {
;     const char* cur = lds + (kt & 1) * 32768;
;     if (kt + 1 < nk) gemm_stage<AI, BI>(A + (kt + 1) * 64, lda, B + (kt + 1) * 64, ldb, lds + ((kt + 1) & 1) * 32768, tid);
; #pragma unroll
;     for (int ks = 0; ks < 4; ++ks) {
;       const int co = ((ks * 2 + h) ^ sw) << 4;
;       s16x8 fa[AI], fb[BI];
; #pragma unroll
;       for (int i = 0; i < AI; ++i) fa[i] = *(const s16x8*)(cur + offA + i * 4096 + co);
; #pragma unroll
;       for (int i = 0; i < BI; ++i) fb[i] = *(const s16x8*)(cur + offB + i * 4096 + co);
; #pragma unroll
;       for (int i = 0; i < AI; ++i)
; #pragma unroll
;         for (int j = 0; j < BI; ++j) acc[i][j] = MFMA(fa[i], fb[j], acc[i][j]);
;     }
;     asm volatile("s_waitcnt vmcnt(0)" ::: "memory");
;     __syncthreads();
;   }
; template <int AI, int BI>
; DI void dn_tile(const Params& p, char* wsb, int layer, int sub, bool final_out, int m0, int n0, char* lds) {
;     ...
;   const int m0e = m0 + opaque0();
;   const int mr = m0 < TL ? (m0 >> 11) : 8;
;   const float* gate = mods + (size_t)mr * 9216 + (2 + 6 * sub) * 1024;
;   GAS float* xsu = uptr(xs);
.LBB0_1264:
	s_add_i32 s15, s13, 0xffff8000
	s_and_b32 s41, s15, 0x8000
	s_and_b32 s15, s13, 0x8000
	v_add_u32_e32 v93, s15, v85
	v_add_u32_e32 v96, s15, v86
	v_readfirstlane_b32 s46, v93
	v_lshl_add_u64 v[94:95], v[66:67], 0, s[6:7]
	s_mov_b32 m0, s46
	v_readfirstlane_b32 s46, v96
	v_add_u32_e32 v97, s15, v87
	global_load_lds_dwordx4 v[94:95], off
	v_lshl_add_u64 v[94:95], v[68:69], 0, s[6:7]
	s_mov_b32 m0, s46
	v_readfirstlane_b32 s46, v97
	v_add_u32_e32 v98, s15, v89
	global_load_lds_dwordx4 v[94:95], off
	v_lshl_add_u64 v[94:95], v[70:71], 0, s[6:7]
	s_mov_b32 m0, s46
	v_readfirstlane_b32 s46, v98
	v_add_u32_e32 v93, 0x4000, v93
	global_load_lds_dwordx4 v[94:95], off
	v_lshl_add_u64 v[94:95], v[72:73], 0, s[6:7]
	s_mov_b32 m0, s46
	v_readfirstlane_b32 s46, v93
	v_add_u32_e32 v93, 0x4000, v96
	global_load_lds_dwordx4 v[94:95], off
	v_lshl_add_u64 v[94:95], v[74:75], 0, s[6:7]
	s_mov_b32 m0, s46
	v_readfirstlane_b32 s46, v93
	v_add_u32_e32 v93, 0x4000, v97
	global_load_lds_dwordx4 v[94:95], off
	v_lshl_add_u64 v[94:95], v[76:77], 0, s[6:7]
	s_mov_b32 m0, s46
	v_readfirstlane_b32 s46, v93
	v_add_u32_e32 v93, 0x4000, v98
	global_load_lds_dwordx4 v[94:95], off
	v_lshl_add_u64 v[94:95], v[78:79], 0, s[6:7]
	s_mov_b32 m0, s46
	v_readfirstlane_b32 s46, v93
	global_load_lds_dwordx4 v[94:95], off
	v_lshl_add_u64 v[94:95], v[80:81], 0, s[6:7]
	s_mov_b32 m0, s46
	v_add_u32_e32 v93, s41, v91
	global_load_lds_dwordx4 v[94:95], off
	v_or_b32_e32 v110, s41, v92
	v_add_u32_e32 v98, v93, v90
	v_add_u32_e32 v106, v110, v90
	ds_read_b128 v[94:97], v98
	ds_read_b128 v[98:101], v98 offset:4096
	ds_read_b128 v[102:105], v106 offset:16384
	ds_read_b128 v[106:109], v106 offset:20480
	s_waitcnt lgkmcnt(0)
	v_mfma_f32_32x32x16_bf16 v[50:65], v[94:97], v[102:105], v[50:65]
	s_add_u32 s6, s6, 0x80
	s_addc_u32 s7, s7, 0
	s_add_i32 s13, s13, 0x8000
	s_cmpk_eq_i32 s6, 0x1580
	v_mfma_f32_32x32x16_bf16 v[18:33], v[94:97], v[106:109], v[18:33]
	v_mfma_f32_32x32x16_bf16 v[34:49], v[98:101], v[102:105], v[34:49]
	v_mfma_f32_32x32x16_bf16 v[2:17], v[98:101], v[106:109], v[2:17]
	v_add_u32_e32 v98, v93, v88
	v_add_u32_e32 v106, v110, v88
	ds_read_b128 v[94:97], v98
	ds_read_b128 v[98:101], v98 offset:4096
	ds_read_b128 v[102:105], v106 offset:16384
	ds_read_b128 v[106:109], v106 offset:20480
	s_waitcnt lgkmcnt(1)
	v_mfma_f32_32x32x16_bf16 v[50:65], v[94:97], v[102:105], v[50:65]
	s_waitcnt lgkmcnt(0)
	v_mfma_f32_32x32x16_bf16 v[18:33], v[94:97], v[106:109], v[18:33]
	v_mfma_f32_32x32x16_bf16 v[34:49], v[98:101], v[102:105], v[34:49]
	v_mfma_f32_32x32x16_bf16 v[2:17], v[98:101], v[106:109], v[2:17]
	v_add_u32_e32 v98, v93, v84
	v_add_u32_e32 v106, v110, v84
	ds_read_b128 v[94:97], v98
	ds_read_b128 v[98:101], v98 offset:4096
	ds_read_b128 v[102:105], v106 offset:16384
	ds_read_b128 v[106:109], v106 offset:20480
	v_add_u32_e32 v93, v93, v0
	s_waitcnt lgkmcnt(1)
	v_mfma_f32_32x32x16_bf16 v[50:65], v[94:97], v[102:105], v[50:65]
	s_waitcnt lgkmcnt(0)
	v_mfma_f32_32x32x16_bf16 v[18:33], v[94:97], v[106:109], v[18:33]
	v_mfma_f32_32x32x16_bf16 v[34:49], v[98:101], v[102:105], v[34:49]
	v_mfma_f32_32x32x16_bf16 v[2:17], v[98:101], v[106:109], v[2:17]
	ds_read_b128 v[94:97], v93
	ds_read_b128 v[98:101], v93 offset:4096
	v_add_u32_e32 v93, v110, v0
	ds_read_b128 v[102:105], v93 offset:16384
	ds_read_b128 v[106:109], v93 offset:20480
	s_waitcnt vmcnt(0)
	s_waitcnt lgkmcnt(0)
	s_barrier
	v_mfma_f32_32x32x16_bf16 v[50:65], v[94:97], v[102:105], v[50:65]
	v_mfma_f32_32x32x16_bf16 v[18:33], v[94:97], v[106:109], v[18:33]
	v_mfma_f32_32x32x16_bf16 v[34:49], v[98:101], v[102:105], v[34:49]
	v_mfma_f32_32x32x16_bf16 v[2:17], v[98:101], v[106:109], v[2:17]
	s_cbranch_scc0 .LBB0_1264
	v_add_u32_e32 v86, s15, v91
	v_add_u32_e32 v87, s15, v92
	v_add_u32_e32 v70, v86, v90
	v_add_u32_e32 v78, v87, v90
	ds_read_b128 v[66:69], v70
	ds_read_b128 v[70:73], v70 offset:4096
	ds_read_b128 v[74:77], v78 offset:16384
	ds_read_b128 v[78:81], v78 offset:20480
	s_waitcnt lgkmcnt(1)
	v_mfma_f32_32x32x16_bf16 v[50:65], v[66:69], v[74:77], v[50:65]
	s_lshr_b32 s7, s40, 7
	s_lshl_b32 s6, s12, 7
	s_mul_i32 s7, s7, 0x9000
	v_and_b32_e32 v85, 31, v82
	s_add_u32 s7, s34, s7
	s_addc_u32 s13, s35, 0
	s_add_u32 s12, s7, 0xc000
	s_waitcnt lgkmcnt(0)
	v_mfma_f32_32x32x16_bf16 v[18:33], v[66:69], v[78:81], v[18:33]
	s_addc_u32 s13, s13, 0
	s_and_b64 vcc, exec, s[48:49]
	v_mfma_f32_32x32x16_bf16 v[34:49], v[70:73], v[74:77], v[34:49]
	v_mfma_f32_32x32x16_bf16 v[2:17], v[70:73], v[78:81], v[2:17]
	v_add_u32_e32 v70, v86, v88
	v_add_u32_e32 v78, v87, v88
	ds_read_b128 v[66:69], v70
	ds_read_b128 v[70:73], v70 offset:4096
	ds_read_b128 v[74:77], v78 offset:16384
	ds_read_b128 v[78:81], v78 offset:20480
	s_waitcnt lgkmcnt(1)
	v_mfma_f32_32x32x16_bf16 v[50:65], v[66:69], v[74:77], v[50:65]
	s_waitcnt lgkmcnt(0)
	v_mfma_f32_32x32x16_bf16 v[18:33], v[66:69], v[78:81], v[18:33]
	v_mfma_f32_32x32x16_bf16 v[34:49], v[70:73], v[74:77], v[34:49]
	v_mfma_f32_32x32x16_bf16 v[2:17], v[70:73], v[78:81], v[2:17]
	v_add_u32_e32 v70, v86, v84
	v_add_u32_e32 v78, v87, v84
	ds_read_b128 v[66:69], v70
	ds_read_b128 v[70:73], v70 offset:4096
	ds_read_b128 v[74:77], v78 offset:16384
	ds_read_b128 v[78:81], v78 offset:20480
	s_waitcnt lgkmcnt(1)
	v_mfma_f32_32x32x16_bf16 v[50:65], v[66:69], v[74:77], v[50:65]
	s_waitcnt lgkmcnt(0)
	v_mfma_f32_32x32x16_bf16 v[18:33], v[66:69], v[78:81], v[18:33]
	v_mfma_f32_32x32x16_bf16 v[34:49], v[70:73], v[74:77], v[34:49]
	v_mfma_f32_32x32x16_bf16 v[2:17], v[70:73], v[78:81], v[2:17]
	v_add_u32_e32 v70, v86, v0
	v_add_u32_e32 v0, v87, v0
	ds_read_b128 v[66:69], v70
	ds_read_b128 v[70:73], v70 offset:4096
	ds_read_b128 v[74:77], v0 offset:16384
	ds_read_b128 v[78:81], v0 offset:20480
	v_mov_b32_e32 v0, v1
	s_waitcnt vmcnt(0)
	s_waitcnt lgkmcnt(0)
	v_mfma_f32_32x32x16_bf16 v[50:65], v[66:69], v[74:77], v[50:65]
	s_barrier
; #define GAS __attribute__((address_space(1)))
; DI int opaque0() { int z = 0; asm volatile("" : "+v"(z)); return z; }
; template <int AI, int BI>
; DI void dn_tile(const Params& p, char* wsb, int layer, int sub, bool final_out, int m0, int n0, char* lds) {
;     ...
;   const int m0e = m0 + opaque0();
;   const int mr = m0 < TL ? (m0 >> 11) : 8;
;   const float* gate = mods + (size_t)mr * 9216 + (2 + 6 * sub) * 1024;
;   GAS float* xsu = uptr(xs);
;   GAS float* outu = uptr(p.out);
; #pragma unroll
;   for (int bi = 0; bi < BI; ++bi) {
;     const int n = n0 + wb * 32 * BI + bi * 32 + r;
;     const float gv = 0.5f * gate[n];
;     const unsigned ib = (unsigned)((m0e + wa * 32 * AI + 4 * h) * 1024 + n);
; #pragma unroll
;     for (int ai = 0; ai < AI; ++ai)
; #pragma unroll
;       for (int reg = 0; reg < 16; ++reg) {
;         const unsigned idx = ib + (unsigned)((ai * 32 + (reg & 3) + 8 * (reg >> 2)) * 1024);
;         float v = xsu[idx] + gv * acc[ai][bi][reg];
;         if (final_out) outu[idx] = v; else xsu[idx] = v;
;         if ((reg & 7) == 7) __builtin_amdgcn_sched_barrier(0);
;       }
;   }
	v_mfma_f32_32x32x16_bf16 v[18:33], v[66:69], v[78:81], v[18:33]
	v_mfma_f32_32x32x16_bf16 v[34:49], v[70:73], v[74:77], v[34:49]
	v_mfma_f32_32x32x16_bf16 v[2:17], v[70:73], v[78:81], v[2:17]
	v_and_b32_e32 v143, 31, v178
	v_and_b32_e32 v140, 64, v178
	v_or_b32_e32 v140, v140, v143
	v_bfe_u32 v143, v178, 5, 1
	v_bfe_u32 v139, v178, 7, 1
	v_lshlrev_b32_e32 v139, 6, v139
	v_lshl_add_u32 v139, v143, 2, v139
	v_lshl_add_u32 v139, v139, 10, v140
	v_lshlrev_b32_e32 v139, 2, v139
	v_add_u32_e32 v140, s14, v140
	v_lshlrev_b32_e32 v140, 2, v140
	global_load_dword v141, v140, s[12:13]
	global_load_dword v142, v140, s[12:13] offset:128
	s_lshl_b32 s56, s6, 10
	s_add_u32 s56, s56, s14
	s_lshl_b32 s56, s56, 2
	s_add_u32 s54, s8, s56
	s_addc_u32 s55, s9, 0
	s_mov_b64 s[52:53], s[54:55]
	global_load_dword v66, v139, s[52:53]
	global_load_dword v67, v139, s[52:53] offset:128
	s_add_u32 s52, s52, 4096
	s_addc_u32 s53, s53, 0
	global_load_dword v68, v139, s[52:53]
	global_load_dword v69, v139, s[52:53] offset:128
	s_add_u32 s52, s52, 4096
	s_addc_u32 s53, s53, 0
	global_load_dword v70, v139, s[52:53]
	global_load_dword v71, v139, s[52:53] offset:128
	s_add_u32 s52, s52, 4096
	s_addc_u32 s53, s53, 0
	global_load_dword v72, v139, s[52:53]
	global_load_dword v73, v139, s[52:53] offset:128
	s_add_u32 s52, s52, 20480
	s_addc_u32 s53, s53, 0
	global_load_dword v74, v139, s[52:53]
	global_load_dword v75, v139, s[52:53] offset:128
	s_add_u32 s52, s52, 4096
	s_addc_u32 s53, s53, 0
	global_load_dword v76, v139, s[52:53]
	global_load_dword v77, v139, s[52:53] offset:128
	s_add_u32 s52, s52, 4096
	s_addc_u32 s53, s53, 0
	global_load_dword v78, v139, s[52:53]
	global_load_dword v79, v139, s[52:53] offset:128
	s_add_u32 s52, s52, 4096
	s_addc_u32 s53, s53, 0
	global_load_dword v80, v139, s[52:53]
	global_load_dword v81, v139, s[52:53] offset:128
	s_add_u32 s52, s52, 20480
	s_addc_u32 s53, s53, 0
	global_load_dword v82, v139, s[52:53]
	global_load_dword v83, v139, s[52:53] offset:128
	s_add_u32 s52, s52, 4096
	s_addc_u32 s53, s53, 0
	global_load_dword v84, v139, s[52:53]
	global_load_dword v85, v139, s[52:53] offset:128
	s_add_u32 s52, s52, 4096
	s_addc_u32 s53, s53, 0
	global_load_dword v86, v139, s[52:53]
	global_load_dword v87, v139, s[52:53] offset:128
	s_add_u32 s52, s52, 4096
	s_addc_u32 s53, s53, 0
	global_load_dword v88, v139, s[52:53]
	global_load_dword v89, v139, s[52:53] offset:128
	s_add_u32 s52, s52, 20480
	s_addc_u32 s53, s53, 0
	global_load_dword v90, v139, s[52:53]
	global_load_dword v91, v139, s[52:53] offset:128
	s_add_u32 s52, s52, 4096
	s_addc_u32 s53, s53, 0
	global_load_dword v92, v139, s[52:53]
	global_load_dword v93, v139, s[52:53] offset:128
	s_add_u32 s52, s52, 4096
	s_addc_u32 s53, s53, 0
	global_load_dword v94, v139, s[52:53]
	global_load_dword v95, v139, s[52:53] offset:128
	s_add_u32 s52, s52, 4096
	s_addc_u32 s53, s53, 0
	global_load_dword v96, v139, s[52:53]
	global_load_dword v97, v139, s[52:53] offset:128
	s_add_u32 s52, s52, 20480
	s_addc_u32 s53, s53, 0
	global_load_dword v98, v139, s[52:53]
	global_load_dword v99, v139, s[52:53] offset:128
	s_add_u32 s52, s52, 4096
	s_addc_u32 s53, s53, 0
	global_load_dword v100, v139, s[52:53]
	global_load_dword v101, v139, s[52:53] offset:128
	s_add_u32 s52, s52, 4096
	s_addc_u32 s53, s53, 0
	global_load_dword v102, v139, s[52:53]
	global_load_dword v103, v139, s[52:53] offset:128
	s_add_u32 s52, s52, 4096
	s_addc_u32 s53, s53, 0
	global_load_dword v104, v139, s[52:53]
	global_load_dword v105, v139, s[52:53] offset:128
	s_add_u32 s52, s52, 20480
	s_addc_u32 s53, s53, 0
	global_load_dword v106, v139, s[52:53]
	global_load_dword v107, v139, s[52:53] offset:128
	s_add_u32 s52, s52, 4096
	s_addc_u32 s53, s53, 0
	global_load_dword v108, v139, s[52:53]
	global_load_dword v109, v139, s[52:53] offset:128
	s_add_u32 s52, s52, 4096
	s_addc_u32 s53, s53, 0
	global_load_dword v110, v139, s[52:53]
	global_load_dword v111, v139, s[52:53] offset:128
	s_add_u32 s52, s52, 4096
	s_addc_u32 s53, s53, 0
	global_load_dword v112, v139, s[52:53]
	global_load_dword v113, v139, s[52:53] offset:128
	s_add_u32 s52, s52, 20480
	s_addc_u32 s53, s53, 0
	global_load_dword v114, v139, s[52:53]
	global_load_dword v115, v139, s[52:53] offset:128
	s_add_u32 s52, s52, 4096
	s_addc_u32 s53, s53, 0
	global_load_dword v116, v139, s[52:53]
	global_load_dword v117, v139, s[52:53] offset:128
	s_add_u32 s52, s52, 4096
	s_addc_u32 s53, s53, 0
	global_load_dword v118, v139, s[52:53]
	global_load_dword v119, v139, s[52:53] offset:128
	s_add_u32 s52, s52, 4096
	s_addc_u32 s53, s53, 0
	global_load_dword v120, v139, s[52:53]
	global_load_dword v121, v139, s[52:53] offset:128
	s_add_u32 s52, s52, 20480
	s_addc_u32 s53, s53, 0
	global_load_dword v122, v139, s[52:53]
	global_load_dword v123, v139, s[52:53] offset:128
	s_add_u32 s52, s52, 4096
	s_addc_u32 s53, s53, 0
	global_load_dword v124, v139, s[52:53]
	global_load_dword v134, v139, s[52:53] offset:128
	s_add_u32 s52, s52, 4096
	s_addc_u32 s53, s53, 0
	global_load_dword v135, v139, s[52:53]
	global_load_dword v136, v139, s[52:53] offset:128
	s_add_u32 s52, s52, 4096
	s_addc_u32 s53, s53, 0
	global_load_dword v137, v139, s[52:53]
	global_load_dword v138, v139, s[52:53] offset:128
	s_waitcnt vmcnt(48)
	v_mul_f32_e32 v141, 0.5, v141
	v_mul_f32_e32 v142, 0.5, v142
	v_fmac_f32_e32 v66, v50, v141
	v_fmac_f32_e32 v67, v18, v142
	v_fmac_f32_e32 v68, v51, v141
	v_fmac_f32_e32 v69, v19, v142
	v_fmac_f32_e32 v70, v52, v141
	v_fmac_f32_e32 v71, v20, v142
	v_fmac_f32_e32 v72, v53, v141
	v_fmac_f32_e32 v73, v21, v142
	v_fmac_f32_e32 v74, v54, v141
	v_fmac_f32_e32 v75, v22, v142
	v_fmac_f32_e32 v76, v55, v141
	v_fmac_f32_e32 v77, v23, v142
	v_fmac_f32_e32 v78, v56, v141
	v_fmac_f32_e32 v79, v24, v142
	v_fmac_f32_e32 v80, v57, v141
	v_fmac_f32_e32 v81, v25, v142
	s_waitcnt vmcnt(32)
; #define GAS __attribute__((address_space(1)))
; DI int opaque0() { int z = 0; asm volatile("" : "+v"(z)); return z; }
; template <int AI, int BI>
; DI void dn_tile(const Params& p, char* wsb, int layer, int sub, bool final_out, int m0, int n0, char* lds) {
;     ...
;   const int m0e = m0 + opaque0();
;   const int mr = m0 < TL ? (m0 >> 11) : 8;
;   const float* gate = mods + (size_t)mr * 9216 + (2 + 6 * sub) * 1024;
;   GAS float* xsu = uptr(xs);
;   GAS float* outu = uptr(p.out);
; #pragma unroll
;   for (int bi = 0; bi < BI; ++bi) {
;     const int n = n0 + wb * 32 * BI + bi * 32 + r;
;     const float gv = 0.5f * gate[n];
;     const unsigned ib = (unsigned)((m0e + wa * 32 * AI + 4 * h) * 1024 + n);
; #pragma unroll
;     for (int ai = 0; ai < AI; ++ai)
; #pragma unroll
;       for (int reg = 0; reg < 16; ++reg) {
;         const unsigned idx = ib + (unsigned)((ai * 32 + (reg & 3) + 8 * (reg >> 2)) * 1024);
;         float v = xsu[idx] + gv * acc[ai][bi][reg];
;         if (final_out) outu[idx] = v; else xsu[idx] = v;
;         if ((reg & 7) == 7) __builtin_amdgcn_sched_barrier(0);
;       }
;   }
	v_fmac_f32_e32 v82, v58, v141
	v_fmac_f32_e32 v83, v26, v142
	v_fmac_f32_e32 v84, v59, v141
	v_fmac_f32_e32 v85, v27, v142
	v_fmac_f32_e32 v86, v60, v141
	v_fmac_f32_e32 v87, v28, v142
	v_fmac_f32_e32 v88, v61, v141
	v_fmac_f32_e32 v89, v29, v142
	v_fmac_f32_e32 v90, v62, v141
	v_fmac_f32_e32 v91, v30, v142
	v_fmac_f32_e32 v92, v63, v141
	v_fmac_f32_e32 v93, v31, v142
	v_fmac_f32_e32 v94, v64, v141
	v_fmac_f32_e32 v95, v32, v142
	v_fmac_f32_e32 v96, v65, v141
	v_fmac_f32_e32 v97, v33, v142
	s_waitcnt vmcnt(16)
	v_fmac_f32_e32 v98, v34, v141
	v_fmac_f32_e32 v99, v2, v142
	v_fmac_f32_e32 v100, v35, v141
	v_fmac_f32_e32 v101, v3, v142
	v_fmac_f32_e32 v102, v36, v141
	v_fmac_f32_e32 v103, v4, v142
	v_fmac_f32_e32 v104, v37, v141
	v_fmac_f32_e32 v105, v5, v142
	v_fmac_f32_e32 v106, v38, v141
	v_fmac_f32_e32 v107, v6, v142
	v_fmac_f32_e32 v108, v39, v141
	v_fmac_f32_e32 v109, v7, v142
	v_fmac_f32_e32 v110, v40, v141
	v_fmac_f32_e32 v111, v8, v142
	v_fmac_f32_e32 v112, v41, v141
	v_fmac_f32_e32 v113, v9, v142
	s_waitcnt vmcnt(0)
	v_fmac_f32_e32 v114, v42, v141
	v_fmac_f32_e32 v115, v10, v142
	v_fmac_f32_e32 v116, v43, v141
	v_fmac_f32_e32 v117, v11, v142
	v_fmac_f32_e32 v118, v44, v141
	v_fmac_f32_e32 v119, v12, v142
	v_fmac_f32_e32 v120, v45, v141
	v_fmac_f32_e32 v121, v13, v142
	v_fmac_f32_e32 v122, v46, v141
	v_fmac_f32_e32 v123, v14, v142
	v_fmac_f32_e32 v124, v47, v141
	v_fmac_f32_e32 v134, v15, v142
	v_fmac_f32_e32 v135, v48, v141
	v_fmac_f32_e32 v136, v16, v142
	v_fmac_f32_e32 v137, v49, v141
	v_fmac_f32_e32 v138, v17, v142
	s_and_b64 s[64:65], s[48:49], exec
	s_cselect_b32 s64, s8, s24
	s_cselect_b32 s65, s9, s25
	s_add_u32 s54, s64, s56
	s_addc_u32 s55, s65, 0
	s_mov_b64 s[52:53], s[54:55]
	global_store_dword v139, v66, s[52:53]
	global_store_dword v139, v67, s[52:53] offset:128
	s_add_u32 s52, s52, 4096
	s_addc_u32 s53, s53, 0
	global_store_dword v139, v68, s[52:53]
	global_store_dword v139, v69, s[52:53] offset:128
	s_add_u32 s52, s52, 4096
	s_addc_u32 s53, s53, 0
	global_store_dword v139, v70, s[52:53]
	global_store_dword v139, v71, s[52:53] offset:128
	s_add_u32 s52, s52, 4096
	s_addc_u32 s53, s53, 0
	global_store_dword v139, v72, s[52:53]
	global_store_dword v139, v73, s[52:53] offset:128
	s_add_u32 s52, s52, 20480
	s_addc_u32 s53, s53, 0
	global_store_dword v139, v74, s[52:53]
	global_store_dword v139, v75, s[52:53] offset:128
	s_add_u32 s52, s52, 4096
	s_addc_u32 s53, s53, 0
	global_store_dword v139, v76, s[52:53]
	global_store_dword v139, v77, s[52:53] offset:128
	s_add_u32 s52, s52, 4096
	s_addc_u32 s53, s53, 0
	global_store_dword v139, v78, s[52:53]
	global_store_dword v139, v79, s[52:53] offset:128
	s_add_u32 s52, s52, 4096
	s_addc_u32 s53, s53, 0
	global_store_dword v139, v80, s[52:53]
	global_store_dword v139, v81, s[52:53] offset:128
	s_add_u32 s52, s52, 20480
	s_addc_u32 s53, s53, 0
	global_store_dword v139, v82, s[52:53]
	global_store_dword v139, v83, s[52:53] offset:128
	s_add_u32 s52, s52, 4096
	s_addc_u32 s53, s53, 0
	global_store_dword v139, v84, s[52:53]
	global_store_dword v139, v85, s[52:53] offset:128
	s_add_u32 s52, s52, 4096
	s_addc_u32 s53, s53, 0
	global_store_dword v139, v86, s[52:53]
	global_store_dword v139, v87, s[52:53] offset:128
	s_add_u32 s52, s52, 4096
	s_addc_u32 s53, s53, 0
	global_store_dword v139, v88, s[52:53]
	global_store_dword v139, v89, s[52:53] offset:128
	s_add_u32 s52, s52, 20480
	s_addc_u32 s53, s53, 0
	global_store_dword v139, v90, s[52:53]
	global_store_dword v139, v91, s[52:53] offset:128
	s_add_u32 s52, s52, 4096
	s_addc_u32 s53, s53, 0
	global_store_dword v139, v92, s[52:53]
	global_store_dword v139, v93, s[52:53] offset:128
	s_add_u32 s52, s52, 4096
	s_addc_u32 s53, s53, 0
	global_store_dword v139, v94, s[52:53]
	global_store_dword v139, v95, s[52:53] offset:128
	s_add_u32 s52, s52, 4096
	s_addc_u32 s53, s53, 0
	global_store_dword v139, v96, s[52:53]
	global_store_dword v139, v97, s[52:53] offset:128
	s_add_u32 s52, s52, 20480
	s_addc_u32 s53, s53, 0
	global_store_dword v139, v98, s[52:53]
	global_store_dword v139, v99, s[52:53] offset:128
	s_add_u32 s52, s52, 4096
	s_addc_u32 s53, s53, 0
	global_store_dword v139, v100, s[52:53]
	global_store_dword v139, v101, s[52:53] offset:128
	s_add_u32 s52, s52, 4096
	s_addc_u32 s53, s53, 0
	global_store_dword v139, v102, s[52:53]
	global_store_dword v139, v103, s[52:53] offset:128
	s_add_u32 s52, s52, 4096
	s_addc_u32 s53, s53, 0
	global_store_dword v139, v104, s[52:53]
	global_store_dword v139, v105, s[52:53] offset:128
	s_add_u32 s52, s52, 20480
	s_addc_u32 s53, s53, 0
	global_store_dword v139, v106, s[52:53]
	global_store_dword v139, v107, s[52:53] offset:128
	s_add_u32 s52, s52, 4096
	s_addc_u32 s53, s53, 0
	global_store_dword v139, v108, s[52:53]
	global_store_dword v139, v109, s[52:53] offset:128
	s_add_u32 s52, s52, 4096
	s_addc_u32 s53, s53, 0
	global_store_dword v139, v110, s[52:53]
	global_store_dword v139, v111, s[52:53] offset:128
	s_add_u32 s52, s52, 4096
	s_addc_u32 s53, s53, 0
	global_store_dword v139, v112, s[52:53]
	global_store_dword v139, v113, s[52:53] offset:128
	s_add_u32 s52, s52, 20480
	s_addc_u32 s53, s53, 0
	global_store_dword v139, v114, s[52:53]
	global_store_dword v139, v115, s[52:53] offset:128
	s_add_u32 s52, s52, 4096
	s_addc_u32 s53, s53, 0
	global_store_dword v139, v116, s[52:53]
	global_store_dword v139, v117, s[52:53] offset:128
	s_add_u32 s52, s52, 4096
	s_addc_u32 s53, s53, 0
	global_store_dword v139, v118, s[52:53]
	global_store_dword v139, v119, s[52:53] offset:128
	s_add_u32 s52, s52, 4096
	s_addc_u32 s53, s53, 0
	global_store_dword v139, v120, s[52:53]
	global_store_dword v139, v121, s[52:53] offset:128
	s_add_u32 s52, s52, 20480
	s_addc_u32 s53, s53, 0
	global_store_dword v139, v122, s[52:53]
	global_store_dword v139, v123, s[52:53] offset:128
	s_add_u32 s52, s52, 4096
	s_addc_u32 s53, s53, 0
	global_store_dword v139, v124, s[52:53]
	global_store_dword v139, v134, s[52:53] offset:128
	s_add_u32 s52, s52, 4096
	s_addc_u32 s53, s53, 0
	global_store_dword v139, v135, s[52:53]
	global_store_dword v139, v136, s[52:53] offset:128
	s_add_u32 s52, s52, 4096
	s_addc_u32 s53, s53, 0
	global_store_dword v139, v137, s[52:53]
	global_store_dword v139, v138, s[52:53] offset:128
	v_readlane_b32 s14, v243, 7
	s_branch .LBB0_1262

; __global__ void __launch_bounds__(NTHR, 2) fwd_megakernel(Params p0) {
;   __shared__ __attribute__((aligned(16))) char lds[65536];
	.amdhsa_kernel _Z14fwd_megakernel6Params
		.amdhsa_group_segment_fixed_size 73856
		.amdhsa_private_segment_fixed_size 0
		.amdhsa_kernarg_size 512
		.amdhsa_user_sgpr_count 2
		.amdhsa_user_sgpr_dispatch_ptr 0
		.amdhsa_user_sgpr_queue_ptr 0
		.amdhsa_user_sgpr_kernarg_segment_ptr 1
		.amdhsa_user_sgpr_dispatch_id 0
		.amdhsa_user_sgpr_kernarg_preload_length 0
		.amdhsa_user_sgpr_kernarg_preload_offset 0
		.amdhsa_user_sgpr_private_segment_size 0
		.amdhsa_uses_dynamic_stack 0
		.amdhsa_enable_private_segment 0
		.amdhsa_system_sgpr_workgroup_id_x 1
		.amdhsa_system_sgpr_workgroup_id_y 0
		.amdhsa_system_sgpr_workgroup_id_z 0
		.amdhsa_system_sgpr_workgroup_info 0
		.amdhsa_system_vgpr_workitem_id 2
		.amdhsa_next_free_vgpr 256
		.amdhsa_next_free_sgpr 100
		.amdhsa_accum_offset 256
		.amdhsa_reserve_vcc 1
		.amdhsa_float_round_mode_32 0
		.amdhsa_float_round_mode_16_64 0
		.amdhsa_float_denorm_mode_32 3
		.amdhsa_float_denorm_mode_16_64 3
		.amdhsa_dx10_clamp 1
		.amdhsa_ieee_mode 1
		.amdhsa_fp16_overflow 0
		.amdhsa_tg_split 0
		.amdhsa_exception_fp_ieee_invalid_op 0
		.amdhsa_exception_fp_denorm_src 0
		.amdhsa_exception_fp_ieee_div_zero 0
		.amdhsa_exception_fp_ieee_overflow 0
		.amdhsa_exception_fp_ieee_underflow 0
		.amdhsa_exception_fp_ieee_inexact 0
		.amdhsa_exception_int_div_zero 0
	.end_amdhsa_kernel

; __global__ void __launch_bounds__(NTHR, 2) fwd_megakernel(Params p0) {
;   __shared__ __attribute__((aligned(16))) char lds[65536];
amdhsa.kernels:
  - .agpr_count:     0
    .args:
      - .offset:         0
        .size:           256
        .value_kind:     by_value
      - .offset:         256
        .size:           4
        .value_kind:     hidden_block_count_x
      - .offset:         260
        .size:           4
        .value_kind:     hidden_block_count_y
      - .offset:         264
        .size:           4
        .value_kind:     hidden_block_count_z
      - .offset:         268
        .size:           2
        .value_kind:     hidden_group_size_x
      - .offset:         270
        .size:           2
        .value_kind:     hidden_group_size_y
      - .offset:         272
        .size:           2
        .value_kind:     hidden_group_size_z
      - .offset:         274
        .size:           2
        .value_kind:     hidden_remainder_x
      - .offset:         276
        .size:           2
        .value_kind:     hidden_remainder_y
      - .offset:         278
        .size:           2
        .value_kind:     hidden_remainder_z
      - .offset:         296
        .size:           8
        .value_kind:     hidden_global_offset_x
      - .offset:         304
        .size:           8
        .value_kind:     hidden_global_offset_y
      - .offset:         312
        .size:           8
        .value_kind:     hidden_global_offset_z
      - .offset:         320
        .size:           2
        .value_kind:     hidden_grid_dims
      - .offset:         344
        .size:           8
        .value_kind:     hidden_multigrid_sync_arg
    .group_segment_fixed_size: 73856
    .kernarg_segment_align: 8
    .kernarg_segment_size: 512
    .language:       OpenCL C
    .language_version:
      - 2
      - 0
    .max_flat_workgroup_size: 256
    .name:           _Z14fwd_megakernel6Params
    .private_segment_fixed_size: 0
    .sgpr_count:     106
    .sgpr_spill_count: 192
    .symbol:         _Z14fwd_megakernel6Params.kd
    .uniform_work_group_size: 1
    .uses_dynamic_stack: false
    .vgpr_count:     256
    .vgpr_spill_count: 0
    .wavefront_size: 64
